# norm fix + loader-priority flips (setprio 1 during load segments, 0 during MFMA blocks)
# baseline (speedup 1.0000x reference)
.LBB0_261:
	s_ashr_i32 s75, s74, 31
	s_lshl_b64 s[40:41], s[74:75], 20
	s_add_u32 s76, s58, s40
	ds_read_b128 v[2:5], v156
	ds_read_b128 v[6:9], v156 offset:1024
	ds_read_b128 v[10:13], v156 offset:2048
	ds_read_b128 v[14:17], v156 offset:3072
	ds_read_b128 v[18:21], v157
	ds_read_b128 v[22:25], v157 offset:1024
	ds_read_b128 v[26:29], v157 offset:2048
	ds_read_b128 v[30:33], v157 offset:3072
	s_addc_u32 s77, s59, s41
	s_ashr_i32 s73, s72, 31
	s_lshl_b64 s[40:41], s[72:73], 20
	s_add_u32 s78, s84, s40
	s_addc_u32 s79, s85, s41
	s_and_b64 s[40:41], s[8:9], exec
	s_cselect_b32 s3, s77, s83
	s_cselect_b32 s11, s76, s82
	s_cselect_b32 s13, s79, s81
	s_cselect_b32 s42, s78, s80
	v_lshl_add_u64 v[138:139], s[82:83], 0, v[140:141]
	s_mov_b32 m0, s89
	v_lshl_add_u64 v[66:67], v[138:139], 0, s[20:21]
	ds_read_b128 v[34:37], v158
	ds_read_b128 v[38:41], v158 offset:1024
	ds_read_b128 v[42:45], v158 offset:2048
	ds_read_b128 v[46:49], v158 offset:3072
	ds_read_b128 v[50:53], v158 offset:4096
	ds_read_b128 v[54:57], v158 offset:5120
	ds_read_b128 v[58:61], v158 offset:6144
	ds_read_b128 v[62:65], v158 offset:7168
	global_load_lds_dwordx4 v[66:67], off
	v_lshl_add_u64 v[66:67], v[138:139], 0, s[22:23]
	s_mov_b32 m0, s45
	s_nop 0
	global_load_lds_dwordx4 v[66:67], off
	s_waitcnt vmcnt(24)
	s_waitcnt lgkmcnt(0)
	s_barrier
	s_waitcnt lgkmcnt(0)
	s_setprio 0
	v_mfma_f32_16x16x32_bf16 v[86:89], v[10:13], v[50:53], 0
	v_mfma_f32_16x16x32_bf16 v[90:93], v[14:17], v[54:57], v[86:89]
	v_mfma_f32_16x16x32_bf16 v[86:89], v[2:5], v[58:61], 0
	v_mfma_f32_16x16x32_bf16 v[66:69], v[2:5], v[34:37], 0
	v_mfma_f32_16x16x32_bf16 v[70:73], v[10:13], v[34:37], 0
	v_mfma_f32_16x16x32_bf16 v[74:77], v[2:5], v[42:45], 0
	v_mfma_f32_16x16x32_bf16 v[78:81], v[10:13], v[42:45], 0
	v_mfma_f32_16x16x32_bf16 v[82:85], v[2:5], v[50:53], 0
	v_mfma_f32_16x16x32_bf16 v[94:97], v[6:9], v[62:65], v[86:89]
	v_mfma_f32_16x16x32_bf16 v[86:89], v[10:13], v[58:61], 0
	v_mfma_f32_16x16x32_bf16 v[66:69], v[6:9], v[38:41], v[66:69]
	v_mfma_f32_16x16x32_bf16 v[70:73], v[14:17], v[38:41], v[70:73]
	v_mfma_f32_16x16x32_bf16 v[74:77], v[6:9], v[46:49], v[74:77]
	v_mfma_f32_16x16x32_bf16 v[78:81], v[14:17], v[46:49], v[78:81]
	v_mfma_f32_16x16x32_bf16 v[82:85], v[6:9], v[54:57], v[82:85]
	v_mfma_f32_16x16x32_bf16 v[106:109], v[14:17], v[62:65], v[86:89]
	v_mfma_f32_16x16x32_bf16 v[86:89], v[18:21], v[34:37], 0
	v_mfma_f32_16x16x32_bf16 v[34:37], v[26:29], v[34:37], 0
	v_mfma_f32_16x16x32_bf16 v[110:113], v[22:25], v[38:41], v[86:89]
	v_mfma_f32_16x16x32_bf16 v[34:37], v[30:33], v[38:41], v[34:37]
	v_mfma_f32_16x16x32_bf16 v[38:41], v[18:21], v[42:45], 0
	v_mfma_f32_16x16x32_bf16 v[42:45], v[26:29], v[42:45], 0
	v_mfma_f32_16x16x32_bf16 v[38:41], v[22:25], v[46:49], v[38:41]
	v_mfma_f32_16x16x32_bf16 v[42:45], v[30:33], v[46:49], v[42:45]
	v_mfma_f32_16x16x32_bf16 v[46:49], v[18:21], v[50:53], 0
	v_mfma_f32_16x16x32_bf16 v[50:53], v[26:29], v[50:53], 0
	v_mfma_f32_16x16x32_bf16 v[46:49], v[22:25], v[54:57], v[46:49]
	v_mfma_f32_16x16x32_bf16 v[50:53], v[30:33], v[54:57], v[50:53]
	v_mfma_f32_16x16x32_bf16 v[54:57], v[18:21], v[58:61], 0
	v_mfma_f32_16x16x32_bf16 v[58:61], v[26:29], v[58:61], 0
	v_mfma_f32_16x16x32_bf16 v[54:57], v[22:25], v[62:65], v[54:57]
	v_mfma_f32_16x16x32_bf16 v[58:61], v[30:33], v[62:65], v[58:61]
	s_setprio 1
	s_barrier
	v_lshl_add_u64 v[154:155], s[80:81], 0, v[142:143]
	s_add_i32 s43, s62, s88
	v_lshl_add_u64 v[130:131], v[154:155], 0, s[24:25]
	s_mov_b32 m0, s43
	s_add_i32 s53, s43, 0x2000
	ds_read_b128 v[62:65], v158 offset:16384
	ds_read_b128 v[86:89], v158 offset:17408
	ds_read_b128 v[98:101], v158 offset:18432
	ds_read_b128 v[102:105], v158 offset:19456
	ds_read_b128 v[114:117], v158 offset:20480
	ds_read_b128 v[118:121], v158 offset:21504
	ds_read_b128 v[122:125], v158 offset:22528
	ds_read_b128 v[126:129], v158 offset:23552
	global_load_lds_dwordx4 v[130:131], off
	v_lshl_add_u64 v[130:131], v[154:155], 0, s[26:27]
	s_mov_b32 m0, s53
	s_add_i32 s73, s63, s88
	global_load_lds_dwordx4 v[130:131], off
	v_lshl_add_u64 v[130:131], v[154:155], 0, s[28:29]
	s_mov_b32 m0, s73
	s_add_i32 s40, s73, 0x2000
	global_load_lds_dwordx4 v[130:131], off
	v_lshl_add_u64 v[130:131], v[154:155], 0, s[30:31]
	s_mov_b32 m0, s40
	s_nop 0
	global_load_lds_dwordx4 v[130:131], off
	v_lshl_add_u64 v[130:131], v[138:139], 0, s[24:25]
	s_mov_b32 m0, s44
	s_nop 0
	global_load_lds_dwordx4 v[130:131], off
	v_lshl_add_u64 v[130:131], v[138:139], 0, s[26:27]
	s_mov_b32 m0, s90
	s_nop 0
	global_load_lds_dwordx4 v[130:131], off
	s_waitcnt vmcnt(24)
	s_waitcnt lgkmcnt(0)
	s_barrier
	s_waitcnt lgkmcnt(0)
	s_setprio 0
	v_mfma_f32_16x16x32_bf16 v[130:133], v[2:5], v[62:65], 0
	v_mfma_f32_16x16x32_bf16 v[150:153], v[2:5], v[98:101], 0
	v_mfma_f32_16x16x32_bf16 v[170:173], v[2:5], v[114:117], 0
	v_mfma_f32_16x16x32_bf16 v[2:5], v[2:5], v[122:125], 0
	v_mfma_f32_16x16x32_bf16 v[130:133], v[6:9], v[86:89], v[130:133]
	v_mfma_f32_16x16x32_bf16 v[150:153], v[6:9], v[102:105], v[150:153]
	v_mfma_f32_16x16x32_bf16 v[170:173], v[6:9], v[118:121], v[170:173]
	v_mfma_f32_16x16x32_bf16 v[2:5], v[6:9], v[126:129], v[2:5]
	v_mfma_f32_16x16x32_bf16 v[6:9], v[10:13], v[122:125], 0
	v_mfma_f32_16x16x32_bf16 v[134:137], v[10:13], v[62:65], 0
	v_mfma_f32_16x16x32_bf16 v[166:169], v[10:13], v[98:101], 0
	v_mfma_f32_16x16x32_bf16 v[174:177], v[10:13], v[114:117], 0
	v_mfma_f32_16x16x32_bf16 v[6:9], v[14:17], v[126:129], v[6:9]
	v_mfma_f32_16x16x32_bf16 v[134:137], v[14:17], v[86:89], v[134:137]
	v_mfma_f32_16x16x32_bf16 v[166:169], v[14:17], v[102:105], v[166:169]
	v_mfma_f32_16x16x32_bf16 v[174:177], v[14:17], v[118:121], v[174:177]
	v_mfma_f32_16x16x32_bf16 v[10:13], v[18:21], v[62:65], 0
	v_mfma_f32_16x16x32_bf16 v[14:17], v[26:29], v[62:65], 0
	v_mfma_f32_16x16x32_bf16 v[62:65], v[18:21], v[98:101], 0
	v_mfma_f32_16x16x32_bf16 v[178:181], v[22:25], v[102:105], v[62:65]
	v_mfma_f32_16x16x32_bf16 v[62:65], v[26:29], v[98:101], 0
	v_mfma_f32_16x16x32_bf16 v[182:185], v[30:33], v[102:105], v[62:65]
	v_mfma_f32_16x16x32_bf16 v[62:65], v[18:21], v[114:117], 0
	v_mfma_f32_16x16x32_bf16 v[18:21], v[18:21], v[122:125], 0
	v_mfma_f32_16x16x32_bf16 v[10:13], v[22:25], v[86:89], v[10:13]
	v_mfma_f32_16x16x32_bf16 v[14:17], v[30:33], v[86:89], v[14:17]
	v_mfma_f32_16x16x32_bf16 v[186:189], v[22:25], v[118:121], v[62:65]
	v_mfma_f32_16x16x32_bf16 v[62:65], v[26:29], v[114:117], 0
	v_mfma_f32_16x16x32_bf16 v[194:197], v[22:25], v[126:129], v[18:21]
	v_mfma_f32_16x16x32_bf16 v[18:21], v[26:29], v[122:125], 0
	v_mfma_f32_16x16x32_bf16 v[190:193], v[30:33], v[118:121], v[62:65]
	v_mfma_f32_16x16x32_bf16 v[198:201], v[30:33], v[126:129], v[18:21]
	s_setprio 1
	s_barrier
	ds_read_b128 v[26:29], v159
	ds_read_b128 v[30:33], v159 offset:1024
	s_nop 0
	ds_read_b128 v[62:65], v159 offset:2048
	ds_read_b128 v[202:205], v159 offset:3072
	ds_read_b128 v[206:209], v160
	ds_read_b128 v[210:213], v160 offset:1024
	ds_read_b128 v[214:217], v160 offset:2048
	ds_read_b128 v[218:221], v160 offset:3072
	s_mov_b32 m0, s91
	v_lshl_add_u64 v[86:87], v[138:139], 0, s[28:29]
	ds_read_b128 v[18:21], v158 offset:32768
	ds_read_b128 v[22:25], v158 offset:33792
	ds_read_b128 v[222:225], v158 offset:34816
	ds_read_b128 v[226:229], v158 offset:35840
	ds_read_b128 v[230:233], v158 offset:36864
	ds_read_b128 v[234:237], v158 offset:37888
	ds_read_b128 v[238:241], v158 offset:38912
	ds_read_b128 v[242:245], v158 offset:39936
	global_load_lds_dwordx4 v[86:87], off
	v_lshl_add_u64 v[86:87], v[138:139], 0, s[30:31]
	s_mov_b32 m0, s92
	s_nop 0
	global_load_lds_dwordx4 v[86:87], off
	s_waitcnt vmcnt(8)
	s_waitcnt lgkmcnt(0)
	s_barrier
	s_waitcnt lgkmcnt(0)
	s_setprio 0
	v_mfma_f32_16x16x32_bf16 v[66:69], v[26:29], v[18:21], v[66:69]
	v_mfma_f32_16x16x32_bf16 v[118:121], v[30:33], v[22:25], v[66:69]
	v_mfma_f32_16x16x32_bf16 v[66:69], v[62:65], v[18:21], v[70:73]
	v_mfma_f32_16x16x32_bf16 v[114:117], v[202:205], v[22:25], v[66:69]
	v_mfma_f32_16x16x32_bf16 v[66:69], v[26:29], v[222:225], v[74:77]
	v_mfma_f32_16x16x32_bf16 v[102:105], v[30:33], v[226:229], v[66:69]
	v_mfma_f32_16x16x32_bf16 v[66:69], v[62:65], v[222:225], v[78:81]
	v_mfma_f32_16x16x32_bf16 v[98:101], v[202:205], v[226:229], v[66:69]
	v_mfma_f32_16x16x32_bf16 v[66:69], v[26:29], v[230:233], v[82:85]
	v_mfma_f32_16x16x32_bf16 v[86:89], v[30:33], v[234:237], v[66:69]
	v_mfma_f32_16x16x32_bf16 v[66:69], v[62:65], v[230:233], v[90:93]
	v_mfma_f32_16x16x32_bf16 v[82:85], v[202:205], v[234:237], v[66:69]
	v_mfma_f32_16x16x32_bf16 v[66:69], v[26:29], v[238:241], v[94:97]
	v_mfma_f32_16x16x32_bf16 v[70:73], v[62:65], v[238:241], v[106:109]
	v_mfma_f32_16x16x32_bf16 v[66:69], v[30:33], v[242:245], v[66:69]
	v_mfma_f32_16x16x32_bf16 v[70:73], v[202:205], v[242:245], v[70:73]
	v_mfma_f32_16x16x32_bf16 v[74:77], v[206:209], v[18:21], v[110:113]
	v_mfma_f32_16x16x32_bf16 v[18:21], v[214:217], v[18:21], v[34:37]
	v_mfma_f32_16x16x32_bf16 v[122:125], v[218:221], v[22:25], v[18:21]
	v_mfma_f32_16x16x32_bf16 v[18:21], v[206:209], v[222:225], v[38:41]
	v_mfma_f32_16x16x32_bf16 v[110:113], v[210:213], v[226:229], v[18:21]
	v_mfma_f32_16x16x32_bf16 v[18:21], v[214:217], v[222:225], v[42:45]
	v_mfma_f32_16x16x32_bf16 v[106:109], v[218:221], v[226:229], v[18:21]
	v_mfma_f32_16x16x32_bf16 v[18:21], v[206:209], v[230:233], v[46:49]
	v_mfma_f32_16x16x32_bf16 v[94:97], v[210:213], v[234:237], v[18:21]
	v_mfma_f32_16x16x32_bf16 v[18:21], v[214:217], v[230:233], v[50:53]
	v_mfma_f32_16x16x32_bf16 v[90:93], v[218:221], v[234:237], v[18:21]
	v_mfma_f32_16x16x32_bf16 v[18:21], v[206:209], v[238:241], v[54:57]
	v_mfma_f32_16x16x32_bf16 v[126:129], v[210:213], v[22:25], v[74:77]
	v_mfma_f32_16x16x32_bf16 v[74:77], v[210:213], v[242:245], v[18:21]
	v_mfma_f32_16x16x32_bf16 v[18:21], v[214:217], v[238:241], v[58:61]
	v_mfma_f32_16x16x32_bf16 v[78:81], v[218:221], v[242:245], v[18:21]
	s_setprio 1
	s_barrier
; #define PG8_WAIT_V(n) asm volatile("s_waitcnt vmcnt(" #n ")" ::: "memory")
; template <class Epi, class Sched, bool ALIGN_EPI = true, bool SP2 = true, bool FULLLINE = false, bool NOSTAGE = false, bool FP8 = false>
; __device__ __forceinline__ void gemm_phase(PG8_LAS unsigned char* lds, const Gemm g, const Sched& S, const Epi& E) {
;     ...
;         static_assert(SP2, "only the SP2 loop is kept");
;         { const int t = 0; if constexpr (Epi::NST == 16) PG8_ITER(PG8_WAIT_V(24)); else if constexpr (Epi::NST == 8) PG8_ITER(PG8_WAIT_V(16)); else PG8_ITER(PG8_WAIT_V(8)); }
;         for (int t = 2; t < nt; t += 2) PG8_ITER(PG8_WAIT_V(8));
	s_add_i32 s41, s46, s88
	s_nop 4
	v_lshl_add_u64 v[18:19], v[154:155], 0, s[34:35]
	s_mov_b32 m0, s41
	s_add_i32 s50, s41, 0x2000
	ds_read_b128 v[42:45], v158 offset:49152
	ds_read_b128 v[46:49], v158 offset:50176
	ds_read_b128 v[222:225], v158 offset:51200
	ds_read_b128 v[226:229], v158 offset:52224
	ds_read_b128 v[230:233], v158 offset:53248
	ds_read_b128 v[234:237], v158 offset:54272
	ds_read_b128 v[238:241], v158 offset:55296
	ds_read_b128 v[242:245], v158 offset:56320
	global_load_lds_dwordx4 v[18:19], off
	v_lshl_add_u64 v[18:19], v[154:155], 0, s[36:37]
	s_mov_b32 m0, s50
	s_mov_b64 s[56:57], 0x80180
	s_add_i32 s51, s47, s88
	global_load_lds_dwordx4 v[18:19], off
	v_lshl_add_u64 v[18:19], v[154:155], 0, s[56:57]
	s_mov_b32 m0, s51
	s_mov_b64 s[56:57], 0xc0180
	s_add_i32 s33, s51, 0x2000
	global_load_lds_dwordx4 v[18:19], off
	v_lshl_add_u64 v[18:19], v[154:155], 0, s[56:57]
	s_mov_b32 m0, s33
	s_nop 0
	global_load_lds_dwordx4 v[18:19], off
	v_lshl_add_u64 v[18:19], v[138:139], 0, s[34:35]
	s_mov_b32 m0, s93
	s_nop 0
	global_load_lds_dwordx4 v[18:19], off
	v_lshl_add_u64 v[18:19], v[138:139], 0, s[36:37]
	s_mov_b32 m0, s94
	s_nop 0
	global_load_lds_dwordx4 v[18:19], off
	s_waitcnt vmcnt(8)
	s_waitcnt lgkmcnt(0)
	s_barrier
	s_waitcnt lgkmcnt(0)
	s_setprio 0
	v_mfma_f32_16x16x32_bf16 v[18:21], v[26:29], v[42:45], v[130:133]
	v_mfma_f32_16x16x32_bf16 v[50:53], v[30:33], v[46:49], v[18:21]
	v_mfma_f32_16x16x32_bf16 v[18:21], v[62:65], v[42:45], v[134:137]
	v_mfma_f32_16x16x32_bf16 v[54:57], v[202:205], v[46:49], v[18:21]
	v_mfma_f32_16x16x32_bf16 v[18:21], v[26:29], v[222:225], v[150:153]
	v_mfma_f32_16x16x32_bf16 v[34:37], v[30:33], v[226:229], v[18:21]
	v_mfma_f32_16x16x32_bf16 v[18:21], v[62:65], v[222:225], v[166:169]
	v_mfma_f32_16x16x32_bf16 v[38:41], v[202:205], v[226:229], v[18:21]
	v_mfma_f32_16x16x32_bf16 v[18:21], v[26:29], v[230:233], v[170:173]
	v_mfma_f32_16x16x32_bf16 v[22:25], v[62:65], v[230:233], v[174:177]
	v_mfma_f32_16x16x32_bf16 v[2:5], v[26:29], v[238:241], v[2:5]
	v_mfma_f32_16x16x32_bf16 v[6:9], v[62:65], v[238:241], v[6:9]
	v_mfma_f32_16x16x32_bf16 v[18:21], v[30:33], v[234:237], v[18:21]
	v_mfma_f32_16x16x32_bf16 v[22:25], v[202:205], v[234:237], v[22:25]
	v_mfma_f32_16x16x32_bf16 v[2:5], v[30:33], v[242:245], v[2:5]
	v_mfma_f32_16x16x32_bf16 v[6:9], v[202:205], v[242:245], v[6:9]
	v_mfma_f32_16x16x32_bf16 v[10:13], v[206:209], v[42:45], v[10:13]
	v_mfma_f32_16x16x32_bf16 v[58:61], v[210:213], v[46:49], v[10:13]
	v_mfma_f32_16x16x32_bf16 v[10:13], v[214:217], v[42:45], v[14:17]
	v_mfma_f32_16x16x32_bf16 v[62:65], v[218:221], v[46:49], v[10:13]
	v_mfma_f32_16x16x32_bf16 v[10:13], v[206:209], v[222:225], v[178:181]
	v_mfma_f32_16x16x32_bf16 v[42:45], v[210:213], v[226:229], v[10:13]
	v_mfma_f32_16x16x32_bf16 v[10:13], v[214:217], v[222:225], v[182:185]
	v_mfma_f32_16x16x32_bf16 v[46:49], v[218:221], v[226:229], v[10:13]
	v_mfma_f32_16x16x32_bf16 v[10:13], v[206:209], v[230:233], v[186:189]
	v_mfma_f32_16x16x32_bf16 v[26:29], v[210:213], v[234:237], v[10:13]
	v_mfma_f32_16x16x32_bf16 v[10:13], v[214:217], v[230:233], v[190:193]
	v_mfma_f32_16x16x32_bf16 v[30:33], v[218:221], v[234:237], v[10:13]
	v_mfma_f32_16x16x32_bf16 v[10:13], v[206:209], v[238:241], v[194:197]
	v_mfma_f32_16x16x32_bf16 v[14:17], v[214:217], v[238:241], v[198:201]
	v_mfma_f32_16x16x32_bf16 v[10:13], v[210:213], v[242:245], v[10:13]
	v_mfma_f32_16x16x32_bf16 v[14:17], v[218:221], v[242:245], v[14:17]
	s_setprio 1
	s_barrier
	s_add_u32 s82, s82, 0x80180
	s_addc_u32 s83, s83, 0
	s_add_u32 s56, s80, 0x200
	s_addc_u32 s57, s81, 0
	s_mov_b32 s75, 0
.LBB0_262:
	ds_read_b128 v[130:133], v156
	ds_read_b128 v[134:137], v156 offset:1024
	ds_read_b128 v[150:153], v156 offset:2048
	ds_read_b128 v[166:169], v156 offset:3072
	ds_read_b128 v[170:173], v157
	ds_read_b128 v[174:177], v157 offset:1024
	ds_read_b128 v[178:181], v157 offset:2048
	ds_read_b128 v[182:185], v157 offset:3072
	s_add_u32 s0, s82, 0xfff80080
	s_addc_u32 s1, s83, -1
	s_cmp_eq_u32 s75, 28
	s_cselect_b32 s81, s3, s1
	s_cselect_b32 s80, s11, s0
	s_cselect_b32 vcc_hi, s13, s57
	s_cselect_b32 vcc_lo, s42, s56
	s_mov_b32 m0, s89
	v_lshl_add_u64 v[138:139], s[82:83], 0, v[144:145]
	ds_read_b128 v[186:189], v158
	ds_read_b128 v[190:193], v158 offset:1024
	ds_read_b128 v[194:197], v158 offset:2048
	ds_read_b128 v[198:201], v158 offset:3072
	ds_read_b128 v[202:205], v158 offset:4096
	ds_read_b128 v[206:209], v158 offset:5120
	ds_read_b128 v[210:213], v158 offset:6144
	ds_read_b128 v[214:217], v158 offset:7168
	global_load_lds_dwordx4 v[138:139], off
	v_lshl_add_u64 v[138:139], v[138:139], 0, s[38:39]
	s_mov_b32 m0, s45
	s_nop 0
	global_load_lds_dwordx4 v[138:139], off
	s_waitcnt vmcnt(8)
	s_waitcnt lgkmcnt(0)
	s_barrier
	s_waitcnt lgkmcnt(0)
	s_setprio 0
	v_mfma_f32_16x16x32_bf16 v[118:121], v[130:133], v[186:189], v[118:121]
	v_mfma_f32_16x16x32_bf16 v[114:117], v[150:153], v[186:189], v[114:117]
	v_mfma_f32_16x16x32_bf16 v[102:105], v[130:133], v[194:197], v[102:105]
	v_mfma_f32_16x16x32_bf16 v[98:101], v[150:153], v[194:197], v[98:101]
	v_mfma_f32_16x16x32_bf16 v[86:89], v[130:133], v[202:205], v[86:89]
	v_mfma_f32_16x16x32_bf16 v[82:85], v[150:153], v[202:205], v[82:85]
	v_mfma_f32_16x16x32_bf16 v[66:69], v[130:133], v[210:213], v[66:69]
	v_mfma_f32_16x16x32_bf16 v[70:73], v[150:153], v[210:213], v[70:73]
	v_mfma_f32_16x16x32_bf16 v[118:121], v[134:137], v[190:193], v[118:121]
	v_mfma_f32_16x16x32_bf16 v[114:117], v[166:169], v[190:193], v[114:117]
	v_mfma_f32_16x16x32_bf16 v[102:105], v[134:137], v[198:201], v[102:105]
	v_mfma_f32_16x16x32_bf16 v[98:101], v[166:169], v[198:201], v[98:101]
	v_mfma_f32_16x16x32_bf16 v[86:89], v[134:137], v[206:209], v[86:89]
	v_mfma_f32_16x16x32_bf16 v[82:85], v[166:169], v[206:209], v[82:85]
	v_mfma_f32_16x16x32_bf16 v[66:69], v[134:137], v[214:217], v[66:69]
	v_mfma_f32_16x16x32_bf16 v[70:73], v[166:169], v[214:217], v[70:73]
	v_mfma_f32_16x16x32_bf16 v[126:129], v[170:173], v[186:189], v[126:129]
	v_mfma_f32_16x16x32_bf16 v[122:125], v[178:181], v[186:189], v[122:125]
	v_mfma_f32_16x16x32_bf16 v[110:113], v[170:173], v[194:197], v[110:113]
	v_mfma_f32_16x16x32_bf16 v[106:109], v[178:181], v[194:197], v[106:109]
	v_mfma_f32_16x16x32_bf16 v[94:97], v[170:173], v[202:205], v[94:97]
	v_mfma_f32_16x16x32_bf16 v[90:93], v[178:181], v[202:205], v[90:93]
	v_mfma_f32_16x16x32_bf16 v[74:77], v[170:173], v[210:213], v[74:77]
	v_mfma_f32_16x16x32_bf16 v[78:81], v[178:181], v[210:213], v[78:81]
	v_mfma_f32_16x16x32_bf16 v[126:129], v[174:177], v[190:193], v[126:129]
	v_mfma_f32_16x16x32_bf16 v[122:125], v[182:185], v[190:193], v[122:125]
	v_mfma_f32_16x16x32_bf16 v[110:113], v[174:177], v[198:201], v[110:113]
	v_mfma_f32_16x16x32_bf16 v[106:109], v[182:185], v[198:201], v[106:109]
	v_mfma_f32_16x16x32_bf16 v[94:97], v[174:177], v[206:209], v[94:97]
	v_mfma_f32_16x16x32_bf16 v[90:93], v[182:185], v[206:209], v[90:93]
	v_mfma_f32_16x16x32_bf16 v[74:77], v[174:177], v[214:217], v[74:77]
	v_mfma_f32_16x16x32_bf16 v[78:81], v[182:185], v[214:217], v[78:81]
	s_setprio 1
	s_barrier
	s_mov_b32 m0, s43
	v_lshl_add_u64 v[138:139], vcc, 0, v[142:143]
	ds_read_b128 v[186:189], v158 offset:16384
	ds_read_b128 v[190:193], v158 offset:17408
	ds_read_b128 v[194:197], v158 offset:18432
	ds_read_b128 v[198:201], v158 offset:19456
	ds_read_b128 v[202:205], v158 offset:20480
	ds_read_b128 v[206:209], v158 offset:21504
	ds_read_b128 v[210:213], v158 offset:22528
	ds_read_b128 v[214:217], v158 offset:23552
	global_load_lds_dwordx4 v[138:139], off
	v_lshl_add_u64 v[154:155], v[138:139], 0, s[38:39]
	s_mov_b32 m0, s53
	s_nop 0
	global_load_lds_dwordx4 v[154:155], off
	v_lshl_add_u64 v[154:155], v[138:139], 0, s[60:61]
	s_mov_b32 m0, s73
	s_nop 0
	global_load_lds_dwordx4 v[154:155], off
	v_lshl_add_u64 v[154:155], v[138:139], 0, s[66:67]
	s_mov_b32 m0, s40
	s_nop 0
	global_load_lds_dwordx4 v[154:155], off
	v_lshl_add_u64 v[154:155], s[80:81], 0, v[140:141]
	s_mov_b32 m0, s44
	v_lshl_add_u64 v[218:219], v[154:155], 0, s[38:39]
	global_load_lds_dwordx4 v[154:155], off
	s_mov_b32 m0, s90
	s_nop 0
	global_load_lds_dwordx4 v[218:219], off
	s_waitcnt vmcnt(8)
	s_waitcnt lgkmcnt(0)
	s_barrier
	s_waitcnt lgkmcnt(0)
	s_setprio 0
	v_mfma_f32_16x16x32_bf16 v[50:53], v[130:133], v[186:189], v[50:53]
	v_mfma_f32_16x16x32_bf16 v[54:57], v[150:153], v[186:189], v[54:57]
	v_mfma_f32_16x16x32_bf16 v[34:37], v[130:133], v[194:197], v[34:37]
	v_mfma_f32_16x16x32_bf16 v[38:41], v[150:153], v[194:197], v[38:41]
	v_mfma_f32_16x16x32_bf16 v[18:21], v[130:133], v[202:205], v[18:21]
	v_mfma_f32_16x16x32_bf16 v[22:25], v[150:153], v[202:205], v[22:25]
	v_mfma_f32_16x16x32_bf16 v[2:5], v[130:133], v[210:213], v[2:5]
	v_mfma_f32_16x16x32_bf16 v[6:9], v[150:153], v[210:213], v[6:9]
	v_mfma_f32_16x16x32_bf16 v[50:53], v[134:137], v[190:193], v[50:53]
	v_mfma_f32_16x16x32_bf16 v[54:57], v[166:169], v[190:193], v[54:57]
	v_mfma_f32_16x16x32_bf16 v[34:37], v[134:137], v[198:201], v[34:37]
	v_mfma_f32_16x16x32_bf16 v[38:41], v[166:169], v[198:201], v[38:41]
	v_mfma_f32_16x16x32_bf16 v[18:21], v[134:137], v[206:209], v[18:21]
	v_mfma_f32_16x16x32_bf16 v[22:25], v[166:169], v[206:209], v[22:25]
	v_mfma_f32_16x16x32_bf16 v[2:5], v[134:137], v[214:217], v[2:5]
	v_mfma_f32_16x16x32_bf16 v[6:9], v[166:169], v[214:217], v[6:9]
	v_mfma_f32_16x16x32_bf16 v[58:61], v[170:173], v[186:189], v[58:61]
	v_mfma_f32_16x16x32_bf16 v[62:65], v[178:181], v[186:189], v[62:65]
	v_mfma_f32_16x16x32_bf16 v[42:45], v[170:173], v[194:197], v[42:45]
	v_mfma_f32_16x16x32_bf16 v[46:49], v[178:181], v[194:197], v[46:49]
	v_mfma_f32_16x16x32_bf16 v[26:29], v[170:173], v[202:205], v[26:29]
	v_mfma_f32_16x16x32_bf16 v[30:33], v[178:181], v[202:205], v[30:33]
	v_mfma_f32_16x16x32_bf16 v[10:13], v[170:173], v[210:213], v[10:13]
	v_mfma_f32_16x16x32_bf16 v[14:17], v[178:181], v[210:213], v[14:17]
	v_mfma_f32_16x16x32_bf16 v[58:61], v[174:177], v[190:193], v[58:61]
	v_mfma_f32_16x16x32_bf16 v[62:65], v[182:185], v[190:193], v[62:65]
	v_mfma_f32_16x16x32_bf16 v[42:45], v[174:177], v[198:201], v[42:45]
	v_mfma_f32_16x16x32_bf16 v[46:49], v[182:185], v[198:201], v[46:49]
	v_mfma_f32_16x16x32_bf16 v[26:29], v[174:177], v[206:209], v[26:29]
	v_mfma_f32_16x16x32_bf16 v[30:33], v[182:185], v[206:209], v[30:33]
	v_mfma_f32_16x16x32_bf16 v[10:13], v[174:177], v[214:217], v[10:13]
	v_mfma_f32_16x16x32_bf16 v[14:17], v[182:185], v[214:217], v[14:17]
	s_setprio 1
	s_barrier
; #define PG8_WAIT_V(n) asm volatile("s_waitcnt vmcnt(" #n ")" ::: "memory")
; template <class Epi, class Sched, bool ALIGN_EPI = true, bool SP2 = true, bool FULLLINE = false, bool NOSTAGE = false, bool FP8 = false>
; __device__ __forceinline__ void gemm_phase(PG8_LAS unsigned char* lds, const Gemm g, const Sched& S, const Epi& E) {
;     ...
;         static_assert(SP2, "only the SP2 loop is kept");
;         { const int t = 0; if constexpr (Epi::NST == 16) PG8_ITER(PG8_WAIT_V(24)); else if constexpr (Epi::NST == 8) PG8_ITER(PG8_WAIT_V(16)); else PG8_ITER(PG8_WAIT_V(8)); }
;         for (int t = 2; t < nt; t += 2) PG8_ITER(PG8_WAIT_V(8));
	ds_read_b128 v[130:133], v159
	ds_read_b128 v[134:137], v159 offset:1024
	ds_read_b128 v[150:153], v159 offset:2048
	ds_read_b128 v[166:169], v159 offset:3072
	ds_read_b128 v[170:173], v160
	ds_read_b128 v[174:177], v160 offset:1024
	ds_read_b128 v[178:181], v160 offset:2048
	ds_read_b128 v[182:185], v160 offset:3072
	s_mov_b32 m0, s91
	v_lshl_add_u64 v[218:219], v[154:155], 0, s[60:61]
	ds_read_b128 v[186:189], v158 offset:32768
	ds_read_b128 v[190:193], v158 offset:33792
	ds_read_b128 v[194:197], v158 offset:34816
	ds_read_b128 v[198:201], v158 offset:35840
	ds_read_b128 v[202:205], v158 offset:36864
	ds_read_b128 v[206:209], v158 offset:37888
	ds_read_b128 v[210:213], v158 offset:38912
	ds_read_b128 v[214:217], v158 offset:39936
	global_load_lds_dwordx4 v[218:219], off
	v_lshl_add_u64 v[218:219], v[154:155], 0, s[66:67]
	s_mov_b32 m0, s92
	s_nop 0
	global_load_lds_dwordx4 v[218:219], off
	s_waitcnt vmcnt(8)
	s_waitcnt lgkmcnt(0)
	s_barrier
	s_waitcnt lgkmcnt(0)
	s_setprio 0
	v_mfma_f32_16x16x32_bf16 v[118:121], v[130:133], v[186:189], v[118:121]
	v_mfma_f32_16x16x32_bf16 v[114:117], v[150:153], v[186:189], v[114:117]
	v_mfma_f32_16x16x32_bf16 v[102:105], v[130:133], v[194:197], v[102:105]
	v_mfma_f32_16x16x32_bf16 v[98:101], v[150:153], v[194:197], v[98:101]
	v_mfma_f32_16x16x32_bf16 v[86:89], v[130:133], v[202:205], v[86:89]
	v_mfma_f32_16x16x32_bf16 v[82:85], v[150:153], v[202:205], v[82:85]
	v_mfma_f32_16x16x32_bf16 v[66:69], v[130:133], v[210:213], v[66:69]
	v_mfma_f32_16x16x32_bf16 v[70:73], v[150:153], v[210:213], v[70:73]
	v_mfma_f32_16x16x32_bf16 v[118:121], v[134:137], v[190:193], v[118:121]
	v_mfma_f32_16x16x32_bf16 v[114:117], v[166:169], v[190:193], v[114:117]
	v_mfma_f32_16x16x32_bf16 v[102:105], v[134:137], v[198:201], v[102:105]
	v_mfma_f32_16x16x32_bf16 v[98:101], v[166:169], v[198:201], v[98:101]
	v_mfma_f32_16x16x32_bf16 v[86:89], v[134:137], v[206:209], v[86:89]
	v_mfma_f32_16x16x32_bf16 v[82:85], v[166:169], v[206:209], v[82:85]
	v_mfma_f32_16x16x32_bf16 v[66:69], v[134:137], v[214:217], v[66:69]
	v_mfma_f32_16x16x32_bf16 v[70:73], v[166:169], v[214:217], v[70:73]
	v_mfma_f32_16x16x32_bf16 v[126:129], v[170:173], v[186:189], v[126:129]
	v_mfma_f32_16x16x32_bf16 v[122:125], v[178:181], v[186:189], v[122:125]
	v_mfma_f32_16x16x32_bf16 v[110:113], v[170:173], v[194:197], v[110:113]
	v_mfma_f32_16x16x32_bf16 v[106:109], v[178:181], v[194:197], v[106:109]
	v_mfma_f32_16x16x32_bf16 v[94:97], v[170:173], v[202:205], v[94:97]
	v_mfma_f32_16x16x32_bf16 v[90:93], v[178:181], v[202:205], v[90:93]
	v_mfma_f32_16x16x32_bf16 v[74:77], v[170:173], v[210:213], v[74:77]
	v_mfma_f32_16x16x32_bf16 v[78:81], v[178:181], v[210:213], v[78:81]
	v_mfma_f32_16x16x32_bf16 v[126:129], v[174:177], v[190:193], v[126:129]
	v_mfma_f32_16x16x32_bf16 v[122:125], v[182:185], v[190:193], v[122:125]
	v_mfma_f32_16x16x32_bf16 v[110:113], v[174:177], v[198:201], v[110:113]
	v_mfma_f32_16x16x32_bf16 v[106:109], v[182:185], v[198:201], v[106:109]
	v_mfma_f32_16x16x32_bf16 v[94:97], v[174:177], v[206:209], v[94:97]
	v_mfma_f32_16x16x32_bf16 v[90:93], v[182:185], v[206:209], v[90:93]
	v_mfma_f32_16x16x32_bf16 v[74:77], v[174:177], v[214:217], v[74:77]
	v_mfma_f32_16x16x32_bf16 v[78:81], v[182:185], v[214:217], v[78:81]
	s_setprio 1
	s_barrier
	s_mov_b32 m0, s41
	v_lshl_add_u64 v[218:219], v[138:139], 0, s[68:69]
	ds_read_b128 v[186:189], v158 offset:49152
	ds_read_b128 v[190:193], v158 offset:50176
	ds_read_b128 v[194:197], v158 offset:51200
	ds_read_b128 v[198:201], v158 offset:52224
	ds_read_b128 v[202:205], v158 offset:53248
	ds_read_b128 v[206:209], v158 offset:54272
	ds_read_b128 v[210:213], v158 offset:55296
	ds_read_b128 v[214:217], v158 offset:56320
	global_load_lds_dwordx4 v[218:219], off
	v_lshl_add_u64 v[218:219], v[138:139], 0, s[70:71]
	s_mov_b32 m0, s50
	s_nop 0
	global_load_lds_dwordx4 v[218:219], off
	v_lshl_add_u64 v[218:219], v[138:139], 0, s[20:21]
	s_mov_b32 m0, s51
	v_lshl_add_u64 v[138:139], v[138:139], 0, s[22:23]
	global_load_lds_dwordx4 v[218:219], off
	s_mov_b32 m0, s33
	s_nop 0
	global_load_lds_dwordx4 v[138:139], off
	v_lshl_add_u64 v[138:139], v[154:155], 0, s[68:69]
	s_mov_b32 m0, s93
	s_nop 0
	global_load_lds_dwordx4 v[138:139], off
	v_lshl_add_u64 v[138:139], v[154:155], 0, s[70:71]
	s_mov_b32 m0, s94
	s_nop 0
	global_load_lds_dwordx4 v[138:139], off
	s_waitcnt vmcnt(8)
	s_waitcnt lgkmcnt(0)
	s_barrier
	s_waitcnt lgkmcnt(0)
	s_setprio 0
	v_mfma_f32_16x16x32_bf16 v[50:53], v[130:133], v[186:189], v[50:53]
	v_mfma_f32_16x16x32_bf16 v[54:57], v[150:153], v[186:189], v[54:57]
	v_mfma_f32_16x16x32_bf16 v[34:37], v[130:133], v[194:197], v[34:37]
	v_mfma_f32_16x16x32_bf16 v[38:41], v[150:153], v[194:197], v[38:41]
	v_mfma_f32_16x16x32_bf16 v[18:21], v[130:133], v[202:205], v[18:21]
	v_mfma_f32_16x16x32_bf16 v[22:25], v[150:153], v[202:205], v[22:25]
	v_mfma_f32_16x16x32_bf16 v[2:5], v[130:133], v[210:213], v[2:5]
	v_mfma_f32_16x16x32_bf16 v[6:9], v[150:153], v[210:213], v[6:9]
	v_mfma_f32_16x16x32_bf16 v[50:53], v[134:137], v[190:193], v[50:53]
	v_mfma_f32_16x16x32_bf16 v[54:57], v[166:169], v[190:193], v[54:57]
	v_mfma_f32_16x16x32_bf16 v[34:37], v[134:137], v[198:201], v[34:37]
	v_mfma_f32_16x16x32_bf16 v[38:41], v[166:169], v[198:201], v[38:41]
	v_mfma_f32_16x16x32_bf16 v[18:21], v[134:137], v[206:209], v[18:21]
	v_mfma_f32_16x16x32_bf16 v[22:25], v[166:169], v[206:209], v[22:25]
	v_mfma_f32_16x16x32_bf16 v[2:5], v[134:137], v[214:217], v[2:5]
	v_mfma_f32_16x16x32_bf16 v[6:9], v[166:169], v[214:217], v[6:9]
	v_mfma_f32_16x16x32_bf16 v[58:61], v[170:173], v[186:189], v[58:61]
	v_mfma_f32_16x16x32_bf16 v[62:65], v[178:181], v[186:189], v[62:65]
	v_mfma_f32_16x16x32_bf16 v[42:45], v[170:173], v[194:197], v[42:45]
	v_mfma_f32_16x16x32_bf16 v[46:49], v[178:181], v[194:197], v[46:49]
	v_mfma_f32_16x16x32_bf16 v[26:29], v[170:173], v[202:205], v[26:29]
	v_mfma_f32_16x16x32_bf16 v[30:33], v[178:181], v[202:205], v[30:33]
	v_mfma_f32_16x16x32_bf16 v[10:13], v[170:173], v[210:213], v[10:13]
	v_mfma_f32_16x16x32_bf16 v[14:17], v[178:181], v[210:213], v[14:17]
	v_mfma_f32_16x16x32_bf16 v[58:61], v[174:177], v[190:193], v[58:61]
	v_mfma_f32_16x16x32_bf16 v[62:65], v[182:185], v[190:193], v[62:65]
	v_mfma_f32_16x16x32_bf16 v[42:45], v[174:177], v[198:201], v[42:45]
	v_mfma_f32_16x16x32_bf16 v[46:49], v[182:185], v[198:201], v[46:49]
	v_mfma_f32_16x16x32_bf16 v[26:29], v[174:177], v[206:209], v[26:29]
	v_mfma_f32_16x16x32_bf16 v[30:33], v[182:185], v[206:209], v[30:33]
	v_mfma_f32_16x16x32_bf16 v[10:13], v[174:177], v[214:217], v[10:13]
	v_mfma_f32_16x16x32_bf16 v[14:17], v[182:185], v[214:217], v[14:17]
	s_setprio 1
	s_barrier
	s_add_i32 s75, s75, 2
	s_add_u32 s82, s82, 0x100
	s_addc_u32 s83, s83, 0
	s_add_u32 s56, s56, 0x100
	s_addc_u32 s57, s57, 0
	s_cmp_gt_u32 s75, 29
	s_cbranch_scc0 .LBB0_262
	s_and_b64 vcc, exec, s[18:19]
	s_cbranch_vccz .LBB0_265
	s_barrier

; #define PG8_WAIT_V(n) asm volatile("s_waitcnt vmcnt(" #n ")" ::: "memory")
; template <class Epi, class Sched, bool ALIGN_EPI = true, bool SP2 = true, bool FULLLINE = false, bool NOSTAGE = false, bool FP8 = false>
; __device__ __forceinline__ void gemm_phase(PG8_LAS unsigned char* lds, const Gemm g, const Sched& S, const Epi& E) {
;     ...
;         const bool has_next = S.next(ui + 1, nxt);
;         const char* nA = has_next ? PG8_ABASE(nxt) : cA; const char* nB = has_next ? PG8_BBASE(nxt) : cB;
;     ...
;         { const int t = 0; if constexpr (Epi::NST == 16) PG8_ITER(PG8_WAIT_V(24)); else if constexpr (Epi::NST == 8) PG8_ITER(PG8_WAIT_V(16)); else PG8_ITER(PG8_WAIT_V(8)); }
.LBB0_593:
	s_ashr_i32 s69, s68, 31
	s_lshl_b64 s[40:41], s[68:69], 21
	s_add_u32 s70, s42, s40
	ds_read_b128 v[2:5], v160
	ds_read_b128 v[6:9], v160 offset:1024
	ds_read_b128 v[10:13], v160 offset:2048
	ds_read_b128 v[14:17], v160 offset:3072
	ds_read_b128 v[18:21], v161
	ds_read_b128 v[22:25], v161 offset:1024
	ds_read_b128 v[26:29], v161 offset:2048
	ds_read_b128 v[30:33], v161 offset:3072
	s_addc_u32 s71, s43, s41
	s_ashr_i32 s67, s66, 31
	s_lshl_b64 s[40:41], s[66:67], 21
	s_add_u32 s72, s44, s40
	s_addc_u32 s73, s45, s41
	s_and_b64 s[40:41], s[8:9], exec
	s_cselect_b32 s67, s71, s79
	s_cselect_b32 s69, s70, s78
	s_cselect_b32 s92, s73, s77
	s_cselect_b32 s93, s72, s76
	v_lshl_add_u64 v[246:247], s[78:79], 0, v[146:147]
	s_mov_b32 m0, s88
	v_lshl_add_u64 v[66:67], v[246:247], 0, s[12:13]
	ds_read_b128 v[34:37], v162
	ds_read_b128 v[38:41], v162 offset:1024
	ds_read_b128 v[42:45], v162 offset:2048
	ds_read_b128 v[46:49], v162 offset:3072
	ds_read_b128 v[50:53], v162 offset:4096
	ds_read_b128 v[54:57], v162 offset:5120
	ds_read_b128 v[58:61], v162 offset:6144
	ds_read_b128 v[62:65], v162 offset:7168
	global_load_lds_dwordx4 v[66:67], off
	v_lshl_add_u64 v[66:67], v[246:247], 0, s[14:15]
	s_mov_b32 m0, s89
	s_nop 0
	global_load_lds_dwordx4 v[66:67], off
	s_waitcnt vmcnt(24)
	s_waitcnt lgkmcnt(0)
	s_barrier
	s_waitcnt lgkmcnt(0)
	s_setprio 0
	v_mfma_f32_16x16x32_bf16 v[66:69], v[2:5], v[34:37], 0
	v_mfma_f32_16x16x32_bf16 v[70:73], v[10:13], v[34:37], 0
	v_mfma_f32_16x16x32_bf16 v[74:77], v[2:5], v[42:45], 0
	v_mfma_f32_16x16x32_bf16 v[78:81], v[10:13], v[42:45], 0
	v_mfma_f32_16x16x32_bf16 v[82:85], v[2:5], v[50:53], 0
	v_mfma_f32_16x16x32_bf16 v[86:89], v[10:13], v[50:53], 0
	v_mfma_f32_16x16x32_bf16 v[90:93], v[2:5], v[58:61], 0
	v_mfma_f32_16x16x32_bf16 v[94:97], v[10:13], v[58:61], 0
	v_mfma_f32_16x16x32_bf16 v[66:69], v[6:9], v[38:41], v[66:69]
	v_mfma_f32_16x16x32_bf16 v[70:73], v[14:17], v[38:41], v[70:73]
	v_mfma_f32_16x16x32_bf16 v[74:77], v[6:9], v[46:49], v[74:77]
	v_mfma_f32_16x16x32_bf16 v[78:81], v[14:17], v[46:49], v[78:81]
	v_mfma_f32_16x16x32_bf16 v[82:85], v[6:9], v[54:57], v[82:85]
	v_mfma_f32_16x16x32_bf16 v[86:89], v[14:17], v[54:57], v[86:89]
	v_mfma_f32_16x16x32_bf16 v[90:93], v[6:9], v[62:65], v[90:93]
	v_mfma_f32_16x16x32_bf16 v[94:97], v[14:17], v[62:65], v[94:97]
	v_mfma_f32_16x16x32_bf16 v[98:101], v[18:21], v[34:37], 0
	v_mfma_f32_16x16x32_bf16 v[34:37], v[26:29], v[34:37], 0
	v_mfma_f32_16x16x32_bf16 v[106:109], v[22:25], v[38:41], v[98:101]
	v_mfma_f32_16x16x32_bf16 v[34:37], v[30:33], v[38:41], v[34:37]
	v_mfma_f32_16x16x32_bf16 v[38:41], v[18:21], v[42:45], 0
	v_mfma_f32_16x16x32_bf16 v[42:45], v[26:29], v[42:45], 0
	v_mfma_f32_16x16x32_bf16 v[38:41], v[22:25], v[46:49], v[38:41]
	v_mfma_f32_16x16x32_bf16 v[42:45], v[30:33], v[46:49], v[42:45]
	v_mfma_f32_16x16x32_bf16 v[46:49], v[18:21], v[50:53], 0
	v_mfma_f32_16x16x32_bf16 v[50:53], v[26:29], v[50:53], 0
	v_mfma_f32_16x16x32_bf16 v[46:49], v[22:25], v[54:57], v[46:49]
	v_mfma_f32_16x16x32_bf16 v[50:53], v[30:33], v[54:57], v[50:53]
	v_mfma_f32_16x16x32_bf16 v[54:57], v[18:21], v[58:61], 0
	v_mfma_f32_16x16x32_bf16 v[58:61], v[26:29], v[58:61], 0
	v_mfma_f32_16x16x32_bf16 v[54:57], v[22:25], v[62:65], v[54:57]
	v_mfma_f32_16x16x32_bf16 v[58:61], v[30:33], v[62:65], v[58:61]
	s_setprio 1
	s_barrier
	v_lshl_add_u64 v[248:249], s[76:77], 0, v[148:149]
	s_add_i32 s94, s85, s46
	v_lshl_add_u64 v[130:131], v[248:249], 0, s[16:17]
	s_mov_b32 m0, s94
	s_add_i32 s95, s94, 0x2000
	ds_read_b128 v[62:65], v162 offset:16384
	ds_read_b128 v[98:101], v162 offset:17408
	ds_read_b128 v[102:105], v162 offset:18432
	ds_read_b128 v[110:113], v162 offset:19456
	ds_read_b128 v[114:117], v162 offset:20480
	ds_read_b128 v[118:121], v162 offset:21504
	ds_read_b128 v[122:125], v162 offset:22528
	ds_read_b128 v[126:129], v162 offset:23552
	global_load_lds_dwordx4 v[130:131], off
	v_lshl_add_u64 v[130:131], v[248:249], 0, s[18:19]
	s_mov_b32 m0, s95
	s_add_i32 s96, s87, s46
	global_load_lds_dwordx4 v[130:131], off
	v_lshl_add_u64 v[130:131], v[248:249], 0, s[20:21]
	s_mov_b32 m0, s96
	s_add_i32 s40, s96, 0x2000
	global_load_lds_dwordx4 v[130:131], off
	v_lshl_add_u64 v[130:131], v[248:249], 0, s[22:23]
	s_mov_b32 m0, s40
	s_nop 0
	global_load_lds_dwordx4 v[130:131], off
	v_lshl_add_u64 v[130:131], v[246:247], 0, s[16:17]
	s_mov_b32 m0, s47
	s_nop 0
	global_load_lds_dwordx4 v[130:131], off
	v_lshl_add_u64 v[130:131], v[246:247], 0, s[18:19]
	s_mov_b32 m0, s52
	s_nop 0
	global_load_lds_dwordx4 v[130:131], off
	s_waitcnt vmcnt(24)
	s_waitcnt lgkmcnt(0)
	s_barrier
	s_waitcnt lgkmcnt(0)
	s_setprio 0
	v_mfma_f32_16x16x32_bf16 v[130:133], v[2:5], v[62:65], 0
	v_mfma_f32_16x16x32_bf16 v[156:159], v[6:9], v[98:101], v[130:133]
	v_mfma_f32_16x16x32_bf16 v[130:133], v[10:13], v[62:65], 0
	v_mfma_f32_16x16x32_bf16 v[166:169], v[14:17], v[98:101], v[130:133]
	v_mfma_f32_16x16x32_bf16 v[130:133], v[2:5], v[102:105], 0
	v_mfma_f32_16x16x32_bf16 v[170:173], v[6:9], v[110:113], v[130:133]
	v_mfma_f32_16x16x32_bf16 v[130:133], v[10:13], v[102:105], 0
	v_mfma_f32_16x16x32_bf16 v[174:177], v[14:17], v[110:113], v[130:133]
	v_mfma_f32_16x16x32_bf16 v[130:133], v[2:5], v[114:117], 0
	v_mfma_f32_16x16x32_bf16 v[2:5], v[2:5], v[122:125], 0
	v_mfma_f32_16x16x32_bf16 v[178:181], v[6:9], v[118:121], v[130:133]
	v_mfma_f32_16x16x32_bf16 v[2:5], v[6:9], v[126:129], v[2:5]
	v_mfma_f32_16x16x32_bf16 v[6:9], v[10:13], v[122:125], 0
	v_mfma_f32_16x16x32_bf16 v[130:133], v[10:13], v[114:117], 0
	v_mfma_f32_16x16x32_bf16 v[6:9], v[14:17], v[126:129], v[6:9]
	v_mfma_f32_16x16x32_bf16 v[182:185], v[14:17], v[118:121], v[130:133]
	v_mfma_f32_16x16x32_bf16 v[10:13], v[18:21], v[62:65], 0
	v_mfma_f32_16x16x32_bf16 v[186:189], v[22:25], v[98:101], v[10:13]
	v_mfma_f32_16x16x32_bf16 v[10:13], v[26:29], v[62:65], 0
	v_mfma_f32_16x16x32_bf16 v[62:65], v[30:33], v[98:101], v[10:13]
	v_mfma_f32_16x16x32_bf16 v[10:13], v[18:21], v[102:105], 0
	v_mfma_f32_16x16x32_bf16 v[190:193], v[22:25], v[110:113], v[10:13]
	v_mfma_f32_16x16x32_bf16 v[10:13], v[26:29], v[102:105], 0
	v_mfma_f32_16x16x32_bf16 v[194:197], v[30:33], v[110:113], v[10:13]
	v_mfma_f32_16x16x32_bf16 v[10:13], v[18:21], v[114:117], 0
	v_mfma_f32_16x16x32_bf16 v[198:201], v[22:25], v[118:121], v[10:13]
	v_mfma_f32_16x16x32_bf16 v[10:13], v[26:29], v[114:117], 0
	v_mfma_f32_16x16x32_bf16 v[202:205], v[30:33], v[118:121], v[10:13]
	v_mfma_f32_16x16x32_bf16 v[10:13], v[18:21], v[122:125], 0
	v_mfma_f32_16x16x32_bf16 v[206:209], v[22:25], v[126:129], v[10:13]
	v_mfma_f32_16x16x32_bf16 v[10:13], v[26:29], v[122:125], 0
	v_mfma_f32_16x16x32_bf16 v[210:213], v[30:33], v[126:129], v[10:13]
	s_setprio 1
	s_barrier
	s_nop 5
	ds_read_b128 v[10:13], v163
	ds_read_b128 v[14:17], v163 offset:1024
	ds_read_b128 v[26:29], v163 offset:2048
	ds_read_b128 v[30:33], v163 offset:3072
	ds_read_b128 v[214:217], v164
	ds_read_b128 v[218:221], v164 offset:1024
	ds_read_b128 v[222:225], v164 offset:2048
	ds_read_b128 v[226:229], v164 offset:3072
	s_mov_b32 m0, s53
	v_lshl_add_u64 v[98:99], v[246:247], 0, s[20:21]
	ds_read_b128 v[18:21], v162 offset:32768
	ds_read_b128 v[22:25], v162 offset:33792
	ds_read_b128 v[110:113], v162 offset:34816
	ds_read_b128 v[122:125], v162 offset:35840
	ds_read_b128 v[230:233], v162 offset:36864
	ds_read_b128 v[234:237], v162 offset:37888
	ds_read_b128 v[238:241], v162 offset:38912
	ds_read_b128 v[242:245], v162 offset:39936
	global_load_lds_dwordx4 v[98:99], off
	v_lshl_add_u64 v[98:99], v[246:247], 0, s[22:23]
	s_mov_b32 m0, s54
	s_nop 0
	global_load_lds_dwordx4 v[98:99], off
	s_waitcnt vmcnt(8)
	s_waitcnt lgkmcnt(0)
	s_barrier
	s_waitcnt lgkmcnt(0)
	s_setprio 0
	v_mfma_f32_16x16x32_bf16 v[66:69], v[10:13], v[18:21], v[66:69]
	v_mfma_f32_16x16x32_bf16 v[142:145], v[14:17], v[22:25], v[66:69]
	v_mfma_f32_16x16x32_bf16 v[66:69], v[26:29], v[18:21], v[70:73]
	v_mfma_f32_16x16x32_bf16 v[138:141], v[30:33], v[22:25], v[66:69]
	v_mfma_f32_16x16x32_bf16 v[66:69], v[10:13], v[110:113], v[74:77]
	v_mfma_f32_16x16x32_bf16 v[118:121], v[14:17], v[122:125], v[66:69]
	v_mfma_f32_16x16x32_bf16 v[66:69], v[26:29], v[110:113], v[78:81]
	v_mfma_f32_16x16x32_bf16 v[114:117], v[30:33], v[122:125], v[66:69]
	v_mfma_f32_16x16x32_bf16 v[66:69], v[10:13], v[230:233], v[82:85]
	v_mfma_f32_16x16x32_bf16 v[102:105], v[14:17], v[234:237], v[66:69]
	v_mfma_f32_16x16x32_bf16 v[66:69], v[26:29], v[230:233], v[86:89]
	v_mfma_f32_16x16x32_bf16 v[98:101], v[30:33], v[234:237], v[66:69]
	v_mfma_f32_16x16x32_bf16 v[66:69], v[10:13], v[238:241], v[90:93]
	v_mfma_f32_16x16x32_bf16 v[86:89], v[14:17], v[242:245], v[66:69]
	v_mfma_f32_16x16x32_bf16 v[66:69], v[26:29], v[238:241], v[94:97]
	v_mfma_f32_16x16x32_bf16 v[82:85], v[30:33], v[242:245], v[66:69]
	v_mfma_f32_16x16x32_bf16 v[66:69], v[214:217], v[18:21], v[106:109]
	v_mfma_f32_16x16x32_bf16 v[18:21], v[222:225], v[18:21], v[34:37]
	v_mfma_f32_16x16x32_bf16 v[130:133], v[226:229], v[22:25], v[18:21]
	v_mfma_f32_16x16x32_bf16 v[18:21], v[214:217], v[110:113], v[38:41]
	v_mfma_f32_16x16x32_bf16 v[126:129], v[218:221], v[122:125], v[18:21]
	v_mfma_f32_16x16x32_bf16 v[18:21], v[222:225], v[110:113], v[42:45]
	v_mfma_f32_16x16x32_bf16 v[122:125], v[226:229], v[122:125], v[18:21]
	v_mfma_f32_16x16x32_bf16 v[18:21], v[214:217], v[230:233], v[46:49]
	v_mfma_f32_16x16x32_bf16 v[110:113], v[218:221], v[234:237], v[18:21]
	v_mfma_f32_16x16x32_bf16 v[18:21], v[222:225], v[230:233], v[50:53]
	v_mfma_f32_16x16x32_bf16 v[106:109], v[226:229], v[234:237], v[18:21]
	v_mfma_f32_16x16x32_bf16 v[18:21], v[214:217], v[238:241], v[54:57]
	v_mfma_f32_16x16x32_bf16 v[94:97], v[218:221], v[242:245], v[18:21]
	v_mfma_f32_16x16x32_bf16 v[18:21], v[222:225], v[238:241], v[58:61]
	v_mfma_f32_16x16x32_bf16 v[134:137], v[218:221], v[22:25], v[66:69]
	v_mfma_f32_16x16x32_bf16 v[90:93], v[226:229], v[242:245], v[18:21]
	s_setprio 1
	s_barrier
; #define PG8_WAIT_V(n) asm volatile("s_waitcnt vmcnt(" #n ")" ::: "memory")
; template <class Epi, class Sched, bool ALIGN_EPI = true, bool SP2 = true, bool FULLLINE = false, bool NOSTAGE = false, bool FP8 = false>
; __device__ __forceinline__ void gemm_phase(PG8_LAS unsigned char* lds, const Gemm g, const Sched& S, const Epi& E) {
;     ...
;         static_assert(SP2, "only the SP2 loop is kept");
;         { const int t = 0; if constexpr (Epi::NST == 16) PG8_ITER(PG8_WAIT_V(24)); else if constexpr (Epi::NST == 8) PG8_ITER(PG8_WAIT_V(16)); else PG8_ITER(PG8_WAIT_V(8)); }
;         for (int t = 2; t < nt; t += 2) PG8_ITER(PG8_WAIT_V(8));
	s_add_i32 s41, s90, s46
	s_nop 3
	v_lshl_add_u64 v[18:19], v[248:249], 0, s[24:25]
	s_mov_b32 m0, s41
	s_add_i32 s50, s41, 0x2000
	ds_read_b128 v[34:37], v162 offset:49152
	ds_read_b128 v[38:41], v162 offset:50176
	ds_read_b128 v[42:45], v162 offset:51200
	ds_read_b128 v[46:49], v162 offset:52224
	ds_read_b128 v[230:233], v162 offset:53248
	ds_read_b128 v[234:237], v162 offset:54272
	ds_read_b128 v[238:241], v162 offset:55296
	ds_read_b128 v[242:245], v162 offset:56320
	global_load_lds_dwordx4 v[18:19], off
	v_lshl_add_u64 v[18:19], v[248:249], 0, s[26:27]
	s_mov_b32 m0, s50
	s_mov_b64 s[56:57], 0x100180
	s_add_i32 s51, s91, s46
	global_load_lds_dwordx4 v[18:19], off
	v_lshl_add_u64 v[18:19], v[248:249], 0, s[56:57]
	s_mov_b32 m0, s51
	s_mov_b64 s[56:57], 0x180180
	s_add_i32 s33, s51, 0x2000
	global_load_lds_dwordx4 v[18:19], off
	v_lshl_add_u64 v[18:19], v[248:249], 0, s[56:57]
	s_mov_b32 m0, s33
	s_nop 0
	global_load_lds_dwordx4 v[18:19], off
	v_lshl_add_u64 v[18:19], v[246:247], 0, s[24:25]
	s_mov_b32 m0, s55
	s_nop 0
	global_load_lds_dwordx4 v[18:19], off
	v_lshl_add_u64 v[18:19], v[246:247], 0, s[26:27]
	s_mov_b32 m0, s62
	s_nop 0
	global_load_lds_dwordx4 v[18:19], off
	s_waitcnt vmcnt(8)
	s_waitcnt lgkmcnt(0)
	s_barrier
	s_waitcnt lgkmcnt(0)
	s_setprio 0
	v_mfma_f32_16x16x32_bf16 v[18:21], v[10:13], v[34:37], v[156:159]
	v_mfma_f32_16x16x32_bf16 v[70:73], v[14:17], v[38:41], v[18:21]
	v_mfma_f32_16x16x32_bf16 v[18:21], v[26:29], v[34:37], v[166:169]
	v_mfma_f32_16x16x32_bf16 v[66:69], v[30:33], v[38:41], v[18:21]
	v_mfma_f32_16x16x32_bf16 v[18:21], v[10:13], v[42:45], v[170:173]
	v_mfma_f32_16x16x32_bf16 v[54:57], v[14:17], v[46:49], v[18:21]
	v_mfma_f32_16x16x32_bf16 v[18:21], v[26:29], v[42:45], v[174:177]
	v_mfma_f32_16x16x32_bf16 v[50:53], v[30:33], v[46:49], v[18:21]
	v_mfma_f32_16x16x32_bf16 v[18:21], v[10:13], v[230:233], v[178:181]
	v_mfma_f32_16x16x32_bf16 v[2:5], v[10:13], v[238:241], v[2:5]
	v_mfma_f32_16x16x32_bf16 v[22:25], v[14:17], v[234:237], v[18:21]
	v_mfma_f32_16x16x32_bf16 v[18:21], v[26:29], v[230:233], v[182:185]
	v_mfma_f32_16x16x32_bf16 v[14:17], v[14:17], v[242:245], v[2:5]
	v_mfma_f32_16x16x32_bf16 v[2:5], v[26:29], v[238:241], v[6:9]
	v_mfma_f32_16x16x32_bf16 v[18:21], v[30:33], v[234:237], v[18:21]
	v_mfma_f32_16x16x32_bf16 v[10:13], v[30:33], v[242:245], v[2:5]
	v_mfma_f32_16x16x32_bf16 v[2:5], v[214:217], v[34:37], v[186:189]
	v_mfma_f32_16x16x32_bf16 v[78:81], v[218:221], v[38:41], v[2:5]
	v_mfma_f32_16x16x32_bf16 v[2:5], v[222:225], v[34:37], v[62:65]
	v_mfma_f32_16x16x32_bf16 v[74:77], v[226:229], v[38:41], v[2:5]
	v_mfma_f32_16x16x32_bf16 v[2:5], v[214:217], v[42:45], v[190:193]
	v_mfma_f32_16x16x32_bf16 v[62:65], v[218:221], v[46:49], v[2:5]
	v_mfma_f32_16x16x32_bf16 v[2:5], v[222:225], v[42:45], v[194:197]
	v_mfma_f32_16x16x32_bf16 v[58:61], v[226:229], v[46:49], v[2:5]
	v_mfma_f32_16x16x32_bf16 v[2:5], v[214:217], v[230:233], v[198:201]
	v_mfma_f32_16x16x32_bf16 v[30:33], v[218:221], v[234:237], v[2:5]
	v_mfma_f32_16x16x32_bf16 v[2:5], v[222:225], v[230:233], v[202:205]
	v_mfma_f32_16x16x32_bf16 v[26:29], v[226:229], v[234:237], v[2:5]
	v_mfma_f32_16x16x32_bf16 v[2:5], v[214:217], v[238:241], v[206:209]
	v_mfma_f32_16x16x32_bf16 v[6:9], v[218:221], v[242:245], v[2:5]
	v_mfma_f32_16x16x32_bf16 v[2:5], v[222:225], v[238:241], v[210:213]
	v_mfma_f32_16x16x32_bf16 v[2:5], v[226:229], v[242:245], v[2:5]
	s_setprio 1
	s_barrier
	s_add_u32 s78, s78, 0x100180
	s_addc_u32 s79, s79, 0
	s_add_u32 s56, s76, 0x200
	s_addc_u32 s57, s77, 0
	s_mov_b32 s76, 0
.LBB0_594:
	ds_read_b128 v[34:37], v160
	ds_read_b128 v[38:41], v160 offset:1024
	ds_read_b128 v[42:45], v160 offset:2048
	ds_read_b128 v[46:49], v160 offset:3072
	ds_read_b128 v[156:159], v161
	ds_read_b128 v[166:169], v161 offset:1024
	ds_read_b128 v[170:173], v161 offset:2048
	ds_read_b128 v[174:177], v161 offset:3072
	s_add_u32 s0, s78, 0xfff00080
	s_addc_u32 s1, s79, -1
	s_cmp_eq_u32 s76, 60
	s_cselect_b32 vcc_hi, s67, s1
	s_cselect_b32 vcc_lo, s69, s0
	s_cselect_b32 s65, s92, s57
	s_cselect_b32 s64, s93, s56
	s_mov_b32 m0, s88
	v_lshl_add_u64 v[210:211], s[78:79], 0, v[150:151]
	ds_read_b128 v[178:181], v162
	ds_read_b128 v[182:185], v162 offset:1024
	ds_read_b128 v[186:189], v162 offset:2048
	ds_read_b128 v[190:193], v162 offset:3072
	ds_read_b128 v[194:197], v162 offset:4096
	ds_read_b128 v[198:201], v162 offset:5120
	ds_read_b128 v[202:205], v162 offset:6144
	ds_read_b128 v[206:209], v162 offset:7168
	global_load_lds_dwordx4 v[210:211], off
	v_lshl_add_u64 v[210:211], v[210:211], 0, s[28:29]
	s_mov_b32 m0, s89
	s_nop 0
	global_load_lds_dwordx4 v[210:211], off
	s_waitcnt vmcnt(8)
	s_waitcnt lgkmcnt(0)
	s_barrier
	s_waitcnt lgkmcnt(0)
	s_setprio 0
	v_mfma_f32_16x16x32_bf16 v[142:145], v[34:37], v[178:181], v[142:145]
	v_mfma_f32_16x16x32_bf16 v[138:141], v[42:45], v[178:181], v[138:141]
	v_mfma_f32_16x16x32_bf16 v[118:121], v[34:37], v[186:189], v[118:121]
	v_mfma_f32_16x16x32_bf16 v[114:117], v[42:45], v[186:189], v[114:117]
	v_mfma_f32_16x16x32_bf16 v[102:105], v[34:37], v[194:197], v[102:105]
	v_mfma_f32_16x16x32_bf16 v[98:101], v[42:45], v[194:197], v[98:101]
	v_mfma_f32_16x16x32_bf16 v[86:89], v[34:37], v[202:205], v[86:89]
	v_mfma_f32_16x16x32_bf16 v[82:85], v[42:45], v[202:205], v[82:85]
	v_mfma_f32_16x16x32_bf16 v[142:145], v[38:41], v[182:185], v[142:145]
	v_mfma_f32_16x16x32_bf16 v[138:141], v[46:49], v[182:185], v[138:141]
	v_mfma_f32_16x16x32_bf16 v[118:121], v[38:41], v[190:193], v[118:121]
	v_mfma_f32_16x16x32_bf16 v[114:117], v[46:49], v[190:193], v[114:117]
	v_mfma_f32_16x16x32_bf16 v[102:105], v[38:41], v[198:201], v[102:105]
	v_mfma_f32_16x16x32_bf16 v[98:101], v[46:49], v[198:201], v[98:101]
	v_mfma_f32_16x16x32_bf16 v[86:89], v[38:41], v[206:209], v[86:89]
	v_mfma_f32_16x16x32_bf16 v[82:85], v[46:49], v[206:209], v[82:85]
	v_mfma_f32_16x16x32_bf16 v[134:137], v[156:159], v[178:181], v[134:137]
	v_mfma_f32_16x16x32_bf16 v[130:133], v[170:173], v[178:181], v[130:133]
	v_mfma_f32_16x16x32_bf16 v[126:129], v[156:159], v[186:189], v[126:129]
	v_mfma_f32_16x16x32_bf16 v[122:125], v[170:173], v[186:189], v[122:125]
	v_mfma_f32_16x16x32_bf16 v[110:113], v[156:159], v[194:197], v[110:113]
	v_mfma_f32_16x16x32_bf16 v[106:109], v[170:173], v[194:197], v[106:109]
	v_mfma_f32_16x16x32_bf16 v[94:97], v[156:159], v[202:205], v[94:97]
	v_mfma_f32_16x16x32_bf16 v[90:93], v[170:173], v[202:205], v[90:93]
	v_mfma_f32_16x16x32_bf16 v[134:137], v[166:169], v[182:185], v[134:137]
	v_mfma_f32_16x16x32_bf16 v[130:133], v[174:177], v[182:185], v[130:133]
	v_mfma_f32_16x16x32_bf16 v[126:129], v[166:169], v[190:193], v[126:129]
	v_mfma_f32_16x16x32_bf16 v[122:125], v[174:177], v[190:193], v[122:125]
	v_mfma_f32_16x16x32_bf16 v[110:113], v[166:169], v[198:201], v[110:113]
	v_mfma_f32_16x16x32_bf16 v[106:109], v[174:177], v[198:201], v[106:109]
	v_mfma_f32_16x16x32_bf16 v[94:97], v[166:169], v[206:209], v[94:97]
	v_mfma_f32_16x16x32_bf16 v[90:93], v[174:177], v[206:209], v[90:93]
	s_setprio 1
	s_barrier
	s_mov_b32 m0, s94
	v_lshl_add_u64 v[210:211], s[64:65], 0, v[148:149]
	ds_read_b128 v[178:181], v162 offset:16384
	ds_read_b128 v[182:185], v162 offset:17408
	ds_read_b128 v[186:189], v162 offset:18432
	ds_read_b128 v[190:193], v162 offset:19456
	ds_read_b128 v[194:197], v162 offset:20480
	ds_read_b128 v[198:201], v162 offset:21504
	ds_read_b128 v[202:205], v162 offset:22528
	ds_read_b128 v[206:209], v162 offset:23552
	global_load_lds_dwordx4 v[210:211], off
	v_lshl_add_u64 v[212:213], v[210:211], 0, s[28:29]
	s_mov_b32 m0, s95
	s_nop 0
	global_load_lds_dwordx4 v[212:213], off
	v_lshl_add_u64 v[212:213], v[210:211], 0, s[30:31]
	s_mov_b32 m0, s96
	s_nop 0
	global_load_lds_dwordx4 v[212:213], off
	v_lshl_add_u64 v[212:213], v[210:211], 0, s[34:35]
	s_mov_b32 m0, s40
	s_nop 0
	global_load_lds_dwordx4 v[212:213], off
	v_lshl_add_u64 v[212:213], vcc, 0, v[146:147]
	s_mov_b32 m0, s47
	v_lshl_add_u64 v[214:215], v[212:213], 0, s[28:29]
	global_load_lds_dwordx4 v[212:213], off
	s_mov_b32 m0, s52
	s_nop 0
	global_load_lds_dwordx4 v[214:215], off
	s_waitcnt vmcnt(8)
	s_waitcnt lgkmcnt(0)
	s_barrier
	s_waitcnt lgkmcnt(0)
	s_setprio 0
	v_mfma_f32_16x16x32_bf16 v[70:73], v[34:37], v[178:181], v[70:73]
	v_mfma_f32_16x16x32_bf16 v[66:69], v[42:45], v[178:181], v[66:69]
	v_mfma_f32_16x16x32_bf16 v[54:57], v[34:37], v[186:189], v[54:57]
	v_mfma_f32_16x16x32_bf16 v[50:53], v[42:45], v[186:189], v[50:53]
	v_mfma_f32_16x16x32_bf16 v[22:25], v[34:37], v[194:197], v[22:25]
	v_mfma_f32_16x16x32_bf16 v[18:21], v[42:45], v[194:197], v[18:21]
	v_mfma_f32_16x16x32_bf16 v[14:17], v[34:37], v[202:205], v[14:17]
	v_mfma_f32_16x16x32_bf16 v[10:13], v[42:45], v[202:205], v[10:13]
	v_mfma_f32_16x16x32_bf16 v[70:73], v[38:41], v[182:185], v[70:73]
	v_mfma_f32_16x16x32_bf16 v[66:69], v[46:49], v[182:185], v[66:69]
	v_mfma_f32_16x16x32_bf16 v[54:57], v[38:41], v[190:193], v[54:57]
	v_mfma_f32_16x16x32_bf16 v[50:53], v[46:49], v[190:193], v[50:53]
	v_mfma_f32_16x16x32_bf16 v[22:25], v[38:41], v[198:201], v[22:25]
	v_mfma_f32_16x16x32_bf16 v[18:21], v[46:49], v[198:201], v[18:21]
	v_mfma_f32_16x16x32_bf16 v[14:17], v[38:41], v[206:209], v[14:17]
	v_mfma_f32_16x16x32_bf16 v[10:13], v[46:49], v[206:209], v[10:13]
	v_mfma_f32_16x16x32_bf16 v[30:33], v[156:159], v[194:197], v[30:33]
	v_mfma_f32_16x16x32_bf16 v[26:29], v[170:173], v[194:197], v[26:29]
	v_mfma_f32_16x16x32_bf16 v[6:9], v[156:159], v[202:205], v[6:9]
	v_mfma_f32_16x16x32_bf16 v[2:5], v[170:173], v[202:205], v[2:5]
	v_mfma_f32_16x16x32_bf16 v[34:37], v[156:159], v[178:181], v[78:81]
	v_mfma_f32_16x16x32_bf16 v[38:41], v[170:173], v[178:181], v[74:77]
	v_mfma_f32_16x16x32_bf16 v[42:45], v[156:159], v[186:189], v[62:65]
	v_mfma_f32_16x16x32_bf16 v[46:49], v[170:173], v[186:189], v[58:61]
	v_mfma_f32_16x16x32_bf16 v[30:33], v[166:169], v[198:201], v[30:33]
	v_mfma_f32_16x16x32_bf16 v[26:29], v[174:177], v[198:201], v[26:29]
	v_mfma_f32_16x16x32_bf16 v[6:9], v[166:169], v[206:209], v[6:9]
	v_mfma_f32_16x16x32_bf16 v[2:5], v[174:177], v[206:209], v[2:5]
	v_mfma_f32_16x16x32_bf16 v[34:37], v[166:169], v[182:185], v[34:37]
	v_mfma_f32_16x16x32_bf16 v[38:41], v[174:177], v[182:185], v[38:41]
	v_mfma_f32_16x16x32_bf16 v[42:45], v[166:169], v[190:193], v[42:45]
	v_mfma_f32_16x16x32_bf16 v[46:49], v[174:177], v[190:193], v[46:49]
	s_setprio 1
	s_barrier
; #define PG8_WAIT_V(n) asm volatile("s_waitcnt vmcnt(" #n ")" ::: "memory")
; template <class Epi, class Sched, bool ALIGN_EPI = true, bool SP2 = true, bool FULLLINE = false, bool NOSTAGE = false, bool FP8 = false>
; __device__ __forceinline__ void gemm_phase(PG8_LAS unsigned char* lds, const Gemm g, const Sched& S, const Epi& E) {
;     ...
;         static_assert(SP2, "only the SP2 loop is kept");
;         { const int t = 0; if constexpr (Epi::NST == 16) PG8_ITER(PG8_WAIT_V(24)); else if constexpr (Epi::NST == 8) PG8_ITER(PG8_WAIT_V(16)); else PG8_ITER(PG8_WAIT_V(8)); }
;         for (int t = 2; t < nt; t += 2) PG8_ITER(PG8_WAIT_V(8));
	ds_read_b128 v[58:61], v163
	ds_read_b128 v[62:65], v163 offset:1024
	ds_read_b128 v[74:77], v163 offset:2048
	ds_read_b128 v[78:81], v163 offset:3072
	ds_read_b128 v[156:159], v164
	ds_read_b128 v[166:169], v164 offset:1024
	ds_read_b128 v[170:173], v164 offset:2048
	ds_read_b128 v[174:177], v164 offset:3072
	s_mov_b32 m0, s53
	v_lshl_add_u64 v[214:215], v[212:213], 0, s[30:31]
	ds_read_b128 v[178:181], v162 offset:32768
	ds_read_b128 v[182:185], v162 offset:33792
	ds_read_b128 v[186:189], v162 offset:34816
	ds_read_b128 v[190:193], v162 offset:35840
	ds_read_b128 v[194:197], v162 offset:36864
	ds_read_b128 v[198:201], v162 offset:37888
	ds_read_b128 v[202:205], v162 offset:38912
	ds_read_b128 v[206:209], v162 offset:39936
	global_load_lds_dwordx4 v[214:215], off
	v_lshl_add_u64 v[214:215], v[212:213], 0, s[34:35]
	s_mov_b32 m0, s54
	s_nop 0
	global_load_lds_dwordx4 v[214:215], off
	s_waitcnt vmcnt(8)
	s_waitcnt lgkmcnt(0)
	s_barrier
	s_waitcnt lgkmcnt(0)
	s_setprio 0
	v_mfma_f32_16x16x32_bf16 v[142:145], v[58:61], v[178:181], v[142:145]
	v_mfma_f32_16x16x32_bf16 v[138:141], v[74:77], v[178:181], v[138:141]
	v_mfma_f32_16x16x32_bf16 v[118:121], v[58:61], v[186:189], v[118:121]
	v_mfma_f32_16x16x32_bf16 v[114:117], v[74:77], v[186:189], v[114:117]
	v_mfma_f32_16x16x32_bf16 v[102:105], v[58:61], v[194:197], v[102:105]
	v_mfma_f32_16x16x32_bf16 v[98:101], v[74:77], v[194:197], v[98:101]
	v_mfma_f32_16x16x32_bf16 v[86:89], v[58:61], v[202:205], v[86:89]
	v_mfma_f32_16x16x32_bf16 v[82:85], v[74:77], v[202:205], v[82:85]
	v_mfma_f32_16x16x32_bf16 v[142:145], v[62:65], v[182:185], v[142:145]
	v_mfma_f32_16x16x32_bf16 v[138:141], v[78:81], v[182:185], v[138:141]
	v_mfma_f32_16x16x32_bf16 v[118:121], v[62:65], v[190:193], v[118:121]
	v_mfma_f32_16x16x32_bf16 v[114:117], v[78:81], v[190:193], v[114:117]
	v_mfma_f32_16x16x32_bf16 v[102:105], v[62:65], v[198:201], v[102:105]
	v_mfma_f32_16x16x32_bf16 v[98:101], v[78:81], v[198:201], v[98:101]
	v_mfma_f32_16x16x32_bf16 v[86:89], v[62:65], v[206:209], v[86:89]
	v_mfma_f32_16x16x32_bf16 v[82:85], v[78:81], v[206:209], v[82:85]
	v_mfma_f32_16x16x32_bf16 v[134:137], v[156:159], v[178:181], v[134:137]
	v_mfma_f32_16x16x32_bf16 v[130:133], v[170:173], v[178:181], v[130:133]
	v_mfma_f32_16x16x32_bf16 v[126:129], v[156:159], v[186:189], v[126:129]
	v_mfma_f32_16x16x32_bf16 v[122:125], v[170:173], v[186:189], v[122:125]
	v_mfma_f32_16x16x32_bf16 v[110:113], v[156:159], v[194:197], v[110:113]
	v_mfma_f32_16x16x32_bf16 v[106:109], v[170:173], v[194:197], v[106:109]
	v_mfma_f32_16x16x32_bf16 v[94:97], v[156:159], v[202:205], v[94:97]
	v_mfma_f32_16x16x32_bf16 v[90:93], v[170:173], v[202:205], v[90:93]
	v_mfma_f32_16x16x32_bf16 v[134:137], v[166:169], v[182:185], v[134:137]
	v_mfma_f32_16x16x32_bf16 v[130:133], v[174:177], v[182:185], v[130:133]
	v_mfma_f32_16x16x32_bf16 v[126:129], v[166:169], v[190:193], v[126:129]
	v_mfma_f32_16x16x32_bf16 v[122:125], v[174:177], v[190:193], v[122:125]
	v_mfma_f32_16x16x32_bf16 v[110:113], v[166:169], v[198:201], v[110:113]
	v_mfma_f32_16x16x32_bf16 v[106:109], v[174:177], v[198:201], v[106:109]
	v_mfma_f32_16x16x32_bf16 v[94:97], v[166:169], v[206:209], v[94:97]
	v_mfma_f32_16x16x32_bf16 v[90:93], v[174:177], v[206:209], v[90:93]
	s_setprio 1
	s_barrier
	s_mov_b32 m0, s41
	v_lshl_add_u64 v[214:215], v[210:211], 0, s[36:37]
	ds_read_b128 v[178:181], v162 offset:49152
	ds_read_b128 v[182:185], v162 offset:50176
	ds_read_b128 v[186:189], v162 offset:51200
	ds_read_b128 v[190:193], v162 offset:52224
	ds_read_b128 v[194:197], v162 offset:53248
	ds_read_b128 v[198:201], v162 offset:54272
	ds_read_b128 v[202:205], v162 offset:55296
	ds_read_b128 v[206:209], v162 offset:56320
	global_load_lds_dwordx4 v[214:215], off
	v_lshl_add_u64 v[214:215], v[210:211], 0, s[38:39]
	s_mov_b32 m0, s50
	s_nop 0
	global_load_lds_dwordx4 v[214:215], off
	v_lshl_add_u64 v[214:215], v[210:211], 0, s[12:13]
	s_mov_b32 m0, s51
	v_lshl_add_u64 v[210:211], v[210:211], 0, s[14:15]
	global_load_lds_dwordx4 v[214:215], off
	s_mov_b32 m0, s33
	s_nop 0
	global_load_lds_dwordx4 v[210:211], off
	v_lshl_add_u64 v[210:211], v[212:213], 0, s[36:37]
	s_mov_b32 m0, s55
	s_nop 0
	global_load_lds_dwordx4 v[210:211], off
	v_lshl_add_u64 v[210:211], v[212:213], 0, s[38:39]
	s_mov_b32 m0, s62
	s_nop 0
	global_load_lds_dwordx4 v[210:211], off
	s_waitcnt vmcnt(8)
	s_waitcnt lgkmcnt(0)
	s_barrier
	s_waitcnt lgkmcnt(0)
	s_setprio 0
	v_mfma_f32_16x16x32_bf16 v[70:73], v[58:61], v[178:181], v[70:73]
	v_mfma_f32_16x16x32_bf16 v[66:69], v[74:77], v[178:181], v[66:69]
	v_mfma_f32_16x16x32_bf16 v[54:57], v[58:61], v[186:189], v[54:57]
	v_mfma_f32_16x16x32_bf16 v[50:53], v[74:77], v[186:189], v[50:53]
	v_mfma_f32_16x16x32_bf16 v[22:25], v[58:61], v[194:197], v[22:25]
	v_mfma_f32_16x16x32_bf16 v[18:21], v[74:77], v[194:197], v[18:21]
	v_mfma_f32_16x16x32_bf16 v[14:17], v[58:61], v[202:205], v[14:17]
	v_mfma_f32_16x16x32_bf16 v[10:13], v[74:77], v[202:205], v[10:13]
	v_mfma_f32_16x16x32_bf16 v[70:73], v[62:65], v[182:185], v[70:73]
	v_mfma_f32_16x16x32_bf16 v[66:69], v[78:81], v[182:185], v[66:69]
	v_mfma_f32_16x16x32_bf16 v[54:57], v[62:65], v[190:193], v[54:57]
	v_mfma_f32_16x16x32_bf16 v[50:53], v[78:81], v[190:193], v[50:53]
	v_mfma_f32_16x16x32_bf16 v[22:25], v[62:65], v[198:201], v[22:25]
	v_mfma_f32_16x16x32_bf16 v[18:21], v[78:81], v[198:201], v[18:21]
	v_mfma_f32_16x16x32_bf16 v[14:17], v[62:65], v[206:209], v[14:17]
	v_mfma_f32_16x16x32_bf16 v[10:13], v[78:81], v[206:209], v[10:13]
	v_mfma_f32_16x16x32_bf16 v[34:37], v[156:159], v[178:181], v[34:37]
	v_mfma_f32_16x16x32_bf16 v[78:81], v[166:169], v[182:185], v[34:37]
	v_mfma_f32_16x16x32_bf16 v[34:37], v[170:173], v[178:181], v[38:41]
	v_mfma_f32_16x16x32_bf16 v[74:77], v[174:177], v[182:185], v[34:37]
	v_mfma_f32_16x16x32_bf16 v[34:37], v[156:159], v[186:189], v[42:45]
	v_mfma_f32_16x16x32_bf16 v[62:65], v[166:169], v[190:193], v[34:37]
	v_mfma_f32_16x16x32_bf16 v[34:37], v[170:173], v[186:189], v[46:49]
	v_mfma_f32_16x16x32_bf16 v[30:33], v[156:159], v[194:197], v[30:33]
	v_mfma_f32_16x16x32_bf16 v[26:29], v[170:173], v[194:197], v[26:29]
	v_mfma_f32_16x16x32_bf16 v[6:9], v[156:159], v[202:205], v[6:9]
	v_mfma_f32_16x16x32_bf16 v[2:5], v[170:173], v[202:205], v[2:5]
	v_mfma_f32_16x16x32_bf16 v[58:61], v[174:177], v[190:193], v[34:37]
	v_mfma_f32_16x16x32_bf16 v[30:33], v[166:169], v[198:201], v[30:33]
	v_mfma_f32_16x16x32_bf16 v[26:29], v[174:177], v[198:201], v[26:29]
	v_mfma_f32_16x16x32_bf16 v[6:9], v[166:169], v[206:209], v[6:9]
	v_mfma_f32_16x16x32_bf16 v[2:5], v[174:177], v[206:209], v[2:5]
	s_setprio 1
	s_barrier
	s_add_i32 s76, s76, 2
	s_add_u32 s78, s78, 0x100
	s_addc_u32 s79, s79, 0
	s_add_u32 s56, s56, 0x100
	s_addc_u32 s57, s57, 0
	s_cmp_gt_u32 s76, 61
	s_cbranch_scc0 .LBB0_594
	s_and_b64 vcc, exec, s[10:11]
	s_cbranch_vccz .LBB0_597
	s_barrier

; #define PG8_WAIT_V(n) asm volatile("s_waitcnt vmcnt(" #n ")" ::: "memory")
; template <class Epi, class Sched, bool ALIGN_EPI = true, bool SP2 = true, bool FULLLINE = false, bool NOSTAGE = false, bool FP8 = false>
; __device__ __forceinline__ void gemm_phase(PG8_LAS unsigned char* lds, const Gemm g, const Sched& S, const Epi& E) {
;     ...
;         const bool has_next = S.next(ui + 1, nxt);
;         const char* nA = has_next ? PG8_ABASE(nxt) : cA; const char* nB = has_next ? PG8_BBASE(nxt) : cB;
;     ...
;         { const int t = 0; if constexpr (Epi::NST == 16) PG8_ITER(PG8_WAIT_V(24)); else if constexpr (Epi::NST == 8) PG8_ITER(PG8_WAIT_V(16)); else PG8_ITER(PG8_WAIT_V(8)); }
.LBB0_766:
	s_ashr_i32 s69, s68, 31
	s_lshl_b64 s[40:41], s[68:69], 20
	s_add_u32 s70, s58, s40
	ds_read_b128 v[2:5], v1
	ds_read_b128 v[6:9], v1 offset:1024
	ds_read_b128 v[10:13], v1 offset:2048
	ds_read_b128 v[14:17], v1 offset:3072
	ds_read_b128 v[18:21], v142
	ds_read_b128 v[22:25], v142 offset:1024
	ds_read_b128 v[26:29], v142 offset:2048
	ds_read_b128 v[30:33], v142 offset:3072
	s_addc_u32 s71, s59, s41
	s_ashr_i32 s67, s66, 31
	s_lshl_b64 s[40:41], s[66:67], 20
	s_add_u32 s72, s3, s40
	s_addc_u32 s73, s42, s41
	s_and_b64 s[40:41], s[8:9], exec
	s_cselect_b32 s67, s71, s79
	s_cselect_b32 s69, s70, s78
	s_cselect_b32 s89, s73, s77
	s_cselect_b32 s90, s72, s76
	v_lshl_add_u64 v[140:141], s[78:79], 0, v[132:133]
	s_mov_b32 m0, s81
	v_lshl_add_u64 v[66:67], v[140:141], 0, s[12:13]
	ds_read_b128 v[34:37], v143
	ds_read_b128 v[38:41], v143 offset:1024
	ds_read_b128 v[42:45], v143 offset:2048
	ds_read_b128 v[46:49], v143 offset:3072
	ds_read_b128 v[50:53], v143 offset:4096
	ds_read_b128 v[54:57], v143 offset:5120
	ds_read_b128 v[58:61], v143 offset:6144
	ds_read_b128 v[62:65], v143 offset:7168
	global_load_lds_dwordx4 v[66:67], off
	v_lshl_add_u64 v[66:67], v[140:141], 0, s[14:15]
	s_mov_b32 m0, s82
	s_nop 0
	global_load_lds_dwordx4 v[66:67], off
	s_waitcnt vmcnt(16)
	s_waitcnt lgkmcnt(0)
	s_barrier
	s_waitcnt lgkmcnt(0)
	s_setprio 0
	v_mfma_f32_16x16x32_bf16 v[86:89], v[10:13], v[50:53], 0
	v_mfma_f32_16x16x32_bf16 v[90:93], v[14:17], v[54:57], v[86:89]
	v_mfma_f32_16x16x32_bf16 v[86:89], v[2:5], v[58:61], 0
	v_mfma_f32_16x16x32_bf16 v[66:69], v[2:5], v[34:37], 0
	v_mfma_f32_16x16x32_bf16 v[70:73], v[10:13], v[34:37], 0
	v_mfma_f32_16x16x32_bf16 v[74:77], v[2:5], v[42:45], 0
	v_mfma_f32_16x16x32_bf16 v[78:81], v[10:13], v[42:45], 0
	v_mfma_f32_16x16x32_bf16 v[82:85], v[2:5], v[50:53], 0
	v_mfma_f32_16x16x32_bf16 v[94:97], v[6:9], v[62:65], v[86:89]
	v_mfma_f32_16x16x32_bf16 v[86:89], v[10:13], v[58:61], 0
	v_mfma_f32_16x16x32_bf16 v[66:69], v[6:9], v[38:41], v[66:69]
	v_mfma_f32_16x16x32_bf16 v[70:73], v[14:17], v[38:41], v[70:73]
	v_mfma_f32_16x16x32_bf16 v[74:77], v[6:9], v[46:49], v[74:77]
	v_mfma_f32_16x16x32_bf16 v[78:81], v[14:17], v[46:49], v[78:81]
	v_mfma_f32_16x16x32_bf16 v[82:85], v[6:9], v[54:57], v[82:85]
	v_mfma_f32_16x16x32_bf16 v[106:109], v[14:17], v[62:65], v[86:89]
	v_mfma_f32_16x16x32_bf16 v[86:89], v[18:21], v[34:37], 0
	v_mfma_f32_16x16x32_bf16 v[34:37], v[26:29], v[34:37], 0
	v_mfma_f32_16x16x32_bf16 v[110:113], v[22:25], v[38:41], v[86:89]
	v_mfma_f32_16x16x32_bf16 v[34:37], v[30:33], v[38:41], v[34:37]
	v_mfma_f32_16x16x32_bf16 v[38:41], v[18:21], v[42:45], 0
	v_mfma_f32_16x16x32_bf16 v[42:45], v[26:29], v[42:45], 0
	v_mfma_f32_16x16x32_bf16 v[38:41], v[22:25], v[46:49], v[38:41]
	v_mfma_f32_16x16x32_bf16 v[42:45], v[30:33], v[46:49], v[42:45]
	v_mfma_f32_16x16x32_bf16 v[46:49], v[18:21], v[50:53], 0
	v_mfma_f32_16x16x32_bf16 v[50:53], v[26:29], v[50:53], 0
	v_mfma_f32_16x16x32_bf16 v[46:49], v[22:25], v[54:57], v[46:49]
	v_mfma_f32_16x16x32_bf16 v[50:53], v[30:33], v[54:57], v[50:53]
	v_mfma_f32_16x16x32_bf16 v[54:57], v[18:21], v[58:61], 0
	v_mfma_f32_16x16x32_bf16 v[58:61], v[26:29], v[58:61], 0
	v_mfma_f32_16x16x32_bf16 v[54:57], v[22:25], v[62:65], v[54:57]
	v_mfma_f32_16x16x32_bf16 v[58:61], v[30:33], v[62:65], v[58:61]
	s_setprio 1
	s_barrier
	v_lshl_add_u64 v[238:239], s[76:77], 0, v[130:131]
	s_mov_b32 m0, s83
	v_lshl_add_u64 v[146:147], v[238:239], 0, s[16:17]
	s_add_i32 s91, s83, 0x2000
	ds_read_b128 v[62:65], v143 offset:16384
	ds_read_b128 v[86:89], v143 offset:17408
	ds_read_b128 v[98:101], v143 offset:18432
	ds_read_b128 v[102:105], v143 offset:19456
	ds_read_b128 v[114:117], v143 offset:20480
	ds_read_b128 v[118:121], v143 offset:21504
	ds_read_b128 v[122:125], v143 offset:22528
	ds_read_b128 v[126:129], v143 offset:23552
	global_load_lds_dwordx4 v[146:147], off
	v_lshl_add_u64 v[146:147], v[238:239], 0, s[18:19]
	s_mov_b32 m0, s91
	s_add_i32 s92, s80, s43
	global_load_lds_dwordx4 v[146:147], off
	v_lshl_add_u64 v[146:147], v[238:239], 0, s[20:21]
	s_mov_b32 m0, s92
	s_add_i32 s40, s92, 0x2000
	global_load_lds_dwordx4 v[146:147], off
	v_lshl_add_u64 v[146:147], v[238:239], 0, s[22:23]
	s_mov_b32 m0, s40
	s_nop 0
	global_load_lds_dwordx4 v[146:147], off
	v_lshl_add_u64 v[146:147], v[140:141], 0, s[16:17]
	s_mov_b32 m0, s45
	s_nop 0
	global_load_lds_dwordx4 v[146:147], off
	v_lshl_add_u64 v[146:147], v[140:141], 0, s[18:19]
	s_mov_b32 m0, s46
	s_nop 0
	global_load_lds_dwordx4 v[146:147], off
	s_waitcnt vmcnt(16)
	s_waitcnt lgkmcnt(0)
	s_barrier
	s_waitcnt lgkmcnt(0)
	s_setprio 0
	v_mfma_f32_16x16x32_bf16 v[146:149], v[2:5], v[62:65], 0
	v_mfma_f32_16x16x32_bf16 v[154:157], v[2:5], v[98:101], 0
	v_mfma_f32_16x16x32_bf16 v[162:165], v[2:5], v[114:117], 0
	v_mfma_f32_16x16x32_bf16 v[2:5], v[2:5], v[122:125], 0
	v_mfma_f32_16x16x32_bf16 v[146:149], v[6:9], v[86:89], v[146:149]
	v_mfma_f32_16x16x32_bf16 v[154:157], v[6:9], v[102:105], v[154:157]
	v_mfma_f32_16x16x32_bf16 v[162:165], v[6:9], v[118:121], v[162:165]
	v_mfma_f32_16x16x32_bf16 v[2:5], v[6:9], v[126:129], v[2:5]
	v_mfma_f32_16x16x32_bf16 v[6:9], v[10:13], v[122:125], 0
	v_mfma_f32_16x16x32_bf16 v[150:153], v[10:13], v[62:65], 0
	v_mfma_f32_16x16x32_bf16 v[158:161], v[10:13], v[98:101], 0
	v_mfma_f32_16x16x32_bf16 v[166:169], v[10:13], v[114:117], 0
	v_mfma_f32_16x16x32_bf16 v[10:13], v[14:17], v[126:129], v[6:9]
	v_mfma_f32_16x16x32_bf16 v[150:153], v[14:17], v[86:89], v[150:153]
	v_mfma_f32_16x16x32_bf16 v[158:161], v[14:17], v[102:105], v[158:161]
	v_mfma_f32_16x16x32_bf16 v[166:169], v[14:17], v[118:121], v[166:169]
	v_mfma_f32_16x16x32_bf16 v[6:9], v[18:21], v[62:65], 0
	v_mfma_f32_16x16x32_bf16 v[14:17], v[22:25], v[86:89], v[6:9]
	v_mfma_f32_16x16x32_bf16 v[6:9], v[26:29], v[62:65], 0
	v_mfma_f32_16x16x32_bf16 v[170:173], v[30:33], v[86:89], v[6:9]
	v_mfma_f32_16x16x32_bf16 v[6:9], v[18:21], v[98:101], 0
	v_mfma_f32_16x16x32_bf16 v[174:177], v[22:25], v[102:105], v[6:9]
	v_mfma_f32_16x16x32_bf16 v[6:9], v[26:29], v[98:101], 0
	v_mfma_f32_16x16x32_bf16 v[178:181], v[30:33], v[102:105], v[6:9]
	v_mfma_f32_16x16x32_bf16 v[6:9], v[18:21], v[114:117], 0
	v_mfma_f32_16x16x32_bf16 v[182:185], v[22:25], v[118:121], v[6:9]
	v_mfma_f32_16x16x32_bf16 v[6:9], v[26:29], v[114:117], 0
	v_mfma_f32_16x16x32_bf16 v[186:189], v[30:33], v[118:121], v[6:9]
	v_mfma_f32_16x16x32_bf16 v[6:9], v[18:21], v[122:125], 0
	v_mfma_f32_16x16x32_bf16 v[190:193], v[22:25], v[126:129], v[6:9]
	v_mfma_f32_16x16x32_bf16 v[6:9], v[26:29], v[122:125], 0
	v_mfma_f32_16x16x32_bf16 v[194:197], v[30:33], v[126:129], v[6:9]
	s_setprio 1
	s_barrier
; #define PG8_WAIT_V(n) asm volatile("s_waitcnt vmcnt(" #n ")" ::: "memory")
; template <class Epi, class Sched, bool ALIGN_EPI = true, bool SP2 = true, bool FULLLINE = false, bool NOSTAGE = false, bool FP8 = false>
; __device__ __forceinline__ void gemm_phase(PG8_LAS unsigned char* lds, const Gemm g, const Sched& S, const Epi& E) {
;     ...
;         static_assert(SP2, "only the SP2 loop is kept");
;         { const int t = 0; if constexpr (Epi::NST == 16) PG8_ITER(PG8_WAIT_V(24)); else if constexpr (Epi::NST == 8) PG8_ITER(PG8_WAIT_V(16)); else PG8_ITER(PG8_WAIT_V(8)); }
;         for (int t = 2; t < nt; t += 2) PG8_ITER(PG8_WAIT_V(8));
	s_nop 5
	ds_read_b128 v[6:9], v144
	ds_read_b128 v[26:29], v144 offset:1024
	ds_read_b128 v[30:33], v144 offset:2048
	ds_read_b128 v[62:65], v144 offset:3072
	ds_read_b128 v[198:201], v145
	ds_read_b128 v[202:205], v145 offset:1024
	ds_read_b128 v[206:209], v145 offset:2048
	ds_read_b128 v[210:213], v145 offset:3072
	s_mov_b32 m0, s47
	v_lshl_add_u64 v[86:87], v[140:141], 0, s[20:21]
	ds_read_b128 v[18:21], v143 offset:32768
	ds_read_b128 v[22:25], v143 offset:33792
	ds_read_b128 v[214:217], v143 offset:34816
	ds_read_b128 v[218:221], v143 offset:35840
	ds_read_b128 v[222:225], v143 offset:36864
	ds_read_b128 v[226:229], v143 offset:37888
	ds_read_b128 v[230:233], v143 offset:38912
	ds_read_b128 v[234:237], v143 offset:39936
	global_load_lds_dwordx4 v[86:87], off
	v_lshl_add_u64 v[86:87], v[140:141], 0, s[22:23]
	s_mov_b32 m0, s52
	s_nop 0
	global_load_lds_dwordx4 v[86:87], off
	s_waitcnt vmcnt(8)
	s_waitcnt lgkmcnt(0)
	s_barrier
	s_waitcnt lgkmcnt(0)
	s_setprio 0
	v_mfma_f32_16x16x32_bf16 v[66:69], v[6:9], v[18:21], v[66:69]
	v_mfma_f32_16x16x32_bf16 v[118:121], v[26:29], v[22:25], v[66:69]
	v_mfma_f32_16x16x32_bf16 v[66:69], v[30:33], v[18:21], v[70:73]
	v_mfma_f32_16x16x32_bf16 v[114:117], v[62:65], v[22:25], v[66:69]
	v_mfma_f32_16x16x32_bf16 v[66:69], v[6:9], v[214:217], v[74:77]
	v_mfma_f32_16x16x32_bf16 v[102:105], v[26:29], v[218:221], v[66:69]
	v_mfma_f32_16x16x32_bf16 v[66:69], v[30:33], v[214:217], v[78:81]
	v_mfma_f32_16x16x32_bf16 v[98:101], v[62:65], v[218:221], v[66:69]
	v_mfma_f32_16x16x32_bf16 v[66:69], v[6:9], v[222:225], v[82:85]
	v_mfma_f32_16x16x32_bf16 v[86:89], v[26:29], v[226:229], v[66:69]
	v_mfma_f32_16x16x32_bf16 v[66:69], v[30:33], v[222:225], v[90:93]
	v_mfma_f32_16x16x32_bf16 v[82:85], v[62:65], v[226:229], v[66:69]
	v_mfma_f32_16x16x32_bf16 v[66:69], v[6:9], v[230:233], v[94:97]
	v_mfma_f32_16x16x32_bf16 v[70:73], v[26:29], v[234:237], v[66:69]
	v_mfma_f32_16x16x32_bf16 v[66:69], v[30:33], v[230:233], v[106:109]
	v_mfma_f32_16x16x32_bf16 v[66:69], v[62:65], v[234:237], v[66:69]
	v_mfma_f32_16x16x32_bf16 v[74:77], v[198:201], v[18:21], v[110:113]
	v_mfma_f32_16x16x32_bf16 v[18:21], v[206:209], v[18:21], v[34:37]
	v_mfma_f32_16x16x32_bf16 v[122:125], v[210:213], v[22:25], v[18:21]
	v_mfma_f32_16x16x32_bf16 v[18:21], v[198:201], v[214:217], v[38:41]
	v_mfma_f32_16x16x32_bf16 v[110:113], v[202:205], v[218:221], v[18:21]
	v_mfma_f32_16x16x32_bf16 v[18:21], v[206:209], v[214:217], v[42:45]
	v_mfma_f32_16x16x32_bf16 v[106:109], v[210:213], v[218:221], v[18:21]
	v_mfma_f32_16x16x32_bf16 v[18:21], v[198:201], v[222:225], v[46:49]
	v_mfma_f32_16x16x32_bf16 v[94:97], v[202:205], v[226:229], v[18:21]
	v_mfma_f32_16x16x32_bf16 v[18:21], v[206:209], v[222:225], v[50:53]
	v_mfma_f32_16x16x32_bf16 v[90:93], v[210:213], v[226:229], v[18:21]
	v_mfma_f32_16x16x32_bf16 v[18:21], v[198:201], v[230:233], v[54:57]
	v_mfma_f32_16x16x32_bf16 v[78:81], v[202:205], v[234:237], v[18:21]
	v_mfma_f32_16x16x32_bf16 v[18:21], v[206:209], v[230:233], v[58:61]
	v_mfma_f32_16x16x32_bf16 v[126:129], v[202:205], v[22:25], v[74:77]
	v_mfma_f32_16x16x32_bf16 v[74:77], v[210:213], v[234:237], v[18:21]
	s_setprio 1
	s_barrier
	s_add_i32 s41, s84, s43
	s_nop 3
	v_lshl_add_u64 v[18:19], v[238:239], 0, s[24:25]
	s_mov_b32 m0, s41
	s_add_i32 s50, s41, 0x2000
	ds_read_b128 v[42:45], v143 offset:49152
	ds_read_b128 v[46:49], v143 offset:50176
	ds_read_b128 v[214:217], v143 offset:51200
	ds_read_b128 v[218:221], v143 offset:52224
	ds_read_b128 v[222:225], v143 offset:53248
	ds_read_b128 v[226:229], v143 offset:54272
	ds_read_b128 v[230:233], v143 offset:55296
	ds_read_b128 v[234:237], v143 offset:56320
	global_load_lds_dwordx4 v[18:19], off
	v_lshl_add_u64 v[18:19], v[238:239], 0, s[26:27]
	s_mov_b32 m0, s50
	s_mov_b64 s[56:57], 0x80180
	s_add_i32 s51, s85, s43
	global_load_lds_dwordx4 v[18:19], off
	v_lshl_add_u64 v[18:19], v[238:239], 0, s[56:57]
	s_mov_b32 m0, s51
	s_mov_b64 s[56:57], 0xc0180
	s_add_i32 s33, s51, 0x2000
	global_load_lds_dwordx4 v[18:19], off
	v_lshl_add_u64 v[18:19], v[238:239], 0, s[56:57]
	s_mov_b32 m0, s33
	s_nop 0
	global_load_lds_dwordx4 v[18:19], off
	v_lshl_add_u64 v[18:19], v[140:141], 0, s[24:25]
	s_mov_b32 m0, s53
	s_nop 0
	global_load_lds_dwordx4 v[18:19], off
	v_lshl_add_u64 v[18:19], v[140:141], 0, s[26:27]
	s_mov_b32 m0, s54
	s_nop 0
	global_load_lds_dwordx4 v[18:19], off
	s_waitcnt vmcnt(8)
	s_waitcnt lgkmcnt(0)
	s_barrier
	s_waitcnt lgkmcnt(0)
	s_setprio 0
	v_mfma_f32_16x16x32_bf16 v[18:21], v[6:9], v[42:45], v[146:149]
	v_mfma_f32_16x16x32_bf16 v[54:57], v[26:29], v[46:49], v[18:21]
	v_mfma_f32_16x16x32_bf16 v[18:21], v[30:33], v[42:45], v[150:153]
	v_mfma_f32_16x16x32_bf16 v[50:53], v[62:65], v[46:49], v[18:21]
	v_mfma_f32_16x16x32_bf16 v[18:21], v[6:9], v[214:217], v[154:157]
	v_mfma_f32_16x16x32_bf16 v[38:41], v[26:29], v[218:221], v[18:21]
	v_mfma_f32_16x16x32_bf16 v[18:21], v[30:33], v[214:217], v[158:161]
	v_mfma_f32_16x16x32_bf16 v[34:37], v[62:65], v[218:221], v[18:21]
	v_mfma_f32_16x16x32_bf16 v[18:21], v[6:9], v[222:225], v[162:165]
	v_mfma_f32_16x16x32_bf16 v[2:5], v[6:9], v[230:233], v[2:5]
	v_mfma_f32_16x16x32_bf16 v[22:25], v[26:29], v[226:229], v[18:21]
	v_mfma_f32_16x16x32_bf16 v[18:21], v[30:33], v[222:225], v[166:169]
	v_mfma_f32_16x16x32_bf16 v[6:9], v[26:29], v[234:237], v[2:5]
	v_mfma_f32_16x16x32_bf16 v[2:5], v[30:33], v[230:233], v[10:13]
	v_mfma_f32_16x16x32_bf16 v[18:21], v[62:65], v[226:229], v[18:21]
	v_mfma_f32_16x16x32_bf16 v[2:5], v[62:65], v[234:237], v[2:5]
	v_mfma_f32_16x16x32_bf16 v[10:13], v[198:201], v[42:45], v[14:17]
	v_mfma_f32_16x16x32_bf16 v[62:65], v[202:205], v[46:49], v[10:13]
	v_mfma_f32_16x16x32_bf16 v[10:13], v[206:209], v[42:45], v[170:173]
	v_mfma_f32_16x16x32_bf16 v[58:61], v[210:213], v[46:49], v[10:13]
	v_mfma_f32_16x16x32_bf16 v[10:13], v[198:201], v[214:217], v[174:177]
	v_mfma_f32_16x16x32_bf16 v[46:49], v[202:205], v[218:221], v[10:13]
	v_mfma_f32_16x16x32_bf16 v[10:13], v[206:209], v[214:217], v[178:181]
	v_mfma_f32_16x16x32_bf16 v[42:45], v[210:213], v[218:221], v[10:13]
	v_mfma_f32_16x16x32_bf16 v[10:13], v[198:201], v[222:225], v[182:185]
	v_mfma_f32_16x16x32_bf16 v[30:33], v[202:205], v[226:229], v[10:13]
	v_mfma_f32_16x16x32_bf16 v[10:13], v[206:209], v[222:225], v[186:189]
	v_mfma_f32_16x16x32_bf16 v[26:29], v[210:213], v[226:229], v[10:13]
	v_mfma_f32_16x16x32_bf16 v[10:13], v[198:201], v[230:233], v[190:193]
	v_mfma_f32_16x16x32_bf16 v[14:17], v[202:205], v[234:237], v[10:13]
	v_mfma_f32_16x16x32_bf16 v[10:13], v[206:209], v[230:233], v[194:197]
	v_mfma_f32_16x16x32_bf16 v[10:13], v[210:213], v[234:237], v[10:13]
	s_setprio 1
	s_barrier
	s_add_u32 s78, s78, 0x80180
	s_addc_u32 s79, s79, 0
	s_add_u32 s56, s76, 0x200
	s_addc_u32 s57, s77, 0
	s_mov_b32 s76, 0
.LBB0_767:
	ds_read_b128 v[146:149], v1
	ds_read_b128 v[150:153], v1 offset:1024
	ds_read_b128 v[154:157], v1 offset:2048
	ds_read_b128 v[158:161], v1 offset:3072
	ds_read_b128 v[162:165], v142
	ds_read_b128 v[166:169], v142 offset:1024
	ds_read_b128 v[170:173], v142 offset:2048
	ds_read_b128 v[174:177], v142 offset:3072
	s_add_u32 s0, s78, 0xfff80080
	s_addc_u32 s1, s79, -1
	s_cmp_eq_u32 s76, 28
	s_cselect_b32 s95, s67, s1
	s_cselect_b32 s94, s69, s0
	s_cselect_b32 s97, s89, s57
	s_cselect_b32 s96, s90, s56
	s_mov_b32 m0, s81
	v_lshl_add_u64 v[140:141], s[78:79], 0, v[134:135]
	ds_read_b128 v[178:181], v143
	ds_read_b128 v[182:185], v143 offset:1024
	ds_read_b128 v[186:189], v143 offset:2048
	ds_read_b128 v[190:193], v143 offset:3072
	ds_read_b128 v[194:197], v143 offset:4096
	ds_read_b128 v[198:201], v143 offset:5120
	ds_read_b128 v[202:205], v143 offset:6144
	ds_read_b128 v[206:209], v143 offset:7168
	global_load_lds_dwordx4 v[140:141], off
	v_lshl_add_u64 v[140:141], v[140:141], 0, s[28:29]
	s_mov_b32 m0, s82
	s_nop 0
	global_load_lds_dwordx4 v[140:141], off
	s_waitcnt vmcnt(8)
	s_waitcnt lgkmcnt(0)
	s_barrier
	s_waitcnt lgkmcnt(0)
	s_setprio 0
	v_mfma_f32_16x16x32_bf16 v[118:121], v[146:149], v[178:181], v[118:121]
	v_mfma_f32_16x16x32_bf16 v[114:117], v[154:157], v[178:181], v[114:117]
	v_mfma_f32_16x16x32_bf16 v[102:105], v[146:149], v[186:189], v[102:105]
	v_mfma_f32_16x16x32_bf16 v[98:101], v[154:157], v[186:189], v[98:101]
	v_mfma_f32_16x16x32_bf16 v[86:89], v[146:149], v[194:197], v[86:89]
	v_mfma_f32_16x16x32_bf16 v[82:85], v[154:157], v[194:197], v[82:85]
	v_mfma_f32_16x16x32_bf16 v[70:73], v[146:149], v[202:205], v[70:73]
	v_mfma_f32_16x16x32_bf16 v[66:69], v[154:157], v[202:205], v[66:69]
	v_mfma_f32_16x16x32_bf16 v[118:121], v[150:153], v[182:185], v[118:121]
	v_mfma_f32_16x16x32_bf16 v[114:117], v[158:161], v[182:185], v[114:117]
	v_mfma_f32_16x16x32_bf16 v[102:105], v[150:153], v[190:193], v[102:105]
	v_mfma_f32_16x16x32_bf16 v[98:101], v[158:161], v[190:193], v[98:101]
	v_mfma_f32_16x16x32_bf16 v[86:89], v[150:153], v[198:201], v[86:89]
	v_mfma_f32_16x16x32_bf16 v[82:85], v[158:161], v[198:201], v[82:85]
	v_mfma_f32_16x16x32_bf16 v[70:73], v[150:153], v[206:209], v[70:73]
	v_mfma_f32_16x16x32_bf16 v[66:69], v[158:161], v[206:209], v[66:69]
	v_mfma_f32_16x16x32_bf16 v[126:129], v[162:165], v[178:181], v[126:129]
	v_mfma_f32_16x16x32_bf16 v[122:125], v[170:173], v[178:181], v[122:125]
	v_mfma_f32_16x16x32_bf16 v[110:113], v[162:165], v[186:189], v[110:113]
	v_mfma_f32_16x16x32_bf16 v[106:109], v[170:173], v[186:189], v[106:109]
	v_mfma_f32_16x16x32_bf16 v[94:97], v[162:165], v[194:197], v[94:97]
	v_mfma_f32_16x16x32_bf16 v[90:93], v[170:173], v[194:197], v[90:93]
	v_mfma_f32_16x16x32_bf16 v[78:81], v[162:165], v[202:205], v[78:81]
	v_mfma_f32_16x16x32_bf16 v[74:77], v[170:173], v[202:205], v[74:77]
	v_mfma_f32_16x16x32_bf16 v[126:129], v[166:169], v[182:185], v[126:129]
	v_mfma_f32_16x16x32_bf16 v[122:125], v[174:177], v[182:185], v[122:125]
	v_mfma_f32_16x16x32_bf16 v[110:113], v[166:169], v[190:193], v[110:113]
	v_mfma_f32_16x16x32_bf16 v[106:109], v[174:177], v[190:193], v[106:109]
	v_mfma_f32_16x16x32_bf16 v[94:97], v[166:169], v[198:201], v[94:97]
	v_mfma_f32_16x16x32_bf16 v[90:93], v[174:177], v[198:201], v[90:93]
	v_mfma_f32_16x16x32_bf16 v[78:81], v[166:169], v[206:209], v[78:81]
	v_mfma_f32_16x16x32_bf16 v[74:77], v[174:177], v[206:209], v[74:77]
	s_setprio 1
	s_barrier
	s_mov_b32 m0, s83
	v_lshl_add_u64 v[140:141], s[96:97], 0, v[130:131]
	ds_read_b128 v[178:181], v143 offset:16384
	ds_read_b128 v[182:185], v143 offset:17408
	ds_read_b128 v[186:189], v143 offset:18432
	ds_read_b128 v[190:193], v143 offset:19456
	ds_read_b128 v[194:197], v143 offset:20480
	ds_read_b128 v[198:201], v143 offset:21504
	ds_read_b128 v[202:205], v143 offset:22528
	ds_read_b128 v[206:209], v143 offset:23552
	global_load_lds_dwordx4 v[140:141], off
	v_lshl_add_u64 v[210:211], v[140:141], 0, s[28:29]
	s_mov_b32 m0, s91
	s_nop 0
	global_load_lds_dwordx4 v[210:211], off
	v_lshl_add_u64 v[210:211], v[140:141], 0, s[30:31]
	s_mov_b32 m0, s92
	s_nop 0
	global_load_lds_dwordx4 v[210:211], off
	v_lshl_add_u64 v[210:211], v[140:141], 0, s[34:35]
	s_mov_b32 m0, s40
	s_nop 0
	global_load_lds_dwordx4 v[210:211], off
	v_lshl_add_u64 v[210:211], s[94:95], 0, v[132:133]
	s_mov_b32 m0, s45
	v_lshl_add_u64 v[212:213], v[210:211], 0, s[28:29]
	global_load_lds_dwordx4 v[210:211], off
	s_mov_b32 m0, s46
	s_nop 0
	global_load_lds_dwordx4 v[212:213], off
	s_waitcnt vmcnt(8)
	s_waitcnt lgkmcnt(0)
	s_barrier
	s_waitcnt lgkmcnt(0)
	s_setprio 0
	v_mfma_f32_16x16x32_bf16 v[54:57], v[146:149], v[178:181], v[54:57]
	v_mfma_f32_16x16x32_bf16 v[50:53], v[154:157], v[178:181], v[50:53]
	v_mfma_f32_16x16x32_bf16 v[38:41], v[146:149], v[186:189], v[38:41]
	v_mfma_f32_16x16x32_bf16 v[34:37], v[154:157], v[186:189], v[34:37]
	v_mfma_f32_16x16x32_bf16 v[22:25], v[146:149], v[194:197], v[22:25]
	v_mfma_f32_16x16x32_bf16 v[18:21], v[154:157], v[194:197], v[18:21]
	v_mfma_f32_16x16x32_bf16 v[6:9], v[146:149], v[202:205], v[6:9]
	v_mfma_f32_16x16x32_bf16 v[2:5], v[154:157], v[202:205], v[2:5]
	v_mfma_f32_16x16x32_bf16 v[54:57], v[150:153], v[182:185], v[54:57]
	v_mfma_f32_16x16x32_bf16 v[50:53], v[158:161], v[182:185], v[50:53]
	v_mfma_f32_16x16x32_bf16 v[38:41], v[150:153], v[190:193], v[38:41]
	v_mfma_f32_16x16x32_bf16 v[34:37], v[158:161], v[190:193], v[34:37]
	v_mfma_f32_16x16x32_bf16 v[22:25], v[150:153], v[198:201], v[22:25]
	v_mfma_f32_16x16x32_bf16 v[18:21], v[158:161], v[198:201], v[18:21]
	v_mfma_f32_16x16x32_bf16 v[6:9], v[150:153], v[206:209], v[6:9]
	v_mfma_f32_16x16x32_bf16 v[2:5], v[158:161], v[206:209], v[2:5]
	v_mfma_f32_16x16x32_bf16 v[62:65], v[162:165], v[178:181], v[62:65]
	v_mfma_f32_16x16x32_bf16 v[58:61], v[170:173], v[178:181], v[58:61]
	v_mfma_f32_16x16x32_bf16 v[46:49], v[162:165], v[186:189], v[46:49]
	v_mfma_f32_16x16x32_bf16 v[42:45], v[170:173], v[186:189], v[42:45]
	v_mfma_f32_16x16x32_bf16 v[30:33], v[162:165], v[194:197], v[30:33]
	v_mfma_f32_16x16x32_bf16 v[26:29], v[170:173], v[194:197], v[26:29]
	v_mfma_f32_16x16x32_bf16 v[14:17], v[162:165], v[202:205], v[14:17]
	v_mfma_f32_16x16x32_bf16 v[10:13], v[170:173], v[202:205], v[10:13]
	v_mfma_f32_16x16x32_bf16 v[62:65], v[166:169], v[182:185], v[62:65]
	v_mfma_f32_16x16x32_bf16 v[58:61], v[174:177], v[182:185], v[58:61]
	v_mfma_f32_16x16x32_bf16 v[46:49], v[166:169], v[190:193], v[46:49]
	v_mfma_f32_16x16x32_bf16 v[42:45], v[174:177], v[190:193], v[42:45]
	v_mfma_f32_16x16x32_bf16 v[30:33], v[166:169], v[198:201], v[30:33]
	v_mfma_f32_16x16x32_bf16 v[26:29], v[174:177], v[198:201], v[26:29]
	v_mfma_f32_16x16x32_bf16 v[14:17], v[166:169], v[206:209], v[14:17]
	v_mfma_f32_16x16x32_bf16 v[10:13], v[174:177], v[206:209], v[10:13]
	s_setprio 1
	s_barrier
	ds_read_b128 v[146:149], v144
	ds_read_b128 v[150:153], v144 offset:1024
	ds_read_b128 v[154:157], v144 offset:2048
	ds_read_b128 v[158:161], v144 offset:3072
	ds_read_b128 v[162:165], v145
	ds_read_b128 v[166:169], v145 offset:1024
	ds_read_b128 v[170:173], v145 offset:2048
	ds_read_b128 v[174:177], v145 offset:3072
	s_mov_b32 m0, s47
	v_lshl_add_u64 v[212:213], v[210:211], 0, s[30:31]
	ds_read_b128 v[178:181], v143 offset:32768
	ds_read_b128 v[182:185], v143 offset:33792
	ds_read_b128 v[186:189], v143 offset:34816
	ds_read_b128 v[190:193], v143 offset:35840
	ds_read_b128 v[194:197], v143 offset:36864
	ds_read_b128 v[198:201], v143 offset:37888
	ds_read_b128 v[202:205], v143 offset:38912
	ds_read_b128 v[206:209], v143 offset:39936
	global_load_lds_dwordx4 v[212:213], off
	v_lshl_add_u64 v[212:213], v[210:211], 0, s[34:35]
	s_mov_b32 m0, s52
	s_nop 0
	global_load_lds_dwordx4 v[212:213], off
	s_waitcnt vmcnt(8)
	s_waitcnt lgkmcnt(0)
	s_barrier
	s_waitcnt lgkmcnt(0)
	s_setprio 0
	v_mfma_f32_16x16x32_bf16 v[118:121], v[146:149], v[178:181], v[118:121]
	v_mfma_f32_16x16x32_bf16 v[114:117], v[154:157], v[178:181], v[114:117]
	v_mfma_f32_16x16x32_bf16 v[102:105], v[146:149], v[186:189], v[102:105]
	v_mfma_f32_16x16x32_bf16 v[98:101], v[154:157], v[186:189], v[98:101]
	v_mfma_f32_16x16x32_bf16 v[86:89], v[146:149], v[194:197], v[86:89]
	v_mfma_f32_16x16x32_bf16 v[82:85], v[154:157], v[194:197], v[82:85]
	v_mfma_f32_16x16x32_bf16 v[70:73], v[146:149], v[202:205], v[70:73]
	v_mfma_f32_16x16x32_bf16 v[66:69], v[154:157], v[202:205], v[66:69]
	v_mfma_f32_16x16x32_bf16 v[118:121], v[150:153], v[182:185], v[118:121]
	v_mfma_f32_16x16x32_bf16 v[114:117], v[158:161], v[182:185], v[114:117]
	v_mfma_f32_16x16x32_bf16 v[102:105], v[150:153], v[190:193], v[102:105]
	v_mfma_f32_16x16x32_bf16 v[98:101], v[158:161], v[190:193], v[98:101]
	v_mfma_f32_16x16x32_bf16 v[86:89], v[150:153], v[198:201], v[86:89]
	v_mfma_f32_16x16x32_bf16 v[82:85], v[158:161], v[198:201], v[82:85]
	v_mfma_f32_16x16x32_bf16 v[70:73], v[150:153], v[206:209], v[70:73]
	v_mfma_f32_16x16x32_bf16 v[66:69], v[158:161], v[206:209], v[66:69]
	v_mfma_f32_16x16x32_bf16 v[126:129], v[162:165], v[178:181], v[126:129]
	v_mfma_f32_16x16x32_bf16 v[122:125], v[170:173], v[178:181], v[122:125]
	v_mfma_f32_16x16x32_bf16 v[110:113], v[162:165], v[186:189], v[110:113]
	v_mfma_f32_16x16x32_bf16 v[106:109], v[170:173], v[186:189], v[106:109]
	v_mfma_f32_16x16x32_bf16 v[94:97], v[162:165], v[194:197], v[94:97]
	v_mfma_f32_16x16x32_bf16 v[90:93], v[170:173], v[194:197], v[90:93]
	v_mfma_f32_16x16x32_bf16 v[78:81], v[162:165], v[202:205], v[78:81]
	v_mfma_f32_16x16x32_bf16 v[74:77], v[170:173], v[202:205], v[74:77]
	v_mfma_f32_16x16x32_bf16 v[126:129], v[166:169], v[182:185], v[126:129]
	v_mfma_f32_16x16x32_bf16 v[122:125], v[174:177], v[182:185], v[122:125]
	v_mfma_f32_16x16x32_bf16 v[110:113], v[166:169], v[190:193], v[110:113]
	v_mfma_f32_16x16x32_bf16 v[106:109], v[174:177], v[190:193], v[106:109]
	v_mfma_f32_16x16x32_bf16 v[94:97], v[166:169], v[198:201], v[94:97]
	v_mfma_f32_16x16x32_bf16 v[90:93], v[174:177], v[198:201], v[90:93]
	v_mfma_f32_16x16x32_bf16 v[78:81], v[166:169], v[206:209], v[78:81]
	v_mfma_f32_16x16x32_bf16 v[74:77], v[174:177], v[206:209], v[74:77]
	s_setprio 1
	s_barrier
; #define PG8_WAIT_V(n) asm volatile("s_waitcnt vmcnt(" #n ")" ::: "memory")
; template <class Epi, class Sched, bool ALIGN_EPI = true, bool SP2 = true, bool FULLLINE = false, bool NOSTAGE = false, bool FP8 = false>
; __device__ __forceinline__ void gemm_phase(PG8_LAS unsigned char* lds, const Gemm g, const Sched& S, const Epi& E) {
;     ...
;         static_assert(SP2, "only the SP2 loop is kept");
;         { const int t = 0; if constexpr (Epi::NST == 16) PG8_ITER(PG8_WAIT_V(24)); else if constexpr (Epi::NST == 8) PG8_ITER(PG8_WAIT_V(16)); else PG8_ITER(PG8_WAIT_V(8)); }
;         for (int t = 2; t < nt; t += 2) PG8_ITER(PG8_WAIT_V(8));
	s_mov_b32 m0, s41
	v_lshl_add_u64 v[212:213], v[140:141], 0, s[36:37]
	ds_read_b128 v[178:181], v143 offset:49152
	ds_read_b128 v[182:185], v143 offset:50176
	ds_read_b128 v[186:189], v143 offset:51200
	ds_read_b128 v[190:193], v143 offset:52224
	ds_read_b128 v[194:197], v143 offset:53248
	ds_read_b128 v[198:201], v143 offset:54272
	ds_read_b128 v[202:205], v143 offset:55296
	ds_read_b128 v[206:209], v143 offset:56320
	global_load_lds_dwordx4 v[212:213], off
	v_lshl_add_u64 v[212:213], v[140:141], 0, s[38:39]
	s_mov_b32 m0, s50
	s_nop 0
	global_load_lds_dwordx4 v[212:213], off
	v_lshl_add_u64 v[212:213], v[140:141], 0, s[12:13]
	s_mov_b32 m0, s51
	v_lshl_add_u64 v[140:141], v[140:141], 0, s[14:15]
	global_load_lds_dwordx4 v[212:213], off
	s_mov_b32 m0, s33
	s_nop 0
	global_load_lds_dwordx4 v[140:141], off
	v_lshl_add_u64 v[140:141], v[210:211], 0, s[36:37]
	s_mov_b32 m0, s53
	s_nop 0
	global_load_lds_dwordx4 v[140:141], off
	v_lshl_add_u64 v[140:141], v[210:211], 0, s[38:39]
	s_mov_b32 m0, s54
	s_nop 0
	global_load_lds_dwordx4 v[140:141], off
	s_waitcnt vmcnt(8)
	s_waitcnt lgkmcnt(0)
	s_barrier
	s_waitcnt lgkmcnt(0)
	s_setprio 0
	v_mfma_f32_16x16x32_bf16 v[54:57], v[146:149], v[178:181], v[54:57]
	v_mfma_f32_16x16x32_bf16 v[50:53], v[154:157], v[178:181], v[50:53]
	v_mfma_f32_16x16x32_bf16 v[38:41], v[146:149], v[186:189], v[38:41]
	v_mfma_f32_16x16x32_bf16 v[34:37], v[154:157], v[186:189], v[34:37]
	v_mfma_f32_16x16x32_bf16 v[22:25], v[146:149], v[194:197], v[22:25]
	v_mfma_f32_16x16x32_bf16 v[18:21], v[154:157], v[194:197], v[18:21]
	v_mfma_f32_16x16x32_bf16 v[6:9], v[146:149], v[202:205], v[6:9]
	v_mfma_f32_16x16x32_bf16 v[2:5], v[154:157], v[202:205], v[2:5]
	v_mfma_f32_16x16x32_bf16 v[54:57], v[150:153], v[182:185], v[54:57]
	v_mfma_f32_16x16x32_bf16 v[50:53], v[158:161], v[182:185], v[50:53]
	v_mfma_f32_16x16x32_bf16 v[38:41], v[150:153], v[190:193], v[38:41]
	v_mfma_f32_16x16x32_bf16 v[34:37], v[158:161], v[190:193], v[34:37]
	v_mfma_f32_16x16x32_bf16 v[22:25], v[150:153], v[198:201], v[22:25]
	v_mfma_f32_16x16x32_bf16 v[18:21], v[158:161], v[198:201], v[18:21]
	v_mfma_f32_16x16x32_bf16 v[6:9], v[150:153], v[206:209], v[6:9]
	v_mfma_f32_16x16x32_bf16 v[2:5], v[158:161], v[206:209], v[2:5]
	v_mfma_f32_16x16x32_bf16 v[62:65], v[162:165], v[178:181], v[62:65]
	v_mfma_f32_16x16x32_bf16 v[58:61], v[170:173], v[178:181], v[58:61]
	v_mfma_f32_16x16x32_bf16 v[46:49], v[162:165], v[186:189], v[46:49]
	v_mfma_f32_16x16x32_bf16 v[42:45], v[170:173], v[186:189], v[42:45]
	v_mfma_f32_16x16x32_bf16 v[30:33], v[162:165], v[194:197], v[30:33]
	v_mfma_f32_16x16x32_bf16 v[26:29], v[170:173], v[194:197], v[26:29]
	v_mfma_f32_16x16x32_bf16 v[14:17], v[162:165], v[202:205], v[14:17]
	v_mfma_f32_16x16x32_bf16 v[10:13], v[170:173], v[202:205], v[10:13]
	v_mfma_f32_16x16x32_bf16 v[62:65], v[166:169], v[182:185], v[62:65]
	v_mfma_f32_16x16x32_bf16 v[58:61], v[174:177], v[182:185], v[58:61]
	v_mfma_f32_16x16x32_bf16 v[46:49], v[166:169], v[190:193], v[46:49]
	v_mfma_f32_16x16x32_bf16 v[42:45], v[174:177], v[190:193], v[42:45]
	v_mfma_f32_16x16x32_bf16 v[30:33], v[166:169], v[198:201], v[30:33]
	v_mfma_f32_16x16x32_bf16 v[26:29], v[174:177], v[198:201], v[26:29]
	v_mfma_f32_16x16x32_bf16 v[14:17], v[166:169], v[206:209], v[14:17]
	v_mfma_f32_16x16x32_bf16 v[10:13], v[174:177], v[206:209], v[10:13]
	s_setprio 1
	s_barrier
	s_add_i32 s76, s76, 2
	s_add_u32 s78, s78, 0x100
	s_addc_u32 s79, s79, 0
	s_add_u32 s56, s56, 0x100
	s_addc_u32 s57, s57, 0
	s_cmp_gt_u32 s76, 29
	s_cbranch_scc0 .LBB0_767
	s_and_b64 vcc, exec, s[10:11]
	s_cbranch_vccz .LBB0_770
	s_barrier

; #define PG8_WAIT_V(n) asm volatile("s_waitcnt vmcnt(" #n ")" ::: "memory")
; template <class Epi, class Sched, bool ALIGN_EPI = true, bool SP2 = true, bool FULLLINE = false, bool NOSTAGE = false, bool FP8 = false>
; __device__ __forceinline__ void gemm_phase(PG8_LAS unsigned char* lds, const Gemm g, const Sched& S, const Epi& E) {
;     ...
;         const bool has_next = S.next(ui + 1, nxt);
;         const char* nA = has_next ? PG8_ABASE(nxt) : cA; const char* nB = has_next ? PG8_BBASE(nxt) : cB;
;     ...
;         { const int t = 0; if constexpr (Epi::NST == 16) PG8_ITER(PG8_WAIT_V(24)); else if constexpr (Epi::NST == 8) PG8_ITER(PG8_WAIT_V(16)); else PG8_ITER(PG8_WAIT_V(8)); }
.LBB0_869:
	ds_read_b128 v[2:5], v1
	ds_read_b128 v[6:9], v1 offset:1024
	ds_read_b128 v[10:13], v1 offset:2048
	ds_read_b128 v[14:17], v1 offset:3072
	ds_read_b128 v[18:21], v192
	ds_read_b128 v[22:25], v192 offset:1024
	ds_read_b128 v[26:29], v192 offset:2048
	ds_read_b128 v[30:33], v192 offset:3072
	v_lshl_add_u64 v[248:249], s[70:71], 0, v[170:171]
	s_add_i32 s85, s45, 0xc000
	v_lshl_add_u64 v[66:67], v[248:249], 0, s[14:15]
	s_mov_b32 m0, s85
	s_add_i32 s87, s45, 0xe000
	ds_read_b128 v[34:37], v193
	ds_read_b128 v[38:41], v193 offset:1024
	ds_read_b128 v[42:45], v193 offset:2048
	ds_read_b128 v[46:49], v193 offset:3072
	ds_read_b128 v[50:53], v193 offset:4096
	ds_read_b128 v[54:57], v193 offset:5120
	ds_read_b128 v[58:61], v193 offset:6144
	ds_read_b128 v[62:65], v193 offset:7168
	global_load_lds_dwordx4 v[66:67], off
	v_lshl_add_u64 v[66:67], v[248:249], 0, s[16:17]
	s_mov_b32 m0, s87
	s_nop 0
	global_load_lds_dwordx4 v[66:67], off
	s_waitcnt vmcnt(24)
	s_waitcnt lgkmcnt(0)
	s_barrier
	s_waitcnt lgkmcnt(0)
	s_setprio 0
	v_mfma_f32_16x16x32_bf16 v[66:69], v[2:5], v[34:37], 0
	v_mfma_f32_16x16x32_bf16 v[70:73], v[10:13], v[34:37], 0
	v_mfma_f32_16x16x32_bf16 v[78:81], v[10:13], v[42:45], 0
	v_mfma_f32_16x16x32_bf16 v[86:89], v[10:13], v[50:53], 0
	v_mfma_f32_16x16x32_bf16 v[66:69], v[6:9], v[38:41], v[66:69]
	v_mfma_f32_16x16x32_bf16 v[70:73], v[14:17], v[38:41], v[70:73]
	v_mfma_f32_16x16x32_bf16 v[74:77], v[2:5], v[42:45], 0
	v_mfma_f32_16x16x32_bf16 v[78:81], v[14:17], v[46:49], v[78:81]
	v_mfma_f32_16x16x32_bf16 v[82:85], v[2:5], v[50:53], 0
	v_mfma_f32_16x16x32_bf16 v[86:89], v[14:17], v[54:57], v[86:89]
	v_mfma_f32_16x16x32_bf16 v[90:93], v[2:5], v[58:61], 0
	v_mfma_f32_16x16x32_bf16 v[94:97], v[10:13], v[58:61], 0
	v_mfma_f32_16x16x32_bf16 v[74:77], v[6:9], v[46:49], v[74:77]
	v_mfma_f32_16x16x32_bf16 v[82:85], v[6:9], v[54:57], v[82:85]
	v_mfma_f32_16x16x32_bf16 v[90:93], v[6:9], v[62:65], v[90:93]
	v_mfma_f32_16x16x32_bf16 v[94:97], v[14:17], v[62:65], v[94:97]
	v_mfma_f32_16x16x32_bf16 v[98:101], v[18:21], v[34:37], 0
	v_mfma_f32_16x16x32_bf16 v[34:37], v[26:29], v[34:37], 0
	v_mfma_f32_16x16x32_bf16 v[98:101], v[22:25], v[38:41], v[98:101]
	v_mfma_f32_16x16x32_bf16 v[34:37], v[30:33], v[38:41], v[34:37]
	v_mfma_f32_16x16x32_bf16 v[38:41], v[18:21], v[42:45], 0
	v_mfma_f32_16x16x32_bf16 v[42:45], v[26:29], v[42:45], 0
	v_mfma_f32_16x16x32_bf16 v[38:41], v[22:25], v[46:49], v[38:41]
	v_mfma_f32_16x16x32_bf16 v[42:45], v[30:33], v[46:49], v[42:45]
	v_mfma_f32_16x16x32_bf16 v[46:49], v[18:21], v[50:53], 0
	v_mfma_f32_16x16x32_bf16 v[50:53], v[26:29], v[50:53], 0
	v_mfma_f32_16x16x32_bf16 v[46:49], v[22:25], v[54:57], v[46:49]
	v_mfma_f32_16x16x32_bf16 v[50:53], v[30:33], v[54:57], v[50:53]
	v_mfma_f32_16x16x32_bf16 v[54:57], v[18:21], v[58:61], 0
	v_mfma_f32_16x16x32_bf16 v[58:61], v[26:29], v[58:61], 0
	v_mfma_f32_16x16x32_bf16 v[54:57], v[22:25], v[62:65], v[54:57]
	v_mfma_f32_16x16x32_bf16 v[58:61], v[30:33], v[62:65], v[58:61]
	s_setprio 1
	s_barrier
	v_lshl_add_u64 v[250:251], s[72:73], 0, v[172:173]
	s_add_i32 s88, s77, s44
	v_lshl_add_u64 v[130:131], v[250:251], 0, s[18:19]
	s_mov_b32 m0, s88
	s_add_i32 s89, s88, 0x2000
	ds_read_b128 v[62:65], v193 offset:16384
	ds_read_b128 v[102:105], v193 offset:17408
	ds_read_b128 v[106:109], v193 offset:18432
	ds_read_b128 v[110:113], v193 offset:19456
	ds_read_b128 v[114:117], v193 offset:20480
	ds_read_b128 v[118:121], v193 offset:21504
	ds_read_b128 v[122:125], v193 offset:22528
	ds_read_b128 v[126:129], v193 offset:23552
	global_load_lds_dwordx4 v[130:131], off
	v_lshl_add_u64 v[130:131], v[250:251], 0, s[20:21]
	s_mov_b32 m0, s89
	s_add_i32 s90, s78, s44
	global_load_lds_dwordx4 v[130:131], off
	v_lshl_add_u64 v[130:131], v[250:251], 0, s[22:23]
	s_mov_b32 m0, s90
	s_add_i32 s40, s90, 0x2000
	global_load_lds_dwordx4 v[130:131], off
	v_lshl_add_u64 v[130:131], v[250:251], 0, s[24:25]
	s_mov_b32 m0, s40
	s_nop 0
	global_load_lds_dwordx4 v[130:131], off
	v_lshl_add_u64 v[130:131], v[248:249], 0, s[18:19]
	s_mov_b32 m0, s45
	s_nop 0
	global_load_lds_dwordx4 v[130:131], off
	v_lshl_add_u64 v[130:131], v[248:249], 0, s[20:21]
	s_mov_b32 m0, s46
	s_nop 0
	global_load_lds_dwordx4 v[130:131], off
	s_waitcnt vmcnt(24)
	s_waitcnt lgkmcnt(0)
	s_barrier
	s_waitcnt lgkmcnt(0)
	s_setprio 0
	v_mfma_f32_16x16x32_bf16 v[130:133], v[2:5], v[62:65], 0
	v_mfma_f32_16x16x32_bf16 v[138:141], v[6:9], v[102:105], v[130:133]
	v_mfma_f32_16x16x32_bf16 v[130:133], v[10:13], v[62:65], 0
	v_mfma_f32_16x16x32_bf16 v[150:153], v[14:17], v[102:105], v[130:133]
	v_mfma_f32_16x16x32_bf16 v[130:133], v[2:5], v[106:109], 0
	v_mfma_f32_16x16x32_bf16 v[154:157], v[6:9], v[110:113], v[130:133]
	v_mfma_f32_16x16x32_bf16 v[130:133], v[10:13], v[106:109], 0
	v_mfma_f32_16x16x32_bf16 v[158:161], v[14:17], v[110:113], v[130:133]
	v_mfma_f32_16x16x32_bf16 v[130:133], v[2:5], v[114:117], 0
	v_mfma_f32_16x16x32_bf16 v[2:5], v[2:5], v[122:125], 0
	v_mfma_f32_16x16x32_bf16 v[162:165], v[6:9], v[118:121], v[130:133]
	v_mfma_f32_16x16x32_bf16 v[2:5], v[6:9], v[126:129], v[2:5]
	v_mfma_f32_16x16x32_bf16 v[6:9], v[10:13], v[122:125], 0
	v_mfma_f32_16x16x32_bf16 v[130:133], v[10:13], v[114:117], 0
	v_mfma_f32_16x16x32_bf16 v[6:9], v[14:17], v[126:129], v[6:9]
	v_mfma_f32_16x16x32_bf16 v[166:169], v[14:17], v[118:121], v[130:133]
	v_mfma_f32_16x16x32_bf16 v[10:13], v[18:21], v[62:65], 0
	v_mfma_f32_16x16x32_bf16 v[180:183], v[22:25], v[102:105], v[10:13]
	v_mfma_f32_16x16x32_bf16 v[10:13], v[26:29], v[62:65], 0
	v_mfma_f32_16x16x32_bf16 v[184:187], v[30:33], v[102:105], v[10:13]
	v_mfma_f32_16x16x32_bf16 v[10:13], v[18:21], v[106:109], 0
	v_mfma_f32_16x16x32_bf16 v[188:191], v[22:25], v[110:113], v[10:13]
	v_mfma_f32_16x16x32_bf16 v[10:13], v[26:29], v[106:109], 0
	v_mfma_f32_16x16x32_bf16 v[196:199], v[30:33], v[110:113], v[10:13]
	v_mfma_f32_16x16x32_bf16 v[10:13], v[18:21], v[114:117], 0
	v_mfma_f32_16x16x32_bf16 v[200:203], v[22:25], v[118:121], v[10:13]
	v_mfma_f32_16x16x32_bf16 v[10:13], v[26:29], v[114:117], 0
	v_mfma_f32_16x16x32_bf16 v[204:207], v[30:33], v[118:121], v[10:13]
	v_mfma_f32_16x16x32_bf16 v[10:13], v[18:21], v[122:125], 0
	v_mfma_f32_16x16x32_bf16 v[208:211], v[22:25], v[126:129], v[10:13]
	v_mfma_f32_16x16x32_bf16 v[10:13], v[26:29], v[122:125], 0
	v_mfma_f32_16x16x32_bf16 v[212:215], v[30:33], v[126:129], v[10:13]
	s_setprio 1
	s_barrier
; #define PG8_WAIT_V(n) asm volatile("s_waitcnt vmcnt(" #n ")" ::: "memory")
; template <class Epi, class Sched, bool ALIGN_EPI = true, bool SP2 = true, bool FULLLINE = false, bool NOSTAGE = false, bool FP8 = false>
; __device__ __forceinline__ void gemm_phase(PG8_LAS unsigned char* lds, const Gemm g, const Sched& S, const Epi& E) {
;     ...
;         static_assert(SP2, "only the SP2 loop is kept");
;         { const int t = 0; if constexpr (Epi::NST == 16) PG8_ITER(PG8_WAIT_V(24)); else if constexpr (Epi::NST == 8) PG8_ITER(PG8_WAIT_V(16)); else PG8_ITER(PG8_WAIT_V(8)); }
;         for (int t = 2; t < nt; t += 2) PG8_ITER(PG8_WAIT_V(8));
	s_nop 5
	ds_read_b128 v[10:13], v194
	ds_read_b128 v[14:17], v194 offset:1024
	ds_read_b128 v[18:21], v194 offset:2048
	ds_read_b128 v[22:25], v194 offset:3072
	ds_read_b128 v[216:219], v195
	ds_read_b128 v[220:223], v195 offset:1024
	ds_read_b128 v[224:227], v195 offset:2048
	ds_read_b128 v[228:231], v195 offset:3072
	s_mov_b32 m0, s47
	v_lshl_add_u64 v[106:107], v[248:249], 0, s[22:23]
	ds_read_b128 v[26:29], v193 offset:32768
	ds_read_b128 v[30:33], v193 offset:33792
	ds_read_b128 v[62:65], v193 offset:34816
	ds_read_b128 v[102:105], v193 offset:35840
	ds_read_b128 v[232:235], v193 offset:36864
	ds_read_b128 v[236:239], v193 offset:37888
	ds_read_b128 v[240:243], v193 offset:38912
	ds_read_b128 v[244:247], v193 offset:39936
	global_load_lds_dwordx4 v[106:107], off
	v_lshl_add_u64 v[106:107], v[248:249], 0, s[24:25]
	s_mov_b32 m0, s52
	s_nop 0
	global_load_lds_dwordx4 v[106:107], off
	s_waitcnt vmcnt(8)
	s_waitcnt lgkmcnt(0)
	s_barrier
	s_waitcnt lgkmcnt(0)
	s_setprio 0
	v_mfma_f32_16x16x32_bf16 v[66:69], v[10:13], v[26:29], v[66:69]
	v_mfma_f32_16x16x32_bf16 v[146:149], v[14:17], v[30:33], v[66:69]
	v_mfma_f32_16x16x32_bf16 v[66:69], v[18:21], v[26:29], v[70:73]
	v_mfma_f32_16x16x32_bf16 v[142:145], v[22:25], v[30:33], v[66:69]
	v_mfma_f32_16x16x32_bf16 v[66:69], v[10:13], v[62:65], v[74:77]
	v_mfma_f32_16x16x32_bf16 v[126:129], v[14:17], v[102:105], v[66:69]
	v_mfma_f32_16x16x32_bf16 v[66:69], v[18:21], v[62:65], v[78:81]
	v_mfma_f32_16x16x32_bf16 v[122:125], v[22:25], v[102:105], v[66:69]
	v_mfma_f32_16x16x32_bf16 v[66:69], v[10:13], v[232:235], v[82:85]
	v_mfma_f32_16x16x32_bf16 v[110:113], v[14:17], v[236:239], v[66:69]
	v_mfma_f32_16x16x32_bf16 v[66:69], v[18:21], v[232:235], v[86:89]
	v_mfma_f32_16x16x32_bf16 v[106:109], v[22:25], v[236:239], v[66:69]
	v_mfma_f32_16x16x32_bf16 v[66:69], v[10:13], v[240:243], v[90:93]
	v_mfma_f32_16x16x32_bf16 v[86:89], v[14:17], v[244:247], v[66:69]
	v_mfma_f32_16x16x32_bf16 v[66:69], v[18:21], v[240:243], v[94:97]
	v_mfma_f32_16x16x32_bf16 v[78:81], v[22:25], v[244:247], v[66:69]
	v_mfma_f32_16x16x32_bf16 v[66:69], v[216:219], v[26:29], v[98:101]
	v_mfma_f32_16x16x32_bf16 v[26:29], v[224:227], v[26:29], v[34:37]
	v_mfma_f32_16x16x32_bf16 v[130:133], v[228:231], v[30:33], v[26:29]
	v_mfma_f32_16x16x32_bf16 v[26:29], v[216:219], v[62:65], v[38:41]
	v_mfma_f32_16x16x32_bf16 v[118:121], v[220:223], v[102:105], v[26:29]
	v_mfma_f32_16x16x32_bf16 v[26:29], v[224:227], v[62:65], v[42:45]
	v_mfma_f32_16x16x32_bf16 v[114:117], v[228:231], v[102:105], v[26:29]
	v_mfma_f32_16x16x32_bf16 v[26:29], v[216:219], v[232:235], v[46:49]
	v_mfma_f32_16x16x32_bf16 v[102:105], v[220:223], v[236:239], v[26:29]
	v_mfma_f32_16x16x32_bf16 v[26:29], v[224:227], v[232:235], v[50:53]
	v_mfma_f32_16x16x32_bf16 v[98:101], v[228:231], v[236:239], v[26:29]
	v_mfma_f32_16x16x32_bf16 v[26:29], v[216:219], v[240:243], v[54:57]
	v_mfma_f32_16x16x32_bf16 v[70:73], v[220:223], v[244:247], v[26:29]
	v_mfma_f32_16x16x32_bf16 v[26:29], v[224:227], v[240:243], v[58:61]
	v_mfma_f32_16x16x32_bf16 v[134:137], v[220:223], v[30:33], v[66:69]
	v_mfma_f32_16x16x32_bf16 v[66:69], v[228:231], v[244:247], v[26:29]
	s_setprio 1
	s_barrier
	s_add_i32 s41, s79, s44
	s_nop 3
	v_lshl_add_u64 v[26:27], v[250:251], 0, s[26:27]
	s_mov_b32 m0, s41
	s_add_i32 s50, s41, 0x2000
	ds_read_b128 v[34:37], v193 offset:49152
	ds_read_b128 v[38:41], v193 offset:50176
	ds_read_b128 v[74:77], v193 offset:51200
	ds_read_b128 v[82:85], v193 offset:52224
	ds_read_b128 v[90:93], v193 offset:53248
	ds_read_b128 v[94:97], v193 offset:54272
	ds_read_b128 v[232:235], v193 offset:55296
	ds_read_b128 v[236:239], v193 offset:56320
	global_load_lds_dwordx4 v[26:27], off
	v_lshl_add_u64 v[26:27], v[250:251], 0, s[28:29]
	s_mov_b32 m0, s50
	s_mov_b64 s[56:57], 0x160180
	s_add_i32 s51, s80, s44
	global_load_lds_dwordx4 v[26:27], off
	v_lshl_add_u64 v[26:27], v[250:251], 0, s[56:57]
	s_mov_b32 m0, s51
	s_mov_b64 s[56:57], 0x210180
	s_add_i32 s33, s51, 0x2000
	global_load_lds_dwordx4 v[26:27], off
	v_lshl_add_u64 v[26:27], v[250:251], 0, s[56:57]
	s_mov_b32 m0, s33
	s_nop 0
	global_load_lds_dwordx4 v[26:27], off
	v_lshl_add_u64 v[26:27], v[248:249], 0, s[26:27]
	s_mov_b32 m0, s53
	s_nop 0
	global_load_lds_dwordx4 v[26:27], off
	v_lshl_add_u64 v[26:27], v[248:249], 0, s[28:29]
	s_mov_b32 m0, s54
	s_nop 0
	global_load_lds_dwordx4 v[26:27], off
	s_waitcnt vmcnt(8)
	s_waitcnt lgkmcnt(0)
	s_barrier
	s_waitcnt lgkmcnt(0)
	s_setprio 0
	v_mfma_f32_16x16x32_bf16 v[26:29], v[10:13], v[34:37], v[138:141]
	v_mfma_f32_16x16x32_bf16 v[62:65], v[14:17], v[38:41], v[26:29]
	v_mfma_f32_16x16x32_bf16 v[26:29], v[18:21], v[34:37], v[150:153]
	v_mfma_f32_16x16x32_bf16 v[58:61], v[22:25], v[38:41], v[26:29]
	v_mfma_f32_16x16x32_bf16 v[26:29], v[10:13], v[74:77], v[154:157]
	v_mfma_f32_16x16x32_bf16 v[46:49], v[14:17], v[82:85], v[26:29]
	v_mfma_f32_16x16x32_bf16 v[26:29], v[18:21], v[74:77], v[158:161]
	v_mfma_f32_16x16x32_bf16 v[42:45], v[22:25], v[82:85], v[26:29]
	v_mfma_f32_16x16x32_bf16 v[26:29], v[10:13], v[90:93], v[162:165]
	v_mfma_f32_16x16x32_bf16 v[2:5], v[10:13], v[232:235], v[2:5]
	v_mfma_f32_16x16x32_bf16 v[30:33], v[14:17], v[94:97], v[26:29]
	v_mfma_f32_16x16x32_bf16 v[26:29], v[18:21], v[90:93], v[166:169]
	v_mfma_f32_16x16x32_bf16 v[14:17], v[14:17], v[236:239], v[2:5]
	v_mfma_f32_16x16x32_bf16 v[2:5], v[18:21], v[232:235], v[6:9]
	v_mfma_f32_16x16x32_bf16 v[26:29], v[22:25], v[94:97], v[26:29]
	v_mfma_f32_16x16x32_bf16 v[10:13], v[22:25], v[236:239], v[2:5]
	v_mfma_f32_16x16x32_bf16 v[2:5], v[216:219], v[34:37], v[180:183]
	v_mfma_f32_16x16x32_bf16 v[54:57], v[220:223], v[38:41], v[2:5]
	v_mfma_f32_16x16x32_bf16 v[2:5], v[224:227], v[34:37], v[184:187]
	v_mfma_f32_16x16x32_bf16 v[50:53], v[228:231], v[38:41], v[2:5]
	v_mfma_f32_16x16x32_bf16 v[2:5], v[216:219], v[74:77], v[188:191]
	v_mfma_f32_16x16x32_bf16 v[38:41], v[220:223], v[82:85], v[2:5]
	v_mfma_f32_16x16x32_bf16 v[2:5], v[224:227], v[74:77], v[196:199]
	v_mfma_f32_16x16x32_bf16 v[34:37], v[228:231], v[82:85], v[2:5]
	v_mfma_f32_16x16x32_bf16 v[2:5], v[216:219], v[90:93], v[200:203]
	v_mfma_f32_16x16x32_bf16 v[22:25], v[220:223], v[94:97], v[2:5]
	v_mfma_f32_16x16x32_bf16 v[2:5], v[224:227], v[90:93], v[204:207]
	v_mfma_f32_16x16x32_bf16 v[18:21], v[228:231], v[94:97], v[2:5]
	v_mfma_f32_16x16x32_bf16 v[2:5], v[216:219], v[232:235], v[208:211]
	v_mfma_f32_16x16x32_bf16 v[6:9], v[220:223], v[236:239], v[2:5]
	v_mfma_f32_16x16x32_bf16 v[2:5], v[224:227], v[232:235], v[212:215]
	v_mfma_f32_16x16x32_bf16 v[2:5], v[228:231], v[236:239], v[2:5]
	s_setprio 1
	s_barrier
	s_add_u32 s70, s70, 0x160180
	s_addc_u32 s71, s71, 0
	s_add_u32 s56, s72, 0x200
	s_addc_u32 s57, s73, 0
	s_mov_b32 s72, 0
.LBB0_870:
	ds_read_b128 v[74:77], v1
	ds_read_b128 v[82:85], v1 offset:1024
	ds_read_b128 v[90:93], v1 offset:2048
	ds_read_b128 v[94:97], v1 offset:3072
	ds_read_b128 v[138:141], v192
	ds_read_b128 v[150:153], v192 offset:1024
	ds_read_b128 v[154:157], v192 offset:2048
	ds_read_b128 v[158:161], v192 offset:3072
	s_add_u32 s0, s70, 0xffea0080
	s_addc_u32 s1, s71, -1
	s_cmpk_eq_i32 s72, 0x54
	s_cselect_b32 s93, s11, s1
	s_cselect_b32 s92, s10, s0
	s_cselect_b32 s95, s69, s57
	s_cselect_b32 s94, s68, s56
	s_mov_b32 m0, s85
	v_lshl_add_u64 v[208:209], s[70:71], 0, v[174:175]
	ds_read_b128 v[162:165], v193
	ds_read_b128 v[166:169], v193 offset:1024
	ds_read_b128 v[180:183], v193 offset:2048
	ds_read_b128 v[184:187], v193 offset:3072
	ds_read_b128 v[188:191], v193 offset:4096
	ds_read_b128 v[196:199], v193 offset:5120
	ds_read_b128 v[200:203], v193 offset:6144
	ds_read_b128 v[204:207], v193 offset:7168
	global_load_lds_dwordx4 v[208:209], off
	v_lshl_add_u64 v[208:209], v[208:209], 0, s[30:31]
	s_mov_b32 m0, s87
	s_nop 0
	global_load_lds_dwordx4 v[208:209], off
	s_waitcnt vmcnt(8)
	s_waitcnt lgkmcnt(0)
	s_barrier
	s_waitcnt lgkmcnt(0)
	s_setprio 0
	v_mfma_f32_16x16x32_bf16 v[146:149], v[74:77], v[162:165], v[146:149]
	v_mfma_f32_16x16x32_bf16 v[142:145], v[90:93], v[162:165], v[142:145]
	v_mfma_f32_16x16x32_bf16 v[126:129], v[74:77], v[180:183], v[126:129]
	v_mfma_f32_16x16x32_bf16 v[122:125], v[90:93], v[180:183], v[122:125]
	v_mfma_f32_16x16x32_bf16 v[110:113], v[74:77], v[188:191], v[110:113]
	v_mfma_f32_16x16x32_bf16 v[106:109], v[90:93], v[188:191], v[106:109]
	v_mfma_f32_16x16x32_bf16 v[86:89], v[74:77], v[200:203], v[86:89]
	v_mfma_f32_16x16x32_bf16 v[78:81], v[90:93], v[200:203], v[78:81]
	v_mfma_f32_16x16x32_bf16 v[146:149], v[82:85], v[166:169], v[146:149]
	v_mfma_f32_16x16x32_bf16 v[142:145], v[94:97], v[166:169], v[142:145]
	v_mfma_f32_16x16x32_bf16 v[126:129], v[82:85], v[184:187], v[126:129]
	v_mfma_f32_16x16x32_bf16 v[122:125], v[94:97], v[184:187], v[122:125]
	v_mfma_f32_16x16x32_bf16 v[110:113], v[82:85], v[196:199], v[110:113]
	v_mfma_f32_16x16x32_bf16 v[106:109], v[94:97], v[196:199], v[106:109]
	v_mfma_f32_16x16x32_bf16 v[86:89], v[82:85], v[204:207], v[86:89]
	v_mfma_f32_16x16x32_bf16 v[78:81], v[94:97], v[204:207], v[78:81]
	v_mfma_f32_16x16x32_bf16 v[134:137], v[138:141], v[162:165], v[134:137]
	v_mfma_f32_16x16x32_bf16 v[130:133], v[154:157], v[162:165], v[130:133]
	v_mfma_f32_16x16x32_bf16 v[118:121], v[138:141], v[180:183], v[118:121]
	v_mfma_f32_16x16x32_bf16 v[114:117], v[154:157], v[180:183], v[114:117]
	v_mfma_f32_16x16x32_bf16 v[102:105], v[138:141], v[188:191], v[102:105]
	v_mfma_f32_16x16x32_bf16 v[98:101], v[154:157], v[188:191], v[98:101]
	v_mfma_f32_16x16x32_bf16 v[70:73], v[138:141], v[200:203], v[70:73]
	v_mfma_f32_16x16x32_bf16 v[66:69], v[154:157], v[200:203], v[66:69]
	v_mfma_f32_16x16x32_bf16 v[134:137], v[150:153], v[166:169], v[134:137]
	v_mfma_f32_16x16x32_bf16 v[130:133], v[158:161], v[166:169], v[130:133]
	v_mfma_f32_16x16x32_bf16 v[118:121], v[150:153], v[184:187], v[118:121]
	v_mfma_f32_16x16x32_bf16 v[114:117], v[158:161], v[184:187], v[114:117]
	v_mfma_f32_16x16x32_bf16 v[102:105], v[150:153], v[196:199], v[102:105]
	v_mfma_f32_16x16x32_bf16 v[98:101], v[158:161], v[196:199], v[98:101]
	v_mfma_f32_16x16x32_bf16 v[70:73], v[150:153], v[204:207], v[70:73]
	v_mfma_f32_16x16x32_bf16 v[66:69], v[158:161], v[204:207], v[66:69]
	s_setprio 1
	s_barrier
	s_mov_b32 m0, s88
	v_lshl_add_u64 v[208:209], s[94:95], 0, v[172:173]
	ds_read_b128 v[162:165], v193 offset:16384
	ds_read_b128 v[166:169], v193 offset:17408
	ds_read_b128 v[180:183], v193 offset:18432
	ds_read_b128 v[184:187], v193 offset:19456
	ds_read_b128 v[188:191], v193 offset:20480
	ds_read_b128 v[196:199], v193 offset:21504
	ds_read_b128 v[200:203], v193 offset:22528
	ds_read_b128 v[204:207], v193 offset:23552
	global_load_lds_dwordx4 v[208:209], off
	v_lshl_add_u64 v[210:211], v[208:209], 0, s[30:31]
	s_mov_b32 m0, s89
	s_nop 0
	global_load_lds_dwordx4 v[210:211], off
	v_lshl_add_u64 v[210:211], v[208:209], 0, s[34:35]
	s_mov_b32 m0, s90
	s_nop 0
	global_load_lds_dwordx4 v[210:211], off
	v_lshl_add_u64 v[210:211], v[208:209], 0, s[36:37]
	s_mov_b32 m0, s40
	s_nop 0
	global_load_lds_dwordx4 v[210:211], off
	v_lshl_add_u64 v[210:211], s[92:93], 0, v[170:171]
	s_mov_b32 m0, s45
	v_lshl_add_u64 v[212:213], v[210:211], 0, s[30:31]
	global_load_lds_dwordx4 v[210:211], off
	s_mov_b32 m0, s46
	s_nop 0
	global_load_lds_dwordx4 v[212:213], off
	s_waitcnt vmcnt(8)
	s_waitcnt lgkmcnt(0)
	s_barrier
	s_waitcnt lgkmcnt(0)
	s_setprio 0
	v_mfma_f32_16x16x32_bf16 v[62:65], v[74:77], v[162:165], v[62:65]
	v_mfma_f32_16x16x32_bf16 v[58:61], v[90:93], v[162:165], v[58:61]
	v_mfma_f32_16x16x32_bf16 v[46:49], v[74:77], v[180:183], v[46:49]
	v_mfma_f32_16x16x32_bf16 v[42:45], v[90:93], v[180:183], v[42:45]
	v_mfma_f32_16x16x32_bf16 v[30:33], v[74:77], v[188:191], v[30:33]
	v_mfma_f32_16x16x32_bf16 v[26:29], v[90:93], v[188:191], v[26:29]
	v_mfma_f32_16x16x32_bf16 v[14:17], v[74:77], v[200:203], v[14:17]
	v_mfma_f32_16x16x32_bf16 v[10:13], v[90:93], v[200:203], v[10:13]
	v_mfma_f32_16x16x32_bf16 v[62:65], v[82:85], v[166:169], v[62:65]
	v_mfma_f32_16x16x32_bf16 v[58:61], v[94:97], v[166:169], v[58:61]
	v_mfma_f32_16x16x32_bf16 v[46:49], v[82:85], v[184:187], v[46:49]
	v_mfma_f32_16x16x32_bf16 v[42:45], v[94:97], v[184:187], v[42:45]
	v_mfma_f32_16x16x32_bf16 v[30:33], v[82:85], v[196:199], v[30:33]
	v_mfma_f32_16x16x32_bf16 v[26:29], v[94:97], v[196:199], v[26:29]
	v_mfma_f32_16x16x32_bf16 v[14:17], v[82:85], v[204:207], v[14:17]
	v_mfma_f32_16x16x32_bf16 v[10:13], v[94:97], v[204:207], v[10:13]
	v_mfma_f32_16x16x32_bf16 v[54:57], v[138:141], v[162:165], v[54:57]
	v_mfma_f32_16x16x32_bf16 v[50:53], v[154:157], v[162:165], v[50:53]
	v_mfma_f32_16x16x32_bf16 v[38:41], v[138:141], v[180:183], v[38:41]
	v_mfma_f32_16x16x32_bf16 v[34:37], v[154:157], v[180:183], v[34:37]
	v_mfma_f32_16x16x32_bf16 v[22:25], v[138:141], v[188:191], v[22:25]
	v_mfma_f32_16x16x32_bf16 v[18:21], v[154:157], v[188:191], v[18:21]
	v_mfma_f32_16x16x32_bf16 v[6:9], v[138:141], v[200:203], v[6:9]
	v_mfma_f32_16x16x32_bf16 v[2:5], v[154:157], v[200:203], v[2:5]
	v_mfma_f32_16x16x32_bf16 v[54:57], v[150:153], v[166:169], v[54:57]
	v_mfma_f32_16x16x32_bf16 v[50:53], v[158:161], v[166:169], v[50:53]
	v_mfma_f32_16x16x32_bf16 v[38:41], v[150:153], v[184:187], v[38:41]
	v_mfma_f32_16x16x32_bf16 v[34:37], v[158:161], v[184:187], v[34:37]
	v_mfma_f32_16x16x32_bf16 v[22:25], v[150:153], v[196:199], v[22:25]
	v_mfma_f32_16x16x32_bf16 v[18:21], v[158:161], v[196:199], v[18:21]
	v_mfma_f32_16x16x32_bf16 v[6:9], v[150:153], v[204:207], v[6:9]
	v_mfma_f32_16x16x32_bf16 v[2:5], v[158:161], v[204:207], v[2:5]
	s_setprio 1
	s_barrier
	ds_read_b128 v[74:77], v194
	ds_read_b128 v[82:85], v194 offset:1024
	ds_read_b128 v[90:93], v194 offset:2048
	ds_read_b128 v[94:97], v194 offset:3072
	ds_read_b128 v[138:141], v195
	ds_read_b128 v[150:153], v195 offset:1024
	ds_read_b128 v[154:157], v195 offset:2048
	ds_read_b128 v[158:161], v195 offset:3072
	s_mov_b32 m0, s47
	v_lshl_add_u64 v[212:213], v[210:211], 0, s[34:35]
	ds_read_b128 v[162:165], v193 offset:32768
	ds_read_b128 v[166:169], v193 offset:33792
	ds_read_b128 v[180:183], v193 offset:34816
	ds_read_b128 v[184:187], v193 offset:35840
	ds_read_b128 v[188:191], v193 offset:36864
	ds_read_b128 v[196:199], v193 offset:37888
	ds_read_b128 v[200:203], v193 offset:38912
	ds_read_b128 v[204:207], v193 offset:39936
	global_load_lds_dwordx4 v[212:213], off
	v_lshl_add_u64 v[212:213], v[210:211], 0, s[36:37]
	s_mov_b32 m0, s52
	s_nop 0
	global_load_lds_dwordx4 v[212:213], off
	s_waitcnt vmcnt(8)
	s_waitcnt lgkmcnt(0)
	s_barrier
	s_waitcnt lgkmcnt(0)
	s_setprio 0
	v_mfma_f32_16x16x32_bf16 v[146:149], v[74:77], v[162:165], v[146:149]
	v_mfma_f32_16x16x32_bf16 v[142:145], v[90:93], v[162:165], v[142:145]
	v_mfma_f32_16x16x32_bf16 v[126:129], v[74:77], v[180:183], v[126:129]
	v_mfma_f32_16x16x32_bf16 v[122:125], v[90:93], v[180:183], v[122:125]
	v_mfma_f32_16x16x32_bf16 v[110:113], v[74:77], v[188:191], v[110:113]
	v_mfma_f32_16x16x32_bf16 v[106:109], v[90:93], v[188:191], v[106:109]
	v_mfma_f32_16x16x32_bf16 v[86:89], v[74:77], v[200:203], v[86:89]
	v_mfma_f32_16x16x32_bf16 v[78:81], v[90:93], v[200:203], v[78:81]
	v_mfma_f32_16x16x32_bf16 v[146:149], v[82:85], v[166:169], v[146:149]
	v_mfma_f32_16x16x32_bf16 v[142:145], v[94:97], v[166:169], v[142:145]
	v_mfma_f32_16x16x32_bf16 v[126:129], v[82:85], v[184:187], v[126:129]
	v_mfma_f32_16x16x32_bf16 v[122:125], v[94:97], v[184:187], v[122:125]
	v_mfma_f32_16x16x32_bf16 v[110:113], v[82:85], v[196:199], v[110:113]
	v_mfma_f32_16x16x32_bf16 v[106:109], v[94:97], v[196:199], v[106:109]
	v_mfma_f32_16x16x32_bf16 v[86:89], v[82:85], v[204:207], v[86:89]
	v_mfma_f32_16x16x32_bf16 v[78:81], v[94:97], v[204:207], v[78:81]
	v_mfma_f32_16x16x32_bf16 v[134:137], v[138:141], v[162:165], v[134:137]
	v_mfma_f32_16x16x32_bf16 v[130:133], v[154:157], v[162:165], v[130:133]
	v_mfma_f32_16x16x32_bf16 v[118:121], v[138:141], v[180:183], v[118:121]
	v_mfma_f32_16x16x32_bf16 v[114:117], v[154:157], v[180:183], v[114:117]
	v_mfma_f32_16x16x32_bf16 v[102:105], v[138:141], v[188:191], v[102:105]
	v_mfma_f32_16x16x32_bf16 v[98:101], v[154:157], v[188:191], v[98:101]
	v_mfma_f32_16x16x32_bf16 v[70:73], v[138:141], v[200:203], v[70:73]
	v_mfma_f32_16x16x32_bf16 v[66:69], v[154:157], v[200:203], v[66:69]
	v_mfma_f32_16x16x32_bf16 v[134:137], v[150:153], v[166:169], v[134:137]
	v_mfma_f32_16x16x32_bf16 v[130:133], v[158:161], v[166:169], v[130:133]
	v_mfma_f32_16x16x32_bf16 v[118:121], v[150:153], v[184:187], v[118:121]
	v_mfma_f32_16x16x32_bf16 v[114:117], v[158:161], v[184:187], v[114:117]
	v_mfma_f32_16x16x32_bf16 v[102:105], v[150:153], v[196:199], v[102:105]
	v_mfma_f32_16x16x32_bf16 v[98:101], v[158:161], v[196:199], v[98:101]
	v_mfma_f32_16x16x32_bf16 v[70:73], v[150:153], v[204:207], v[70:73]
	v_mfma_f32_16x16x32_bf16 v[66:69], v[158:161], v[204:207], v[66:69]
	s_setprio 1
	s_barrier
; #define PG8_WAIT_V(n) asm volatile("s_waitcnt vmcnt(" #n ")" ::: "memory")
; template <class Epi, class Sched, bool ALIGN_EPI = true, bool SP2 = true, bool FULLLINE = false, bool NOSTAGE = false, bool FP8 = false>
; __device__ __forceinline__ void gemm_phase(PG8_LAS unsigned char* lds, const Gemm g, const Sched& S, const Epi& E) {
;     ...
;         static_assert(SP2, "only the SP2 loop is kept");
;         { const int t = 0; if constexpr (Epi::NST == 16) PG8_ITER(PG8_WAIT_V(24)); else if constexpr (Epi::NST == 8) PG8_ITER(PG8_WAIT_V(16)); else PG8_ITER(PG8_WAIT_V(8)); }
;         for (int t = 2; t < nt; t += 2) PG8_ITER(PG8_WAIT_V(8));
	s_mov_b32 m0, s41
	v_lshl_add_u64 v[212:213], v[208:209], 0, s[38:39]
	ds_read_b128 v[162:165], v193 offset:49152
	ds_read_b128 v[166:169], v193 offset:50176
	ds_read_b128 v[180:183], v193 offset:51200
	ds_read_b128 v[184:187], v193 offset:52224
	ds_read_b128 v[188:191], v193 offset:53248
	ds_read_b128 v[196:199], v193 offset:54272
	ds_read_b128 v[200:203], v193 offset:55296
	ds_read_b128 v[204:207], v193 offset:56320
	global_load_lds_dwordx4 v[212:213], off
	v_lshl_add_u64 v[212:213], v[208:209], 0, s[66:67]
	s_mov_b32 m0, s50
	s_nop 0
	global_load_lds_dwordx4 v[212:213], off
	v_lshl_add_u64 v[212:213], v[208:209], 0, s[14:15]
	s_mov_b32 m0, s51
	v_lshl_add_u64 v[208:209], v[208:209], 0, s[16:17]
	global_load_lds_dwordx4 v[212:213], off
	s_mov_b32 m0, s33
	s_nop 0
	global_load_lds_dwordx4 v[208:209], off
	v_lshl_add_u64 v[208:209], v[210:211], 0, s[38:39]
	s_mov_b32 m0, s53
	s_nop 0
	global_load_lds_dwordx4 v[208:209], off
	v_lshl_add_u64 v[208:209], v[210:211], 0, s[66:67]
	s_mov_b32 m0, s54
	s_nop 0
	global_load_lds_dwordx4 v[208:209], off
	s_waitcnt vmcnt(8)
	s_waitcnt lgkmcnt(0)
	s_barrier
	s_waitcnt lgkmcnt(0)
	s_setprio 0
	v_mfma_f32_16x16x32_bf16 v[62:65], v[74:77], v[162:165], v[62:65]
	v_mfma_f32_16x16x32_bf16 v[58:61], v[90:93], v[162:165], v[58:61]
	v_mfma_f32_16x16x32_bf16 v[46:49], v[74:77], v[180:183], v[46:49]
	v_mfma_f32_16x16x32_bf16 v[42:45], v[90:93], v[180:183], v[42:45]
	v_mfma_f32_16x16x32_bf16 v[30:33], v[74:77], v[188:191], v[30:33]
	v_mfma_f32_16x16x32_bf16 v[26:29], v[90:93], v[188:191], v[26:29]
	v_mfma_f32_16x16x32_bf16 v[14:17], v[74:77], v[200:203], v[14:17]
	v_mfma_f32_16x16x32_bf16 v[10:13], v[90:93], v[200:203], v[10:13]
	v_mfma_f32_16x16x32_bf16 v[62:65], v[82:85], v[166:169], v[62:65]
	v_mfma_f32_16x16x32_bf16 v[58:61], v[94:97], v[166:169], v[58:61]
	v_mfma_f32_16x16x32_bf16 v[46:49], v[82:85], v[184:187], v[46:49]
	v_mfma_f32_16x16x32_bf16 v[42:45], v[94:97], v[184:187], v[42:45]
	v_mfma_f32_16x16x32_bf16 v[30:33], v[82:85], v[196:199], v[30:33]
	v_mfma_f32_16x16x32_bf16 v[26:29], v[94:97], v[196:199], v[26:29]
	v_mfma_f32_16x16x32_bf16 v[14:17], v[82:85], v[204:207], v[14:17]
	v_mfma_f32_16x16x32_bf16 v[10:13], v[94:97], v[204:207], v[10:13]
	v_mfma_f32_16x16x32_bf16 v[54:57], v[138:141], v[162:165], v[54:57]
	v_mfma_f32_16x16x32_bf16 v[50:53], v[154:157], v[162:165], v[50:53]
	v_mfma_f32_16x16x32_bf16 v[38:41], v[138:141], v[180:183], v[38:41]
	v_mfma_f32_16x16x32_bf16 v[34:37], v[154:157], v[180:183], v[34:37]
	v_mfma_f32_16x16x32_bf16 v[22:25], v[138:141], v[188:191], v[22:25]
	v_mfma_f32_16x16x32_bf16 v[18:21], v[154:157], v[188:191], v[18:21]
	v_mfma_f32_16x16x32_bf16 v[6:9], v[138:141], v[200:203], v[6:9]
	v_mfma_f32_16x16x32_bf16 v[2:5], v[154:157], v[200:203], v[2:5]
	v_mfma_f32_16x16x32_bf16 v[54:57], v[150:153], v[166:169], v[54:57]
	v_mfma_f32_16x16x32_bf16 v[50:53], v[158:161], v[166:169], v[50:53]
	v_mfma_f32_16x16x32_bf16 v[38:41], v[150:153], v[184:187], v[38:41]
	v_mfma_f32_16x16x32_bf16 v[34:37], v[158:161], v[184:187], v[34:37]
	v_mfma_f32_16x16x32_bf16 v[22:25], v[150:153], v[196:199], v[22:25]
	v_mfma_f32_16x16x32_bf16 v[18:21], v[158:161], v[196:199], v[18:21]
	v_mfma_f32_16x16x32_bf16 v[6:9], v[150:153], v[204:207], v[6:9]
	v_mfma_f32_16x16x32_bf16 v[2:5], v[158:161], v[204:207], v[2:5]
	s_setprio 1
	s_barrier
	s_add_i32 s72, s72, 2
	s_add_u32 s70, s70, 0x100
	s_addc_u32 s71, s71, 0
	s_add_u32 s56, s56, 0x100
	s_addc_u32 s57, s57, 0
	s_cmpk_gt_u32 s72, 0x55
	s_cbranch_scc0 .LBB0_870
	s_and_b64 vcc, exec, s[12:13]
	s_cbranch_vccz .LBB0_873
	s_barrier

; #define PG8_WAIT_V(n) asm volatile("s_waitcnt vmcnt(" #n ")" ::: "memory")
; template <class Epi, class Sched, bool ALIGN_EPI = true, bool SP2 = true, bool FULLLINE = false, bool NOSTAGE = false, bool FP8 = false>
; __device__ __forceinline__ void gemm_phase(PG8_LAS unsigned char* lds, const Gemm g, const Sched& S, const Epi& E) {
;     ...
;         const bool has_next = S.next(ui + 1, nxt);
;         const char* nA = has_next ? PG8_ABASE(nxt) : cA; const char* nB = has_next ? PG8_BBASE(nxt) : cB;
;     ...
;         { const int t = 0; if constexpr (Epi::NST == 16) PG8_ITER(PG8_WAIT_V(24)); else if constexpr (Epi::NST == 8) PG8_ITER(PG8_WAIT_V(16)); else PG8_ITER(PG8_WAIT_V(8)); }
.LBB0_1024:
	s_ashr_i32 s75, s74, 31
	s_lshl_b64 s[40:41], s[74:75], 20
	s_add_u32 s76, s58, s40
	ds_read_b128 v[2:5], v1
	ds_read_b128 v[6:9], v1 offset:1024
	ds_read_b128 v[10:13], v1 offset:2048
	ds_read_b128 v[14:17], v1 offset:3072
	ds_read_b128 v[18:21], v152
	ds_read_b128 v[22:25], v152 offset:1024
	ds_read_b128 v[26:29], v152 offset:2048
	ds_read_b128 v[30:33], v152 offset:3072
	s_addc_u32 s77, s59, s41
	s_ashr_i32 s73, s72, 31
	s_lshl_b64 s[40:41], s[72:73], 20
	s_add_u32 s78, s3, s40
	s_addc_u32 s79, s42, s41
	s_and_b64 s[40:41], s[8:9], exec
	s_cselect_b32 s73, s77, s83
	s_cselect_b32 s75, s76, s82
	s_cselect_b32 s96, s79, s81
	s_cselect_b32 s97, s78, s80
	v_lshl_add_u64 v[244:245], s[82:83], 0, v[132:133]
	s_mov_b32 m0, s87
	v_lshl_add_u64 v[66:67], v[244:245], 0, s[18:19]
	ds_read_b128 v[34:37], v153
	ds_read_b128 v[38:41], v153 offset:1024
	ds_read_b128 v[42:45], v153 offset:2048
	ds_read_b128 v[46:49], v153 offset:3072
	ds_read_b128 v[50:53], v153 offset:4096
	ds_read_b128 v[54:57], v153 offset:5120
	ds_read_b128 v[58:61], v153 offset:6144
	ds_read_b128 v[62:65], v153 offset:7168
	global_load_lds_dwordx4 v[66:67], off
	v_lshl_add_u64 v[66:67], v[244:245], 0, s[20:21]
	s_mov_b32 m0, s88
	s_nop 0
	global_load_lds_dwordx4 v[66:67], off
	s_waitcnt vmcnt(16)
	s_waitcnt lgkmcnt(0)
	s_barrier
	s_waitcnt lgkmcnt(0)
	s_setprio 0
	v_mfma_f32_16x16x32_bf16 v[90:93], v[2:5], v[58:61], 0
	v_mfma_f32_16x16x32_bf16 v[66:69], v[2:5], v[34:37], 0
	v_mfma_f32_16x16x32_bf16 v[70:73], v[10:13], v[34:37], 0
	v_mfma_f32_16x16x32_bf16 v[74:77], v[2:5], v[42:45], 0
	v_mfma_f32_16x16x32_bf16 v[78:81], v[10:13], v[42:45], 0
	v_mfma_f32_16x16x32_bf16 v[82:85], v[2:5], v[50:53], 0
	v_mfma_f32_16x16x32_bf16 v[86:89], v[10:13], v[50:53], 0
	v_mfma_f32_16x16x32_bf16 v[94:97], v[6:9], v[62:65], v[90:93]
	v_mfma_f32_16x16x32_bf16 v[90:93], v[10:13], v[58:61], 0
	v_mfma_f32_16x16x32_bf16 v[66:69], v[6:9], v[38:41], v[66:69]
	v_mfma_f32_16x16x32_bf16 v[70:73], v[14:17], v[38:41], v[70:73]
	v_mfma_f32_16x16x32_bf16 v[74:77], v[6:9], v[46:49], v[74:77]
	v_mfma_f32_16x16x32_bf16 v[78:81], v[14:17], v[46:49], v[78:81]
	v_mfma_f32_16x16x32_bf16 v[82:85], v[6:9], v[54:57], v[82:85]
	v_mfma_f32_16x16x32_bf16 v[86:89], v[14:17], v[54:57], v[86:89]
	v_mfma_f32_16x16x32_bf16 v[102:105], v[14:17], v[62:65], v[90:93]
	v_mfma_f32_16x16x32_bf16 v[90:93], v[18:21], v[34:37], 0
	v_mfma_f32_16x16x32_bf16 v[34:37], v[26:29], v[34:37], 0
	v_mfma_f32_16x16x32_bf16 v[110:113], v[22:25], v[38:41], v[90:93]
	v_mfma_f32_16x16x32_bf16 v[34:37], v[30:33], v[38:41], v[34:37]
	v_mfma_f32_16x16x32_bf16 v[38:41], v[18:21], v[42:45], 0
	v_mfma_f32_16x16x32_bf16 v[42:45], v[26:29], v[42:45], 0
	v_mfma_f32_16x16x32_bf16 v[38:41], v[22:25], v[46:49], v[38:41]
	v_mfma_f32_16x16x32_bf16 v[42:45], v[30:33], v[46:49], v[42:45]
	v_mfma_f32_16x16x32_bf16 v[46:49], v[18:21], v[50:53], 0
	v_mfma_f32_16x16x32_bf16 v[50:53], v[26:29], v[50:53], 0
	v_mfma_f32_16x16x32_bf16 v[46:49], v[22:25], v[54:57], v[46:49]
	v_mfma_f32_16x16x32_bf16 v[54:57], v[30:33], v[54:57], v[50:53]
	v_mfma_f32_16x16x32_bf16 v[50:53], v[18:21], v[58:61], 0
	v_mfma_f32_16x16x32_bf16 v[140:143], v[22:25], v[62:65], v[50:53]
	v_mfma_f32_16x16x32_bf16 v[50:53], v[26:29], v[58:61], 0
	v_mfma_f32_16x16x32_bf16 v[144:147], v[30:33], v[62:65], v[50:53]
	s_setprio 1
	s_barrier
	v_lshl_add_u64 v[246:247], s[80:81], 0, v[130:131]
	s_add_i32 vcc_lo, s84, s43
	v_lshl_add_u64 v[122:123], v[246:247], 0, s[22:23]
	s_mov_b32 m0, vcc_lo
	s_add_i32 vcc_hi, vcc_lo, 0x2000
	s_nop 0
	ds_read_b128 v[50:53], v153 offset:16384
	ds_read_b128 v[58:61], v153 offset:17408
	ds_read_b128 v[62:65], v153 offset:18432
	ds_read_b128 v[90:93], v153 offset:19456
	ds_read_b128 v[98:101], v153 offset:20480
	ds_read_b128 v[106:109], v153 offset:21504
	ds_read_b128 v[114:117], v153 offset:22528
	ds_read_b128 v[118:121], v153 offset:23552
	global_load_lds_dwordx4 v[122:123], off
	v_lshl_add_u64 v[122:123], v[246:247], 0, s[24:25]
	s_mov_b32 m0, vcc_hi
	s_add_i32 s40, s85, s43
	global_load_lds_dwordx4 v[122:123], off
	v_lshl_add_u64 v[122:123], v[246:247], 0, s[26:27]
	s_mov_b32 m0, s40
	s_add_i32 s41, s40, 0x2000
	global_load_lds_dwordx4 v[122:123], off
	v_lshl_add_u64 v[122:123], v[246:247], 0, s[28:29]
	s_mov_b32 m0, s41
	s_nop 0
	global_load_lds_dwordx4 v[122:123], off
	v_lshl_add_u64 v[122:123], v[244:245], 0, s[22:23]
	s_mov_b32 m0, s45
	s_nop 0
	global_load_lds_dwordx4 v[122:123], off
	v_lshl_add_u64 v[122:123], v[244:245], 0, s[24:25]
	s_mov_b32 m0, s46
	s_nop 0
	global_load_lds_dwordx4 v[122:123], off
	s_waitcnt vmcnt(16)
	s_waitcnt lgkmcnt(0)
	s_barrier
	s_waitcnt lgkmcnt(0)
	s_setprio 0
	v_mfma_f32_16x16x32_bf16 v[122:125], v[2:5], v[50:53], 0
	v_mfma_f32_16x16x32_bf16 v[148:151], v[6:9], v[58:61], v[122:125]
	v_mfma_f32_16x16x32_bf16 v[122:125], v[10:13], v[50:53], 0
	v_mfma_f32_16x16x32_bf16 v[156:159], v[14:17], v[58:61], v[122:125]
	v_mfma_f32_16x16x32_bf16 v[122:125], v[2:5], v[62:65], 0
	v_mfma_f32_16x16x32_bf16 v[160:163], v[6:9], v[90:93], v[122:125]
	v_mfma_f32_16x16x32_bf16 v[122:125], v[10:13], v[62:65], 0
	v_mfma_f32_16x16x32_bf16 v[164:167], v[14:17], v[90:93], v[122:125]
	v_mfma_f32_16x16x32_bf16 v[122:125], v[2:5], v[98:101], 0
	v_mfma_f32_16x16x32_bf16 v[2:5], v[2:5], v[114:117], 0
	v_mfma_f32_16x16x32_bf16 v[168:171], v[6:9], v[106:109], v[122:125]
	v_mfma_f32_16x16x32_bf16 v[2:5], v[6:9], v[118:121], v[2:5]
	v_mfma_f32_16x16x32_bf16 v[6:9], v[10:13], v[114:117], 0
	v_mfma_f32_16x16x32_bf16 v[122:125], v[10:13], v[98:101], 0
	v_mfma_f32_16x16x32_bf16 v[6:9], v[14:17], v[118:121], v[6:9]
	v_mfma_f32_16x16x32_bf16 v[172:175], v[14:17], v[106:109], v[122:125]
	v_mfma_f32_16x16x32_bf16 v[10:13], v[18:21], v[50:53], 0
	v_mfma_f32_16x16x32_bf16 v[176:179], v[22:25], v[58:61], v[10:13]
	v_mfma_f32_16x16x32_bf16 v[10:13], v[26:29], v[50:53], 0
	v_mfma_f32_16x16x32_bf16 v[180:183], v[30:33], v[58:61], v[10:13]
	v_mfma_f32_16x16x32_bf16 v[10:13], v[18:21], v[62:65], 0
	v_mfma_f32_16x16x32_bf16 v[184:187], v[22:25], v[90:93], v[10:13]
	v_mfma_f32_16x16x32_bf16 v[10:13], v[26:29], v[62:65], 0
	v_mfma_f32_16x16x32_bf16 v[188:191], v[30:33], v[90:93], v[10:13]
	v_mfma_f32_16x16x32_bf16 v[10:13], v[18:21], v[98:101], 0
	v_mfma_f32_16x16x32_bf16 v[192:195], v[22:25], v[106:109], v[10:13]
	v_mfma_f32_16x16x32_bf16 v[10:13], v[26:29], v[98:101], 0
	v_mfma_f32_16x16x32_bf16 v[196:199], v[30:33], v[106:109], v[10:13]
	v_mfma_f32_16x16x32_bf16 v[10:13], v[18:21], v[114:117], 0
	v_mfma_f32_16x16x32_bf16 v[200:203], v[22:25], v[118:121], v[10:13]
	v_mfma_f32_16x16x32_bf16 v[10:13], v[26:29], v[114:117], 0
	v_mfma_f32_16x16x32_bf16 v[204:207], v[30:33], v[118:121], v[10:13]
	s_setprio 1
	s_barrier
	s_nop 5
	ds_read_b128 v[10:13], v154
	ds_read_b128 v[14:17], v154 offset:1024
	ds_read_b128 v[18:21], v154 offset:2048
	ds_read_b128 v[26:29], v154 offset:3072
	ds_read_b128 v[208:211], v155
	ds_read_b128 v[212:215], v155 offset:1024
	ds_read_b128 v[216:219], v155 offset:2048
	ds_read_b128 v[220:223], v155 offset:3072
	s_mov_b32 m0, s47
	v_lshl_add_u64 v[50:51], v[244:245], 0, s[26:27]
	ds_read_b128 v[22:25], v153 offset:32768
	ds_read_b128 v[30:33], v153 offset:33792
	ds_read_b128 v[62:65], v153 offset:34816
	ds_read_b128 v[224:227], v153 offset:35840
	ds_read_b128 v[228:231], v153 offset:36864
	ds_read_b128 v[232:235], v153 offset:37888
	ds_read_b128 v[236:239], v153 offset:38912
	ds_read_b128 v[240:243], v153 offset:39936
	global_load_lds_dwordx4 v[50:51], off
	v_lshl_add_u64 v[50:51], v[244:245], 0, s[28:29]
	s_mov_b32 m0, s52
	s_nop 0
	global_load_lds_dwordx4 v[50:51], off
	s_waitcnt vmcnt(8)
	s_waitcnt lgkmcnt(0)
	s_barrier
	s_waitcnt lgkmcnt(0)
	s_setprio 0
	v_mfma_f32_16x16x32_bf16 v[50:53], v[10:13], v[22:25], v[66:69]
	v_mfma_f32_16x16x32_bf16 v[122:125], v[14:17], v[30:33], v[50:53]
	v_mfma_f32_16x16x32_bf16 v[50:53], v[18:21], v[22:25], v[70:73]
	v_mfma_f32_16x16x32_bf16 v[114:117], v[26:29], v[30:33], v[50:53]
	v_mfma_f32_16x16x32_bf16 v[50:53], v[10:13], v[62:65], v[74:77]
	v_mfma_f32_16x16x32_bf16 v[106:109], v[14:17], v[224:227], v[50:53]
	v_mfma_f32_16x16x32_bf16 v[50:53], v[18:21], v[62:65], v[78:81]
	v_mfma_f32_16x16x32_bf16 v[98:101], v[26:29], v[224:227], v[50:53]
	v_mfma_f32_16x16x32_bf16 v[50:53], v[10:13], v[228:231], v[82:85]
	v_mfma_f32_16x16x32_bf16 v[90:93], v[14:17], v[232:235], v[50:53]
	v_mfma_f32_16x16x32_bf16 v[50:53], v[18:21], v[228:231], v[86:89]
	v_mfma_f32_16x16x32_bf16 v[82:85], v[26:29], v[232:235], v[50:53]
	v_mfma_f32_16x16x32_bf16 v[50:53], v[10:13], v[236:239], v[94:97]
	v_mfma_f32_16x16x32_bf16 v[58:61], v[14:17], v[240:243], v[50:53]
	v_mfma_f32_16x16x32_bf16 v[50:53], v[18:21], v[236:239], v[102:105]
	v_mfma_f32_16x16x32_bf16 v[50:53], v[26:29], v[240:243], v[50:53]
	v_mfma_f32_16x16x32_bf16 v[66:69], v[208:211], v[22:25], v[110:113]
	v_mfma_f32_16x16x32_bf16 v[22:25], v[216:219], v[22:25], v[34:37]
	v_mfma_f32_16x16x32_bf16 v[118:121], v[220:223], v[30:33], v[22:25]
	v_mfma_f32_16x16x32_bf16 v[22:25], v[208:211], v[62:65], v[38:41]
	v_mfma_f32_16x16x32_bf16 v[110:113], v[212:215], v[224:227], v[22:25]
	v_mfma_f32_16x16x32_bf16 v[22:25], v[216:219], v[62:65], v[42:45]
	v_mfma_f32_16x16x32_bf16 v[102:105], v[220:223], v[224:227], v[22:25]
	v_mfma_f32_16x16x32_bf16 v[22:25], v[208:211], v[228:231], v[46:49]
	v_mfma_f32_16x16x32_bf16 v[94:97], v[212:215], v[232:235], v[22:25]
	v_mfma_f32_16x16x32_bf16 v[22:25], v[216:219], v[228:231], v[54:57]
	v_mfma_f32_16x16x32_bf16 v[86:89], v[220:223], v[232:235], v[22:25]
	v_mfma_f32_16x16x32_bf16 v[22:25], v[208:211], v[236:239], v[140:143]
	v_mfma_f32_16x16x32_bf16 v[62:65], v[212:215], v[240:243], v[22:25]
	v_mfma_f32_16x16x32_bf16 v[22:25], v[216:219], v[236:239], v[144:147]
	v_mfma_f32_16x16x32_bf16 v[126:129], v[212:215], v[30:33], v[66:69]
	v_mfma_f32_16x16x32_bf16 v[54:57], v[220:223], v[240:243], v[22:25]
	s_setprio 1
	s_barrier
; #define PG8_WAIT_V(n) asm volatile("s_waitcnt vmcnt(" #n ")" ::: "memory")
; template <class Epi, class Sched, bool ALIGN_EPI = true, bool SP2 = true, bool FULLLINE = false, bool NOSTAGE = false, bool FP8 = false>
; __device__ __forceinline__ void gemm_phase(PG8_LAS unsigned char* lds, const Gemm g, const Sched& S, const Epi& E) {
;     ...
;         static_assert(SP2, "only the SP2 loop is kept");
;         { const int t = 0; if constexpr (Epi::NST == 16) PG8_ITER(PG8_WAIT_V(24)); else if constexpr (Epi::NST == 8) PG8_ITER(PG8_WAIT_V(16)); else PG8_ITER(PG8_WAIT_V(8)); }
;         for (int t = 2; t < nt; t += 2) PG8_ITER(PG8_WAIT_V(8));
	s_add_i32 s50, s89, s43
	s_nop 3
	v_lshl_add_u64 v[22:23], v[246:247], 0, s[30:31]
	s_mov_b32 m0, s50
	s_add_i32 s51, s50, 0x2000
	ds_read_b128 v[34:37], v153 offset:49152
	ds_read_b128 v[42:45], v153 offset:50176
	ds_read_b128 v[140:143], v153 offset:51200
	ds_read_b128 v[144:147], v153 offset:52224
	ds_read_b128 v[224:227], v153 offset:53248
	ds_read_b128 v[228:231], v153 offset:54272
	ds_read_b128 v[232:235], v153 offset:55296
	ds_read_b128 v[236:239], v153 offset:56320
	global_load_lds_dwordx4 v[22:23], off
	v_lshl_add_u64 v[22:23], v[246:247], 0, s[34:35]
	s_mov_b32 m0, s51
	s_mov_b64 s[56:57], 0x80180
	s_add_i32 s33, s90, s43
	global_load_lds_dwordx4 v[22:23], off
	v_lshl_add_u64 v[22:23], v[246:247], 0, s[56:57]
	s_mov_b32 m0, s33
	s_mov_b64 s[56:57], 0xc0180
	global_load_lds_dwordx4 v[22:23], off
	v_lshl_add_u64 v[22:23], v[246:247], 0, s[56:57]
	s_add_i32 s56, s33, 0x2000
	s_mov_b32 m0, s56
	s_nop 0
	global_load_lds_dwordx4 v[22:23], off
	v_lshl_add_u64 v[22:23], v[244:245], 0, s[30:31]
	s_mov_b32 m0, s53
	s_nop 0
	global_load_lds_dwordx4 v[22:23], off
	v_lshl_add_u64 v[22:23], v[244:245], 0, s[34:35]
	s_mov_b32 m0, s54
	s_nop 0
	global_load_lds_dwordx4 v[22:23], off
	s_waitcnt vmcnt(8)
	s_waitcnt lgkmcnt(0)
	s_barrier
	s_waitcnt lgkmcnt(0)
	s_setprio 0
	v_mfma_f32_16x16x32_bf16 v[22:25], v[10:13], v[34:37], v[148:151]
	v_mfma_f32_16x16x32_bf16 v[78:81], v[14:17], v[42:45], v[22:25]
	v_mfma_f32_16x16x32_bf16 v[22:25], v[18:21], v[34:37], v[156:159]
	v_mfma_f32_16x16x32_bf16 v[70:73], v[26:29], v[42:45], v[22:25]
	v_mfma_f32_16x16x32_bf16 v[22:25], v[10:13], v[140:143], v[160:163]
	v_mfma_f32_16x16x32_bf16 v[46:49], v[14:17], v[144:147], v[22:25]
	v_mfma_f32_16x16x32_bf16 v[22:25], v[18:21], v[140:143], v[164:167]
	v_mfma_f32_16x16x32_bf16 v[38:41], v[26:29], v[144:147], v[22:25]
	v_mfma_f32_16x16x32_bf16 v[22:25], v[10:13], v[224:227], v[168:171]
	v_mfma_f32_16x16x32_bf16 v[2:5], v[10:13], v[232:235], v[2:5]
	v_mfma_f32_16x16x32_bf16 v[30:33], v[14:17], v[228:231], v[22:25]
	v_mfma_f32_16x16x32_bf16 v[22:25], v[18:21], v[224:227], v[172:175]
	v_mfma_f32_16x16x32_bf16 v[14:17], v[14:17], v[236:239], v[2:5]
	v_mfma_f32_16x16x32_bf16 v[2:5], v[18:21], v[232:235], v[6:9]
	v_mfma_f32_16x16x32_bf16 v[22:25], v[26:29], v[228:231], v[22:25]
	v_mfma_f32_16x16x32_bf16 v[10:13], v[26:29], v[236:239], v[2:5]
	v_mfma_f32_16x16x32_bf16 v[2:5], v[208:211], v[34:37], v[176:179]
	v_mfma_f32_16x16x32_bf16 v[74:77], v[212:215], v[42:45], v[2:5]
	v_mfma_f32_16x16x32_bf16 v[2:5], v[216:219], v[34:37], v[180:183]
	v_mfma_f32_16x16x32_bf16 v[66:69], v[220:223], v[42:45], v[2:5]
	v_mfma_f32_16x16x32_bf16 v[2:5], v[208:211], v[140:143], v[184:187]
	v_mfma_f32_16x16x32_bf16 v[42:45], v[212:215], v[144:147], v[2:5]
	v_mfma_f32_16x16x32_bf16 v[2:5], v[216:219], v[140:143], v[188:191]
	v_mfma_f32_16x16x32_bf16 v[34:37], v[220:223], v[144:147], v[2:5]
	v_mfma_f32_16x16x32_bf16 v[2:5], v[208:211], v[224:227], v[192:195]
	v_mfma_f32_16x16x32_bf16 v[26:29], v[212:215], v[228:231], v[2:5]
	v_mfma_f32_16x16x32_bf16 v[2:5], v[216:219], v[224:227], v[196:199]
	v_mfma_f32_16x16x32_bf16 v[18:21], v[220:223], v[228:231], v[2:5]
	v_mfma_f32_16x16x32_bf16 v[2:5], v[208:211], v[232:235], v[200:203]
	v_mfma_f32_16x16x32_bf16 v[6:9], v[212:215], v[236:239], v[2:5]
	v_mfma_f32_16x16x32_bf16 v[2:5], v[216:219], v[232:235], v[204:207]
	v_mfma_f32_16x16x32_bf16 v[2:5], v[220:223], v[236:239], v[2:5]
	s_setprio 1
	s_barrier
	s_add_u32 s82, s82, 0x80180
	s_addc_u32 s83, s83, 0
	s_add_u32 s57, s80, 0x200
	s_addc_u32 s80, s81, 0
	s_mov_b32 s81, 0
.LBB0_1025:
	ds_read_b128 v[140:143], v1
	ds_read_b128 v[144:147], v1 offset:1024
	ds_read_b128 v[148:151], v1 offset:2048
	ds_read_b128 v[156:159], v1 offset:3072
	ds_read_b128 v[160:163], v152
	ds_read_b128 v[164:167], v152 offset:1024
	ds_read_b128 v[168:171], v152 offset:2048
	ds_read_b128 v[172:175], v152 offset:3072
	s_add_u32 s0, s82, 0xfff80080
	s_addc_u32 s1, s83, -1
	s_cmp_eq_u32 s81, 28
	s_cselect_b32 s1, s73, s1
	s_cselect_b32 s0, s75, s0
	s_cselect_b32 s65, s96, s80
	s_cselect_b32 s64, s97, s57
	s_mov_b32 m0, s87
	v_lshl_add_u64 v[208:209], s[82:83], 0, v[134:135]
	ds_read_b128 v[176:179], v153
	ds_read_b128 v[180:183], v153 offset:1024
	ds_read_b128 v[184:187], v153 offset:2048
	ds_read_b128 v[188:191], v153 offset:3072
	ds_read_b128 v[192:195], v153 offset:4096
	ds_read_b128 v[196:199], v153 offset:5120
	ds_read_b128 v[200:203], v153 offset:6144
	ds_read_b128 v[204:207], v153 offset:7168
	global_load_lds_dwordx4 v[208:209], off
	v_lshl_add_u64 v[208:209], v[208:209], 0, s[36:37]
	s_mov_b32 m0, s88
	s_nop 0
	global_load_lds_dwordx4 v[208:209], off
	s_waitcnt vmcnt(8)
	s_waitcnt lgkmcnt(0)
	s_barrier
	s_waitcnt lgkmcnt(0)
	s_setprio 0
	v_mfma_f32_16x16x32_bf16 v[122:125], v[140:143], v[176:179], v[122:125]
	v_mfma_f32_16x16x32_bf16 v[114:117], v[148:151], v[176:179], v[114:117]
	v_mfma_f32_16x16x32_bf16 v[106:109], v[140:143], v[184:187], v[106:109]
	v_mfma_f32_16x16x32_bf16 v[98:101], v[148:151], v[184:187], v[98:101]
	v_mfma_f32_16x16x32_bf16 v[90:93], v[140:143], v[192:195], v[90:93]
	v_mfma_f32_16x16x32_bf16 v[82:85], v[148:151], v[192:195], v[82:85]
	v_mfma_f32_16x16x32_bf16 v[58:61], v[140:143], v[200:203], v[58:61]
	v_mfma_f32_16x16x32_bf16 v[50:53], v[148:151], v[200:203], v[50:53]
	v_mfma_f32_16x16x32_bf16 v[122:125], v[144:147], v[180:183], v[122:125]
	v_mfma_f32_16x16x32_bf16 v[114:117], v[156:159], v[180:183], v[114:117]
	v_mfma_f32_16x16x32_bf16 v[106:109], v[144:147], v[188:191], v[106:109]
	v_mfma_f32_16x16x32_bf16 v[98:101], v[156:159], v[188:191], v[98:101]
	v_mfma_f32_16x16x32_bf16 v[90:93], v[144:147], v[196:199], v[90:93]
	v_mfma_f32_16x16x32_bf16 v[82:85], v[156:159], v[196:199], v[82:85]
	v_mfma_f32_16x16x32_bf16 v[58:61], v[144:147], v[204:207], v[58:61]
	v_mfma_f32_16x16x32_bf16 v[50:53], v[156:159], v[204:207], v[50:53]
	v_mfma_f32_16x16x32_bf16 v[126:129], v[160:163], v[176:179], v[126:129]
	v_mfma_f32_16x16x32_bf16 v[118:121], v[168:171], v[176:179], v[118:121]
	v_mfma_f32_16x16x32_bf16 v[110:113], v[160:163], v[184:187], v[110:113]
	v_mfma_f32_16x16x32_bf16 v[102:105], v[168:171], v[184:187], v[102:105]
	v_mfma_f32_16x16x32_bf16 v[94:97], v[160:163], v[192:195], v[94:97]
	v_mfma_f32_16x16x32_bf16 v[86:89], v[168:171], v[192:195], v[86:89]
	v_mfma_f32_16x16x32_bf16 v[62:65], v[160:163], v[200:203], v[62:65]
	v_mfma_f32_16x16x32_bf16 v[54:57], v[168:171], v[200:203], v[54:57]
	v_mfma_f32_16x16x32_bf16 v[126:129], v[164:167], v[180:183], v[126:129]
	v_mfma_f32_16x16x32_bf16 v[118:121], v[172:175], v[180:183], v[118:121]
	v_mfma_f32_16x16x32_bf16 v[110:113], v[164:167], v[188:191], v[110:113]
	v_mfma_f32_16x16x32_bf16 v[102:105], v[172:175], v[188:191], v[102:105]
	v_mfma_f32_16x16x32_bf16 v[94:97], v[164:167], v[196:199], v[94:97]
	v_mfma_f32_16x16x32_bf16 v[86:89], v[172:175], v[196:199], v[86:89]
	v_mfma_f32_16x16x32_bf16 v[62:65], v[164:167], v[204:207], v[62:65]
	v_mfma_f32_16x16x32_bf16 v[54:57], v[172:175], v[204:207], v[54:57]
	s_setprio 1
	s_barrier
	s_mov_b32 m0, vcc_lo
	v_lshl_add_u64 v[208:209], s[64:65], 0, v[130:131]
	ds_read_b128 v[176:179], v153 offset:16384
	ds_read_b128 v[180:183], v153 offset:17408
	ds_read_b128 v[184:187], v153 offset:18432
	ds_read_b128 v[188:191], v153 offset:19456
	ds_read_b128 v[192:195], v153 offset:20480
	ds_read_b128 v[196:199], v153 offset:21504
	ds_read_b128 v[200:203], v153 offset:22528
	ds_read_b128 v[204:207], v153 offset:23552
	global_load_lds_dwordx4 v[208:209], off
	v_lshl_add_u64 v[210:211], v[208:209], 0, s[36:37]
	s_mov_b32 m0, vcc_hi
	s_nop 0
	global_load_lds_dwordx4 v[210:211], off
	v_lshl_add_u64 v[210:211], v[208:209], 0, s[38:39]
	s_mov_b32 m0, s40
	s_nop 0
	global_load_lds_dwordx4 v[210:211], off
	v_lshl_add_u64 v[210:211], v[208:209], 0, s[66:67]
	s_mov_b32 m0, s41
	s_nop 0
	global_load_lds_dwordx4 v[210:211], off
	v_lshl_add_u64 v[210:211], s[0:1], 0, v[132:133]
	s_mov_b32 m0, s45
	v_lshl_add_u64 v[212:213], v[210:211], 0, s[36:37]
	global_load_lds_dwordx4 v[210:211], off
	s_mov_b32 m0, s46
	s_nop 0
	global_load_lds_dwordx4 v[212:213], off
	s_waitcnt vmcnt(8)
	s_waitcnt lgkmcnt(0)
	s_barrier
	s_waitcnt lgkmcnt(0)
	s_setprio 0
	v_mfma_f32_16x16x32_bf16 v[78:81], v[140:143], v[176:179], v[78:81]
	v_mfma_f32_16x16x32_bf16 v[70:73], v[148:151], v[176:179], v[70:73]
	v_mfma_f32_16x16x32_bf16 v[46:49], v[140:143], v[184:187], v[46:49]
	v_mfma_f32_16x16x32_bf16 v[38:41], v[148:151], v[184:187], v[38:41]
	v_mfma_f32_16x16x32_bf16 v[30:33], v[140:143], v[192:195], v[30:33]
	v_mfma_f32_16x16x32_bf16 v[22:25], v[148:151], v[192:195], v[22:25]
	v_mfma_f32_16x16x32_bf16 v[14:17], v[140:143], v[200:203], v[14:17]
	v_mfma_f32_16x16x32_bf16 v[10:13], v[148:151], v[200:203], v[10:13]
	v_mfma_f32_16x16x32_bf16 v[78:81], v[144:147], v[180:183], v[78:81]
	v_mfma_f32_16x16x32_bf16 v[70:73], v[156:159], v[180:183], v[70:73]
	v_mfma_f32_16x16x32_bf16 v[46:49], v[144:147], v[188:191], v[46:49]
	v_mfma_f32_16x16x32_bf16 v[38:41], v[156:159], v[188:191], v[38:41]
	v_mfma_f32_16x16x32_bf16 v[30:33], v[144:147], v[196:199], v[30:33]
	v_mfma_f32_16x16x32_bf16 v[22:25], v[156:159], v[196:199], v[22:25]
	v_mfma_f32_16x16x32_bf16 v[14:17], v[144:147], v[204:207], v[14:17]
	v_mfma_f32_16x16x32_bf16 v[10:13], v[156:159], v[204:207], v[10:13]
	v_mfma_f32_16x16x32_bf16 v[74:77], v[160:163], v[176:179], v[74:77]
	v_mfma_f32_16x16x32_bf16 v[66:69], v[168:171], v[176:179], v[66:69]
	v_mfma_f32_16x16x32_bf16 v[42:45], v[160:163], v[184:187], v[42:45]
	v_mfma_f32_16x16x32_bf16 v[34:37], v[168:171], v[184:187], v[34:37]
	v_mfma_f32_16x16x32_bf16 v[26:29], v[160:163], v[192:195], v[26:29]
	v_mfma_f32_16x16x32_bf16 v[18:21], v[168:171], v[192:195], v[18:21]
	v_mfma_f32_16x16x32_bf16 v[6:9], v[160:163], v[200:203], v[6:9]
	v_mfma_f32_16x16x32_bf16 v[2:5], v[168:171], v[200:203], v[2:5]
	v_mfma_f32_16x16x32_bf16 v[74:77], v[164:167], v[180:183], v[74:77]
	v_mfma_f32_16x16x32_bf16 v[66:69], v[172:175], v[180:183], v[66:69]
	v_mfma_f32_16x16x32_bf16 v[42:45], v[164:167], v[188:191], v[42:45]
	v_mfma_f32_16x16x32_bf16 v[34:37], v[172:175], v[188:191], v[34:37]
	v_mfma_f32_16x16x32_bf16 v[26:29], v[164:167], v[196:199], v[26:29]
	v_mfma_f32_16x16x32_bf16 v[18:21], v[172:175], v[196:199], v[18:21]
	v_mfma_f32_16x16x32_bf16 v[6:9], v[164:167], v[204:207], v[6:9]
	v_mfma_f32_16x16x32_bf16 v[2:5], v[172:175], v[204:207], v[2:5]
	s_setprio 1
	s_barrier
; #define PG8_WAIT_V(n) asm volatile("s_waitcnt vmcnt(" #n ")" ::: "memory")
; template <class Epi, class Sched, bool ALIGN_EPI = true, bool SP2 = true, bool FULLLINE = false, bool NOSTAGE = false, bool FP8 = false>
; __device__ __forceinline__ void gemm_phase(PG8_LAS unsigned char* lds, const Gemm g, const Sched& S, const Epi& E) {
;     ...
;         static_assert(SP2, "only the SP2 loop is kept");
;         { const int t = 0; if constexpr (Epi::NST == 16) PG8_ITER(PG8_WAIT_V(24)); else if constexpr (Epi::NST == 8) PG8_ITER(PG8_WAIT_V(16)); else PG8_ITER(PG8_WAIT_V(8)); }
;         for (int t = 2; t < nt; t += 2) PG8_ITER(PG8_WAIT_V(8));
	ds_read_b128 v[140:143], v154
	ds_read_b128 v[144:147], v154 offset:1024
	ds_read_b128 v[148:151], v154 offset:2048
	ds_read_b128 v[156:159], v154 offset:3072
	ds_read_b128 v[160:163], v155
	ds_read_b128 v[164:167], v155 offset:1024
	ds_read_b128 v[168:171], v155 offset:2048
	ds_read_b128 v[172:175], v155 offset:3072
	s_mov_b32 m0, s47
	v_lshl_add_u64 v[212:213], v[210:211], 0, s[38:39]
	ds_read_b128 v[176:179], v153 offset:32768
	ds_read_b128 v[180:183], v153 offset:33792
	ds_read_b128 v[184:187], v153 offset:34816
	ds_read_b128 v[188:191], v153 offset:35840
	ds_read_b128 v[192:195], v153 offset:36864
	ds_read_b128 v[196:199], v153 offset:37888
	ds_read_b128 v[200:203], v153 offset:38912
	ds_read_b128 v[204:207], v153 offset:39936
	global_load_lds_dwordx4 v[212:213], off
	v_lshl_add_u64 v[212:213], v[210:211], 0, s[66:67]
	s_mov_b32 m0, s52
	s_nop 0
	global_load_lds_dwordx4 v[212:213], off
	s_waitcnt vmcnt(8)
	s_waitcnt lgkmcnt(0)
	s_barrier
	s_waitcnt lgkmcnt(0)
	s_setprio 0
	v_mfma_f32_16x16x32_bf16 v[122:125], v[140:143], v[176:179], v[122:125]
	v_mfma_f32_16x16x32_bf16 v[114:117], v[148:151], v[176:179], v[114:117]
	v_mfma_f32_16x16x32_bf16 v[106:109], v[140:143], v[184:187], v[106:109]
	v_mfma_f32_16x16x32_bf16 v[98:101], v[148:151], v[184:187], v[98:101]
	v_mfma_f32_16x16x32_bf16 v[90:93], v[140:143], v[192:195], v[90:93]
	v_mfma_f32_16x16x32_bf16 v[82:85], v[148:151], v[192:195], v[82:85]
	v_mfma_f32_16x16x32_bf16 v[58:61], v[140:143], v[200:203], v[58:61]
	v_mfma_f32_16x16x32_bf16 v[50:53], v[148:151], v[200:203], v[50:53]
	v_mfma_f32_16x16x32_bf16 v[122:125], v[144:147], v[180:183], v[122:125]
	v_mfma_f32_16x16x32_bf16 v[114:117], v[156:159], v[180:183], v[114:117]
	v_mfma_f32_16x16x32_bf16 v[106:109], v[144:147], v[188:191], v[106:109]
	v_mfma_f32_16x16x32_bf16 v[98:101], v[156:159], v[188:191], v[98:101]
	v_mfma_f32_16x16x32_bf16 v[90:93], v[144:147], v[196:199], v[90:93]
	v_mfma_f32_16x16x32_bf16 v[82:85], v[156:159], v[196:199], v[82:85]
	v_mfma_f32_16x16x32_bf16 v[58:61], v[144:147], v[204:207], v[58:61]
	v_mfma_f32_16x16x32_bf16 v[50:53], v[156:159], v[204:207], v[50:53]
	v_mfma_f32_16x16x32_bf16 v[126:129], v[160:163], v[176:179], v[126:129]
	v_mfma_f32_16x16x32_bf16 v[118:121], v[168:171], v[176:179], v[118:121]
	v_mfma_f32_16x16x32_bf16 v[110:113], v[160:163], v[184:187], v[110:113]
	v_mfma_f32_16x16x32_bf16 v[102:105], v[168:171], v[184:187], v[102:105]
	v_mfma_f32_16x16x32_bf16 v[94:97], v[160:163], v[192:195], v[94:97]
	v_mfma_f32_16x16x32_bf16 v[86:89], v[168:171], v[192:195], v[86:89]
	v_mfma_f32_16x16x32_bf16 v[62:65], v[160:163], v[200:203], v[62:65]
	v_mfma_f32_16x16x32_bf16 v[54:57], v[168:171], v[200:203], v[54:57]
	v_mfma_f32_16x16x32_bf16 v[126:129], v[164:167], v[180:183], v[126:129]
	v_mfma_f32_16x16x32_bf16 v[118:121], v[172:175], v[180:183], v[118:121]
	v_mfma_f32_16x16x32_bf16 v[110:113], v[164:167], v[188:191], v[110:113]
	v_mfma_f32_16x16x32_bf16 v[102:105], v[172:175], v[188:191], v[102:105]
	v_mfma_f32_16x16x32_bf16 v[94:97], v[164:167], v[196:199], v[94:97]
	v_mfma_f32_16x16x32_bf16 v[86:89], v[172:175], v[196:199], v[86:89]
	v_mfma_f32_16x16x32_bf16 v[62:65], v[164:167], v[204:207], v[62:65]
	v_mfma_f32_16x16x32_bf16 v[54:57], v[172:175], v[204:207], v[54:57]
	s_setprio 1
	s_barrier
	s_mov_b32 m0, s50
	v_lshl_add_u64 v[212:213], v[208:209], 0, s[68:69]
	ds_read_b128 v[176:179], v153 offset:49152
	ds_read_b128 v[180:183], v153 offset:50176
	ds_read_b128 v[184:187], v153 offset:51200
	ds_read_b128 v[188:191], v153 offset:52224
	ds_read_b128 v[192:195], v153 offset:53248
	ds_read_b128 v[196:199], v153 offset:54272
	ds_read_b128 v[200:203], v153 offset:55296
	ds_read_b128 v[204:207], v153 offset:56320
	global_load_lds_dwordx4 v[212:213], off
	v_lshl_add_u64 v[212:213], v[208:209], 0, s[70:71]
	s_mov_b32 m0, s51
	s_nop 0
	global_load_lds_dwordx4 v[212:213], off
	v_lshl_add_u64 v[212:213], v[208:209], 0, s[18:19]
	s_mov_b32 m0, s33
	v_lshl_add_u64 v[208:209], v[208:209], 0, s[20:21]
	global_load_lds_dwordx4 v[212:213], off
	s_mov_b32 m0, s56
	s_nop 0
	global_load_lds_dwordx4 v[208:209], off
	v_lshl_add_u64 v[208:209], v[210:211], 0, s[68:69]
	s_mov_b32 m0, s53
	s_nop 0
	global_load_lds_dwordx4 v[208:209], off
	v_lshl_add_u64 v[208:209], v[210:211], 0, s[70:71]
	s_mov_b32 m0, s54
	s_nop 0
	global_load_lds_dwordx4 v[208:209], off
	s_waitcnt vmcnt(8)
	s_waitcnt lgkmcnt(0)
	s_barrier
	s_waitcnt lgkmcnt(0)
	s_setprio 0
	v_mfma_f32_16x16x32_bf16 v[78:81], v[140:143], v[176:179], v[78:81]
	v_mfma_f32_16x16x32_bf16 v[70:73], v[148:151], v[176:179], v[70:73]
	v_mfma_f32_16x16x32_bf16 v[46:49], v[140:143], v[184:187], v[46:49]
	v_mfma_f32_16x16x32_bf16 v[38:41], v[148:151], v[184:187], v[38:41]
	v_mfma_f32_16x16x32_bf16 v[30:33], v[140:143], v[192:195], v[30:33]
	v_mfma_f32_16x16x32_bf16 v[22:25], v[148:151], v[192:195], v[22:25]
	v_mfma_f32_16x16x32_bf16 v[14:17], v[140:143], v[200:203], v[14:17]
	v_mfma_f32_16x16x32_bf16 v[10:13], v[148:151], v[200:203], v[10:13]
	v_mfma_f32_16x16x32_bf16 v[78:81], v[144:147], v[180:183], v[78:81]
	v_mfma_f32_16x16x32_bf16 v[70:73], v[156:159], v[180:183], v[70:73]
	v_mfma_f32_16x16x32_bf16 v[46:49], v[144:147], v[188:191], v[46:49]
	v_mfma_f32_16x16x32_bf16 v[38:41], v[156:159], v[188:191], v[38:41]
	v_mfma_f32_16x16x32_bf16 v[30:33], v[144:147], v[196:199], v[30:33]
	v_mfma_f32_16x16x32_bf16 v[22:25], v[156:159], v[196:199], v[22:25]
	v_mfma_f32_16x16x32_bf16 v[14:17], v[144:147], v[204:207], v[14:17]
	v_mfma_f32_16x16x32_bf16 v[10:13], v[156:159], v[204:207], v[10:13]
	v_mfma_f32_16x16x32_bf16 v[74:77], v[160:163], v[176:179], v[74:77]
	v_mfma_f32_16x16x32_bf16 v[66:69], v[168:171], v[176:179], v[66:69]
	v_mfma_f32_16x16x32_bf16 v[42:45], v[160:163], v[184:187], v[42:45]
	v_mfma_f32_16x16x32_bf16 v[34:37], v[168:171], v[184:187], v[34:37]
	v_mfma_f32_16x16x32_bf16 v[26:29], v[160:163], v[192:195], v[26:29]
	v_mfma_f32_16x16x32_bf16 v[18:21], v[168:171], v[192:195], v[18:21]
	v_mfma_f32_16x16x32_bf16 v[6:9], v[160:163], v[200:203], v[6:9]
	v_mfma_f32_16x16x32_bf16 v[2:5], v[168:171], v[200:203], v[2:5]
	v_mfma_f32_16x16x32_bf16 v[74:77], v[164:167], v[180:183], v[74:77]
	v_mfma_f32_16x16x32_bf16 v[66:69], v[172:175], v[180:183], v[66:69]
	v_mfma_f32_16x16x32_bf16 v[42:45], v[164:167], v[188:191], v[42:45]
	v_mfma_f32_16x16x32_bf16 v[34:37], v[172:175], v[188:191], v[34:37]
	v_mfma_f32_16x16x32_bf16 v[26:29], v[164:167], v[196:199], v[26:29]
	v_mfma_f32_16x16x32_bf16 v[18:21], v[172:175], v[196:199], v[18:21]
	v_mfma_f32_16x16x32_bf16 v[6:9], v[164:167], v[204:207], v[6:9]
	v_mfma_f32_16x16x32_bf16 v[2:5], v[172:175], v[204:207], v[2:5]
	s_setprio 1
	s_barrier
	s_add_i32 s81, s81, 2
	s_add_u32 s82, s82, 0x100
	s_addc_u32 s83, s83, 0
	s_add_u32 s57, s57, 0x100
	s_addc_u32 s80, s80, 0
	s_cmp_gt_u32 s81, 29
	s_cbranch_scc0 .LBB0_1025
	s_and_b64 vcc, exec, s[14:15]
	s_cbranch_vccz .LBB0_1028
	s_barrier

; template <class Epi, class Sched, bool ALIGN_EPI = true, bool SP2 = true, bool FULLLINE = false, bool NOSTAGE = false, bool FP8 = false>
; __device__ __forceinline__ void gemm_phase(PG8_LAS unsigned char* lds, const Gemm g, const Sched& S, const Epi& E) {
;     ...
;         const bool has_next = S.next(ui + 1, nxt);
;         const char* nA = has_next ? PG8_ABASE(nxt) : cA; const char* nB = has_next ? PG8_BBASE(nxt) : cB;
.LBB0_1207:
	s_ashr_i32 s69, s68, 31
	ds_read_b128 v[2:5], v1
	ds_read_b128 v[6:9], v1 offset:1024
	ds_read_b128 v[10:13], v1 offset:2048
	ds_read_b128 v[14:17], v1 offset:3072
	ds_read_b128 v[18:21], v192
	ds_read_b128 v[22:25], v192 offset:1024
	ds_read_b128 v[26:29], v192 offset:2048
	ds_read_b128 v[30:33], v192 offset:3072
	s_lshl_b64 s[0:1], s[68:69], 20
	s_add_u32 s70, s42, s0
	s_addc_u32 s71, s43, s1
	s_and_b64 s[0:1], s[8:9], exec
	s_cselect_b32 s69, s71, s77
	s_cselect_b32 s92, s70, s76
	s_ashr_i32 s67, s66, 31
	s_lshl_b64 s[0:1], s[66:67], 20
	s_add_u32 s72, s44, s0
	s_addc_u32 s73, s45, s1
	s_and_b64 s[0:1], s[8:9], exec
	s_cselect_b32 s67, s73, s79
	s_cselect_b32 s93, s72, s78
	v_lshl_add_u64 v[248:249], s[76:77], 0, v[170:171]
	s_mov_b32 m0, s88
	v_lshl_add_u64 v[66:67], v[248:249], 0, s[12:13]
	ds_read_b128 v[34:37], v193
	ds_read_b128 v[38:41], v193 offset:1024
	ds_read_b128 v[42:45], v193 offset:2048
	ds_read_b128 v[46:49], v193 offset:3072
	ds_read_b128 v[50:53], v193 offset:4096
	ds_read_b128 v[54:57], v193 offset:5120
	ds_read_b128 v[58:61], v193 offset:6144
	ds_read_b128 v[62:65], v193 offset:7168
	global_load_lds_dwordx4 v[66:67], off
	v_lshl_add_u64 v[66:67], v[248:249], 0, s[14:15]
	s_mov_b32 m0, s89
	s_nop 0
	global_load_lds_dwordx4 v[66:67], off
	s_waitcnt vmcnt(24)
	s_waitcnt lgkmcnt(0)
	s_barrier
	s_waitcnt lgkmcnt(0)
	s_setprio 0
	v_mfma_f32_16x16x32_bf16 v[66:69], v[2:5], v[34:37], 0
	v_mfma_f32_16x16x32_bf16 v[70:73], v[10:13], v[34:37], 0
	v_mfma_f32_16x16x32_bf16 v[78:81], v[10:13], v[42:45], 0
	v_mfma_f32_16x16x32_bf16 v[86:89], v[10:13], v[50:53], 0
	v_mfma_f32_16x16x32_bf16 v[66:69], v[6:9], v[38:41], v[66:69]
	v_mfma_f32_16x16x32_bf16 v[70:73], v[14:17], v[38:41], v[70:73]
	v_mfma_f32_16x16x32_bf16 v[74:77], v[2:5], v[42:45], 0
	v_mfma_f32_16x16x32_bf16 v[78:81], v[14:17], v[46:49], v[78:81]
	v_mfma_f32_16x16x32_bf16 v[82:85], v[2:5], v[50:53], 0
	v_mfma_f32_16x16x32_bf16 v[86:89], v[14:17], v[54:57], v[86:89]
	v_mfma_f32_16x16x32_bf16 v[90:93], v[2:5], v[58:61], 0
	v_mfma_f32_16x16x32_bf16 v[94:97], v[10:13], v[58:61], 0
	v_mfma_f32_16x16x32_bf16 v[74:77], v[6:9], v[46:49], v[74:77]
	v_mfma_f32_16x16x32_bf16 v[82:85], v[6:9], v[54:57], v[82:85]
	v_mfma_f32_16x16x32_bf16 v[90:93], v[6:9], v[62:65], v[90:93]
	v_mfma_f32_16x16x32_bf16 v[94:97], v[14:17], v[62:65], v[94:97]
	v_mfma_f32_16x16x32_bf16 v[98:101], v[18:21], v[34:37], 0
	v_mfma_f32_16x16x32_bf16 v[34:37], v[26:29], v[34:37], 0
	v_mfma_f32_16x16x32_bf16 v[98:101], v[22:25], v[38:41], v[98:101]
	v_mfma_f32_16x16x32_bf16 v[34:37], v[30:33], v[38:41], v[34:37]
	v_mfma_f32_16x16x32_bf16 v[38:41], v[18:21], v[42:45], 0
	v_mfma_f32_16x16x32_bf16 v[42:45], v[26:29], v[42:45], 0
	v_mfma_f32_16x16x32_bf16 v[38:41], v[22:25], v[46:49], v[38:41]
	v_mfma_f32_16x16x32_bf16 v[42:45], v[30:33], v[46:49], v[42:45]
	v_mfma_f32_16x16x32_bf16 v[46:49], v[18:21], v[50:53], 0
	v_mfma_f32_16x16x32_bf16 v[50:53], v[26:29], v[50:53], 0
	v_mfma_f32_16x16x32_bf16 v[46:49], v[22:25], v[54:57], v[46:49]
	v_mfma_f32_16x16x32_bf16 v[50:53], v[30:33], v[54:57], v[50:53]
	v_mfma_f32_16x16x32_bf16 v[54:57], v[18:21], v[58:61], 0
	v_mfma_f32_16x16x32_bf16 v[58:61], v[26:29], v[58:61], 0
	v_mfma_f32_16x16x32_bf16 v[54:57], v[22:25], v[62:65], v[54:57]
	v_mfma_f32_16x16x32_bf16 v[58:61], v[30:33], v[62:65], v[58:61]
	s_setprio 1
	s_barrier
	v_lshl_add_u64 v[250:251], s[78:79], 0, v[172:173]
	s_add_i32 s94, s85, s46
	v_lshl_add_u64 v[130:131], v[250:251], 0, s[16:17]
	s_mov_b32 m0, s94
	s_add_i32 s95, s94, 0x2000
	ds_read_b128 v[62:65], v193 offset:16384
	ds_read_b128 v[102:105], v193 offset:17408
	ds_read_b128 v[106:109], v193 offset:18432
	ds_read_b128 v[110:113], v193 offset:19456
	ds_read_b128 v[114:117], v193 offset:20480
	ds_read_b128 v[118:121], v193 offset:21504
	ds_read_b128 v[122:125], v193 offset:22528
	ds_read_b128 v[126:129], v193 offset:23552
	global_load_lds_dwordx4 v[130:131], off
	v_lshl_add_u64 v[130:131], v[250:251], 0, s[18:19]
	s_mov_b32 m0, s95
	s_add_i32 s40, s87, s46
	global_load_lds_dwordx4 v[130:131], off
	v_lshl_add_u64 v[130:131], v[250:251], 0, s[20:21]
	s_mov_b32 m0, s40
	s_add_i32 s41, s40, 0x2000
	global_load_lds_dwordx4 v[130:131], off
	v_lshl_add_u64 v[130:131], v[250:251], 0, s[22:23]
	s_mov_b32 m0, s41
	s_nop 0
	global_load_lds_dwordx4 v[130:131], off
	v_lshl_add_u64 v[130:131], v[248:249], 0, s[16:17]
	s_mov_b32 m0, s47
	s_nop 0
	global_load_lds_dwordx4 v[130:131], off
	v_lshl_add_u64 v[130:131], v[248:249], 0, s[18:19]
	s_mov_b32 m0, s52
	s_nop 0
	global_load_lds_dwordx4 v[130:131], off
	s_waitcnt vmcnt(24)
	s_waitcnt lgkmcnt(0)
	s_barrier
	s_waitcnt lgkmcnt(0)
	s_setprio 0
	v_mfma_f32_16x16x32_bf16 v[130:133], v[2:5], v[62:65], 0
	v_mfma_f32_16x16x32_bf16 v[138:141], v[6:9], v[102:105], v[130:133]
	v_mfma_f32_16x16x32_bf16 v[130:133], v[10:13], v[62:65], 0
	v_mfma_f32_16x16x32_bf16 v[150:153], v[14:17], v[102:105], v[130:133]
	v_mfma_f32_16x16x32_bf16 v[130:133], v[2:5], v[106:109], 0
	v_mfma_f32_16x16x32_bf16 v[154:157], v[6:9], v[110:113], v[130:133]
	v_mfma_f32_16x16x32_bf16 v[130:133], v[10:13], v[106:109], 0
	v_mfma_f32_16x16x32_bf16 v[158:161], v[14:17], v[110:113], v[130:133]
	v_mfma_f32_16x16x32_bf16 v[130:133], v[2:5], v[114:117], 0
	v_mfma_f32_16x16x32_bf16 v[2:5], v[2:5], v[122:125], 0
	v_mfma_f32_16x16x32_bf16 v[162:165], v[6:9], v[118:121], v[130:133]
	v_mfma_f32_16x16x32_bf16 v[2:5], v[6:9], v[126:129], v[2:5]
	v_mfma_f32_16x16x32_bf16 v[6:9], v[10:13], v[122:125], 0
	v_mfma_f32_16x16x32_bf16 v[130:133], v[10:13], v[114:117], 0
	v_mfma_f32_16x16x32_bf16 v[6:9], v[14:17], v[126:129], v[6:9]
	v_mfma_f32_16x16x32_bf16 v[166:169], v[14:17], v[118:121], v[130:133]
	v_mfma_f32_16x16x32_bf16 v[10:13], v[18:21], v[62:65], 0
	v_mfma_f32_16x16x32_bf16 v[180:183], v[22:25], v[102:105], v[10:13]
	v_mfma_f32_16x16x32_bf16 v[10:13], v[26:29], v[62:65], 0
	v_mfma_f32_16x16x32_bf16 v[184:187], v[30:33], v[102:105], v[10:13]
	v_mfma_f32_16x16x32_bf16 v[10:13], v[18:21], v[106:109], 0
	v_mfma_f32_16x16x32_bf16 v[188:191], v[22:25], v[110:113], v[10:13]
	v_mfma_f32_16x16x32_bf16 v[10:13], v[26:29], v[106:109], 0
	v_mfma_f32_16x16x32_bf16 v[196:199], v[30:33], v[110:113], v[10:13]
	v_mfma_f32_16x16x32_bf16 v[10:13], v[18:21], v[114:117], 0
	v_mfma_f32_16x16x32_bf16 v[200:203], v[22:25], v[118:121], v[10:13]
	v_mfma_f32_16x16x32_bf16 v[10:13], v[26:29], v[114:117], 0
	v_mfma_f32_16x16x32_bf16 v[204:207], v[30:33], v[118:121], v[10:13]
	v_mfma_f32_16x16x32_bf16 v[10:13], v[18:21], v[122:125], 0
	v_mfma_f32_16x16x32_bf16 v[208:211], v[22:25], v[126:129], v[10:13]
	v_mfma_f32_16x16x32_bf16 v[10:13], v[26:29], v[122:125], 0
	v_mfma_f32_16x16x32_bf16 v[212:215], v[30:33], v[126:129], v[10:13]
	s_setprio 1
	s_barrier
	s_nop 5
	ds_read_b128 v[10:13], v194
	ds_read_b128 v[14:17], v194 offset:1024
	ds_read_b128 v[18:21], v194 offset:2048
	ds_read_b128 v[22:25], v194 offset:3072
	ds_read_b128 v[216:219], v195
	ds_read_b128 v[220:223], v195 offset:1024
	ds_read_b128 v[224:227], v195 offset:2048
	ds_read_b128 v[228:231], v195 offset:3072
	s_mov_b32 m0, s53
	v_lshl_add_u64 v[106:107], v[248:249], 0, s[20:21]
	ds_read_b128 v[26:29], v193 offset:32768
	ds_read_b128 v[30:33], v193 offset:33792
	ds_read_b128 v[62:65], v193 offset:34816
	ds_read_b128 v[102:105], v193 offset:35840
	ds_read_b128 v[232:235], v193 offset:36864
	ds_read_b128 v[236:239], v193 offset:37888
	ds_read_b128 v[240:243], v193 offset:38912
	ds_read_b128 v[244:247], v193 offset:39936
	global_load_lds_dwordx4 v[106:107], off
	v_lshl_add_u64 v[106:107], v[248:249], 0, s[22:23]
	s_mov_b32 m0, s54
	s_nop 0
	global_load_lds_dwordx4 v[106:107], off
	s_waitcnt vmcnt(8)
	s_waitcnt lgkmcnt(0)
	s_barrier
	s_waitcnt lgkmcnt(0)
	s_setprio 0
	v_mfma_f32_16x16x32_bf16 v[66:69], v[10:13], v[26:29], v[66:69]
	v_mfma_f32_16x16x32_bf16 v[146:149], v[14:17], v[30:33], v[66:69]
	v_mfma_f32_16x16x32_bf16 v[66:69], v[18:21], v[26:29], v[70:73]
	v_mfma_f32_16x16x32_bf16 v[142:145], v[22:25], v[30:33], v[66:69]
	v_mfma_f32_16x16x32_bf16 v[66:69], v[10:13], v[62:65], v[74:77]
	v_mfma_f32_16x16x32_bf16 v[126:129], v[14:17], v[102:105], v[66:69]
	v_mfma_f32_16x16x32_bf16 v[66:69], v[18:21], v[62:65], v[78:81]
	v_mfma_f32_16x16x32_bf16 v[122:125], v[22:25], v[102:105], v[66:69]
	v_mfma_f32_16x16x32_bf16 v[66:69], v[10:13], v[232:235], v[82:85]
	v_mfma_f32_16x16x32_bf16 v[110:113], v[14:17], v[236:239], v[66:69]
	v_mfma_f32_16x16x32_bf16 v[66:69], v[18:21], v[232:235], v[86:89]
	v_mfma_f32_16x16x32_bf16 v[106:109], v[22:25], v[236:239], v[66:69]
	v_mfma_f32_16x16x32_bf16 v[66:69], v[10:13], v[240:243], v[90:93]
	v_mfma_f32_16x16x32_bf16 v[86:89], v[14:17], v[244:247], v[66:69]
	v_mfma_f32_16x16x32_bf16 v[66:69], v[18:21], v[240:243], v[94:97]
	v_mfma_f32_16x16x32_bf16 v[78:81], v[22:25], v[244:247], v[66:69]
	v_mfma_f32_16x16x32_bf16 v[66:69], v[216:219], v[26:29], v[98:101]
	v_mfma_f32_16x16x32_bf16 v[26:29], v[224:227], v[26:29], v[34:37]
	v_mfma_f32_16x16x32_bf16 v[130:133], v[228:231], v[30:33], v[26:29]
	v_mfma_f32_16x16x32_bf16 v[26:29], v[216:219], v[62:65], v[38:41]
	v_mfma_f32_16x16x32_bf16 v[118:121], v[220:223], v[102:105], v[26:29]
	v_mfma_f32_16x16x32_bf16 v[26:29], v[224:227], v[62:65], v[42:45]
	v_mfma_f32_16x16x32_bf16 v[114:117], v[228:231], v[102:105], v[26:29]
	v_mfma_f32_16x16x32_bf16 v[26:29], v[216:219], v[232:235], v[46:49]
	v_mfma_f32_16x16x32_bf16 v[102:105], v[220:223], v[236:239], v[26:29]
	v_mfma_f32_16x16x32_bf16 v[26:29], v[224:227], v[232:235], v[50:53]
	v_mfma_f32_16x16x32_bf16 v[98:101], v[228:231], v[236:239], v[26:29]
	v_mfma_f32_16x16x32_bf16 v[26:29], v[216:219], v[240:243], v[54:57]
	v_mfma_f32_16x16x32_bf16 v[70:73], v[220:223], v[244:247], v[26:29]
	v_mfma_f32_16x16x32_bf16 v[26:29], v[224:227], v[240:243], v[58:61]
	v_mfma_f32_16x16x32_bf16 v[134:137], v[220:223], v[30:33], v[66:69]
	v_mfma_f32_16x16x32_bf16 v[66:69], v[228:231], v[244:247], v[26:29]
	s_setprio 1
	s_barrier
	s_add_i32 s50, s90, s46
	s_nop 3
	v_lshl_add_u64 v[26:27], v[250:251], 0, s[24:25]
	s_mov_b32 m0, s50
	s_add_i32 s51, s50, 0x2000
	ds_read_b128 v[34:37], v193 offset:49152
	ds_read_b128 v[38:41], v193 offset:50176
	ds_read_b128 v[74:77], v193 offset:51200
	ds_read_b128 v[82:85], v193 offset:52224
	ds_read_b128 v[90:93], v193 offset:53248
	ds_read_b128 v[94:97], v193 offset:54272
	ds_read_b128 v[232:235], v193 offset:55296
	ds_read_b128 v[236:239], v193 offset:56320
	global_load_lds_dwordx4 v[26:27], off
	v_lshl_add_u64 v[26:27], v[250:251], 0, s[26:27]
	s_mov_b32 m0, s51
	s_mov_b64 s[0:1], 0x80180
	s_add_i32 s33, s91, s46
	global_load_lds_dwordx4 v[26:27], off
	v_lshl_add_u64 v[26:27], v[250:251], 0, s[0:1]
	s_mov_b32 m0, s33
	s_mov_b64 s[0:1], 0xc0180
	s_add_i32 s56, s33, 0x2000
	global_load_lds_dwordx4 v[26:27], off
	v_lshl_add_u64 v[26:27], v[250:251], 0, s[0:1]
	s_mov_b32 m0, s56
	s_nop 0
	global_load_lds_dwordx4 v[26:27], off
	v_lshl_add_u64 v[26:27], v[248:249], 0, s[24:25]
	s_mov_b32 m0, s55
	s_nop 0
	global_load_lds_dwordx4 v[26:27], off
	v_lshl_add_u64 v[26:27], v[248:249], 0, s[26:27]
	s_mov_b32 m0, s62
	s_nop 0
	global_load_lds_dwordx4 v[26:27], off
	s_waitcnt vmcnt(8)
	s_waitcnt lgkmcnt(0)
	s_barrier
	s_waitcnt lgkmcnt(0)
	s_setprio 0
	v_mfma_f32_16x16x32_bf16 v[26:29], v[10:13], v[34:37], v[138:141]
	v_mfma_f32_16x16x32_bf16 v[62:65], v[14:17], v[38:41], v[26:29]
	v_mfma_f32_16x16x32_bf16 v[26:29], v[18:21], v[34:37], v[150:153]
	v_mfma_f32_16x16x32_bf16 v[58:61], v[22:25], v[38:41], v[26:29]
	v_mfma_f32_16x16x32_bf16 v[26:29], v[10:13], v[74:77], v[154:157]
	v_mfma_f32_16x16x32_bf16 v[46:49], v[14:17], v[82:85], v[26:29]
	v_mfma_f32_16x16x32_bf16 v[26:29], v[18:21], v[74:77], v[158:161]
	v_mfma_f32_16x16x32_bf16 v[42:45], v[22:25], v[82:85], v[26:29]
	v_mfma_f32_16x16x32_bf16 v[26:29], v[10:13], v[90:93], v[162:165]
	v_mfma_f32_16x16x32_bf16 v[2:5], v[10:13], v[232:235], v[2:5]
	v_mfma_f32_16x16x32_bf16 v[30:33], v[14:17], v[94:97], v[26:29]
	v_mfma_f32_16x16x32_bf16 v[26:29], v[18:21], v[90:93], v[166:169]
	v_mfma_f32_16x16x32_bf16 v[14:17], v[14:17], v[236:239], v[2:5]
	v_mfma_f32_16x16x32_bf16 v[2:5], v[18:21], v[232:235], v[6:9]
	v_mfma_f32_16x16x32_bf16 v[26:29], v[22:25], v[94:97], v[26:29]
	v_mfma_f32_16x16x32_bf16 v[10:13], v[22:25], v[236:239], v[2:5]
	v_mfma_f32_16x16x32_bf16 v[2:5], v[216:219], v[34:37], v[180:183]
	v_mfma_f32_16x16x32_bf16 v[54:57], v[220:223], v[38:41], v[2:5]
	v_mfma_f32_16x16x32_bf16 v[2:5], v[224:227], v[34:37], v[184:187]
	v_mfma_f32_16x16x32_bf16 v[50:53], v[228:231], v[38:41], v[2:5]
	v_mfma_f32_16x16x32_bf16 v[2:5], v[216:219], v[74:77], v[188:191]
	v_mfma_f32_16x16x32_bf16 v[38:41], v[220:223], v[82:85], v[2:5]
	v_mfma_f32_16x16x32_bf16 v[2:5], v[224:227], v[74:77], v[196:199]
	v_mfma_f32_16x16x32_bf16 v[34:37], v[228:231], v[82:85], v[2:5]
	v_mfma_f32_16x16x32_bf16 v[2:5], v[216:219], v[90:93], v[200:203]
	v_mfma_f32_16x16x32_bf16 v[22:25], v[220:223], v[94:97], v[2:5]
	v_mfma_f32_16x16x32_bf16 v[2:5], v[224:227], v[90:93], v[204:207]
	v_mfma_f32_16x16x32_bf16 v[18:21], v[228:231], v[94:97], v[2:5]
	v_mfma_f32_16x16x32_bf16 v[2:5], v[216:219], v[232:235], v[208:211]
	v_mfma_f32_16x16x32_bf16 v[6:9], v[220:223], v[236:239], v[2:5]
	v_mfma_f32_16x16x32_bf16 v[2:5], v[224:227], v[232:235], v[212:215]
	v_mfma_f32_16x16x32_bf16 v[2:5], v[228:231], v[236:239], v[2:5]
	s_setprio 1
	s_barrier
	s_add_u32 s76, s76, 0x80180
	s_addc_u32 s77, s77, 0
	s_add_u32 s57, s78, 0x200
	s_addc_u32 s78, s79, 0
	s_mov_b32 s79, 0
.LBB0_1208:
	ds_read_b128 v[74:77], v1
	ds_read_b128 v[82:85], v1 offset:1024
	ds_read_b128 v[90:93], v1 offset:2048
	ds_read_b128 v[94:97], v1 offset:3072
	ds_read_b128 v[138:141], v192
	ds_read_b128 v[150:153], v192 offset:1024
	ds_read_b128 v[154:157], v192 offset:2048
	ds_read_b128 v[158:161], v192 offset:3072
	s_add_u32 s0, s76, 0xfff80080
	s_addc_u32 s1, s77, -1
	s_cmp_eq_u32 s79, 28
	s_cselect_b32 s1, s69, s1
	s_cselect_b32 s0, s92, s0
	s_cselect_b32 s65, s67, s78
	s_cselect_b32 s64, s93, s57
	s_mov_b32 m0, s88
	v_lshl_add_u64 v[208:209], s[76:77], 0, v[174:175]
	ds_read_b128 v[162:165], v193
	ds_read_b128 v[166:169], v193 offset:1024
	ds_read_b128 v[180:183], v193 offset:2048
	ds_read_b128 v[184:187], v193 offset:3072
	ds_read_b128 v[188:191], v193 offset:4096
	ds_read_b128 v[196:199], v193 offset:5120
	ds_read_b128 v[200:203], v193 offset:6144
	ds_read_b128 v[204:207], v193 offset:7168
	global_load_lds_dwordx4 v[208:209], off
	v_lshl_add_u64 v[208:209], v[208:209], 0, s[28:29]
	s_mov_b32 m0, s89
	s_nop 0
	global_load_lds_dwordx4 v[208:209], off
	s_waitcnt vmcnt(8)
	s_waitcnt lgkmcnt(0)
	s_barrier
	s_waitcnt lgkmcnt(0)
	s_setprio 0
	v_mfma_f32_16x16x32_bf16 v[146:149], v[74:77], v[162:165], v[146:149]
	v_mfma_f32_16x16x32_bf16 v[142:145], v[90:93], v[162:165], v[142:145]
	v_mfma_f32_16x16x32_bf16 v[126:129], v[74:77], v[180:183], v[126:129]
	v_mfma_f32_16x16x32_bf16 v[122:125], v[90:93], v[180:183], v[122:125]
	v_mfma_f32_16x16x32_bf16 v[110:113], v[74:77], v[188:191], v[110:113]
	v_mfma_f32_16x16x32_bf16 v[106:109], v[90:93], v[188:191], v[106:109]
	v_mfma_f32_16x16x32_bf16 v[86:89], v[74:77], v[200:203], v[86:89]
	v_mfma_f32_16x16x32_bf16 v[78:81], v[90:93], v[200:203], v[78:81]
	v_mfma_f32_16x16x32_bf16 v[146:149], v[82:85], v[166:169], v[146:149]
	v_mfma_f32_16x16x32_bf16 v[142:145], v[94:97], v[166:169], v[142:145]
	v_mfma_f32_16x16x32_bf16 v[126:129], v[82:85], v[184:187], v[126:129]
	v_mfma_f32_16x16x32_bf16 v[122:125], v[94:97], v[184:187], v[122:125]
	v_mfma_f32_16x16x32_bf16 v[110:113], v[82:85], v[196:199], v[110:113]
	v_mfma_f32_16x16x32_bf16 v[106:109], v[94:97], v[196:199], v[106:109]
	v_mfma_f32_16x16x32_bf16 v[86:89], v[82:85], v[204:207], v[86:89]
	v_mfma_f32_16x16x32_bf16 v[78:81], v[94:97], v[204:207], v[78:81]
	v_mfma_f32_16x16x32_bf16 v[134:137], v[138:141], v[162:165], v[134:137]
	v_mfma_f32_16x16x32_bf16 v[130:133], v[154:157], v[162:165], v[130:133]
	v_mfma_f32_16x16x32_bf16 v[118:121], v[138:141], v[180:183], v[118:121]
	v_mfma_f32_16x16x32_bf16 v[114:117], v[154:157], v[180:183], v[114:117]
	v_mfma_f32_16x16x32_bf16 v[102:105], v[138:141], v[188:191], v[102:105]
	v_mfma_f32_16x16x32_bf16 v[98:101], v[154:157], v[188:191], v[98:101]
	v_mfma_f32_16x16x32_bf16 v[70:73], v[138:141], v[200:203], v[70:73]
	v_mfma_f32_16x16x32_bf16 v[66:69], v[154:157], v[200:203], v[66:69]
	v_mfma_f32_16x16x32_bf16 v[134:137], v[150:153], v[166:169], v[134:137]
	v_mfma_f32_16x16x32_bf16 v[130:133], v[158:161], v[166:169], v[130:133]
	v_mfma_f32_16x16x32_bf16 v[118:121], v[150:153], v[184:187], v[118:121]
	v_mfma_f32_16x16x32_bf16 v[114:117], v[158:161], v[184:187], v[114:117]
	v_mfma_f32_16x16x32_bf16 v[102:105], v[150:153], v[196:199], v[102:105]
	v_mfma_f32_16x16x32_bf16 v[98:101], v[158:161], v[196:199], v[98:101]
	v_mfma_f32_16x16x32_bf16 v[70:73], v[150:153], v[204:207], v[70:73]
	v_mfma_f32_16x16x32_bf16 v[66:69], v[158:161], v[204:207], v[66:69]
	s_setprio 1
	s_barrier
	s_mov_b32 m0, s94
	v_lshl_add_u64 v[208:209], s[64:65], 0, v[172:173]
	ds_read_b128 v[162:165], v193 offset:16384
	ds_read_b128 v[166:169], v193 offset:17408
	ds_read_b128 v[180:183], v193 offset:18432
	ds_read_b128 v[184:187], v193 offset:19456
	ds_read_b128 v[188:191], v193 offset:20480
	ds_read_b128 v[196:199], v193 offset:21504
	ds_read_b128 v[200:203], v193 offset:22528
	ds_read_b128 v[204:207], v193 offset:23552
	global_load_lds_dwordx4 v[208:209], off
	v_lshl_add_u64 v[210:211], v[208:209], 0, s[28:29]
	s_mov_b32 m0, s95
	s_nop 0
	global_load_lds_dwordx4 v[210:211], off
	v_lshl_add_u64 v[210:211], v[208:209], 0, s[30:31]
	s_mov_b32 m0, s40
	s_nop 0
	global_load_lds_dwordx4 v[210:211], off
	v_lshl_add_u64 v[210:211], v[208:209], 0, s[34:35]
	s_mov_b32 m0, s41
	s_nop 0
	global_load_lds_dwordx4 v[210:211], off
	v_lshl_add_u64 v[210:211], s[0:1], 0, v[170:171]
	s_mov_b32 m0, s47
	v_lshl_add_u64 v[212:213], v[210:211], 0, s[28:29]
	global_load_lds_dwordx4 v[210:211], off
	s_mov_b32 m0, s52
	s_nop 0
	global_load_lds_dwordx4 v[212:213], off
	s_waitcnt vmcnt(8)
	s_waitcnt lgkmcnt(0)
	s_barrier
	s_waitcnt lgkmcnt(0)
	s_setprio 0
	v_mfma_f32_16x16x32_bf16 v[62:65], v[74:77], v[162:165], v[62:65]
	v_mfma_f32_16x16x32_bf16 v[58:61], v[90:93], v[162:165], v[58:61]
	v_mfma_f32_16x16x32_bf16 v[46:49], v[74:77], v[180:183], v[46:49]
	v_mfma_f32_16x16x32_bf16 v[42:45], v[90:93], v[180:183], v[42:45]
	v_mfma_f32_16x16x32_bf16 v[30:33], v[74:77], v[188:191], v[30:33]
	v_mfma_f32_16x16x32_bf16 v[26:29], v[90:93], v[188:191], v[26:29]
	v_mfma_f32_16x16x32_bf16 v[14:17], v[74:77], v[200:203], v[14:17]
	v_mfma_f32_16x16x32_bf16 v[10:13], v[90:93], v[200:203], v[10:13]
	v_mfma_f32_16x16x32_bf16 v[62:65], v[82:85], v[166:169], v[62:65]
	v_mfma_f32_16x16x32_bf16 v[58:61], v[94:97], v[166:169], v[58:61]
	v_mfma_f32_16x16x32_bf16 v[46:49], v[82:85], v[184:187], v[46:49]
	v_mfma_f32_16x16x32_bf16 v[42:45], v[94:97], v[184:187], v[42:45]
	v_mfma_f32_16x16x32_bf16 v[30:33], v[82:85], v[196:199], v[30:33]
	v_mfma_f32_16x16x32_bf16 v[26:29], v[94:97], v[196:199], v[26:29]
	v_mfma_f32_16x16x32_bf16 v[14:17], v[82:85], v[204:207], v[14:17]
	v_mfma_f32_16x16x32_bf16 v[10:13], v[94:97], v[204:207], v[10:13]
	v_mfma_f32_16x16x32_bf16 v[54:57], v[138:141], v[162:165], v[54:57]
	v_mfma_f32_16x16x32_bf16 v[50:53], v[154:157], v[162:165], v[50:53]
	v_mfma_f32_16x16x32_bf16 v[38:41], v[138:141], v[180:183], v[38:41]
	v_mfma_f32_16x16x32_bf16 v[34:37], v[154:157], v[180:183], v[34:37]
	v_mfma_f32_16x16x32_bf16 v[22:25], v[138:141], v[188:191], v[22:25]
	v_mfma_f32_16x16x32_bf16 v[18:21], v[154:157], v[188:191], v[18:21]
	v_mfma_f32_16x16x32_bf16 v[6:9], v[138:141], v[200:203], v[6:9]
	v_mfma_f32_16x16x32_bf16 v[2:5], v[154:157], v[200:203], v[2:5]
	v_mfma_f32_16x16x32_bf16 v[54:57], v[150:153], v[166:169], v[54:57]
	v_mfma_f32_16x16x32_bf16 v[50:53], v[158:161], v[166:169], v[50:53]
	v_mfma_f32_16x16x32_bf16 v[38:41], v[150:153], v[184:187], v[38:41]
	v_mfma_f32_16x16x32_bf16 v[34:37], v[158:161], v[184:187], v[34:37]
	v_mfma_f32_16x16x32_bf16 v[22:25], v[150:153], v[196:199], v[22:25]
	v_mfma_f32_16x16x32_bf16 v[18:21], v[158:161], v[196:199], v[18:21]
	v_mfma_f32_16x16x32_bf16 v[6:9], v[150:153], v[204:207], v[6:9]
	v_mfma_f32_16x16x32_bf16 v[2:5], v[158:161], v[204:207], v[2:5]
	s_setprio 1
	s_barrier
; #define PG8_WAIT_V(n) asm volatile("s_waitcnt vmcnt(" #n ")" ::: "memory")
; template <class Epi, class Sched, bool ALIGN_EPI = true, bool SP2 = true, bool FULLLINE = false, bool NOSTAGE = false, bool FP8 = false>
; __device__ __forceinline__ void gemm_phase(PG8_LAS unsigned char* lds, const Gemm g, const Sched& S, const Epi& E) {
;     ...
;         static_assert(SP2, "only the SP2 loop is kept");
;         { const int t = 0; if constexpr (Epi::NST == 16) PG8_ITER(PG8_WAIT_V(24)); else if constexpr (Epi::NST == 8) PG8_ITER(PG8_WAIT_V(16)); else PG8_ITER(PG8_WAIT_V(8)); }
;         for (int t = 2; t < nt; t += 2) PG8_ITER(PG8_WAIT_V(8));
	ds_read_b128 v[74:77], v194
	ds_read_b128 v[82:85], v194 offset:1024
	ds_read_b128 v[90:93], v194 offset:2048
	ds_read_b128 v[94:97], v194 offset:3072
	ds_read_b128 v[138:141], v195
	ds_read_b128 v[150:153], v195 offset:1024
	ds_read_b128 v[154:157], v195 offset:2048
	ds_read_b128 v[158:161], v195 offset:3072
	s_mov_b32 m0, s53
	v_lshl_add_u64 v[212:213], v[210:211], 0, s[30:31]
	ds_read_b128 v[162:165], v193 offset:32768
	ds_read_b128 v[166:169], v193 offset:33792
	ds_read_b128 v[180:183], v193 offset:34816
	ds_read_b128 v[184:187], v193 offset:35840
	ds_read_b128 v[188:191], v193 offset:36864
	ds_read_b128 v[196:199], v193 offset:37888
	ds_read_b128 v[200:203], v193 offset:38912
	ds_read_b128 v[204:207], v193 offset:39936
	global_load_lds_dwordx4 v[212:213], off
	v_lshl_add_u64 v[212:213], v[210:211], 0, s[34:35]
	s_mov_b32 m0, s54
	s_nop 0
	global_load_lds_dwordx4 v[212:213], off
	s_waitcnt vmcnt(8)
	s_waitcnt lgkmcnt(0)
	s_barrier
	s_waitcnt lgkmcnt(0)
	s_setprio 0
	v_mfma_f32_16x16x32_bf16 v[146:149], v[74:77], v[162:165], v[146:149]
	v_mfma_f32_16x16x32_bf16 v[142:145], v[90:93], v[162:165], v[142:145]
	v_mfma_f32_16x16x32_bf16 v[126:129], v[74:77], v[180:183], v[126:129]
	v_mfma_f32_16x16x32_bf16 v[122:125], v[90:93], v[180:183], v[122:125]
	v_mfma_f32_16x16x32_bf16 v[110:113], v[74:77], v[188:191], v[110:113]
	v_mfma_f32_16x16x32_bf16 v[106:109], v[90:93], v[188:191], v[106:109]
	v_mfma_f32_16x16x32_bf16 v[86:89], v[74:77], v[200:203], v[86:89]
	v_mfma_f32_16x16x32_bf16 v[78:81], v[90:93], v[200:203], v[78:81]
	v_mfma_f32_16x16x32_bf16 v[146:149], v[82:85], v[166:169], v[146:149]
	v_mfma_f32_16x16x32_bf16 v[142:145], v[94:97], v[166:169], v[142:145]
	v_mfma_f32_16x16x32_bf16 v[126:129], v[82:85], v[184:187], v[126:129]
	v_mfma_f32_16x16x32_bf16 v[122:125], v[94:97], v[184:187], v[122:125]
	v_mfma_f32_16x16x32_bf16 v[110:113], v[82:85], v[196:199], v[110:113]
	v_mfma_f32_16x16x32_bf16 v[106:109], v[94:97], v[196:199], v[106:109]
	v_mfma_f32_16x16x32_bf16 v[86:89], v[82:85], v[204:207], v[86:89]
	v_mfma_f32_16x16x32_bf16 v[78:81], v[94:97], v[204:207], v[78:81]
	v_mfma_f32_16x16x32_bf16 v[134:137], v[138:141], v[162:165], v[134:137]
	v_mfma_f32_16x16x32_bf16 v[130:133], v[154:157], v[162:165], v[130:133]
	v_mfma_f32_16x16x32_bf16 v[118:121], v[138:141], v[180:183], v[118:121]
	v_mfma_f32_16x16x32_bf16 v[114:117], v[154:157], v[180:183], v[114:117]
	v_mfma_f32_16x16x32_bf16 v[102:105], v[138:141], v[188:191], v[102:105]
	v_mfma_f32_16x16x32_bf16 v[98:101], v[154:157], v[188:191], v[98:101]
	v_mfma_f32_16x16x32_bf16 v[70:73], v[138:141], v[200:203], v[70:73]
	v_mfma_f32_16x16x32_bf16 v[66:69], v[154:157], v[200:203], v[66:69]
	v_mfma_f32_16x16x32_bf16 v[134:137], v[150:153], v[166:169], v[134:137]
	v_mfma_f32_16x16x32_bf16 v[130:133], v[158:161], v[166:169], v[130:133]
	v_mfma_f32_16x16x32_bf16 v[118:121], v[150:153], v[184:187], v[118:121]
	v_mfma_f32_16x16x32_bf16 v[114:117], v[158:161], v[184:187], v[114:117]
	v_mfma_f32_16x16x32_bf16 v[102:105], v[150:153], v[196:199], v[102:105]
	v_mfma_f32_16x16x32_bf16 v[98:101], v[158:161], v[196:199], v[98:101]
	v_mfma_f32_16x16x32_bf16 v[70:73], v[150:153], v[204:207], v[70:73]
	v_mfma_f32_16x16x32_bf16 v[66:69], v[158:161], v[204:207], v[66:69]
	s_setprio 1
	s_barrier
	s_mov_b32 m0, s50
	v_lshl_add_u64 v[212:213], v[208:209], 0, s[36:37]
	ds_read_b128 v[162:165], v193 offset:49152
	ds_read_b128 v[166:169], v193 offset:50176
	ds_read_b128 v[180:183], v193 offset:51200
	ds_read_b128 v[184:187], v193 offset:52224
	ds_read_b128 v[188:191], v193 offset:53248
	ds_read_b128 v[196:199], v193 offset:54272
	ds_read_b128 v[200:203], v193 offset:55296
	ds_read_b128 v[204:207], v193 offset:56320
	global_load_lds_dwordx4 v[212:213], off
	v_lshl_add_u64 v[212:213], v[208:209], 0, s[38:39]
	s_mov_b32 m0, s51
	s_nop 0
	global_load_lds_dwordx4 v[212:213], off
	v_lshl_add_u64 v[212:213], v[208:209], 0, s[12:13]
	s_mov_b32 m0, s33
	v_lshl_add_u64 v[208:209], v[208:209], 0, s[14:15]
	global_load_lds_dwordx4 v[212:213], off
	s_mov_b32 m0, s56
	s_nop 0
	global_load_lds_dwordx4 v[208:209], off
	v_lshl_add_u64 v[208:209], v[210:211], 0, s[36:37]
	s_mov_b32 m0, s55
	s_nop 0
	global_load_lds_dwordx4 v[208:209], off
	v_lshl_add_u64 v[208:209], v[210:211], 0, s[38:39]
	s_mov_b32 m0, s62
	s_nop 0
	global_load_lds_dwordx4 v[208:209], off
	s_waitcnt vmcnt(8)
	s_waitcnt lgkmcnt(0)
	s_barrier
	s_waitcnt lgkmcnt(0)
	s_setprio 0
	v_mfma_f32_16x16x32_bf16 v[62:65], v[74:77], v[162:165], v[62:65]
	v_mfma_f32_16x16x32_bf16 v[58:61], v[90:93], v[162:165], v[58:61]
	v_mfma_f32_16x16x32_bf16 v[46:49], v[74:77], v[180:183], v[46:49]
	v_mfma_f32_16x16x32_bf16 v[42:45], v[90:93], v[180:183], v[42:45]
	v_mfma_f32_16x16x32_bf16 v[30:33], v[74:77], v[188:191], v[30:33]
	v_mfma_f32_16x16x32_bf16 v[26:29], v[90:93], v[188:191], v[26:29]
	v_mfma_f32_16x16x32_bf16 v[14:17], v[74:77], v[200:203], v[14:17]
	v_mfma_f32_16x16x32_bf16 v[10:13], v[90:93], v[200:203], v[10:13]
	v_mfma_f32_16x16x32_bf16 v[62:65], v[82:85], v[166:169], v[62:65]
	v_mfma_f32_16x16x32_bf16 v[58:61], v[94:97], v[166:169], v[58:61]
	v_mfma_f32_16x16x32_bf16 v[46:49], v[82:85], v[184:187], v[46:49]
	v_mfma_f32_16x16x32_bf16 v[42:45], v[94:97], v[184:187], v[42:45]
	v_mfma_f32_16x16x32_bf16 v[30:33], v[82:85], v[196:199], v[30:33]
	v_mfma_f32_16x16x32_bf16 v[26:29], v[94:97], v[196:199], v[26:29]
	v_mfma_f32_16x16x32_bf16 v[14:17], v[82:85], v[204:207], v[14:17]
	v_mfma_f32_16x16x32_bf16 v[10:13], v[94:97], v[204:207], v[10:13]
	v_mfma_f32_16x16x32_bf16 v[54:57], v[138:141], v[162:165], v[54:57]
	v_mfma_f32_16x16x32_bf16 v[50:53], v[154:157], v[162:165], v[50:53]
	v_mfma_f32_16x16x32_bf16 v[38:41], v[138:141], v[180:183], v[38:41]
	v_mfma_f32_16x16x32_bf16 v[34:37], v[154:157], v[180:183], v[34:37]
	v_mfma_f32_16x16x32_bf16 v[22:25], v[138:141], v[188:191], v[22:25]
	v_mfma_f32_16x16x32_bf16 v[18:21], v[154:157], v[188:191], v[18:21]
	v_mfma_f32_16x16x32_bf16 v[6:9], v[138:141], v[200:203], v[6:9]
	v_mfma_f32_16x16x32_bf16 v[2:5], v[154:157], v[200:203], v[2:5]
	v_mfma_f32_16x16x32_bf16 v[54:57], v[150:153], v[166:169], v[54:57]
	v_mfma_f32_16x16x32_bf16 v[50:53], v[158:161], v[166:169], v[50:53]
	v_mfma_f32_16x16x32_bf16 v[38:41], v[150:153], v[184:187], v[38:41]
	v_mfma_f32_16x16x32_bf16 v[34:37], v[158:161], v[184:187], v[34:37]
	v_mfma_f32_16x16x32_bf16 v[22:25], v[150:153], v[196:199], v[22:25]
	v_mfma_f32_16x16x32_bf16 v[18:21], v[158:161], v[196:199], v[18:21]
	v_mfma_f32_16x16x32_bf16 v[6:9], v[150:153], v[204:207], v[6:9]
	v_mfma_f32_16x16x32_bf16 v[2:5], v[158:161], v[204:207], v[2:5]
	s_setprio 1
	s_barrier
	s_add_i32 s79, s79, 2
	s_add_u32 s76, s76, 0x100
	s_addc_u32 s77, s77, 0
	s_add_u32 s57, s57, 0x100
	s_addc_u32 s78, s78, 0
	s_cmp_gt_u32 s79, 29
	s_cbranch_scc0 .LBB0_1208
	s_and_b64 vcc, exec, s[10:11]
	s_cbranch_vccz .LBB0_1211
	s_barrier

; template <class Epi, class Sched, bool ALIGN_EPI = true, bool SP2 = true, bool FULLLINE = false, bool NOSTAGE = false, bool FP8 = false>
; __device__ __forceinline__ void gemm_phase(PG8_LAS unsigned char* lds, const Gemm g, const Sched& S, const Epi& E) {
;     ...
;         const bool has_next = S.next(ui + 1, nxt);
;         const char* nA = has_next ? PG8_ABASE(nxt) : cA; const char* nB = has_next ? PG8_BBASE(nxt) : cB;
.LBB0_1380:
	s_ashr_i32 s69, s68, 31
	s_lshl_b64 s[0:1], s[68:69], 20
	s_add_u32 s70, s58, s0
	ds_read_b128 v[2:5], v1
	ds_read_b128 v[6:9], v1 offset:1024
	ds_read_b128 v[10:13], v1 offset:2048
	ds_read_b128 v[14:17], v1 offset:3072
	ds_read_b128 v[18:21], v142
	ds_read_b128 v[22:25], v142 offset:1024
	ds_read_b128 v[26:29], v142 offset:2048
	ds_read_b128 v[30:33], v142 offset:3072
	s_addc_u32 s71, s59, s1
	s_ashr_i32 s67, s66, 31
	s_lshl_b64 s[0:1], s[66:67], 20
	s_add_u32 s72, s3, s0
	s_addc_u32 s73, s42, s1
	s_and_b64 s[0:1], s[8:9], exec
	s_cselect_b32 s67, s71, s79
	s_cselect_b32 s69, s70, s78
	s_cselect_b32 s89, s73, s77
	s_cselect_b32 s90, s72, s76
	v_lshl_add_u64 v[140:141], s[78:79], 0, v[132:133]
	s_mov_b32 m0, s81
	v_lshl_add_u64 v[66:67], v[140:141], 0, s[12:13]
	ds_read_b128 v[34:37], v143
	ds_read_b128 v[38:41], v143 offset:1024
	ds_read_b128 v[42:45], v143 offset:2048
	ds_read_b128 v[46:49], v143 offset:3072
	ds_read_b128 v[50:53], v143 offset:4096
	ds_read_b128 v[54:57], v143 offset:5120
	ds_read_b128 v[58:61], v143 offset:6144
	ds_read_b128 v[62:65], v143 offset:7168
	global_load_lds_dwordx4 v[66:67], off
	v_lshl_add_u64 v[66:67], v[140:141], 0, s[14:15]
	s_mov_b32 m0, s82
	s_nop 0
	global_load_lds_dwordx4 v[66:67], off
	s_waitcnt vmcnt(16)
	s_waitcnt lgkmcnt(0)
	s_barrier
	s_waitcnt lgkmcnt(0)
	s_setprio 0
	v_mfma_f32_16x16x32_bf16 v[86:89], v[10:13], v[50:53], 0
	v_mfma_f32_16x16x32_bf16 v[90:93], v[14:17], v[54:57], v[86:89]
	v_mfma_f32_16x16x32_bf16 v[86:89], v[2:5], v[58:61], 0
	v_mfma_f32_16x16x32_bf16 v[66:69], v[2:5], v[34:37], 0
	v_mfma_f32_16x16x32_bf16 v[70:73], v[10:13], v[34:37], 0
	v_mfma_f32_16x16x32_bf16 v[74:77], v[2:5], v[42:45], 0
	v_mfma_f32_16x16x32_bf16 v[78:81], v[10:13], v[42:45], 0
	v_mfma_f32_16x16x32_bf16 v[82:85], v[2:5], v[50:53], 0
	v_mfma_f32_16x16x32_bf16 v[94:97], v[6:9], v[62:65], v[86:89]
	v_mfma_f32_16x16x32_bf16 v[86:89], v[10:13], v[58:61], 0
	v_mfma_f32_16x16x32_bf16 v[66:69], v[6:9], v[38:41], v[66:69]
	v_mfma_f32_16x16x32_bf16 v[70:73], v[14:17], v[38:41], v[70:73]
	v_mfma_f32_16x16x32_bf16 v[74:77], v[6:9], v[46:49], v[74:77]
	v_mfma_f32_16x16x32_bf16 v[78:81], v[14:17], v[46:49], v[78:81]
	v_mfma_f32_16x16x32_bf16 v[82:85], v[6:9], v[54:57], v[82:85]
	v_mfma_f32_16x16x32_bf16 v[106:109], v[14:17], v[62:65], v[86:89]
	v_mfma_f32_16x16x32_bf16 v[86:89], v[18:21], v[34:37], 0
	v_mfma_f32_16x16x32_bf16 v[34:37], v[26:29], v[34:37], 0
	v_mfma_f32_16x16x32_bf16 v[110:113], v[22:25], v[38:41], v[86:89]
	v_mfma_f32_16x16x32_bf16 v[34:37], v[30:33], v[38:41], v[34:37]
	v_mfma_f32_16x16x32_bf16 v[38:41], v[18:21], v[42:45], 0
	v_mfma_f32_16x16x32_bf16 v[42:45], v[26:29], v[42:45], 0
	v_mfma_f32_16x16x32_bf16 v[38:41], v[22:25], v[46:49], v[38:41]
	v_mfma_f32_16x16x32_bf16 v[42:45], v[30:33], v[46:49], v[42:45]
	v_mfma_f32_16x16x32_bf16 v[46:49], v[18:21], v[50:53], 0
	v_mfma_f32_16x16x32_bf16 v[50:53], v[26:29], v[50:53], 0
	v_mfma_f32_16x16x32_bf16 v[46:49], v[22:25], v[54:57], v[46:49]
	v_mfma_f32_16x16x32_bf16 v[50:53], v[30:33], v[54:57], v[50:53]
	v_mfma_f32_16x16x32_bf16 v[54:57], v[18:21], v[58:61], 0
	v_mfma_f32_16x16x32_bf16 v[58:61], v[26:29], v[58:61], 0
	v_mfma_f32_16x16x32_bf16 v[54:57], v[22:25], v[62:65], v[54:57]
	v_mfma_f32_16x16x32_bf16 v[58:61], v[30:33], v[62:65], v[58:61]
	s_setprio 1
	s_barrier
	v_lshl_add_u64 v[238:239], s[76:77], 0, v[130:131]
	s_mov_b32 m0, s83
	v_lshl_add_u64 v[146:147], v[238:239], 0, s[16:17]
	s_add_i32 s91, s83, 0x2000
	ds_read_b128 v[62:65], v143 offset:16384
	ds_read_b128 v[86:89], v143 offset:17408
	ds_read_b128 v[98:101], v143 offset:18432
	ds_read_b128 v[102:105], v143 offset:19456
	ds_read_b128 v[114:117], v143 offset:20480
	ds_read_b128 v[118:121], v143 offset:21504
	ds_read_b128 v[122:125], v143 offset:22528
	ds_read_b128 v[126:129], v143 offset:23552
	global_load_lds_dwordx4 v[146:147], off
	v_lshl_add_u64 v[146:147], v[238:239], 0, s[18:19]
	s_mov_b32 m0, s91
	s_add_i32 s40, s80, s43
	global_load_lds_dwordx4 v[146:147], off
	v_lshl_add_u64 v[146:147], v[238:239], 0, s[20:21]
	s_mov_b32 m0, s40
	s_add_i32 s41, s40, 0x2000
	global_load_lds_dwordx4 v[146:147], off
	v_lshl_add_u64 v[146:147], v[238:239], 0, s[22:23]
	s_mov_b32 m0, s41
	s_nop 0
	global_load_lds_dwordx4 v[146:147], off
	v_lshl_add_u64 v[146:147], v[140:141], 0, s[16:17]
	s_mov_b32 m0, s45
	s_nop 0
	global_load_lds_dwordx4 v[146:147], off
	v_lshl_add_u64 v[146:147], v[140:141], 0, s[18:19]
	s_mov_b32 m0, s46
	s_nop 0
	global_load_lds_dwordx4 v[146:147], off
	s_waitcnt vmcnt(16)
	s_waitcnt lgkmcnt(0)
	s_barrier
	s_waitcnt lgkmcnt(0)
	s_setprio 0
	v_mfma_f32_16x16x32_bf16 v[146:149], v[2:5], v[62:65], 0
	v_mfma_f32_16x16x32_bf16 v[154:157], v[2:5], v[98:101], 0
	v_mfma_f32_16x16x32_bf16 v[162:165], v[2:5], v[114:117], 0
	v_mfma_f32_16x16x32_bf16 v[2:5], v[2:5], v[122:125], 0
	v_mfma_f32_16x16x32_bf16 v[146:149], v[6:9], v[86:89], v[146:149]
	v_mfma_f32_16x16x32_bf16 v[154:157], v[6:9], v[102:105], v[154:157]
	v_mfma_f32_16x16x32_bf16 v[162:165], v[6:9], v[118:121], v[162:165]
	v_mfma_f32_16x16x32_bf16 v[2:5], v[6:9], v[126:129], v[2:5]
	v_mfma_f32_16x16x32_bf16 v[6:9], v[10:13], v[122:125], 0
	v_mfma_f32_16x16x32_bf16 v[150:153], v[10:13], v[62:65], 0
	v_mfma_f32_16x16x32_bf16 v[158:161], v[10:13], v[98:101], 0
	v_mfma_f32_16x16x32_bf16 v[166:169], v[10:13], v[114:117], 0
	v_mfma_f32_16x16x32_bf16 v[10:13], v[14:17], v[126:129], v[6:9]
	v_mfma_f32_16x16x32_bf16 v[150:153], v[14:17], v[86:89], v[150:153]
	v_mfma_f32_16x16x32_bf16 v[158:161], v[14:17], v[102:105], v[158:161]
	v_mfma_f32_16x16x32_bf16 v[166:169], v[14:17], v[118:121], v[166:169]
	v_mfma_f32_16x16x32_bf16 v[6:9], v[18:21], v[62:65], 0
	v_mfma_f32_16x16x32_bf16 v[14:17], v[22:25], v[86:89], v[6:9]
	v_mfma_f32_16x16x32_bf16 v[6:9], v[26:29], v[62:65], 0
	v_mfma_f32_16x16x32_bf16 v[170:173], v[30:33], v[86:89], v[6:9]
	v_mfma_f32_16x16x32_bf16 v[6:9], v[18:21], v[98:101], 0
	v_mfma_f32_16x16x32_bf16 v[174:177], v[22:25], v[102:105], v[6:9]
	v_mfma_f32_16x16x32_bf16 v[6:9], v[26:29], v[98:101], 0
	v_mfma_f32_16x16x32_bf16 v[178:181], v[30:33], v[102:105], v[6:9]
	v_mfma_f32_16x16x32_bf16 v[6:9], v[18:21], v[114:117], 0
	v_mfma_f32_16x16x32_bf16 v[182:185], v[22:25], v[118:121], v[6:9]
	v_mfma_f32_16x16x32_bf16 v[6:9], v[26:29], v[114:117], 0
	v_mfma_f32_16x16x32_bf16 v[186:189], v[30:33], v[118:121], v[6:9]
	v_mfma_f32_16x16x32_bf16 v[6:9], v[18:21], v[122:125], 0
	v_mfma_f32_16x16x32_bf16 v[190:193], v[22:25], v[126:129], v[6:9]
	v_mfma_f32_16x16x32_bf16 v[6:9], v[26:29], v[122:125], 0
	v_mfma_f32_16x16x32_bf16 v[194:197], v[30:33], v[126:129], v[6:9]
	s_setprio 1
	s_barrier
	s_nop 5
	ds_read_b128 v[6:9], v144
	ds_read_b128 v[26:29], v144 offset:1024
	ds_read_b128 v[30:33], v144 offset:2048
	ds_read_b128 v[62:65], v144 offset:3072
	ds_read_b128 v[198:201], v145
	ds_read_b128 v[202:205], v145 offset:1024
	ds_read_b128 v[206:209], v145 offset:2048
	ds_read_b128 v[210:213], v145 offset:3072
	s_mov_b32 m0, s47
	v_lshl_add_u64 v[86:87], v[140:141], 0, s[20:21]
	ds_read_b128 v[18:21], v143 offset:32768
	ds_read_b128 v[22:25], v143 offset:33792
	ds_read_b128 v[214:217], v143 offset:34816
	ds_read_b128 v[218:221], v143 offset:35840
	ds_read_b128 v[222:225], v143 offset:36864
	ds_read_b128 v[226:229], v143 offset:37888
	ds_read_b128 v[230:233], v143 offset:38912
	ds_read_b128 v[234:237], v143 offset:39936
	global_load_lds_dwordx4 v[86:87], off
	v_lshl_add_u64 v[86:87], v[140:141], 0, s[22:23]
	s_mov_b32 m0, s52
	s_nop 0
	global_load_lds_dwordx4 v[86:87], off
	s_waitcnt vmcnt(8)
	s_waitcnt lgkmcnt(0)
	s_barrier
	s_waitcnt lgkmcnt(0)
	s_setprio 0
	v_mfma_f32_16x16x32_bf16 v[66:69], v[6:9], v[18:21], v[66:69]
	v_mfma_f32_16x16x32_bf16 v[118:121], v[26:29], v[22:25], v[66:69]
	v_mfma_f32_16x16x32_bf16 v[66:69], v[30:33], v[18:21], v[70:73]
	v_mfma_f32_16x16x32_bf16 v[114:117], v[62:65], v[22:25], v[66:69]
	v_mfma_f32_16x16x32_bf16 v[66:69], v[6:9], v[214:217], v[74:77]
	v_mfma_f32_16x16x32_bf16 v[102:105], v[26:29], v[218:221], v[66:69]
	v_mfma_f32_16x16x32_bf16 v[66:69], v[30:33], v[214:217], v[78:81]
	v_mfma_f32_16x16x32_bf16 v[98:101], v[62:65], v[218:221], v[66:69]
	v_mfma_f32_16x16x32_bf16 v[66:69], v[6:9], v[222:225], v[82:85]
	v_mfma_f32_16x16x32_bf16 v[86:89], v[26:29], v[226:229], v[66:69]
	v_mfma_f32_16x16x32_bf16 v[66:69], v[30:33], v[222:225], v[90:93]
	v_mfma_f32_16x16x32_bf16 v[82:85], v[62:65], v[226:229], v[66:69]
	v_mfma_f32_16x16x32_bf16 v[66:69], v[6:9], v[230:233], v[94:97]
	v_mfma_f32_16x16x32_bf16 v[70:73], v[26:29], v[234:237], v[66:69]
	v_mfma_f32_16x16x32_bf16 v[66:69], v[30:33], v[230:233], v[106:109]
	v_mfma_f32_16x16x32_bf16 v[66:69], v[62:65], v[234:237], v[66:69]
	v_mfma_f32_16x16x32_bf16 v[74:77], v[198:201], v[18:21], v[110:113]
	v_mfma_f32_16x16x32_bf16 v[18:21], v[206:209], v[18:21], v[34:37]
	v_mfma_f32_16x16x32_bf16 v[122:125], v[210:213], v[22:25], v[18:21]
	v_mfma_f32_16x16x32_bf16 v[18:21], v[198:201], v[214:217], v[38:41]
	v_mfma_f32_16x16x32_bf16 v[110:113], v[202:205], v[218:221], v[18:21]
	v_mfma_f32_16x16x32_bf16 v[18:21], v[206:209], v[214:217], v[42:45]
	v_mfma_f32_16x16x32_bf16 v[106:109], v[210:213], v[218:221], v[18:21]
	v_mfma_f32_16x16x32_bf16 v[18:21], v[198:201], v[222:225], v[46:49]
	v_mfma_f32_16x16x32_bf16 v[94:97], v[202:205], v[226:229], v[18:21]
	v_mfma_f32_16x16x32_bf16 v[18:21], v[206:209], v[222:225], v[50:53]
	v_mfma_f32_16x16x32_bf16 v[90:93], v[210:213], v[226:229], v[18:21]
	v_mfma_f32_16x16x32_bf16 v[18:21], v[198:201], v[230:233], v[54:57]
	v_mfma_f32_16x16x32_bf16 v[78:81], v[202:205], v[234:237], v[18:21]
	v_mfma_f32_16x16x32_bf16 v[18:21], v[206:209], v[230:233], v[58:61]
	v_mfma_f32_16x16x32_bf16 v[126:129], v[202:205], v[22:25], v[74:77]
	v_mfma_f32_16x16x32_bf16 v[74:77], v[210:213], v[234:237], v[18:21]
	s_setprio 1
	s_barrier
	s_add_i32 s50, s84, s43
	s_nop 3
	v_lshl_add_u64 v[18:19], v[238:239], 0, s[24:25]
	s_mov_b32 m0, s50
	s_add_i32 s51, s50, 0x2000
	ds_read_b128 v[42:45], v143 offset:49152
	ds_read_b128 v[46:49], v143 offset:50176
	ds_read_b128 v[214:217], v143 offset:51200
	ds_read_b128 v[218:221], v143 offset:52224
	ds_read_b128 v[222:225], v143 offset:53248
	ds_read_b128 v[226:229], v143 offset:54272
	ds_read_b128 v[230:233], v143 offset:55296
	ds_read_b128 v[234:237], v143 offset:56320
	global_load_lds_dwordx4 v[18:19], off
	v_lshl_add_u64 v[18:19], v[238:239], 0, s[26:27]
	s_mov_b32 m0, s51
	s_mov_b64 s[0:1], 0x80180
	s_add_i32 s33, s85, s43
	global_load_lds_dwordx4 v[18:19], off
	v_lshl_add_u64 v[18:19], v[238:239], 0, s[0:1]
	s_mov_b32 m0, s33
	s_mov_b64 s[0:1], 0xc0180
	s_add_i32 s56, s33, 0x2000
	global_load_lds_dwordx4 v[18:19], off
	v_lshl_add_u64 v[18:19], v[238:239], 0, s[0:1]
	s_mov_b32 m0, s56
	s_nop 0
	global_load_lds_dwordx4 v[18:19], off
	v_lshl_add_u64 v[18:19], v[140:141], 0, s[24:25]
	s_mov_b32 m0, s53
	s_nop 0
	global_load_lds_dwordx4 v[18:19], off
	v_lshl_add_u64 v[18:19], v[140:141], 0, s[26:27]
	s_mov_b32 m0, s54
	s_nop 0
	global_load_lds_dwordx4 v[18:19], off
	s_waitcnt vmcnt(8)
	s_waitcnt lgkmcnt(0)
	s_barrier
	s_waitcnt lgkmcnt(0)
	s_setprio 0
	v_mfma_f32_16x16x32_bf16 v[18:21], v[6:9], v[42:45], v[146:149]
	v_mfma_f32_16x16x32_bf16 v[54:57], v[26:29], v[46:49], v[18:21]
	v_mfma_f32_16x16x32_bf16 v[18:21], v[30:33], v[42:45], v[150:153]
	v_mfma_f32_16x16x32_bf16 v[50:53], v[62:65], v[46:49], v[18:21]
	v_mfma_f32_16x16x32_bf16 v[18:21], v[6:9], v[214:217], v[154:157]
	v_mfma_f32_16x16x32_bf16 v[38:41], v[26:29], v[218:221], v[18:21]
	v_mfma_f32_16x16x32_bf16 v[18:21], v[30:33], v[214:217], v[158:161]
	v_mfma_f32_16x16x32_bf16 v[34:37], v[62:65], v[218:221], v[18:21]
	v_mfma_f32_16x16x32_bf16 v[18:21], v[6:9], v[222:225], v[162:165]
	v_mfma_f32_16x16x32_bf16 v[2:5], v[6:9], v[230:233], v[2:5]
	v_mfma_f32_16x16x32_bf16 v[22:25], v[26:29], v[226:229], v[18:21]
	v_mfma_f32_16x16x32_bf16 v[18:21], v[30:33], v[222:225], v[166:169]
	v_mfma_f32_16x16x32_bf16 v[6:9], v[26:29], v[234:237], v[2:5]
	v_mfma_f32_16x16x32_bf16 v[2:5], v[30:33], v[230:233], v[10:13]
	v_mfma_f32_16x16x32_bf16 v[18:21], v[62:65], v[226:229], v[18:21]
	v_mfma_f32_16x16x32_bf16 v[2:5], v[62:65], v[234:237], v[2:5]
	v_mfma_f32_16x16x32_bf16 v[10:13], v[198:201], v[42:45], v[14:17]
	v_mfma_f32_16x16x32_bf16 v[62:65], v[202:205], v[46:49], v[10:13]
	v_mfma_f32_16x16x32_bf16 v[10:13], v[206:209], v[42:45], v[170:173]
	v_mfma_f32_16x16x32_bf16 v[58:61], v[210:213], v[46:49], v[10:13]
	v_mfma_f32_16x16x32_bf16 v[10:13], v[198:201], v[214:217], v[174:177]
	v_mfma_f32_16x16x32_bf16 v[46:49], v[202:205], v[218:221], v[10:13]
	v_mfma_f32_16x16x32_bf16 v[10:13], v[206:209], v[214:217], v[178:181]
	v_mfma_f32_16x16x32_bf16 v[42:45], v[210:213], v[218:221], v[10:13]
	v_mfma_f32_16x16x32_bf16 v[10:13], v[198:201], v[222:225], v[182:185]
	v_mfma_f32_16x16x32_bf16 v[30:33], v[202:205], v[226:229], v[10:13]
	v_mfma_f32_16x16x32_bf16 v[10:13], v[206:209], v[222:225], v[186:189]
	v_mfma_f32_16x16x32_bf16 v[26:29], v[210:213], v[226:229], v[10:13]
	v_mfma_f32_16x16x32_bf16 v[10:13], v[198:201], v[230:233], v[190:193]
	v_mfma_f32_16x16x32_bf16 v[14:17], v[202:205], v[234:237], v[10:13]
	v_mfma_f32_16x16x32_bf16 v[10:13], v[206:209], v[230:233], v[194:197]
	v_mfma_f32_16x16x32_bf16 v[10:13], v[210:213], v[234:237], v[10:13]
	s_setprio 1
	s_barrier
	s_add_u32 s78, s78, 0x80180
	s_addc_u32 s79, s79, 0
	s_add_u32 s57, s76, 0x200
	s_addc_u32 s76, s77, 0
	s_mov_b32 s77, 0
.LBB0_1381:
	ds_read_b128 v[146:149], v1
	ds_read_b128 v[150:153], v1 offset:1024
	ds_read_b128 v[154:157], v1 offset:2048
	ds_read_b128 v[158:161], v1 offset:3072
	ds_read_b128 v[162:165], v142
	ds_read_b128 v[166:169], v142 offset:1024
	ds_read_b128 v[170:173], v142 offset:2048
	ds_read_b128 v[174:177], v142 offset:3072
	s_add_u32 s0, s78, 0xfff80080
	s_addc_u32 s1, s79, -1
	s_cmp_eq_u32 s77, 28
	s_cselect_b32 s1, s67, s1
	s_cselect_b32 s0, s69, s0
	s_cselect_b32 s65, s89, s76
	s_cselect_b32 s64, s90, s57
	s_mov_b32 m0, s81
	v_lshl_add_u64 v[140:141], s[78:79], 0, v[134:135]
	ds_read_b128 v[178:181], v143
	ds_read_b128 v[182:185], v143 offset:1024
	ds_read_b128 v[186:189], v143 offset:2048
	ds_read_b128 v[190:193], v143 offset:3072
	ds_read_b128 v[194:197], v143 offset:4096
	ds_read_b128 v[198:201], v143 offset:5120
	ds_read_b128 v[202:205], v143 offset:6144
	ds_read_b128 v[206:209], v143 offset:7168
	global_load_lds_dwordx4 v[140:141], off
	v_lshl_add_u64 v[140:141], v[140:141], 0, s[28:29]
	s_mov_b32 m0, s82
	s_nop 0
	global_load_lds_dwordx4 v[140:141], off
	s_waitcnt vmcnt(8)
	s_waitcnt lgkmcnt(0)
	s_barrier
	s_waitcnt lgkmcnt(0)
	s_setprio 0
	v_mfma_f32_16x16x32_bf16 v[118:121], v[146:149], v[178:181], v[118:121]
	v_mfma_f32_16x16x32_bf16 v[114:117], v[154:157], v[178:181], v[114:117]
	v_mfma_f32_16x16x32_bf16 v[102:105], v[146:149], v[186:189], v[102:105]
	v_mfma_f32_16x16x32_bf16 v[98:101], v[154:157], v[186:189], v[98:101]
	v_mfma_f32_16x16x32_bf16 v[86:89], v[146:149], v[194:197], v[86:89]
	v_mfma_f32_16x16x32_bf16 v[82:85], v[154:157], v[194:197], v[82:85]
	v_mfma_f32_16x16x32_bf16 v[70:73], v[146:149], v[202:205], v[70:73]
	v_mfma_f32_16x16x32_bf16 v[66:69], v[154:157], v[202:205], v[66:69]
	v_mfma_f32_16x16x32_bf16 v[118:121], v[150:153], v[182:185], v[118:121]
	v_mfma_f32_16x16x32_bf16 v[114:117], v[158:161], v[182:185], v[114:117]
	v_mfma_f32_16x16x32_bf16 v[102:105], v[150:153], v[190:193], v[102:105]
	v_mfma_f32_16x16x32_bf16 v[98:101], v[158:161], v[190:193], v[98:101]
	v_mfma_f32_16x16x32_bf16 v[86:89], v[150:153], v[198:201], v[86:89]
	v_mfma_f32_16x16x32_bf16 v[82:85], v[158:161], v[198:201], v[82:85]
	v_mfma_f32_16x16x32_bf16 v[70:73], v[150:153], v[206:209], v[70:73]
	v_mfma_f32_16x16x32_bf16 v[66:69], v[158:161], v[206:209], v[66:69]
	v_mfma_f32_16x16x32_bf16 v[126:129], v[162:165], v[178:181], v[126:129]
	v_mfma_f32_16x16x32_bf16 v[122:125], v[170:173], v[178:181], v[122:125]
	v_mfma_f32_16x16x32_bf16 v[110:113], v[162:165], v[186:189], v[110:113]
	v_mfma_f32_16x16x32_bf16 v[106:109], v[170:173], v[186:189], v[106:109]
	v_mfma_f32_16x16x32_bf16 v[94:97], v[162:165], v[194:197], v[94:97]
	v_mfma_f32_16x16x32_bf16 v[90:93], v[170:173], v[194:197], v[90:93]
	v_mfma_f32_16x16x32_bf16 v[78:81], v[162:165], v[202:205], v[78:81]
	v_mfma_f32_16x16x32_bf16 v[74:77], v[170:173], v[202:205], v[74:77]
	v_mfma_f32_16x16x32_bf16 v[126:129], v[166:169], v[182:185], v[126:129]
	v_mfma_f32_16x16x32_bf16 v[122:125], v[174:177], v[182:185], v[122:125]
	v_mfma_f32_16x16x32_bf16 v[110:113], v[166:169], v[190:193], v[110:113]
	v_mfma_f32_16x16x32_bf16 v[106:109], v[174:177], v[190:193], v[106:109]
	v_mfma_f32_16x16x32_bf16 v[94:97], v[166:169], v[198:201], v[94:97]
	v_mfma_f32_16x16x32_bf16 v[90:93], v[174:177], v[198:201], v[90:93]
	v_mfma_f32_16x16x32_bf16 v[78:81], v[166:169], v[206:209], v[78:81]
	v_mfma_f32_16x16x32_bf16 v[74:77], v[174:177], v[206:209], v[74:77]
	s_setprio 1
	s_barrier
	s_mov_b32 m0, s83
	v_lshl_add_u64 v[140:141], s[64:65], 0, v[130:131]
	ds_read_b128 v[178:181], v143 offset:16384
	ds_read_b128 v[182:185], v143 offset:17408
	ds_read_b128 v[186:189], v143 offset:18432
	ds_read_b128 v[190:193], v143 offset:19456
	ds_read_b128 v[194:197], v143 offset:20480
	ds_read_b128 v[198:201], v143 offset:21504
	ds_read_b128 v[202:205], v143 offset:22528
	ds_read_b128 v[206:209], v143 offset:23552
	global_load_lds_dwordx4 v[140:141], off
	v_lshl_add_u64 v[210:211], v[140:141], 0, s[28:29]
	s_mov_b32 m0, s91
	s_nop 0
	global_load_lds_dwordx4 v[210:211], off
	v_lshl_add_u64 v[210:211], v[140:141], 0, s[30:31]
	s_mov_b32 m0, s40
	s_nop 0
	global_load_lds_dwordx4 v[210:211], off
	v_lshl_add_u64 v[210:211], v[140:141], 0, s[34:35]
	s_mov_b32 m0, s41
	s_nop 0
	global_load_lds_dwordx4 v[210:211], off
	v_lshl_add_u64 v[210:211], s[0:1], 0, v[132:133]
	s_mov_b32 m0, s45
	v_lshl_add_u64 v[212:213], v[210:211], 0, s[28:29]
	global_load_lds_dwordx4 v[210:211], off
	s_mov_b32 m0, s46
	s_nop 0
	global_load_lds_dwordx4 v[212:213], off
	s_waitcnt vmcnt(8)
	s_waitcnt lgkmcnt(0)
	s_barrier
	s_waitcnt lgkmcnt(0)
	s_setprio 0
	v_mfma_f32_16x16x32_bf16 v[54:57], v[146:149], v[178:181], v[54:57]
	v_mfma_f32_16x16x32_bf16 v[50:53], v[154:157], v[178:181], v[50:53]
	v_mfma_f32_16x16x32_bf16 v[38:41], v[146:149], v[186:189], v[38:41]
	v_mfma_f32_16x16x32_bf16 v[34:37], v[154:157], v[186:189], v[34:37]
	v_mfma_f32_16x16x32_bf16 v[22:25], v[146:149], v[194:197], v[22:25]
	v_mfma_f32_16x16x32_bf16 v[18:21], v[154:157], v[194:197], v[18:21]
	v_mfma_f32_16x16x32_bf16 v[6:9], v[146:149], v[202:205], v[6:9]
	v_mfma_f32_16x16x32_bf16 v[2:5], v[154:157], v[202:205], v[2:5]
	v_mfma_f32_16x16x32_bf16 v[54:57], v[150:153], v[182:185], v[54:57]
	v_mfma_f32_16x16x32_bf16 v[50:53], v[158:161], v[182:185], v[50:53]
	v_mfma_f32_16x16x32_bf16 v[38:41], v[150:153], v[190:193], v[38:41]
	v_mfma_f32_16x16x32_bf16 v[34:37], v[158:161], v[190:193], v[34:37]
	v_mfma_f32_16x16x32_bf16 v[22:25], v[150:153], v[198:201], v[22:25]
	v_mfma_f32_16x16x32_bf16 v[18:21], v[158:161], v[198:201], v[18:21]
	v_mfma_f32_16x16x32_bf16 v[6:9], v[150:153], v[206:209], v[6:9]
	v_mfma_f32_16x16x32_bf16 v[2:5], v[158:161], v[206:209], v[2:5]
	v_mfma_f32_16x16x32_bf16 v[62:65], v[162:165], v[178:181], v[62:65]
	v_mfma_f32_16x16x32_bf16 v[58:61], v[170:173], v[178:181], v[58:61]
	v_mfma_f32_16x16x32_bf16 v[46:49], v[162:165], v[186:189], v[46:49]
	v_mfma_f32_16x16x32_bf16 v[42:45], v[170:173], v[186:189], v[42:45]
	v_mfma_f32_16x16x32_bf16 v[30:33], v[162:165], v[194:197], v[30:33]
	v_mfma_f32_16x16x32_bf16 v[26:29], v[170:173], v[194:197], v[26:29]
	v_mfma_f32_16x16x32_bf16 v[14:17], v[162:165], v[202:205], v[14:17]
	v_mfma_f32_16x16x32_bf16 v[10:13], v[170:173], v[202:205], v[10:13]
	v_mfma_f32_16x16x32_bf16 v[62:65], v[166:169], v[182:185], v[62:65]
	v_mfma_f32_16x16x32_bf16 v[58:61], v[174:177], v[182:185], v[58:61]
	v_mfma_f32_16x16x32_bf16 v[46:49], v[166:169], v[190:193], v[46:49]
	v_mfma_f32_16x16x32_bf16 v[42:45], v[174:177], v[190:193], v[42:45]
	v_mfma_f32_16x16x32_bf16 v[30:33], v[166:169], v[198:201], v[30:33]
	v_mfma_f32_16x16x32_bf16 v[26:29], v[174:177], v[198:201], v[26:29]
	v_mfma_f32_16x16x32_bf16 v[14:17], v[166:169], v[206:209], v[14:17]
	v_mfma_f32_16x16x32_bf16 v[10:13], v[174:177], v[206:209], v[10:13]
	s_setprio 1
	s_barrier
	ds_read_b128 v[146:149], v144
	ds_read_b128 v[150:153], v144 offset:1024
	ds_read_b128 v[154:157], v144 offset:2048
	ds_read_b128 v[158:161], v144 offset:3072
	ds_read_b128 v[162:165], v145
	ds_read_b128 v[166:169], v145 offset:1024
	ds_read_b128 v[170:173], v145 offset:2048
	ds_read_b128 v[174:177], v145 offset:3072
	s_mov_b32 m0, s47
	v_lshl_add_u64 v[212:213], v[210:211], 0, s[30:31]
	ds_read_b128 v[178:181], v143 offset:32768
	ds_read_b128 v[182:185], v143 offset:33792
	ds_read_b128 v[186:189], v143 offset:34816
	ds_read_b128 v[190:193], v143 offset:35840
	ds_read_b128 v[194:197], v143 offset:36864
	ds_read_b128 v[198:201], v143 offset:37888
	ds_read_b128 v[202:205], v143 offset:38912
	ds_read_b128 v[206:209], v143 offset:39936
	global_load_lds_dwordx4 v[212:213], off
	v_lshl_add_u64 v[212:213], v[210:211], 0, s[34:35]
	s_mov_b32 m0, s52
	s_nop 0
	global_load_lds_dwordx4 v[212:213], off
	s_waitcnt vmcnt(8)
	s_waitcnt lgkmcnt(0)
	s_barrier
	s_waitcnt lgkmcnt(0)
	s_setprio 0
	v_mfma_f32_16x16x32_bf16 v[118:121], v[146:149], v[178:181], v[118:121]
	v_mfma_f32_16x16x32_bf16 v[114:117], v[154:157], v[178:181], v[114:117]
	v_mfma_f32_16x16x32_bf16 v[102:105], v[146:149], v[186:189], v[102:105]
	v_mfma_f32_16x16x32_bf16 v[98:101], v[154:157], v[186:189], v[98:101]
	v_mfma_f32_16x16x32_bf16 v[86:89], v[146:149], v[194:197], v[86:89]
	v_mfma_f32_16x16x32_bf16 v[82:85], v[154:157], v[194:197], v[82:85]
	v_mfma_f32_16x16x32_bf16 v[70:73], v[146:149], v[202:205], v[70:73]
	v_mfma_f32_16x16x32_bf16 v[66:69], v[154:157], v[202:205], v[66:69]
	v_mfma_f32_16x16x32_bf16 v[118:121], v[150:153], v[182:185], v[118:121]
	v_mfma_f32_16x16x32_bf16 v[114:117], v[158:161], v[182:185], v[114:117]
	v_mfma_f32_16x16x32_bf16 v[102:105], v[150:153], v[190:193], v[102:105]
	v_mfma_f32_16x16x32_bf16 v[98:101], v[158:161], v[190:193], v[98:101]
	v_mfma_f32_16x16x32_bf16 v[86:89], v[150:153], v[198:201], v[86:89]
	v_mfma_f32_16x16x32_bf16 v[82:85], v[158:161], v[198:201], v[82:85]
	v_mfma_f32_16x16x32_bf16 v[70:73], v[150:153], v[206:209], v[70:73]
	v_mfma_f32_16x16x32_bf16 v[66:69], v[158:161], v[206:209], v[66:69]
	v_mfma_f32_16x16x32_bf16 v[126:129], v[162:165], v[178:181], v[126:129]
	v_mfma_f32_16x16x32_bf16 v[122:125], v[170:173], v[178:181], v[122:125]
	v_mfma_f32_16x16x32_bf16 v[110:113], v[162:165], v[186:189], v[110:113]
	v_mfma_f32_16x16x32_bf16 v[106:109], v[170:173], v[186:189], v[106:109]
	v_mfma_f32_16x16x32_bf16 v[94:97], v[162:165], v[194:197], v[94:97]
	v_mfma_f32_16x16x32_bf16 v[90:93], v[170:173], v[194:197], v[90:93]
	v_mfma_f32_16x16x32_bf16 v[78:81], v[162:165], v[202:205], v[78:81]
	v_mfma_f32_16x16x32_bf16 v[74:77], v[170:173], v[202:205], v[74:77]
	v_mfma_f32_16x16x32_bf16 v[126:129], v[166:169], v[182:185], v[126:129]
	v_mfma_f32_16x16x32_bf16 v[122:125], v[174:177], v[182:185], v[122:125]
	v_mfma_f32_16x16x32_bf16 v[110:113], v[166:169], v[190:193], v[110:113]
	v_mfma_f32_16x16x32_bf16 v[106:109], v[174:177], v[190:193], v[106:109]
	v_mfma_f32_16x16x32_bf16 v[94:97], v[166:169], v[198:201], v[94:97]
	v_mfma_f32_16x16x32_bf16 v[90:93], v[174:177], v[198:201], v[90:93]
	v_mfma_f32_16x16x32_bf16 v[78:81], v[166:169], v[206:209], v[78:81]
	v_mfma_f32_16x16x32_bf16 v[74:77], v[174:177], v[206:209], v[74:77]
	s_setprio 1
	s_barrier
; #define PG8_WAIT_V(n) asm volatile("s_waitcnt vmcnt(" #n ")" ::: "memory")
; template <class Epi, class Sched, bool ALIGN_EPI = true, bool SP2 = true, bool FULLLINE = false, bool NOSTAGE = false, bool FP8 = false>
; __device__ __forceinline__ void gemm_phase(PG8_LAS unsigned char* lds, const Gemm g, const Sched& S, const Epi& E) {
;     ...
;         static_assert(SP2, "only the SP2 loop is kept");
;         { const int t = 0; if constexpr (Epi::NST == 16) PG8_ITER(PG8_WAIT_V(24)); else if constexpr (Epi::NST == 8) PG8_ITER(PG8_WAIT_V(16)); else PG8_ITER(PG8_WAIT_V(8)); }
;         for (int t = 2; t < nt; t += 2) PG8_ITER(PG8_WAIT_V(8));
	s_mov_b32 m0, s50
	v_lshl_add_u64 v[212:213], v[140:141], 0, s[36:37]
	ds_read_b128 v[178:181], v143 offset:49152
	ds_read_b128 v[182:185], v143 offset:50176
	ds_read_b128 v[186:189], v143 offset:51200
	ds_read_b128 v[190:193], v143 offset:52224
	ds_read_b128 v[194:197], v143 offset:53248
	ds_read_b128 v[198:201], v143 offset:54272
	ds_read_b128 v[202:205], v143 offset:55296
	ds_read_b128 v[206:209], v143 offset:56320
	global_load_lds_dwordx4 v[212:213], off
	v_lshl_add_u64 v[212:213], v[140:141], 0, s[38:39]
	s_mov_b32 m0, s51
	s_nop 0
	global_load_lds_dwordx4 v[212:213], off
	v_lshl_add_u64 v[212:213], v[140:141], 0, s[12:13]
	s_mov_b32 m0, s33
	v_lshl_add_u64 v[140:141], v[140:141], 0, s[14:15]
	global_load_lds_dwordx4 v[212:213], off
	s_mov_b32 m0, s56
	s_nop 0
	global_load_lds_dwordx4 v[140:141], off
	v_lshl_add_u64 v[140:141], v[210:211], 0, s[36:37]
	s_mov_b32 m0, s53
	s_nop 0
	global_load_lds_dwordx4 v[140:141], off
	v_lshl_add_u64 v[140:141], v[210:211], 0, s[38:39]
	s_mov_b32 m0, s54
	s_nop 0
	global_load_lds_dwordx4 v[140:141], off
	s_waitcnt vmcnt(8)
	s_waitcnt lgkmcnt(0)
	s_barrier
	s_waitcnt lgkmcnt(0)
	s_setprio 0
	v_mfma_f32_16x16x32_bf16 v[54:57], v[146:149], v[178:181], v[54:57]
	v_mfma_f32_16x16x32_bf16 v[50:53], v[154:157], v[178:181], v[50:53]
	v_mfma_f32_16x16x32_bf16 v[38:41], v[146:149], v[186:189], v[38:41]
	v_mfma_f32_16x16x32_bf16 v[34:37], v[154:157], v[186:189], v[34:37]
	v_mfma_f32_16x16x32_bf16 v[22:25], v[146:149], v[194:197], v[22:25]
	v_mfma_f32_16x16x32_bf16 v[18:21], v[154:157], v[194:197], v[18:21]
	v_mfma_f32_16x16x32_bf16 v[6:9], v[146:149], v[202:205], v[6:9]
	v_mfma_f32_16x16x32_bf16 v[2:5], v[154:157], v[202:205], v[2:5]
	v_mfma_f32_16x16x32_bf16 v[54:57], v[150:153], v[182:185], v[54:57]
	v_mfma_f32_16x16x32_bf16 v[50:53], v[158:161], v[182:185], v[50:53]
	v_mfma_f32_16x16x32_bf16 v[38:41], v[150:153], v[190:193], v[38:41]
	v_mfma_f32_16x16x32_bf16 v[34:37], v[158:161], v[190:193], v[34:37]
	v_mfma_f32_16x16x32_bf16 v[22:25], v[150:153], v[198:201], v[22:25]
	v_mfma_f32_16x16x32_bf16 v[18:21], v[158:161], v[198:201], v[18:21]
	v_mfma_f32_16x16x32_bf16 v[6:9], v[150:153], v[206:209], v[6:9]
	v_mfma_f32_16x16x32_bf16 v[2:5], v[158:161], v[206:209], v[2:5]
	v_mfma_f32_16x16x32_bf16 v[62:65], v[162:165], v[178:181], v[62:65]
	v_mfma_f32_16x16x32_bf16 v[58:61], v[170:173], v[178:181], v[58:61]
	v_mfma_f32_16x16x32_bf16 v[46:49], v[162:165], v[186:189], v[46:49]
	v_mfma_f32_16x16x32_bf16 v[42:45], v[170:173], v[186:189], v[42:45]
	v_mfma_f32_16x16x32_bf16 v[30:33], v[162:165], v[194:197], v[30:33]
	v_mfma_f32_16x16x32_bf16 v[26:29], v[170:173], v[194:197], v[26:29]
	v_mfma_f32_16x16x32_bf16 v[14:17], v[162:165], v[202:205], v[14:17]
	v_mfma_f32_16x16x32_bf16 v[10:13], v[170:173], v[202:205], v[10:13]
	v_mfma_f32_16x16x32_bf16 v[62:65], v[166:169], v[182:185], v[62:65]
	v_mfma_f32_16x16x32_bf16 v[58:61], v[174:177], v[182:185], v[58:61]
	v_mfma_f32_16x16x32_bf16 v[46:49], v[166:169], v[190:193], v[46:49]
	v_mfma_f32_16x16x32_bf16 v[42:45], v[174:177], v[190:193], v[42:45]
	v_mfma_f32_16x16x32_bf16 v[30:33], v[166:169], v[198:201], v[30:33]
	v_mfma_f32_16x16x32_bf16 v[26:29], v[174:177], v[198:201], v[26:29]
	v_mfma_f32_16x16x32_bf16 v[14:17], v[166:169], v[206:209], v[14:17]
	v_mfma_f32_16x16x32_bf16 v[10:13], v[174:177], v[206:209], v[10:13]
	s_setprio 1
	s_barrier
	s_add_i32 s77, s77, 2
	s_add_u32 s78, s78, 0x100
	s_addc_u32 s79, s79, 0
	s_add_u32 s57, s57, 0x100
	s_addc_u32 s76, s76, 0
	s_cmp_gt_u32 s77, 29
	s_cbranch_scc0 .LBB0_1381
	s_and_b64 vcc, exec, s[10:11]
	s_cbranch_vccz .LBB0_1384
	s_barrier

.LBB0_1483:
	ds_read_b128 v[2:5], v1
	ds_read_b128 v[6:9], v1 offset:1024
	ds_read_b128 v[10:13], v1 offset:2048
	ds_read_b128 v[14:17], v1 offset:3072
	ds_read_b128 v[18:21], v192
	ds_read_b128 v[22:25], v192 offset:1024
	ds_read_b128 v[26:29], v192 offset:2048
	ds_read_b128 v[30:33], v192 offset:3072
	v_lshl_add_u64 v[248:249], s[70:71], 0, v[170:171]
	s_add_i32 s85, s45, 0xc000
	v_lshl_add_u64 v[66:67], v[248:249], 0, s[14:15]
	s_mov_b32 m0, s85
	s_add_i32 s87, s45, 0xe000
	ds_read_b128 v[34:37], v193
	ds_read_b128 v[38:41], v193 offset:1024
	ds_read_b128 v[42:45], v193 offset:2048
	ds_read_b128 v[46:49], v193 offset:3072
	ds_read_b128 v[50:53], v193 offset:4096
	ds_read_b128 v[54:57], v193 offset:5120
	ds_read_b128 v[58:61], v193 offset:6144
	ds_read_b128 v[62:65], v193 offset:7168
	global_load_lds_dwordx4 v[66:67], off
	v_lshl_add_u64 v[66:67], v[248:249], 0, s[16:17]
	s_mov_b32 m0, s87
	s_nop 0
	global_load_lds_dwordx4 v[66:67], off
	s_waitcnt vmcnt(24)
	s_waitcnt lgkmcnt(0)
	s_barrier
	s_waitcnt lgkmcnt(0)
	s_setprio 0
	v_mfma_f32_16x16x32_bf16 v[66:69], v[2:5], v[34:37], 0
	v_mfma_f32_16x16x32_bf16 v[70:73], v[10:13], v[34:37], 0
	v_mfma_f32_16x16x32_bf16 v[78:81], v[10:13], v[42:45], 0
	v_mfma_f32_16x16x32_bf16 v[86:89], v[10:13], v[50:53], 0
	v_mfma_f32_16x16x32_bf16 v[66:69], v[6:9], v[38:41], v[66:69]
	v_mfma_f32_16x16x32_bf16 v[70:73], v[14:17], v[38:41], v[70:73]
	v_mfma_f32_16x16x32_bf16 v[74:77], v[2:5], v[42:45], 0
	v_mfma_f32_16x16x32_bf16 v[78:81], v[14:17], v[46:49], v[78:81]
	v_mfma_f32_16x16x32_bf16 v[82:85], v[2:5], v[50:53], 0
	v_mfma_f32_16x16x32_bf16 v[86:89], v[14:17], v[54:57], v[86:89]
	v_mfma_f32_16x16x32_bf16 v[90:93], v[2:5], v[58:61], 0
	v_mfma_f32_16x16x32_bf16 v[94:97], v[10:13], v[58:61], 0
	v_mfma_f32_16x16x32_bf16 v[74:77], v[6:9], v[46:49], v[74:77]
	v_mfma_f32_16x16x32_bf16 v[82:85], v[6:9], v[54:57], v[82:85]
	v_mfma_f32_16x16x32_bf16 v[90:93], v[6:9], v[62:65], v[90:93]
	v_mfma_f32_16x16x32_bf16 v[94:97], v[14:17], v[62:65], v[94:97]
	v_mfma_f32_16x16x32_bf16 v[98:101], v[18:21], v[34:37], 0
	v_mfma_f32_16x16x32_bf16 v[34:37], v[26:29], v[34:37], 0
	v_mfma_f32_16x16x32_bf16 v[98:101], v[22:25], v[38:41], v[98:101]
	v_mfma_f32_16x16x32_bf16 v[34:37], v[30:33], v[38:41], v[34:37]
	v_mfma_f32_16x16x32_bf16 v[38:41], v[18:21], v[42:45], 0
	v_mfma_f32_16x16x32_bf16 v[42:45], v[26:29], v[42:45], 0
	v_mfma_f32_16x16x32_bf16 v[38:41], v[22:25], v[46:49], v[38:41]
	v_mfma_f32_16x16x32_bf16 v[42:45], v[30:33], v[46:49], v[42:45]
	v_mfma_f32_16x16x32_bf16 v[46:49], v[18:21], v[50:53], 0
	v_mfma_f32_16x16x32_bf16 v[50:53], v[26:29], v[50:53], 0
	v_mfma_f32_16x16x32_bf16 v[46:49], v[22:25], v[54:57], v[46:49]
	v_mfma_f32_16x16x32_bf16 v[50:53], v[30:33], v[54:57], v[50:53]
	v_mfma_f32_16x16x32_bf16 v[54:57], v[18:21], v[58:61], 0
	v_mfma_f32_16x16x32_bf16 v[58:61], v[26:29], v[58:61], 0
	v_mfma_f32_16x16x32_bf16 v[54:57], v[22:25], v[62:65], v[54:57]
	v_mfma_f32_16x16x32_bf16 v[58:61], v[30:33], v[62:65], v[58:61]
	s_setprio 1
	s_barrier
	v_lshl_add_u64 v[250:251], s[72:73], 0, v[172:173]
	s_add_i32 s88, s77, s44
	v_lshl_add_u64 v[130:131], v[250:251], 0, s[18:19]
	s_mov_b32 m0, s88
	s_add_i32 s89, s88, 0x2000
	ds_read_b128 v[62:65], v193 offset:16384
	ds_read_b128 v[102:105], v193 offset:17408
	ds_read_b128 v[106:109], v193 offset:18432
	ds_read_b128 v[110:113], v193 offset:19456
	ds_read_b128 v[114:117], v193 offset:20480
	ds_read_b128 v[118:121], v193 offset:21504
	ds_read_b128 v[122:125], v193 offset:22528
	ds_read_b128 v[126:129], v193 offset:23552
	global_load_lds_dwordx4 v[130:131], off
	v_lshl_add_u64 v[130:131], v[250:251], 0, s[20:21]
	s_mov_b32 m0, s89
	s_add_i32 s40, s78, s44
	global_load_lds_dwordx4 v[130:131], off
	v_lshl_add_u64 v[130:131], v[250:251], 0, s[22:23]
	s_mov_b32 m0, s40
	s_add_i32 s41, s40, 0x2000
	global_load_lds_dwordx4 v[130:131], off
	v_lshl_add_u64 v[130:131], v[250:251], 0, s[24:25]
	s_mov_b32 m0, s41
	s_nop 0
	global_load_lds_dwordx4 v[130:131], off
	v_lshl_add_u64 v[130:131], v[248:249], 0, s[18:19]
	s_mov_b32 m0, s45
	s_nop 0
	global_load_lds_dwordx4 v[130:131], off
	v_lshl_add_u64 v[130:131], v[248:249], 0, s[20:21]
	s_mov_b32 m0, s46
	s_nop 0
	global_load_lds_dwordx4 v[130:131], off
	s_waitcnt vmcnt(24)
	s_waitcnt lgkmcnt(0)
	s_barrier
	s_waitcnt lgkmcnt(0)
	s_setprio 0
	v_mfma_f32_16x16x32_bf16 v[130:133], v[2:5], v[62:65], 0
	v_mfma_f32_16x16x32_bf16 v[138:141], v[6:9], v[102:105], v[130:133]
	v_mfma_f32_16x16x32_bf16 v[130:133], v[10:13], v[62:65], 0
	v_mfma_f32_16x16x32_bf16 v[150:153], v[14:17], v[102:105], v[130:133]
	v_mfma_f32_16x16x32_bf16 v[130:133], v[2:5], v[106:109], 0
	v_mfma_f32_16x16x32_bf16 v[154:157], v[6:9], v[110:113], v[130:133]
	v_mfma_f32_16x16x32_bf16 v[130:133], v[10:13], v[106:109], 0
	v_mfma_f32_16x16x32_bf16 v[158:161], v[14:17], v[110:113], v[130:133]
	v_mfma_f32_16x16x32_bf16 v[130:133], v[2:5], v[114:117], 0
	v_mfma_f32_16x16x32_bf16 v[2:5], v[2:5], v[122:125], 0
	v_mfma_f32_16x16x32_bf16 v[162:165], v[6:9], v[118:121], v[130:133]
	v_mfma_f32_16x16x32_bf16 v[2:5], v[6:9], v[126:129], v[2:5]
	v_mfma_f32_16x16x32_bf16 v[6:9], v[10:13], v[122:125], 0
	v_mfma_f32_16x16x32_bf16 v[130:133], v[10:13], v[114:117], 0
	v_mfma_f32_16x16x32_bf16 v[6:9], v[14:17], v[126:129], v[6:9]
	v_mfma_f32_16x16x32_bf16 v[166:169], v[14:17], v[118:121], v[130:133]
	v_mfma_f32_16x16x32_bf16 v[10:13], v[18:21], v[62:65], 0
	v_mfma_f32_16x16x32_bf16 v[180:183], v[22:25], v[102:105], v[10:13]
	v_mfma_f32_16x16x32_bf16 v[10:13], v[26:29], v[62:65], 0
	v_mfma_f32_16x16x32_bf16 v[184:187], v[30:33], v[102:105], v[10:13]
	v_mfma_f32_16x16x32_bf16 v[10:13], v[18:21], v[106:109], 0
	v_mfma_f32_16x16x32_bf16 v[188:191], v[22:25], v[110:113], v[10:13]
	v_mfma_f32_16x16x32_bf16 v[10:13], v[26:29], v[106:109], 0
	v_mfma_f32_16x16x32_bf16 v[196:199], v[30:33], v[110:113], v[10:13]
	v_mfma_f32_16x16x32_bf16 v[10:13], v[18:21], v[114:117], 0
	v_mfma_f32_16x16x32_bf16 v[200:203], v[22:25], v[118:121], v[10:13]
	v_mfma_f32_16x16x32_bf16 v[10:13], v[26:29], v[114:117], 0
	v_mfma_f32_16x16x32_bf16 v[204:207], v[30:33], v[118:121], v[10:13]
	v_mfma_f32_16x16x32_bf16 v[10:13], v[18:21], v[122:125], 0
	v_mfma_f32_16x16x32_bf16 v[208:211], v[22:25], v[126:129], v[10:13]
	v_mfma_f32_16x16x32_bf16 v[10:13], v[26:29], v[122:125], 0
	v_mfma_f32_16x16x32_bf16 v[212:215], v[30:33], v[126:129], v[10:13]
	s_setprio 1
	s_barrier
	s_nop 5
	ds_read_b128 v[10:13], v194
	ds_read_b128 v[14:17], v194 offset:1024
	ds_read_b128 v[18:21], v194 offset:2048
	ds_read_b128 v[22:25], v194 offset:3072
	ds_read_b128 v[216:219], v195
	ds_read_b128 v[220:223], v195 offset:1024
	ds_read_b128 v[224:227], v195 offset:2048
	ds_read_b128 v[228:231], v195 offset:3072
	s_mov_b32 m0, s47
	v_lshl_add_u64 v[106:107], v[248:249], 0, s[22:23]
	ds_read_b128 v[26:29], v193 offset:32768
	ds_read_b128 v[30:33], v193 offset:33792
	ds_read_b128 v[62:65], v193 offset:34816
	ds_read_b128 v[102:105], v193 offset:35840
	ds_read_b128 v[232:235], v193 offset:36864
	ds_read_b128 v[236:239], v193 offset:37888
	ds_read_b128 v[240:243], v193 offset:38912
	ds_read_b128 v[244:247], v193 offset:39936
	global_load_lds_dwordx4 v[106:107], off
	v_lshl_add_u64 v[106:107], v[248:249], 0, s[24:25]
	s_mov_b32 m0, s52
	s_nop 0
	global_load_lds_dwordx4 v[106:107], off
	s_waitcnt vmcnt(8)
	s_waitcnt lgkmcnt(0)
	s_barrier
	s_waitcnt lgkmcnt(0)
	s_setprio 0
	v_mfma_f32_16x16x32_bf16 v[66:69], v[10:13], v[26:29], v[66:69]
	v_mfma_f32_16x16x32_bf16 v[146:149], v[14:17], v[30:33], v[66:69]
	v_mfma_f32_16x16x32_bf16 v[66:69], v[18:21], v[26:29], v[70:73]
	v_mfma_f32_16x16x32_bf16 v[142:145], v[22:25], v[30:33], v[66:69]
	v_mfma_f32_16x16x32_bf16 v[66:69], v[10:13], v[62:65], v[74:77]
	v_mfma_f32_16x16x32_bf16 v[126:129], v[14:17], v[102:105], v[66:69]
	v_mfma_f32_16x16x32_bf16 v[66:69], v[18:21], v[62:65], v[78:81]
	v_mfma_f32_16x16x32_bf16 v[122:125], v[22:25], v[102:105], v[66:69]
	v_mfma_f32_16x16x32_bf16 v[66:69], v[10:13], v[232:235], v[82:85]
	v_mfma_f32_16x16x32_bf16 v[110:113], v[14:17], v[236:239], v[66:69]
	v_mfma_f32_16x16x32_bf16 v[66:69], v[18:21], v[232:235], v[86:89]
	v_mfma_f32_16x16x32_bf16 v[106:109], v[22:25], v[236:239], v[66:69]
	v_mfma_f32_16x16x32_bf16 v[66:69], v[10:13], v[240:243], v[90:93]
	v_mfma_f32_16x16x32_bf16 v[86:89], v[14:17], v[244:247], v[66:69]
	v_mfma_f32_16x16x32_bf16 v[66:69], v[18:21], v[240:243], v[94:97]
	v_mfma_f32_16x16x32_bf16 v[78:81], v[22:25], v[244:247], v[66:69]
	v_mfma_f32_16x16x32_bf16 v[66:69], v[216:219], v[26:29], v[98:101]
	v_mfma_f32_16x16x32_bf16 v[26:29], v[224:227], v[26:29], v[34:37]
	v_mfma_f32_16x16x32_bf16 v[130:133], v[228:231], v[30:33], v[26:29]
	v_mfma_f32_16x16x32_bf16 v[26:29], v[216:219], v[62:65], v[38:41]
	v_mfma_f32_16x16x32_bf16 v[118:121], v[220:223], v[102:105], v[26:29]
	v_mfma_f32_16x16x32_bf16 v[26:29], v[224:227], v[62:65], v[42:45]
	v_mfma_f32_16x16x32_bf16 v[114:117], v[228:231], v[102:105], v[26:29]
	v_mfma_f32_16x16x32_bf16 v[26:29], v[216:219], v[232:235], v[46:49]
	v_mfma_f32_16x16x32_bf16 v[102:105], v[220:223], v[236:239], v[26:29]
	v_mfma_f32_16x16x32_bf16 v[26:29], v[224:227], v[232:235], v[50:53]
	v_mfma_f32_16x16x32_bf16 v[98:101], v[228:231], v[236:239], v[26:29]
	v_mfma_f32_16x16x32_bf16 v[26:29], v[216:219], v[240:243], v[54:57]
	v_mfma_f32_16x16x32_bf16 v[70:73], v[220:223], v[244:247], v[26:29]
	v_mfma_f32_16x16x32_bf16 v[26:29], v[224:227], v[240:243], v[58:61]
	v_mfma_f32_16x16x32_bf16 v[134:137], v[220:223], v[30:33], v[66:69]
	v_mfma_f32_16x16x32_bf16 v[66:69], v[228:231], v[244:247], v[26:29]
	s_setprio 1
	s_barrier
	s_add_i32 s50, s79, s44
	s_nop 3
	v_lshl_add_u64 v[26:27], v[250:251], 0, s[26:27]
	s_mov_b32 m0, s50
	s_add_i32 s51, s50, 0x2000
	ds_read_b128 v[34:37], v193 offset:49152
	ds_read_b128 v[38:41], v193 offset:50176
	ds_read_b128 v[74:77], v193 offset:51200
	ds_read_b128 v[82:85], v193 offset:52224
	ds_read_b128 v[90:93], v193 offset:53248
	ds_read_b128 v[94:97], v193 offset:54272
	ds_read_b128 v[232:235], v193 offset:55296
	ds_read_b128 v[236:239], v193 offset:56320
	global_load_lds_dwordx4 v[26:27], off
	v_lshl_add_u64 v[26:27], v[250:251], 0, s[28:29]
	s_mov_b32 m0, s51
	s_mov_b64 s[0:1], 0x160180
	s_add_i32 s33, s80, s44
	global_load_lds_dwordx4 v[26:27], off
	v_lshl_add_u64 v[26:27], v[250:251], 0, s[0:1]
	s_mov_b32 m0, s33
	s_mov_b64 s[0:1], 0x210180
	s_add_i32 s56, s33, 0x2000
	global_load_lds_dwordx4 v[26:27], off
	v_lshl_add_u64 v[26:27], v[250:251], 0, s[0:1]
	s_mov_b32 m0, s56
	s_nop 0
	global_load_lds_dwordx4 v[26:27], off
	v_lshl_add_u64 v[26:27], v[248:249], 0, s[26:27]
	s_mov_b32 m0, s53
	s_nop 0
	global_load_lds_dwordx4 v[26:27], off
	v_lshl_add_u64 v[26:27], v[248:249], 0, s[28:29]
	s_mov_b32 m0, s54
	s_nop 0
	global_load_lds_dwordx4 v[26:27], off
	s_waitcnt vmcnt(8)
	s_waitcnt lgkmcnt(0)
	s_barrier
	s_waitcnt lgkmcnt(0)
	s_setprio 0
	v_mfma_f32_16x16x32_bf16 v[26:29], v[10:13], v[34:37], v[138:141]
	v_mfma_f32_16x16x32_bf16 v[62:65], v[14:17], v[38:41], v[26:29]
	v_mfma_f32_16x16x32_bf16 v[26:29], v[18:21], v[34:37], v[150:153]
	v_mfma_f32_16x16x32_bf16 v[58:61], v[22:25], v[38:41], v[26:29]
	v_mfma_f32_16x16x32_bf16 v[26:29], v[10:13], v[74:77], v[154:157]
	v_mfma_f32_16x16x32_bf16 v[46:49], v[14:17], v[82:85], v[26:29]
	v_mfma_f32_16x16x32_bf16 v[26:29], v[18:21], v[74:77], v[158:161]
	v_mfma_f32_16x16x32_bf16 v[42:45], v[22:25], v[82:85], v[26:29]
	v_mfma_f32_16x16x32_bf16 v[26:29], v[10:13], v[90:93], v[162:165]
	v_mfma_f32_16x16x32_bf16 v[2:5], v[10:13], v[232:235], v[2:5]
	v_mfma_f32_16x16x32_bf16 v[30:33], v[14:17], v[94:97], v[26:29]
	v_mfma_f32_16x16x32_bf16 v[26:29], v[18:21], v[90:93], v[166:169]
	v_mfma_f32_16x16x32_bf16 v[14:17], v[14:17], v[236:239], v[2:5]
	v_mfma_f32_16x16x32_bf16 v[2:5], v[18:21], v[232:235], v[6:9]
	v_mfma_f32_16x16x32_bf16 v[26:29], v[22:25], v[94:97], v[26:29]
	v_mfma_f32_16x16x32_bf16 v[10:13], v[22:25], v[236:239], v[2:5]
	v_mfma_f32_16x16x32_bf16 v[2:5], v[216:219], v[34:37], v[180:183]
	v_mfma_f32_16x16x32_bf16 v[54:57], v[220:223], v[38:41], v[2:5]
	v_mfma_f32_16x16x32_bf16 v[2:5], v[224:227], v[34:37], v[184:187]
	v_mfma_f32_16x16x32_bf16 v[50:53], v[228:231], v[38:41], v[2:5]
	v_mfma_f32_16x16x32_bf16 v[2:5], v[216:219], v[74:77], v[188:191]
	v_mfma_f32_16x16x32_bf16 v[38:41], v[220:223], v[82:85], v[2:5]
	v_mfma_f32_16x16x32_bf16 v[2:5], v[224:227], v[74:77], v[196:199]
	v_mfma_f32_16x16x32_bf16 v[34:37], v[228:231], v[82:85], v[2:5]
	v_mfma_f32_16x16x32_bf16 v[2:5], v[216:219], v[90:93], v[200:203]
	v_mfma_f32_16x16x32_bf16 v[22:25], v[220:223], v[94:97], v[2:5]
	v_mfma_f32_16x16x32_bf16 v[2:5], v[224:227], v[90:93], v[204:207]
	v_mfma_f32_16x16x32_bf16 v[18:21], v[228:231], v[94:97], v[2:5]
	v_mfma_f32_16x16x32_bf16 v[2:5], v[216:219], v[232:235], v[208:211]
	v_mfma_f32_16x16x32_bf16 v[6:9], v[220:223], v[236:239], v[2:5]
	v_mfma_f32_16x16x32_bf16 v[2:5], v[224:227], v[232:235], v[212:215]
	v_mfma_f32_16x16x32_bf16 v[2:5], v[228:231], v[236:239], v[2:5]
	s_setprio 1
	s_barrier
	s_add_u32 s70, s70, 0x160180
	s_addc_u32 s71, s71, 0
	s_add_u32 s57, s72, 0x200
	s_addc_u32 s72, s73, 0
	s_mov_b32 s73, 0
.LBB0_1484:
	ds_read_b128 v[74:77], v1
	ds_read_b128 v[82:85], v1 offset:1024
	ds_read_b128 v[90:93], v1 offset:2048
	ds_read_b128 v[94:97], v1 offset:3072
	ds_read_b128 v[138:141], v192
	ds_read_b128 v[150:153], v192 offset:1024
	ds_read_b128 v[154:157], v192 offset:2048
	ds_read_b128 v[158:161], v192 offset:3072
	s_add_u32 s0, s70, 0xffea0080
	s_addc_u32 s1, s71, -1
	s_cmpk_eq_i32 s73, 0x54
	s_cselect_b32 s1, s11, s1
	s_cselect_b32 s0, s10, s0
	s_cselect_b32 s65, s69, s72
	s_cselect_b32 s64, s68, s57
	s_mov_b32 m0, s85
	v_lshl_add_u64 v[208:209], s[70:71], 0, v[174:175]
	ds_read_b128 v[162:165], v193
	ds_read_b128 v[166:169], v193 offset:1024
	ds_read_b128 v[180:183], v193 offset:2048
	ds_read_b128 v[184:187], v193 offset:3072
	ds_read_b128 v[188:191], v193 offset:4096
	ds_read_b128 v[196:199], v193 offset:5120
	ds_read_b128 v[200:203], v193 offset:6144
	ds_read_b128 v[204:207], v193 offset:7168
	global_load_lds_dwordx4 v[208:209], off
	v_lshl_add_u64 v[208:209], v[208:209], 0, s[30:31]
	s_mov_b32 m0, s87
	s_nop 0
	global_load_lds_dwordx4 v[208:209], off
	s_waitcnt vmcnt(8)
	s_waitcnt lgkmcnt(0)
	s_barrier
	s_waitcnt lgkmcnt(0)
	s_setprio 0
	v_mfma_f32_16x16x32_bf16 v[146:149], v[74:77], v[162:165], v[146:149]
	v_mfma_f32_16x16x32_bf16 v[142:145], v[90:93], v[162:165], v[142:145]
	v_mfma_f32_16x16x32_bf16 v[126:129], v[74:77], v[180:183], v[126:129]
	v_mfma_f32_16x16x32_bf16 v[122:125], v[90:93], v[180:183], v[122:125]
	v_mfma_f32_16x16x32_bf16 v[110:113], v[74:77], v[188:191], v[110:113]
	v_mfma_f32_16x16x32_bf16 v[106:109], v[90:93], v[188:191], v[106:109]
	v_mfma_f32_16x16x32_bf16 v[86:89], v[74:77], v[200:203], v[86:89]
	v_mfma_f32_16x16x32_bf16 v[78:81], v[90:93], v[200:203], v[78:81]
	v_mfma_f32_16x16x32_bf16 v[146:149], v[82:85], v[166:169], v[146:149]
	v_mfma_f32_16x16x32_bf16 v[142:145], v[94:97], v[166:169], v[142:145]
	v_mfma_f32_16x16x32_bf16 v[126:129], v[82:85], v[184:187], v[126:129]
	v_mfma_f32_16x16x32_bf16 v[122:125], v[94:97], v[184:187], v[122:125]
	v_mfma_f32_16x16x32_bf16 v[110:113], v[82:85], v[196:199], v[110:113]
	v_mfma_f32_16x16x32_bf16 v[106:109], v[94:97], v[196:199], v[106:109]
	v_mfma_f32_16x16x32_bf16 v[86:89], v[82:85], v[204:207], v[86:89]
	v_mfma_f32_16x16x32_bf16 v[78:81], v[94:97], v[204:207], v[78:81]
	v_mfma_f32_16x16x32_bf16 v[134:137], v[138:141], v[162:165], v[134:137]
	v_mfma_f32_16x16x32_bf16 v[130:133], v[154:157], v[162:165], v[130:133]
	v_mfma_f32_16x16x32_bf16 v[118:121], v[138:141], v[180:183], v[118:121]
	v_mfma_f32_16x16x32_bf16 v[114:117], v[154:157], v[180:183], v[114:117]
	v_mfma_f32_16x16x32_bf16 v[102:105], v[138:141], v[188:191], v[102:105]
	v_mfma_f32_16x16x32_bf16 v[98:101], v[154:157], v[188:191], v[98:101]
	v_mfma_f32_16x16x32_bf16 v[70:73], v[138:141], v[200:203], v[70:73]
	v_mfma_f32_16x16x32_bf16 v[66:69], v[154:157], v[200:203], v[66:69]
	v_mfma_f32_16x16x32_bf16 v[134:137], v[150:153], v[166:169], v[134:137]
	v_mfma_f32_16x16x32_bf16 v[130:133], v[158:161], v[166:169], v[130:133]
	v_mfma_f32_16x16x32_bf16 v[118:121], v[150:153], v[184:187], v[118:121]
	v_mfma_f32_16x16x32_bf16 v[114:117], v[158:161], v[184:187], v[114:117]
	v_mfma_f32_16x16x32_bf16 v[102:105], v[150:153], v[196:199], v[102:105]
	v_mfma_f32_16x16x32_bf16 v[98:101], v[158:161], v[196:199], v[98:101]
	v_mfma_f32_16x16x32_bf16 v[70:73], v[150:153], v[204:207], v[70:73]
	v_mfma_f32_16x16x32_bf16 v[66:69], v[158:161], v[204:207], v[66:69]
	s_setprio 1
	s_barrier
	s_mov_b32 m0, s88
	v_lshl_add_u64 v[208:209], s[64:65], 0, v[172:173]
	ds_read_b128 v[162:165], v193 offset:16384
	ds_read_b128 v[166:169], v193 offset:17408
	ds_read_b128 v[180:183], v193 offset:18432
	ds_read_b128 v[184:187], v193 offset:19456
	ds_read_b128 v[188:191], v193 offset:20480
	ds_read_b128 v[196:199], v193 offset:21504
	ds_read_b128 v[200:203], v193 offset:22528
	ds_read_b128 v[204:207], v193 offset:23552
	global_load_lds_dwordx4 v[208:209], off
	v_lshl_add_u64 v[210:211], v[208:209], 0, s[30:31]
	s_mov_b32 m0, s89
	s_nop 0
	global_load_lds_dwordx4 v[210:211], off
	v_lshl_add_u64 v[210:211], v[208:209], 0, s[34:35]
	s_mov_b32 m0, s40
	s_nop 0
	global_load_lds_dwordx4 v[210:211], off
	v_lshl_add_u64 v[210:211], v[208:209], 0, s[36:37]
	s_mov_b32 m0, s41
	s_nop 0
	global_load_lds_dwordx4 v[210:211], off
	v_lshl_add_u64 v[210:211], s[0:1], 0, v[170:171]
	s_mov_b32 m0, s45
	v_lshl_add_u64 v[212:213], v[210:211], 0, s[30:31]
	global_load_lds_dwordx4 v[210:211], off
	s_mov_b32 m0, s46
	s_nop 0
	global_load_lds_dwordx4 v[212:213], off
	s_waitcnt vmcnt(8)
	s_waitcnt lgkmcnt(0)
	s_barrier
	s_waitcnt lgkmcnt(0)
	s_setprio 0
	v_mfma_f32_16x16x32_bf16 v[62:65], v[74:77], v[162:165], v[62:65]
	v_mfma_f32_16x16x32_bf16 v[58:61], v[90:93], v[162:165], v[58:61]
	v_mfma_f32_16x16x32_bf16 v[46:49], v[74:77], v[180:183], v[46:49]
	v_mfma_f32_16x16x32_bf16 v[42:45], v[90:93], v[180:183], v[42:45]
	v_mfma_f32_16x16x32_bf16 v[30:33], v[74:77], v[188:191], v[30:33]
	v_mfma_f32_16x16x32_bf16 v[26:29], v[90:93], v[188:191], v[26:29]
	v_mfma_f32_16x16x32_bf16 v[14:17], v[74:77], v[200:203], v[14:17]
	v_mfma_f32_16x16x32_bf16 v[10:13], v[90:93], v[200:203], v[10:13]
	v_mfma_f32_16x16x32_bf16 v[62:65], v[82:85], v[166:169], v[62:65]
	v_mfma_f32_16x16x32_bf16 v[58:61], v[94:97], v[166:169], v[58:61]
	v_mfma_f32_16x16x32_bf16 v[46:49], v[82:85], v[184:187], v[46:49]
	v_mfma_f32_16x16x32_bf16 v[42:45], v[94:97], v[184:187], v[42:45]
	v_mfma_f32_16x16x32_bf16 v[30:33], v[82:85], v[196:199], v[30:33]
	v_mfma_f32_16x16x32_bf16 v[26:29], v[94:97], v[196:199], v[26:29]
	v_mfma_f32_16x16x32_bf16 v[14:17], v[82:85], v[204:207], v[14:17]
	v_mfma_f32_16x16x32_bf16 v[10:13], v[94:97], v[204:207], v[10:13]
	v_mfma_f32_16x16x32_bf16 v[54:57], v[138:141], v[162:165], v[54:57]
	v_mfma_f32_16x16x32_bf16 v[50:53], v[154:157], v[162:165], v[50:53]
	v_mfma_f32_16x16x32_bf16 v[38:41], v[138:141], v[180:183], v[38:41]
	v_mfma_f32_16x16x32_bf16 v[34:37], v[154:157], v[180:183], v[34:37]
	v_mfma_f32_16x16x32_bf16 v[22:25], v[138:141], v[188:191], v[22:25]
	v_mfma_f32_16x16x32_bf16 v[18:21], v[154:157], v[188:191], v[18:21]
	v_mfma_f32_16x16x32_bf16 v[6:9], v[138:141], v[200:203], v[6:9]
	v_mfma_f32_16x16x32_bf16 v[2:5], v[154:157], v[200:203], v[2:5]
	v_mfma_f32_16x16x32_bf16 v[54:57], v[150:153], v[166:169], v[54:57]
	v_mfma_f32_16x16x32_bf16 v[50:53], v[158:161], v[166:169], v[50:53]
	v_mfma_f32_16x16x32_bf16 v[38:41], v[150:153], v[184:187], v[38:41]
	v_mfma_f32_16x16x32_bf16 v[34:37], v[158:161], v[184:187], v[34:37]
	v_mfma_f32_16x16x32_bf16 v[22:25], v[150:153], v[196:199], v[22:25]
	v_mfma_f32_16x16x32_bf16 v[18:21], v[158:161], v[196:199], v[18:21]
	v_mfma_f32_16x16x32_bf16 v[6:9], v[150:153], v[204:207], v[6:9]
	v_mfma_f32_16x16x32_bf16 v[2:5], v[158:161], v[204:207], v[2:5]
	s_setprio 1
	s_barrier
	ds_read_b128 v[74:77], v194
	ds_read_b128 v[82:85], v194 offset:1024
	ds_read_b128 v[90:93], v194 offset:2048
	ds_read_b128 v[94:97], v194 offset:3072
	ds_read_b128 v[138:141], v195
	ds_read_b128 v[150:153], v195 offset:1024
	ds_read_b128 v[154:157], v195 offset:2048
	ds_read_b128 v[158:161], v195 offset:3072
	s_mov_b32 m0, s47
	v_lshl_add_u64 v[212:213], v[210:211], 0, s[34:35]
	ds_read_b128 v[162:165], v193 offset:32768
	ds_read_b128 v[166:169], v193 offset:33792
	ds_read_b128 v[180:183], v193 offset:34816
	ds_read_b128 v[184:187], v193 offset:35840
	ds_read_b128 v[188:191], v193 offset:36864
	ds_read_b128 v[196:199], v193 offset:37888
	ds_read_b128 v[200:203], v193 offset:38912
	ds_read_b128 v[204:207], v193 offset:39936
	global_load_lds_dwordx4 v[212:213], off
	v_lshl_add_u64 v[212:213], v[210:211], 0, s[36:37]
	s_mov_b32 m0, s52
	s_nop 0
	global_load_lds_dwordx4 v[212:213], off
	s_waitcnt vmcnt(8)
	s_waitcnt lgkmcnt(0)
	s_barrier
	s_waitcnt lgkmcnt(0)
	s_setprio 0
	v_mfma_f32_16x16x32_bf16 v[146:149], v[74:77], v[162:165], v[146:149]
	v_mfma_f32_16x16x32_bf16 v[142:145], v[90:93], v[162:165], v[142:145]
	v_mfma_f32_16x16x32_bf16 v[126:129], v[74:77], v[180:183], v[126:129]
	v_mfma_f32_16x16x32_bf16 v[122:125], v[90:93], v[180:183], v[122:125]
	v_mfma_f32_16x16x32_bf16 v[110:113], v[74:77], v[188:191], v[110:113]
	v_mfma_f32_16x16x32_bf16 v[106:109], v[90:93], v[188:191], v[106:109]
	v_mfma_f32_16x16x32_bf16 v[86:89], v[74:77], v[200:203], v[86:89]
	v_mfma_f32_16x16x32_bf16 v[78:81], v[90:93], v[200:203], v[78:81]
	v_mfma_f32_16x16x32_bf16 v[146:149], v[82:85], v[166:169], v[146:149]
	v_mfma_f32_16x16x32_bf16 v[142:145], v[94:97], v[166:169], v[142:145]
	v_mfma_f32_16x16x32_bf16 v[126:129], v[82:85], v[184:187], v[126:129]
	v_mfma_f32_16x16x32_bf16 v[122:125], v[94:97], v[184:187], v[122:125]
	v_mfma_f32_16x16x32_bf16 v[110:113], v[82:85], v[196:199], v[110:113]
	v_mfma_f32_16x16x32_bf16 v[106:109], v[94:97], v[196:199], v[106:109]
	v_mfma_f32_16x16x32_bf16 v[86:89], v[82:85], v[204:207], v[86:89]
	v_mfma_f32_16x16x32_bf16 v[78:81], v[94:97], v[204:207], v[78:81]
	v_mfma_f32_16x16x32_bf16 v[134:137], v[138:141], v[162:165], v[134:137]
	v_mfma_f32_16x16x32_bf16 v[130:133], v[154:157], v[162:165], v[130:133]
	v_mfma_f32_16x16x32_bf16 v[118:121], v[138:141], v[180:183], v[118:121]
	v_mfma_f32_16x16x32_bf16 v[114:117], v[154:157], v[180:183], v[114:117]
	v_mfma_f32_16x16x32_bf16 v[102:105], v[138:141], v[188:191], v[102:105]
	v_mfma_f32_16x16x32_bf16 v[98:101], v[154:157], v[188:191], v[98:101]
	v_mfma_f32_16x16x32_bf16 v[70:73], v[138:141], v[200:203], v[70:73]
	v_mfma_f32_16x16x32_bf16 v[66:69], v[154:157], v[200:203], v[66:69]
	v_mfma_f32_16x16x32_bf16 v[134:137], v[150:153], v[166:169], v[134:137]
	v_mfma_f32_16x16x32_bf16 v[130:133], v[158:161], v[166:169], v[130:133]
	v_mfma_f32_16x16x32_bf16 v[118:121], v[150:153], v[184:187], v[118:121]
	v_mfma_f32_16x16x32_bf16 v[114:117], v[158:161], v[184:187], v[114:117]
	v_mfma_f32_16x16x32_bf16 v[102:105], v[150:153], v[196:199], v[102:105]
	v_mfma_f32_16x16x32_bf16 v[98:101], v[158:161], v[196:199], v[98:101]
	v_mfma_f32_16x16x32_bf16 v[70:73], v[150:153], v[204:207], v[70:73]
	v_mfma_f32_16x16x32_bf16 v[66:69], v[158:161], v[204:207], v[66:69]
	s_setprio 1
	s_barrier
; #define PG8_WAIT_V(n) asm volatile("s_waitcnt vmcnt(" #n ")" ::: "memory")
; template <class Epi, class Sched, bool ALIGN_EPI = true, bool SP2 = true, bool FULLLINE = false, bool NOSTAGE = false, bool FP8 = false>
; __device__ __forceinline__ void gemm_phase(PG8_LAS unsigned char* lds, const Gemm g, const Sched& S, const Epi& E) {
;     ...
;         static_assert(SP2, "only the SP2 loop is kept");
;         { const int t = 0; if constexpr (Epi::NST == 16) PG8_ITER(PG8_WAIT_V(24)); else if constexpr (Epi::NST == 8) PG8_ITER(PG8_WAIT_V(16)); else PG8_ITER(PG8_WAIT_V(8)); }
;         for (int t = 2; t < nt; t += 2) PG8_ITER(PG8_WAIT_V(8));
	s_mov_b32 m0, s50
	v_lshl_add_u64 v[212:213], v[208:209], 0, s[38:39]
	ds_read_b128 v[162:165], v193 offset:49152
	ds_read_b128 v[166:169], v193 offset:50176
	ds_read_b128 v[180:183], v193 offset:51200
	ds_read_b128 v[184:187], v193 offset:52224
	ds_read_b128 v[188:191], v193 offset:53248
	ds_read_b128 v[196:199], v193 offset:54272
	ds_read_b128 v[200:203], v193 offset:55296
	ds_read_b128 v[204:207], v193 offset:56320
	global_load_lds_dwordx4 v[212:213], off
	v_lshl_add_u64 v[212:213], v[208:209], 0, s[66:67]
	s_mov_b32 m0, s51
	s_nop 0
	global_load_lds_dwordx4 v[212:213], off
	v_lshl_add_u64 v[212:213], v[208:209], 0, s[14:15]
	s_mov_b32 m0, s33
	v_lshl_add_u64 v[208:209], v[208:209], 0, s[16:17]
	global_load_lds_dwordx4 v[212:213], off
	s_mov_b32 m0, s56
	s_nop 0
	global_load_lds_dwordx4 v[208:209], off
	v_lshl_add_u64 v[208:209], v[210:211], 0, s[38:39]
	s_mov_b32 m0, s53
	s_nop 0
	global_load_lds_dwordx4 v[208:209], off
	v_lshl_add_u64 v[208:209], v[210:211], 0, s[66:67]
	s_mov_b32 m0, s54
	s_nop 0
	global_load_lds_dwordx4 v[208:209], off
	s_waitcnt vmcnt(8)
	s_waitcnt lgkmcnt(0)
	s_barrier
	s_waitcnt lgkmcnt(0)
	s_setprio 0
	v_mfma_f32_16x16x32_bf16 v[62:65], v[74:77], v[162:165], v[62:65]
	v_mfma_f32_16x16x32_bf16 v[58:61], v[90:93], v[162:165], v[58:61]
	v_mfma_f32_16x16x32_bf16 v[46:49], v[74:77], v[180:183], v[46:49]
	v_mfma_f32_16x16x32_bf16 v[42:45], v[90:93], v[180:183], v[42:45]
	v_mfma_f32_16x16x32_bf16 v[30:33], v[74:77], v[188:191], v[30:33]
	v_mfma_f32_16x16x32_bf16 v[26:29], v[90:93], v[188:191], v[26:29]
	v_mfma_f32_16x16x32_bf16 v[14:17], v[74:77], v[200:203], v[14:17]
	v_mfma_f32_16x16x32_bf16 v[10:13], v[90:93], v[200:203], v[10:13]
	v_mfma_f32_16x16x32_bf16 v[62:65], v[82:85], v[166:169], v[62:65]
	v_mfma_f32_16x16x32_bf16 v[58:61], v[94:97], v[166:169], v[58:61]
	v_mfma_f32_16x16x32_bf16 v[46:49], v[82:85], v[184:187], v[46:49]
	v_mfma_f32_16x16x32_bf16 v[42:45], v[94:97], v[184:187], v[42:45]
	v_mfma_f32_16x16x32_bf16 v[30:33], v[82:85], v[196:199], v[30:33]
	v_mfma_f32_16x16x32_bf16 v[26:29], v[94:97], v[196:199], v[26:29]
	v_mfma_f32_16x16x32_bf16 v[14:17], v[82:85], v[204:207], v[14:17]
	v_mfma_f32_16x16x32_bf16 v[10:13], v[94:97], v[204:207], v[10:13]
	v_mfma_f32_16x16x32_bf16 v[54:57], v[138:141], v[162:165], v[54:57]
	v_mfma_f32_16x16x32_bf16 v[50:53], v[154:157], v[162:165], v[50:53]
	v_mfma_f32_16x16x32_bf16 v[38:41], v[138:141], v[180:183], v[38:41]
	v_mfma_f32_16x16x32_bf16 v[34:37], v[154:157], v[180:183], v[34:37]
	v_mfma_f32_16x16x32_bf16 v[22:25], v[138:141], v[188:191], v[22:25]
	v_mfma_f32_16x16x32_bf16 v[18:21], v[154:157], v[188:191], v[18:21]
	v_mfma_f32_16x16x32_bf16 v[6:9], v[138:141], v[200:203], v[6:9]
	v_mfma_f32_16x16x32_bf16 v[2:5], v[154:157], v[200:203], v[2:5]
	v_mfma_f32_16x16x32_bf16 v[54:57], v[150:153], v[166:169], v[54:57]
	v_mfma_f32_16x16x32_bf16 v[50:53], v[158:161], v[166:169], v[50:53]
	v_mfma_f32_16x16x32_bf16 v[38:41], v[150:153], v[184:187], v[38:41]
	v_mfma_f32_16x16x32_bf16 v[34:37], v[158:161], v[184:187], v[34:37]
	v_mfma_f32_16x16x32_bf16 v[22:25], v[150:153], v[196:199], v[22:25]
	v_mfma_f32_16x16x32_bf16 v[18:21], v[158:161], v[196:199], v[18:21]
	v_mfma_f32_16x16x32_bf16 v[6:9], v[150:153], v[204:207], v[6:9]
	v_mfma_f32_16x16x32_bf16 v[2:5], v[158:161], v[204:207], v[2:5]
	s_setprio 1
	s_barrier
	s_add_i32 s73, s73, 2
	s_add_u32 s70, s70, 0x100
	s_addc_u32 s71, s71, 0
	s_add_u32 s57, s57, 0x100
	s_addc_u32 s72, s72, 0
	s_cmpk_gt_u32 s73, 0x55
	s_cbranch_scc0 .LBB0_1484
	s_and_b64 vcc, exec, s[12:13]
	s_cbranch_vccz .LBB0_1487
	s_barrier

; template <class Epi, class Sched, bool ALIGN_EPI = true, bool SP2 = true, bool FULLLINE = false, bool NOSTAGE = false, bool FP8 = false>
; __device__ __forceinline__ void gemm_phase(PG8_LAS unsigned char* lds, const Gemm g, const Sched& S, const Epi& E) {
;     ...
;         const bool has_next = S.next(ui + 1, nxt);
;         const char* nA = has_next ? PG8_ABASE(nxt) : cA; const char* nB = has_next ? PG8_BBASE(nxt) : cB;
.LBB0_1645:
	s_ashr_i32 s71, s70, 31
	s_lshl_b64 s[0:1], s[70:71], 20
	s_add_u32 s72, s58, s0
	ds_read_b128 v[2:5], v144
	ds_read_b128 v[6:9], v144 offset:1024
	ds_read_b128 v[10:13], v144 offset:2048
	ds_read_b128 v[14:17], v144 offset:3072
	ds_read_b128 v[18:21], v145
	ds_read_b128 v[22:25], v145 offset:1024
	ds_read_b128 v[26:29], v145 offset:2048
	ds_read_b128 v[30:33], v145 offset:3072
	s_addc_u32 s73, s59, s1
	s_ashr_i32 s69, s68, 31
	s_lshl_b64 s[0:1], s[68:69], 20
	s_add_u32 s74, s44, s0
	s_addc_u32 s75, s45, s1
	s_and_b64 s[0:1], s[8:9], exec
	s_cselect_b32 s11, s73, s79
	s_cselect_b32 s14, s72, s78
	s_cselect_b32 s69, s75, s77
	s_cselect_b32 s71, s74, s76
	v_lshl_add_u64 v[242:243], s[78:79], 0, v[130:131]
	s_mov_b32 m0, s97
	v_lshl_add_u64 v[66:67], v[242:243], 0, s[16:17]
	ds_read_b128 v[34:37], v146
	ds_read_b128 v[38:41], v146 offset:1024
	ds_read_b128 v[42:45], v146 offset:2048
	ds_read_b128 v[46:49], v146 offset:3072
	ds_read_b128 v[50:53], v146 offset:4096
	ds_read_b128 v[54:57], v146 offset:5120
	ds_read_b128 v[58:61], v146 offset:6144
	ds_read_b128 v[62:65], v146 offset:7168
	global_load_lds_dwordx4 v[66:67], off
	v_lshl_add_u64 v[66:67], v[242:243], 0, s[18:19]
	s_mov_b32 m0, s47
	s_nop 0
	global_load_lds_dwordx4 v[66:67], off
	s_waitcnt vmcnt(24)
	s_waitcnt lgkmcnt(0)
	s_barrier
	s_waitcnt lgkmcnt(0)
	s_setprio 0
	v_mfma_f32_16x16x32_bf16 v[90:93], v[2:5], v[58:61], 0
	v_mfma_f32_16x16x32_bf16 v[66:69], v[2:5], v[34:37], 0
	v_mfma_f32_16x16x32_bf16 v[70:73], v[10:13], v[34:37], 0
	v_mfma_f32_16x16x32_bf16 v[74:77], v[2:5], v[42:45], 0
	v_mfma_f32_16x16x32_bf16 v[78:81], v[10:13], v[42:45], 0
	v_mfma_f32_16x16x32_bf16 v[82:85], v[2:5], v[50:53], 0
	v_mfma_f32_16x16x32_bf16 v[86:89], v[10:13], v[50:53], 0
	v_mfma_f32_16x16x32_bf16 v[98:101], v[6:9], v[62:65], v[90:93]
	v_mfma_f32_16x16x32_bf16 v[90:93], v[10:13], v[58:61], 0
	v_mfma_f32_16x16x32_bf16 v[66:69], v[6:9], v[38:41], v[66:69]
	v_mfma_f32_16x16x32_bf16 v[70:73], v[14:17], v[38:41], v[70:73]
	v_mfma_f32_16x16x32_bf16 v[74:77], v[6:9], v[46:49], v[74:77]
	v_mfma_f32_16x16x32_bf16 v[78:81], v[14:17], v[46:49], v[78:81]
	v_mfma_f32_16x16x32_bf16 v[82:85], v[6:9], v[54:57], v[82:85]
	v_mfma_f32_16x16x32_bf16 v[86:89], v[14:17], v[54:57], v[86:89]
	v_mfma_f32_16x16x32_bf16 v[102:105], v[14:17], v[62:65], v[90:93]
	v_mfma_f32_16x16x32_bf16 v[90:93], v[18:21], v[34:37], 0
	v_mfma_f32_16x16x32_bf16 v[34:37], v[26:29], v[34:37], 0
	v_mfma_f32_16x16x32_bf16 v[114:117], v[22:25], v[38:41], v[90:93]
	v_mfma_f32_16x16x32_bf16 v[34:37], v[30:33], v[38:41], v[34:37]
	v_mfma_f32_16x16x32_bf16 v[38:41], v[18:21], v[42:45], 0
	v_mfma_f32_16x16x32_bf16 v[42:45], v[26:29], v[42:45], 0
	v_mfma_f32_16x16x32_bf16 v[38:41], v[22:25], v[46:49], v[38:41]
	v_mfma_f32_16x16x32_bf16 v[42:45], v[30:33], v[46:49], v[42:45]
	v_mfma_f32_16x16x32_bf16 v[46:49], v[18:21], v[50:53], 0
	v_mfma_f32_16x16x32_bf16 v[50:53], v[26:29], v[50:53], 0
	v_mfma_f32_16x16x32_bf16 v[46:49], v[22:25], v[54:57], v[46:49]
	v_mfma_f32_16x16x32_bf16 v[50:53], v[30:33], v[54:57], v[50:53]
	v_mfma_f32_16x16x32_bf16 v[54:57], v[18:21], v[58:61], 0
	v_mfma_f32_16x16x32_bf16 v[58:61], v[26:29], v[58:61], 0
	v_mfma_f32_16x16x32_bf16 v[54:57], v[22:25], v[62:65], v[54:57]
	v_mfma_f32_16x16x32_bf16 v[58:61], v[30:33], v[62:65], v[58:61]
	s_setprio 1
	s_barrier
	v_lshl_add_u64 v[244:245], s[76:77], 0, v[132:133]
	s_add_i32 s81, s95, s46
	v_lshl_add_u64 v[140:141], v[244:245], 0, s[20:21]
	s_mov_b32 m0, s81
	s_add_i32 s82, s81, 0x2000
	ds_read_b128 v[62:65], v146 offset:16384
	ds_read_b128 v[90:93], v146 offset:17408
	ds_read_b128 v[94:97], v146 offset:18432
	ds_read_b128 v[106:109], v146 offset:19456
	ds_read_b128 v[110:113], v146 offset:20480
	ds_read_b128 v[118:121], v146 offset:21504
	ds_read_b128 v[122:125], v146 offset:22528
	ds_read_b128 v[126:129], v146 offset:23552
	global_load_lds_dwordx4 v[140:141], off
	v_lshl_add_u64 v[140:141], v[244:245], 0, s[22:23]
	s_mov_b32 m0, s82
	s_add_i32 s83, s96, s46
	global_load_lds_dwordx4 v[140:141], off
	v_lshl_add_u64 v[140:141], v[244:245], 0, s[24:25]
	s_mov_b32 m0, s83
	s_add_i32 s84, s83, 0x2000
	global_load_lds_dwordx4 v[140:141], off
	v_lshl_add_u64 v[140:141], v[244:245], 0, s[26:27]
	s_mov_b32 m0, s84
	s_nop 0
	global_load_lds_dwordx4 v[140:141], off
	v_lshl_add_u64 v[140:141], v[242:243], 0, s[20:21]
	s_mov_b32 m0, s87
	s_nop 0
	global_load_lds_dwordx4 v[140:141], off
	v_lshl_add_u64 v[140:141], v[242:243], 0, s[22:23]
	s_mov_b32 m0, s52
	s_nop 0
	global_load_lds_dwordx4 v[140:141], off
	s_waitcnt vmcnt(24)
	s_waitcnt lgkmcnt(0)
	s_barrier
	s_waitcnt lgkmcnt(0)
	s_setprio 0
	v_mfma_f32_16x16x32_bf16 v[140:143], v[2:5], v[62:65], 0
	v_mfma_f32_16x16x32_bf16 v[154:157], v[2:5], v[94:97], 0
	v_mfma_f32_16x16x32_bf16 v[162:165], v[2:5], v[110:113], 0
	v_mfma_f32_16x16x32_bf16 v[2:5], v[2:5], v[122:125], 0
	v_mfma_f32_16x16x32_bf16 v[140:143], v[6:9], v[90:93], v[140:143]
	v_mfma_f32_16x16x32_bf16 v[154:157], v[6:9], v[106:109], v[154:157]
	v_mfma_f32_16x16x32_bf16 v[162:165], v[6:9], v[118:121], v[162:165]
	v_mfma_f32_16x16x32_bf16 v[2:5], v[6:9], v[126:129], v[2:5]
	v_mfma_f32_16x16x32_bf16 v[6:9], v[10:13], v[122:125], 0
	v_mfma_f32_16x16x32_bf16 v[150:153], v[10:13], v[62:65], 0
	v_mfma_f32_16x16x32_bf16 v[158:161], v[10:13], v[94:97], 0
	v_mfma_f32_16x16x32_bf16 v[166:169], v[10:13], v[110:113], 0
	v_mfma_f32_16x16x32_bf16 v[6:9], v[14:17], v[126:129], v[6:9]
	v_mfma_f32_16x16x32_bf16 v[150:153], v[14:17], v[90:93], v[150:153]
	v_mfma_f32_16x16x32_bf16 v[158:161], v[14:17], v[106:109], v[158:161]
	v_mfma_f32_16x16x32_bf16 v[166:169], v[14:17], v[118:121], v[166:169]
	v_mfma_f32_16x16x32_bf16 v[10:13], v[18:21], v[62:65], 0
	v_mfma_f32_16x16x32_bf16 v[170:173], v[22:25], v[90:93], v[10:13]
	v_mfma_f32_16x16x32_bf16 v[10:13], v[26:29], v[62:65], 0
	v_mfma_f32_16x16x32_bf16 v[174:177], v[30:33], v[90:93], v[10:13]
	v_mfma_f32_16x16x32_bf16 v[10:13], v[18:21], v[94:97], 0
	v_mfma_f32_16x16x32_bf16 v[178:181], v[22:25], v[106:109], v[10:13]
	v_mfma_f32_16x16x32_bf16 v[10:13], v[26:29], v[94:97], 0
	v_mfma_f32_16x16x32_bf16 v[182:185], v[30:33], v[106:109], v[10:13]
	v_mfma_f32_16x16x32_bf16 v[10:13], v[18:21], v[110:113], 0
	v_mfma_f32_16x16x32_bf16 v[186:189], v[22:25], v[118:121], v[10:13]
	v_mfma_f32_16x16x32_bf16 v[10:13], v[26:29], v[110:113], 0
	v_mfma_f32_16x16x32_bf16 v[190:193], v[30:33], v[118:121], v[10:13]
	v_mfma_f32_16x16x32_bf16 v[10:13], v[18:21], v[122:125], 0
	v_mfma_f32_16x16x32_bf16 v[194:197], v[22:25], v[126:129], v[10:13]
	v_mfma_f32_16x16x32_bf16 v[10:13], v[26:29], v[122:125], 0
	v_mfma_f32_16x16x32_bf16 v[198:201], v[30:33], v[126:129], v[10:13]
	s_setprio 1
	s_barrier
	s_nop 5
	ds_read_b128 v[10:13], v147
	ds_read_b128 v[14:17], v147 offset:1024
	ds_read_b128 v[18:21], v147 offset:2048
	ds_read_b128 v[22:25], v147 offset:3072
	ds_read_b128 v[202:205], v148
	ds_read_b128 v[206:209], v148 offset:1024
	ds_read_b128 v[210:213], v148 offset:2048
	ds_read_b128 v[214:217], v148 offset:3072
	s_mov_b32 m0, s53
	v_lshl_add_u64 v[90:91], v[242:243], 0, s[24:25]
	ds_read_b128 v[26:29], v146 offset:32768
	ds_read_b128 v[30:33], v146 offset:33792
	ds_read_b128 v[62:65], v146 offset:34816
	ds_read_b128 v[218:221], v146 offset:35840
	ds_read_b128 v[222:225], v146 offset:36864
	ds_read_b128 v[226:229], v146 offset:37888
	ds_read_b128 v[230:233], v146 offset:38912
	ds_read_b128 v[234:237], v146 offset:39936
	global_load_lds_dwordx4 v[90:91], off
	v_lshl_add_u64 v[90:91], v[242:243], 0, s[26:27]
	s_mov_b32 m0, s54
	s_nop 0
	global_load_lds_dwordx4 v[90:91], off
	s_waitcnt vmcnt(8)
	s_waitcnt lgkmcnt(0)
	s_barrier
	s_waitcnt lgkmcnt(0)
	s_setprio 0
	v_mfma_f32_16x16x32_bf16 v[66:69], v[10:13], v[26:29], v[66:69]
	v_mfma_f32_16x16x32_bf16 v[126:129], v[14:17], v[30:33], v[66:69]
	v_mfma_f32_16x16x32_bf16 v[66:69], v[18:21], v[26:29], v[70:73]
	v_mfma_f32_16x16x32_bf16 v[122:125], v[22:25], v[30:33], v[66:69]
	v_mfma_f32_16x16x32_bf16 v[66:69], v[10:13], v[62:65], v[74:77]
	v_mfma_f32_16x16x32_bf16 v[110:113], v[14:17], v[218:221], v[66:69]
	v_mfma_f32_16x16x32_bf16 v[66:69], v[18:21], v[62:65], v[78:81]
	v_mfma_f32_16x16x32_bf16 v[106:109], v[22:25], v[218:221], v[66:69]
	v_mfma_f32_16x16x32_bf16 v[66:69], v[10:13], v[222:225], v[82:85]
	v_mfma_f32_16x16x32_bf16 v[94:97], v[14:17], v[226:229], v[66:69]
	v_mfma_f32_16x16x32_bf16 v[66:69], v[18:21], v[222:225], v[86:89]
	v_mfma_f32_16x16x32_bf16 v[90:93], v[22:25], v[226:229], v[66:69]
	v_mfma_f32_16x16x32_bf16 v[66:69], v[10:13], v[230:233], v[98:101]
	v_mfma_f32_16x16x32_bf16 v[78:81], v[14:17], v[234:237], v[66:69]
	v_mfma_f32_16x16x32_bf16 v[66:69], v[18:21], v[230:233], v[102:105]
	v_mfma_f32_16x16x32_bf16 v[74:77], v[22:25], v[234:237], v[66:69]
	v_mfma_f32_16x16x32_bf16 v[66:69], v[202:205], v[26:29], v[114:117]
	v_mfma_f32_16x16x32_bf16 v[26:29], v[210:213], v[26:29], v[34:37]
	v_mfma_f32_16x16x32_bf16 v[114:117], v[214:217], v[30:33], v[26:29]
	v_mfma_f32_16x16x32_bf16 v[26:29], v[202:205], v[62:65], v[38:41]
	v_mfma_f32_16x16x32_bf16 v[102:105], v[206:209], v[218:221], v[26:29]
	v_mfma_f32_16x16x32_bf16 v[26:29], v[210:213], v[62:65], v[42:45]
	v_mfma_f32_16x16x32_bf16 v[98:101], v[214:217], v[218:221], v[26:29]
	v_mfma_f32_16x16x32_bf16 v[26:29], v[202:205], v[222:225], v[46:49]
	v_mfma_f32_16x16x32_bf16 v[86:89], v[206:209], v[226:229], v[26:29]
	v_mfma_f32_16x16x32_bf16 v[26:29], v[210:213], v[222:225], v[50:53]
	v_mfma_f32_16x16x32_bf16 v[82:85], v[214:217], v[226:229], v[26:29]
	v_mfma_f32_16x16x32_bf16 v[26:29], v[202:205], v[230:233], v[54:57]
	v_mfma_f32_16x16x32_bf16 v[70:73], v[206:209], v[234:237], v[26:29]
	v_mfma_f32_16x16x32_bf16 v[26:29], v[210:213], v[230:233], v[58:61]
	v_mfma_f32_16x16x32_bf16 v[118:121], v[206:209], v[30:33], v[66:69]
	v_mfma_f32_16x16x32_bf16 v[66:69], v[214:217], v[234:237], v[26:29]
	s_setprio 1
	s_barrier
	s_add_i32 s50, s3, s46
	s_nop 3
	v_lshl_add_u64 v[26:27], v[244:245], 0, s[28:29]
	s_mov_b32 m0, s50
	s_add_i32 s51, s50, 0x2000
	ds_read_b128 v[34:37], v146 offset:49152
	ds_read_b128 v[38:41], v146 offset:50176
	ds_read_b128 v[218:221], v146 offset:51200
	ds_read_b128 v[222:225], v146 offset:52224
	ds_read_b128 v[226:229], v146 offset:53248
	ds_read_b128 v[230:233], v146 offset:54272
	ds_read_b128 v[234:237], v146 offset:55296
	ds_read_b128 v[238:241], v146 offset:56320
	global_load_lds_dwordx4 v[26:27], off
	v_lshl_add_u64 v[26:27], v[244:245], 0, s[30:31]
	s_mov_b32 m0, s51
	s_mov_b64 s[0:1], 0x80180
	s_add_i32 s33, s42, s46
	global_load_lds_dwordx4 v[26:27], off
	v_lshl_add_u64 v[26:27], v[244:245], 0, s[0:1]
	s_mov_b32 m0, s33
	s_mov_b64 s[0:1], 0xc0180
	s_add_i32 s56, s33, 0x2000
	global_load_lds_dwordx4 v[26:27], off
	v_lshl_add_u64 v[26:27], v[244:245], 0, s[0:1]
	s_mov_b32 m0, s56
	s_nop 0
	global_load_lds_dwordx4 v[26:27], off
	v_lshl_add_u64 v[26:27], v[242:243], 0, s[28:29]
	s_mov_b32 m0, s55
	s_nop 0
	global_load_lds_dwordx4 v[26:27], off
	v_lshl_add_u64 v[26:27], v[242:243], 0, s[30:31]
	s_mov_b32 m0, s62
	s_nop 0
	global_load_lds_dwordx4 v[26:27], off
	s_waitcnt vmcnt(8)
	s_waitcnt lgkmcnt(0)
	s_barrier
	s_waitcnt lgkmcnt(0)
	s_setprio 0
	v_mfma_f32_16x16x32_bf16 v[26:29], v[10:13], v[34:37], v[140:143]
	v_mfma_f32_16x16x32_bf16 v[62:65], v[14:17], v[38:41], v[26:29]
	v_mfma_f32_16x16x32_bf16 v[26:29], v[18:21], v[34:37], v[150:153]
	v_mfma_f32_16x16x32_bf16 v[58:61], v[22:25], v[38:41], v[26:29]
	v_mfma_f32_16x16x32_bf16 v[26:29], v[10:13], v[218:221], v[154:157]
	v_mfma_f32_16x16x32_bf16 v[46:49], v[14:17], v[222:225], v[26:29]
	v_mfma_f32_16x16x32_bf16 v[26:29], v[18:21], v[218:221], v[158:161]
	v_mfma_f32_16x16x32_bf16 v[42:45], v[22:25], v[222:225], v[26:29]
	v_mfma_f32_16x16x32_bf16 v[26:29], v[10:13], v[226:229], v[162:165]
	v_mfma_f32_16x16x32_bf16 v[2:5], v[10:13], v[234:237], v[2:5]
	v_mfma_f32_16x16x32_bf16 v[30:33], v[14:17], v[230:233], v[26:29]
	v_mfma_f32_16x16x32_bf16 v[26:29], v[18:21], v[226:229], v[166:169]
	v_mfma_f32_16x16x32_bf16 v[14:17], v[14:17], v[238:241], v[2:5]
	v_mfma_f32_16x16x32_bf16 v[2:5], v[18:21], v[234:237], v[6:9]
	v_mfma_f32_16x16x32_bf16 v[26:29], v[22:25], v[230:233], v[26:29]
	v_mfma_f32_16x16x32_bf16 v[10:13], v[22:25], v[238:241], v[2:5]
	v_mfma_f32_16x16x32_bf16 v[2:5], v[202:205], v[34:37], v[170:173]
	v_mfma_f32_16x16x32_bf16 v[54:57], v[206:209], v[38:41], v[2:5]
	v_mfma_f32_16x16x32_bf16 v[2:5], v[210:213], v[34:37], v[174:177]
	v_mfma_f32_16x16x32_bf16 v[50:53], v[214:217], v[38:41], v[2:5]
	v_mfma_f32_16x16x32_bf16 v[2:5], v[202:205], v[218:221], v[178:181]
	v_mfma_f32_16x16x32_bf16 v[38:41], v[206:209], v[222:225], v[2:5]
	v_mfma_f32_16x16x32_bf16 v[2:5], v[210:213], v[218:221], v[182:185]
	v_mfma_f32_16x16x32_bf16 v[34:37], v[214:217], v[222:225], v[2:5]
	v_mfma_f32_16x16x32_bf16 v[2:5], v[202:205], v[226:229], v[186:189]
	v_mfma_f32_16x16x32_bf16 v[22:25], v[206:209], v[230:233], v[2:5]
	v_mfma_f32_16x16x32_bf16 v[2:5], v[210:213], v[226:229], v[190:193]
	v_mfma_f32_16x16x32_bf16 v[18:21], v[214:217], v[230:233], v[2:5]
	v_mfma_f32_16x16x32_bf16 v[2:5], v[202:205], v[234:237], v[194:197]
	v_mfma_f32_16x16x32_bf16 v[6:9], v[206:209], v[238:241], v[2:5]
	v_mfma_f32_16x16x32_bf16 v[2:5], v[210:213], v[234:237], v[198:201]
	v_mfma_f32_16x16x32_bf16 v[2:5], v[214:217], v[238:241], v[2:5]
	s_setprio 1
	s_barrier
	s_add_u32 s78, s78, 0x80180
	s_addc_u32 s79, s79, 0
	s_add_u32 s57, s76, 0x200
	s_addc_u32 s76, s77, 0
	s_mov_b32 s77, 0
.LBB0_1646:
	ds_read_b128 v[140:143], v144
	ds_read_b128 v[150:153], v144 offset:1024
	ds_read_b128 v[154:157], v144 offset:2048
	ds_read_b128 v[158:161], v144 offset:3072
	ds_read_b128 v[162:165], v145
	ds_read_b128 v[166:169], v145 offset:1024
	ds_read_b128 v[170:173], v145 offset:2048
	ds_read_b128 v[174:177], v145 offset:3072
	s_add_u32 s0, s78, 0xfff80080
	s_addc_u32 s1, s79, -1
	s_cmp_eq_u32 s77, 28
	s_cselect_b32 s1, s11, s1
	s_cselect_b32 s0, s14, s0
	s_cselect_b32 s65, s69, s76
	s_cselect_b32 s64, s71, s57
	s_mov_b32 m0, s97
	v_lshl_add_u64 v[210:211], s[78:79], 0, v[134:135]
	ds_read_b128 v[178:181], v146
	ds_read_b128 v[182:185], v146 offset:1024
	ds_read_b128 v[186:189], v146 offset:2048
	ds_read_b128 v[190:193], v146 offset:3072
	ds_read_b128 v[194:197], v146 offset:4096
	ds_read_b128 v[198:201], v146 offset:5120
	ds_read_b128 v[202:205], v146 offset:6144
	ds_read_b128 v[206:209], v146 offset:7168
	global_load_lds_dwordx4 v[210:211], off
	v_lshl_add_u64 v[210:211], v[210:211], 0, s[34:35]
	s_mov_b32 m0, s47
	s_nop 0
	global_load_lds_dwordx4 v[210:211], off
	s_waitcnt vmcnt(8)
	s_waitcnt lgkmcnt(0)
	s_barrier
	s_waitcnt lgkmcnt(0)
	s_setprio 0
	v_mfma_f32_16x16x32_bf16 v[126:129], v[140:143], v[178:181], v[126:129]
	v_mfma_f32_16x16x32_bf16 v[122:125], v[154:157], v[178:181], v[122:125]
	v_mfma_f32_16x16x32_bf16 v[110:113], v[140:143], v[186:189], v[110:113]
	v_mfma_f32_16x16x32_bf16 v[106:109], v[154:157], v[186:189], v[106:109]
	v_mfma_f32_16x16x32_bf16 v[94:97], v[140:143], v[194:197], v[94:97]
	v_mfma_f32_16x16x32_bf16 v[90:93], v[154:157], v[194:197], v[90:93]
	v_mfma_f32_16x16x32_bf16 v[78:81], v[140:143], v[202:205], v[78:81]
	v_mfma_f32_16x16x32_bf16 v[74:77], v[154:157], v[202:205], v[74:77]
	v_mfma_f32_16x16x32_bf16 v[126:129], v[150:153], v[182:185], v[126:129]
	v_mfma_f32_16x16x32_bf16 v[122:125], v[158:161], v[182:185], v[122:125]
	v_mfma_f32_16x16x32_bf16 v[110:113], v[150:153], v[190:193], v[110:113]
	v_mfma_f32_16x16x32_bf16 v[106:109], v[158:161], v[190:193], v[106:109]
	v_mfma_f32_16x16x32_bf16 v[94:97], v[150:153], v[198:201], v[94:97]
	v_mfma_f32_16x16x32_bf16 v[90:93], v[158:161], v[198:201], v[90:93]
	v_mfma_f32_16x16x32_bf16 v[78:81], v[150:153], v[206:209], v[78:81]
	v_mfma_f32_16x16x32_bf16 v[74:77], v[158:161], v[206:209], v[74:77]
	v_mfma_f32_16x16x32_bf16 v[118:121], v[162:165], v[178:181], v[118:121]
	v_mfma_f32_16x16x32_bf16 v[114:117], v[170:173], v[178:181], v[114:117]
	v_mfma_f32_16x16x32_bf16 v[102:105], v[162:165], v[186:189], v[102:105]
	v_mfma_f32_16x16x32_bf16 v[98:101], v[170:173], v[186:189], v[98:101]
	v_mfma_f32_16x16x32_bf16 v[86:89], v[162:165], v[194:197], v[86:89]
	v_mfma_f32_16x16x32_bf16 v[82:85], v[170:173], v[194:197], v[82:85]
	v_mfma_f32_16x16x32_bf16 v[70:73], v[162:165], v[202:205], v[70:73]
	v_mfma_f32_16x16x32_bf16 v[66:69], v[170:173], v[202:205], v[66:69]
	v_mfma_f32_16x16x32_bf16 v[118:121], v[166:169], v[182:185], v[118:121]
	v_mfma_f32_16x16x32_bf16 v[114:117], v[174:177], v[182:185], v[114:117]
	v_mfma_f32_16x16x32_bf16 v[102:105], v[166:169], v[190:193], v[102:105]
	v_mfma_f32_16x16x32_bf16 v[98:101], v[174:177], v[190:193], v[98:101]
	v_mfma_f32_16x16x32_bf16 v[86:89], v[166:169], v[198:201], v[86:89]
	v_mfma_f32_16x16x32_bf16 v[82:85], v[174:177], v[198:201], v[82:85]
	v_mfma_f32_16x16x32_bf16 v[70:73], v[166:169], v[206:209], v[70:73]
	v_mfma_f32_16x16x32_bf16 v[66:69], v[174:177], v[206:209], v[66:69]
	s_setprio 1
	s_barrier
	s_mov_b32 m0, s81
	v_lshl_add_u64 v[210:211], s[64:65], 0, v[132:133]
	ds_read_b128 v[178:181], v146 offset:16384
	ds_read_b128 v[182:185], v146 offset:17408
	ds_read_b128 v[186:189], v146 offset:18432
	ds_read_b128 v[190:193], v146 offset:19456
	ds_read_b128 v[194:197], v146 offset:20480
	ds_read_b128 v[198:201], v146 offset:21504
	ds_read_b128 v[202:205], v146 offset:22528
	ds_read_b128 v[206:209], v146 offset:23552
	global_load_lds_dwordx4 v[210:211], off
	v_lshl_add_u64 v[212:213], v[210:211], 0, s[34:35]
	s_mov_b32 m0, s82
	s_nop 0
	global_load_lds_dwordx4 v[212:213], off
	v_lshl_add_u64 v[212:213], v[210:211], 0, s[36:37]
	s_mov_b32 m0, s83
	s_nop 0
	global_load_lds_dwordx4 v[212:213], off
	v_lshl_add_u64 v[212:213], v[210:211], 0, s[38:39]
	s_mov_b32 m0, s84
	s_nop 0
	global_load_lds_dwordx4 v[212:213], off
	v_lshl_add_u64 v[212:213], s[0:1], 0, v[130:131]
	s_mov_b32 m0, s87
	v_lshl_add_u64 v[214:215], v[212:213], 0, s[34:35]
	global_load_lds_dwordx4 v[212:213], off
	s_mov_b32 m0, s52
	s_nop 0
	global_load_lds_dwordx4 v[214:215], off
	s_waitcnt vmcnt(8)
	s_waitcnt lgkmcnt(0)
	s_barrier
	s_waitcnt lgkmcnt(0)
	s_setprio 0
	v_mfma_f32_16x16x32_bf16 v[62:65], v[140:143], v[178:181], v[62:65]
	v_mfma_f32_16x16x32_bf16 v[58:61], v[154:157], v[178:181], v[58:61]
	v_mfma_f32_16x16x32_bf16 v[46:49], v[140:143], v[186:189], v[46:49]
	v_mfma_f32_16x16x32_bf16 v[42:45], v[154:157], v[186:189], v[42:45]
	v_mfma_f32_16x16x32_bf16 v[30:33], v[140:143], v[194:197], v[30:33]
	v_mfma_f32_16x16x32_bf16 v[26:29], v[154:157], v[194:197], v[26:29]
	v_mfma_f32_16x16x32_bf16 v[14:17], v[140:143], v[202:205], v[14:17]
	v_mfma_f32_16x16x32_bf16 v[10:13], v[154:157], v[202:205], v[10:13]
	v_mfma_f32_16x16x32_bf16 v[62:65], v[150:153], v[182:185], v[62:65]
	v_mfma_f32_16x16x32_bf16 v[58:61], v[158:161], v[182:185], v[58:61]
	v_mfma_f32_16x16x32_bf16 v[46:49], v[150:153], v[190:193], v[46:49]
	v_mfma_f32_16x16x32_bf16 v[42:45], v[158:161], v[190:193], v[42:45]
	v_mfma_f32_16x16x32_bf16 v[30:33], v[150:153], v[198:201], v[30:33]
	v_mfma_f32_16x16x32_bf16 v[26:29], v[158:161], v[198:201], v[26:29]
	v_mfma_f32_16x16x32_bf16 v[14:17], v[150:153], v[206:209], v[14:17]
	v_mfma_f32_16x16x32_bf16 v[10:13], v[158:161], v[206:209], v[10:13]
	v_mfma_f32_16x16x32_bf16 v[54:57], v[162:165], v[178:181], v[54:57]
	v_mfma_f32_16x16x32_bf16 v[50:53], v[170:173], v[178:181], v[50:53]
	v_mfma_f32_16x16x32_bf16 v[38:41], v[162:165], v[186:189], v[38:41]
	v_mfma_f32_16x16x32_bf16 v[34:37], v[170:173], v[186:189], v[34:37]
	v_mfma_f32_16x16x32_bf16 v[22:25], v[162:165], v[194:197], v[22:25]
	v_mfma_f32_16x16x32_bf16 v[18:21], v[170:173], v[194:197], v[18:21]
	v_mfma_f32_16x16x32_bf16 v[6:9], v[162:165], v[202:205], v[6:9]
	v_mfma_f32_16x16x32_bf16 v[2:5], v[170:173], v[202:205], v[2:5]
	v_mfma_f32_16x16x32_bf16 v[54:57], v[166:169], v[182:185], v[54:57]
	v_mfma_f32_16x16x32_bf16 v[50:53], v[174:177], v[182:185], v[50:53]
	v_mfma_f32_16x16x32_bf16 v[38:41], v[166:169], v[190:193], v[38:41]
	v_mfma_f32_16x16x32_bf16 v[34:37], v[174:177], v[190:193], v[34:37]
	v_mfma_f32_16x16x32_bf16 v[22:25], v[166:169], v[198:201], v[22:25]
	v_mfma_f32_16x16x32_bf16 v[18:21], v[174:177], v[198:201], v[18:21]
	v_mfma_f32_16x16x32_bf16 v[6:9], v[166:169], v[206:209], v[6:9]
	v_mfma_f32_16x16x32_bf16 v[2:5], v[174:177], v[206:209], v[2:5]
	s_setprio 1
	s_barrier
	ds_read_b128 v[140:143], v147
	ds_read_b128 v[150:153], v147 offset:1024
	ds_read_b128 v[154:157], v147 offset:2048
	ds_read_b128 v[158:161], v147 offset:3072
	ds_read_b128 v[162:165], v148
	ds_read_b128 v[166:169], v148 offset:1024
	ds_read_b128 v[170:173], v148 offset:2048
	ds_read_b128 v[174:177], v148 offset:3072
	s_mov_b32 m0, s53
	v_lshl_add_u64 v[214:215], v[212:213], 0, s[36:37]
	ds_read_b128 v[178:181], v146 offset:32768
	ds_read_b128 v[182:185], v146 offset:33792
	ds_read_b128 v[186:189], v146 offset:34816
	ds_read_b128 v[190:193], v146 offset:35840
	ds_read_b128 v[194:197], v146 offset:36864
	ds_read_b128 v[198:201], v146 offset:37888
	ds_read_b128 v[202:205], v146 offset:38912
	ds_read_b128 v[206:209], v146 offset:39936
	global_load_lds_dwordx4 v[214:215], off
	v_lshl_add_u64 v[214:215], v[212:213], 0, s[38:39]
	s_mov_b32 m0, s54
	s_nop 0
	global_load_lds_dwordx4 v[214:215], off
	s_waitcnt vmcnt(8)
	s_waitcnt lgkmcnt(0)
	s_barrier
	s_waitcnt lgkmcnt(0)
	s_setprio 0
	v_mfma_f32_16x16x32_bf16 v[126:129], v[140:143], v[178:181], v[126:129]
	v_mfma_f32_16x16x32_bf16 v[122:125], v[154:157], v[178:181], v[122:125]
	v_mfma_f32_16x16x32_bf16 v[110:113], v[140:143], v[186:189], v[110:113]
	v_mfma_f32_16x16x32_bf16 v[106:109], v[154:157], v[186:189], v[106:109]
	v_mfma_f32_16x16x32_bf16 v[94:97], v[140:143], v[194:197], v[94:97]
	v_mfma_f32_16x16x32_bf16 v[90:93], v[154:157], v[194:197], v[90:93]
	v_mfma_f32_16x16x32_bf16 v[78:81], v[140:143], v[202:205], v[78:81]
	v_mfma_f32_16x16x32_bf16 v[74:77], v[154:157], v[202:205], v[74:77]
	v_mfma_f32_16x16x32_bf16 v[126:129], v[150:153], v[182:185], v[126:129]
	v_mfma_f32_16x16x32_bf16 v[122:125], v[158:161], v[182:185], v[122:125]
	v_mfma_f32_16x16x32_bf16 v[110:113], v[150:153], v[190:193], v[110:113]
	v_mfma_f32_16x16x32_bf16 v[106:109], v[158:161], v[190:193], v[106:109]
	v_mfma_f32_16x16x32_bf16 v[94:97], v[150:153], v[198:201], v[94:97]
	v_mfma_f32_16x16x32_bf16 v[90:93], v[158:161], v[198:201], v[90:93]
	v_mfma_f32_16x16x32_bf16 v[78:81], v[150:153], v[206:209], v[78:81]
	v_mfma_f32_16x16x32_bf16 v[74:77], v[158:161], v[206:209], v[74:77]
	v_mfma_f32_16x16x32_bf16 v[118:121], v[162:165], v[178:181], v[118:121]
	v_mfma_f32_16x16x32_bf16 v[114:117], v[170:173], v[178:181], v[114:117]
	v_mfma_f32_16x16x32_bf16 v[102:105], v[162:165], v[186:189], v[102:105]
	v_mfma_f32_16x16x32_bf16 v[98:101], v[170:173], v[186:189], v[98:101]
	v_mfma_f32_16x16x32_bf16 v[86:89], v[162:165], v[194:197], v[86:89]
	v_mfma_f32_16x16x32_bf16 v[82:85], v[170:173], v[194:197], v[82:85]
	v_mfma_f32_16x16x32_bf16 v[70:73], v[162:165], v[202:205], v[70:73]
	v_mfma_f32_16x16x32_bf16 v[66:69], v[170:173], v[202:205], v[66:69]
	v_mfma_f32_16x16x32_bf16 v[118:121], v[166:169], v[182:185], v[118:121]
	v_mfma_f32_16x16x32_bf16 v[114:117], v[174:177], v[182:185], v[114:117]
	v_mfma_f32_16x16x32_bf16 v[102:105], v[166:169], v[190:193], v[102:105]
	v_mfma_f32_16x16x32_bf16 v[98:101], v[174:177], v[190:193], v[98:101]
	v_mfma_f32_16x16x32_bf16 v[86:89], v[166:169], v[198:201], v[86:89]
	v_mfma_f32_16x16x32_bf16 v[82:85], v[174:177], v[198:201], v[82:85]
	v_mfma_f32_16x16x32_bf16 v[70:73], v[166:169], v[206:209], v[70:73]
	v_mfma_f32_16x16x32_bf16 v[66:69], v[174:177], v[206:209], v[66:69]
	s_setprio 1
	s_barrier
; #define PG8_WAIT_V(n) asm volatile("s_waitcnt vmcnt(" #n ")" ::: "memory")
; template <class Epi, class Sched, bool ALIGN_EPI = true, bool SP2 = true, bool FULLLINE = false, bool NOSTAGE = false, bool FP8 = false>
; __device__ __forceinline__ void gemm_phase(PG8_LAS unsigned char* lds, const Gemm g, const Sched& S, const Epi& E) {
;     ...
;         static_assert(SP2, "only the SP2 loop is kept");
;         { const int t = 0; if constexpr (Epi::NST == 16) PG8_ITER(PG8_WAIT_V(24)); else if constexpr (Epi::NST == 8) PG8_ITER(PG8_WAIT_V(16)); else PG8_ITER(PG8_WAIT_V(8)); }
;         for (int t = 2; t < nt; t += 2) PG8_ITER(PG8_WAIT_V(8));
	s_mov_b32 m0, s50
	v_lshl_add_u64 v[214:215], v[210:211], 0, s[40:41]
	ds_read_b128 v[178:181], v146 offset:49152
	ds_read_b128 v[182:185], v146 offset:50176
	ds_read_b128 v[186:189], v146 offset:51200
	ds_read_b128 v[190:193], v146 offset:52224
	ds_read_b128 v[194:197], v146 offset:53248
	ds_read_b128 v[198:201], v146 offset:54272
	ds_read_b128 v[202:205], v146 offset:55296
	ds_read_b128 v[206:209], v146 offset:56320
	global_load_lds_dwordx4 v[214:215], off
	v_lshl_add_u64 v[214:215], v[210:211], 0, s[66:67]
	s_mov_b32 m0, s51
	s_nop 0
	global_load_lds_dwordx4 v[214:215], off
	v_lshl_add_u64 v[214:215], v[210:211], 0, s[16:17]
	s_mov_b32 m0, s33
	v_lshl_add_u64 v[210:211], v[210:211], 0, s[18:19]
	global_load_lds_dwordx4 v[214:215], off
	s_mov_b32 m0, s56
	s_nop 0
	global_load_lds_dwordx4 v[210:211], off
	v_lshl_add_u64 v[210:211], v[212:213], 0, s[40:41]
	s_mov_b32 m0, s55
	s_nop 0
	global_load_lds_dwordx4 v[210:211], off
	v_lshl_add_u64 v[210:211], v[212:213], 0, s[66:67]
	s_mov_b32 m0, s62
	s_nop 0
	global_load_lds_dwordx4 v[210:211], off
	s_waitcnt vmcnt(8)
	s_waitcnt lgkmcnt(0)
	s_barrier
	s_waitcnt lgkmcnt(0)
	s_setprio 0
	v_mfma_f32_16x16x32_bf16 v[62:65], v[140:143], v[178:181], v[62:65]
	v_mfma_f32_16x16x32_bf16 v[58:61], v[154:157], v[178:181], v[58:61]
	v_mfma_f32_16x16x32_bf16 v[46:49], v[140:143], v[186:189], v[46:49]
	v_mfma_f32_16x16x32_bf16 v[42:45], v[154:157], v[186:189], v[42:45]
	v_mfma_f32_16x16x32_bf16 v[30:33], v[140:143], v[194:197], v[30:33]
	v_mfma_f32_16x16x32_bf16 v[26:29], v[154:157], v[194:197], v[26:29]
	v_mfma_f32_16x16x32_bf16 v[14:17], v[140:143], v[202:205], v[14:17]
	v_mfma_f32_16x16x32_bf16 v[10:13], v[154:157], v[202:205], v[10:13]
	v_mfma_f32_16x16x32_bf16 v[62:65], v[150:153], v[182:185], v[62:65]
	v_mfma_f32_16x16x32_bf16 v[58:61], v[158:161], v[182:185], v[58:61]
	v_mfma_f32_16x16x32_bf16 v[46:49], v[150:153], v[190:193], v[46:49]
	v_mfma_f32_16x16x32_bf16 v[42:45], v[158:161], v[190:193], v[42:45]
	v_mfma_f32_16x16x32_bf16 v[30:33], v[150:153], v[198:201], v[30:33]
	v_mfma_f32_16x16x32_bf16 v[26:29], v[158:161], v[198:201], v[26:29]
	v_mfma_f32_16x16x32_bf16 v[14:17], v[150:153], v[206:209], v[14:17]
	v_mfma_f32_16x16x32_bf16 v[10:13], v[158:161], v[206:209], v[10:13]
	v_mfma_f32_16x16x32_bf16 v[54:57], v[162:165], v[178:181], v[54:57]
	v_mfma_f32_16x16x32_bf16 v[50:53], v[170:173], v[178:181], v[50:53]
	v_mfma_f32_16x16x32_bf16 v[38:41], v[162:165], v[186:189], v[38:41]
	v_mfma_f32_16x16x32_bf16 v[34:37], v[170:173], v[186:189], v[34:37]
	v_mfma_f32_16x16x32_bf16 v[22:25], v[162:165], v[194:197], v[22:25]
	v_mfma_f32_16x16x32_bf16 v[18:21], v[170:173], v[194:197], v[18:21]
	v_mfma_f32_16x16x32_bf16 v[6:9], v[162:165], v[202:205], v[6:9]
	v_mfma_f32_16x16x32_bf16 v[2:5], v[170:173], v[202:205], v[2:5]
	v_mfma_f32_16x16x32_bf16 v[54:57], v[166:169], v[182:185], v[54:57]
	v_mfma_f32_16x16x32_bf16 v[50:53], v[174:177], v[182:185], v[50:53]
	v_mfma_f32_16x16x32_bf16 v[38:41], v[166:169], v[190:193], v[38:41]
	v_mfma_f32_16x16x32_bf16 v[34:37], v[174:177], v[190:193], v[34:37]
	v_mfma_f32_16x16x32_bf16 v[22:25], v[166:169], v[198:201], v[22:25]
	v_mfma_f32_16x16x32_bf16 v[18:21], v[174:177], v[198:201], v[18:21]
	v_mfma_f32_16x16x32_bf16 v[6:9], v[166:169], v[206:209], v[6:9]
	v_mfma_f32_16x16x32_bf16 v[2:5], v[174:177], v[206:209], v[2:5]
	s_setprio 1
	s_barrier
	s_add_i32 s77, s77, 2
	s_add_u32 s78, s78, 0x100
	s_addc_u32 s79, s79, 0
	s_add_u32 s57, s57, 0x100
	s_addc_u32 s76, s76, 0
	s_cmp_gt_u32 s77, 29
	s_cbranch_scc0 .LBB0_1646
	s_and_b64 vcc, exec, s[12:13]
	s_cbranch_vccz .LBB0_1649
	s_barrier

; template <class Epi, class Sched, bool ALIGN_EPI = true, bool SP2 = true, bool FULLLINE = false, bool NOSTAGE = false, bool FP8 = false>
; __device__ __forceinline__ void gemm_phase(PG8_LAS unsigned char* lds, const Gemm g, const Sched& S, const Epi& E) {
;     ...
;         const bool has_next = S.next(ui + 1, nxt);
;         const char* nA = has_next ? PG8_ABASE(nxt) : cA; const char* nB = has_next ? PG8_BBASE(nxt) : cB;
.LBB0_2096:
	s_ashr_i32 s67, s66, 31
	ds_read_b128 v[2:5], v1
	ds_read_b128 v[6:9], v1 offset:1024
	ds_read_b128 v[10:13], v1 offset:2048
	ds_read_b128 v[14:17], v1 offset:3072
	ds_read_b128 v[18:21], v192
	ds_read_b128 v[22:25], v192 offset:1024
	ds_read_b128 v[26:29], v192 offset:2048
	ds_read_b128 v[30:33], v192 offset:3072
	s_lshl_b64 s[0:1], s[66:67], 20
	s_add_u32 s68, s42, s0
	s_addc_u32 s69, s43, s1
	s_and_b64 s[0:1], s[8:9], exec
	s_cselect_b32 s67, s69, s75
	s_cselect_b32 s90, s68, s74
	s_ashr_i32 s41, s40, 31
	s_lshl_b64 s[0:1], s[40:41], 20
	s_add_u32 s70, s44, s0
	s_addc_u32 s71, s45, s1
	s_and_b64 s[0:1], s[8:9], exec
	s_cselect_b32 s41, s71, s77
	s_cselect_b32 s91, s70, s76
	v_lshl_add_u64 v[248:249], s[74:75], 0, v[170:171]
	s_mov_b32 m0, s85
	v_lshl_add_u64 v[66:67], v[248:249], 0, s[12:13]
	ds_read_b128 v[34:37], v193
	ds_read_b128 v[38:41], v193 offset:1024
	ds_read_b128 v[42:45], v193 offset:2048
	ds_read_b128 v[46:49], v193 offset:3072
	ds_read_b128 v[50:53], v193 offset:4096
	ds_read_b128 v[54:57], v193 offset:5120
	ds_read_b128 v[58:61], v193 offset:6144
	ds_read_b128 v[62:65], v193 offset:7168
	global_load_lds_dwordx4 v[66:67], off
	v_lshl_add_u64 v[66:67], v[248:249], 0, s[14:15]
	s_mov_b32 m0, s87
	s_nop 0
	global_load_lds_dwordx4 v[66:67], off
	s_waitcnt vmcnt(24)
	s_waitcnt lgkmcnt(0)
	s_barrier
	s_waitcnt lgkmcnt(0)
	s_setprio 0
	v_mfma_f32_16x16x32_bf16 v[66:69], v[2:5], v[34:37], 0
	v_mfma_f32_16x16x32_bf16 v[70:73], v[10:13], v[34:37], 0
	v_mfma_f32_16x16x32_bf16 v[78:81], v[10:13], v[42:45], 0
	v_mfma_f32_16x16x32_bf16 v[86:89], v[10:13], v[50:53], 0
	v_mfma_f32_16x16x32_bf16 v[66:69], v[6:9], v[38:41], v[66:69]
	v_mfma_f32_16x16x32_bf16 v[70:73], v[14:17], v[38:41], v[70:73]
	v_mfma_f32_16x16x32_bf16 v[74:77], v[2:5], v[42:45], 0
	v_mfma_f32_16x16x32_bf16 v[78:81], v[14:17], v[46:49], v[78:81]
	v_mfma_f32_16x16x32_bf16 v[82:85], v[2:5], v[50:53], 0
	v_mfma_f32_16x16x32_bf16 v[86:89], v[14:17], v[54:57], v[86:89]
	v_mfma_f32_16x16x32_bf16 v[90:93], v[2:5], v[58:61], 0
	v_mfma_f32_16x16x32_bf16 v[94:97], v[10:13], v[58:61], 0
	v_mfma_f32_16x16x32_bf16 v[74:77], v[6:9], v[46:49], v[74:77]
	v_mfma_f32_16x16x32_bf16 v[82:85], v[6:9], v[54:57], v[82:85]
	v_mfma_f32_16x16x32_bf16 v[90:93], v[6:9], v[62:65], v[90:93]
	v_mfma_f32_16x16x32_bf16 v[94:97], v[14:17], v[62:65], v[94:97]
	v_mfma_f32_16x16x32_bf16 v[98:101], v[18:21], v[34:37], 0
	v_mfma_f32_16x16x32_bf16 v[34:37], v[26:29], v[34:37], 0
	v_mfma_f32_16x16x32_bf16 v[98:101], v[22:25], v[38:41], v[98:101]
	v_mfma_f32_16x16x32_bf16 v[34:37], v[30:33], v[38:41], v[34:37]
	v_mfma_f32_16x16x32_bf16 v[38:41], v[18:21], v[42:45], 0
	v_mfma_f32_16x16x32_bf16 v[42:45], v[26:29], v[42:45], 0
	v_mfma_f32_16x16x32_bf16 v[38:41], v[22:25], v[46:49], v[38:41]
	v_mfma_f32_16x16x32_bf16 v[42:45], v[30:33], v[46:49], v[42:45]
	v_mfma_f32_16x16x32_bf16 v[46:49], v[18:21], v[50:53], 0
	v_mfma_f32_16x16x32_bf16 v[50:53], v[26:29], v[50:53], 0
	v_mfma_f32_16x16x32_bf16 v[46:49], v[22:25], v[54:57], v[46:49]
	v_mfma_f32_16x16x32_bf16 v[50:53], v[30:33], v[54:57], v[50:53]
	v_mfma_f32_16x16x32_bf16 v[54:57], v[18:21], v[58:61], 0
	v_mfma_f32_16x16x32_bf16 v[58:61], v[26:29], v[58:61], 0
	v_mfma_f32_16x16x32_bf16 v[54:57], v[22:25], v[62:65], v[54:57]
	v_mfma_f32_16x16x32_bf16 v[58:61], v[30:33], v[62:65], v[58:61]
	s_setprio 1
	s_barrier
	v_lshl_add_u64 v[250:251], s[76:77], 0, v[172:173]
	s_add_i32 s92, s83, s46
	v_lshl_add_u64 v[130:131], v[250:251], 0, s[16:17]
	s_mov_b32 m0, s92
	s_add_i32 s93, s92, 0x2000
	ds_read_b128 v[62:65], v193 offset:16384
	ds_read_b128 v[102:105], v193 offset:17408
	ds_read_b128 v[106:109], v193 offset:18432
	ds_read_b128 v[110:113], v193 offset:19456
	ds_read_b128 v[114:117], v193 offset:20480
	ds_read_b128 v[118:121], v193 offset:21504
	ds_read_b128 v[122:125], v193 offset:22528
	ds_read_b128 v[126:129], v193 offset:23552
	global_load_lds_dwordx4 v[130:131], off
	v_lshl_add_u64 v[130:131], v[250:251], 0, s[18:19]
	s_mov_b32 m0, s93
	s_add_i32 s94, s84, s46
	global_load_lds_dwordx4 v[130:131], off
	v_lshl_add_u64 v[130:131], v[250:251], 0, s[20:21]
	s_mov_b32 m0, s94
	s_add_i32 s95, s94, 0x2000
	global_load_lds_dwordx4 v[130:131], off
	v_lshl_add_u64 v[130:131], v[250:251], 0, s[22:23]
	s_mov_b32 m0, s95
	s_nop 0
	global_load_lds_dwordx4 v[130:131], off
	v_lshl_add_u64 v[130:131], v[248:249], 0, s[16:17]
	s_mov_b32 m0, s47
	s_nop 0
	global_load_lds_dwordx4 v[130:131], off
	v_lshl_add_u64 v[130:131], v[248:249], 0, s[18:19]
	s_mov_b32 m0, s52
	s_nop 0
	global_load_lds_dwordx4 v[130:131], off
	s_waitcnt vmcnt(24)
	s_waitcnt lgkmcnt(0)
	s_barrier
	s_waitcnt lgkmcnt(0)
	s_setprio 0
	v_mfma_f32_16x16x32_bf16 v[130:133], v[2:5], v[62:65], 0
	v_mfma_f32_16x16x32_bf16 v[138:141], v[6:9], v[102:105], v[130:133]
	v_mfma_f32_16x16x32_bf16 v[130:133], v[10:13], v[62:65], 0
	v_mfma_f32_16x16x32_bf16 v[150:153], v[14:17], v[102:105], v[130:133]
	v_mfma_f32_16x16x32_bf16 v[130:133], v[2:5], v[106:109], 0
	v_mfma_f32_16x16x32_bf16 v[154:157], v[6:9], v[110:113], v[130:133]
	v_mfma_f32_16x16x32_bf16 v[130:133], v[10:13], v[106:109], 0
	v_mfma_f32_16x16x32_bf16 v[158:161], v[14:17], v[110:113], v[130:133]
	v_mfma_f32_16x16x32_bf16 v[130:133], v[2:5], v[114:117], 0
	v_mfma_f32_16x16x32_bf16 v[2:5], v[2:5], v[122:125], 0
	v_mfma_f32_16x16x32_bf16 v[162:165], v[6:9], v[118:121], v[130:133]
	v_mfma_f32_16x16x32_bf16 v[2:5], v[6:9], v[126:129], v[2:5]
	v_mfma_f32_16x16x32_bf16 v[6:9], v[10:13], v[122:125], 0
	v_mfma_f32_16x16x32_bf16 v[130:133], v[10:13], v[114:117], 0
	v_mfma_f32_16x16x32_bf16 v[6:9], v[14:17], v[126:129], v[6:9]
	v_mfma_f32_16x16x32_bf16 v[166:169], v[14:17], v[118:121], v[130:133]
	v_mfma_f32_16x16x32_bf16 v[10:13], v[18:21], v[62:65], 0
	v_mfma_f32_16x16x32_bf16 v[180:183], v[22:25], v[102:105], v[10:13]
	v_mfma_f32_16x16x32_bf16 v[10:13], v[26:29], v[62:65], 0
	v_mfma_f32_16x16x32_bf16 v[184:187], v[30:33], v[102:105], v[10:13]
	v_mfma_f32_16x16x32_bf16 v[10:13], v[18:21], v[106:109], 0
	v_mfma_f32_16x16x32_bf16 v[188:191], v[22:25], v[110:113], v[10:13]
	v_mfma_f32_16x16x32_bf16 v[10:13], v[26:29], v[106:109], 0
	v_mfma_f32_16x16x32_bf16 v[196:199], v[30:33], v[110:113], v[10:13]
	v_mfma_f32_16x16x32_bf16 v[10:13], v[18:21], v[114:117], 0
	v_mfma_f32_16x16x32_bf16 v[200:203], v[22:25], v[118:121], v[10:13]
	v_mfma_f32_16x16x32_bf16 v[10:13], v[26:29], v[114:117], 0
	v_mfma_f32_16x16x32_bf16 v[204:207], v[30:33], v[118:121], v[10:13]
	v_mfma_f32_16x16x32_bf16 v[10:13], v[18:21], v[122:125], 0
	v_mfma_f32_16x16x32_bf16 v[208:211], v[22:25], v[126:129], v[10:13]
	v_mfma_f32_16x16x32_bf16 v[10:13], v[26:29], v[122:125], 0
	v_mfma_f32_16x16x32_bf16 v[212:215], v[30:33], v[126:129], v[10:13]
	s_setprio 1
	s_barrier
	s_nop 5
	ds_read_b128 v[10:13], v194
	ds_read_b128 v[14:17], v194 offset:1024
	ds_read_b128 v[18:21], v194 offset:2048
	ds_read_b128 v[22:25], v194 offset:3072
	ds_read_b128 v[216:219], v195
	ds_read_b128 v[220:223], v195 offset:1024
	ds_read_b128 v[224:227], v195 offset:2048
	ds_read_b128 v[228:231], v195 offset:3072
	s_mov_b32 m0, s53
	v_lshl_add_u64 v[106:107], v[248:249], 0, s[20:21]
	ds_read_b128 v[26:29], v193 offset:32768
	ds_read_b128 v[30:33], v193 offset:33792
	ds_read_b128 v[62:65], v193 offset:34816
	ds_read_b128 v[102:105], v193 offset:35840
	ds_read_b128 v[232:235], v193 offset:36864
	ds_read_b128 v[236:239], v193 offset:37888
	ds_read_b128 v[240:243], v193 offset:38912
	ds_read_b128 v[244:247], v193 offset:39936
	global_load_lds_dwordx4 v[106:107], off
	v_lshl_add_u64 v[106:107], v[248:249], 0, s[22:23]
	s_mov_b32 m0, s54
	s_nop 0
	global_load_lds_dwordx4 v[106:107], off
	s_waitcnt vmcnt(8)
	s_waitcnt lgkmcnt(0)
	s_barrier
	s_waitcnt lgkmcnt(0)
	s_setprio 0
	v_mfma_f32_16x16x32_bf16 v[66:69], v[10:13], v[26:29], v[66:69]
	v_mfma_f32_16x16x32_bf16 v[146:149], v[14:17], v[30:33], v[66:69]
	v_mfma_f32_16x16x32_bf16 v[66:69], v[18:21], v[26:29], v[70:73]
	v_mfma_f32_16x16x32_bf16 v[142:145], v[22:25], v[30:33], v[66:69]
	v_mfma_f32_16x16x32_bf16 v[66:69], v[10:13], v[62:65], v[74:77]
	v_mfma_f32_16x16x32_bf16 v[126:129], v[14:17], v[102:105], v[66:69]
	v_mfma_f32_16x16x32_bf16 v[66:69], v[18:21], v[62:65], v[78:81]
	v_mfma_f32_16x16x32_bf16 v[122:125], v[22:25], v[102:105], v[66:69]
	v_mfma_f32_16x16x32_bf16 v[66:69], v[10:13], v[232:235], v[82:85]
	v_mfma_f32_16x16x32_bf16 v[110:113], v[14:17], v[236:239], v[66:69]
	v_mfma_f32_16x16x32_bf16 v[66:69], v[18:21], v[232:235], v[86:89]
	v_mfma_f32_16x16x32_bf16 v[106:109], v[22:25], v[236:239], v[66:69]
	v_mfma_f32_16x16x32_bf16 v[66:69], v[10:13], v[240:243], v[90:93]
	v_mfma_f32_16x16x32_bf16 v[86:89], v[14:17], v[244:247], v[66:69]
	v_mfma_f32_16x16x32_bf16 v[66:69], v[18:21], v[240:243], v[94:97]
	v_mfma_f32_16x16x32_bf16 v[78:81], v[22:25], v[244:247], v[66:69]
	v_mfma_f32_16x16x32_bf16 v[66:69], v[216:219], v[26:29], v[98:101]
	v_mfma_f32_16x16x32_bf16 v[26:29], v[224:227], v[26:29], v[34:37]
	v_mfma_f32_16x16x32_bf16 v[130:133], v[228:231], v[30:33], v[26:29]
	v_mfma_f32_16x16x32_bf16 v[26:29], v[216:219], v[62:65], v[38:41]
	v_mfma_f32_16x16x32_bf16 v[118:121], v[220:223], v[102:105], v[26:29]
	v_mfma_f32_16x16x32_bf16 v[26:29], v[224:227], v[62:65], v[42:45]
	v_mfma_f32_16x16x32_bf16 v[114:117], v[228:231], v[102:105], v[26:29]
	v_mfma_f32_16x16x32_bf16 v[26:29], v[216:219], v[232:235], v[46:49]
	v_mfma_f32_16x16x32_bf16 v[102:105], v[220:223], v[236:239], v[26:29]
	v_mfma_f32_16x16x32_bf16 v[26:29], v[224:227], v[232:235], v[50:53]
	v_mfma_f32_16x16x32_bf16 v[98:101], v[228:231], v[236:239], v[26:29]
	v_mfma_f32_16x16x32_bf16 v[26:29], v[216:219], v[240:243], v[54:57]
	v_mfma_f32_16x16x32_bf16 v[70:73], v[220:223], v[244:247], v[26:29]
	v_mfma_f32_16x16x32_bf16 v[26:29], v[224:227], v[240:243], v[58:61]
	v_mfma_f32_16x16x32_bf16 v[134:137], v[220:223], v[30:33], v[66:69]
	v_mfma_f32_16x16x32_bf16 v[66:69], v[228:231], v[244:247], v[26:29]
	s_setprio 1
	s_barrier
	s_add_i32 s50, s88, s46
	s_nop 3
	v_lshl_add_u64 v[26:27], v[250:251], 0, s[24:25]
	s_mov_b32 m0, s50
	s_add_i32 s51, s50, 0x2000
	ds_read_b128 v[34:37], v193 offset:49152
	ds_read_b128 v[38:41], v193 offset:50176
	ds_read_b128 v[74:77], v193 offset:51200
	ds_read_b128 v[82:85], v193 offset:52224
	ds_read_b128 v[90:93], v193 offset:53248
	ds_read_b128 v[94:97], v193 offset:54272
	ds_read_b128 v[232:235], v193 offset:55296
	ds_read_b128 v[236:239], v193 offset:56320
	global_load_lds_dwordx4 v[26:27], off
	v_lshl_add_u64 v[26:27], v[250:251], 0, s[26:27]
	s_mov_b32 m0, s51
	s_mov_b64 s[0:1], 0x80180
	s_add_i32 s33, s89, s46
	global_load_lds_dwordx4 v[26:27], off
	v_lshl_add_u64 v[26:27], v[250:251], 0, s[0:1]
	s_mov_b32 m0, s33
	s_mov_b64 s[0:1], 0xc0180
	s_add_i32 s56, s33, 0x2000
	global_load_lds_dwordx4 v[26:27], off
	v_lshl_add_u64 v[26:27], v[250:251], 0, s[0:1]
	s_mov_b32 m0, s56
	s_nop 0
	global_load_lds_dwordx4 v[26:27], off
	v_lshl_add_u64 v[26:27], v[248:249], 0, s[24:25]
	s_mov_b32 m0, s55
	s_nop 0
	global_load_lds_dwordx4 v[26:27], off
	v_lshl_add_u64 v[26:27], v[248:249], 0, s[26:27]
	s_mov_b32 m0, s62
	s_nop 0
	global_load_lds_dwordx4 v[26:27], off
	s_waitcnt vmcnt(8)
	s_waitcnt lgkmcnt(0)
	s_barrier
	s_waitcnt lgkmcnt(0)
	s_setprio 0
	v_mfma_f32_16x16x32_bf16 v[26:29], v[10:13], v[34:37], v[138:141]
	v_mfma_f32_16x16x32_bf16 v[62:65], v[14:17], v[38:41], v[26:29]
	v_mfma_f32_16x16x32_bf16 v[26:29], v[18:21], v[34:37], v[150:153]
	v_mfma_f32_16x16x32_bf16 v[58:61], v[22:25], v[38:41], v[26:29]
	v_mfma_f32_16x16x32_bf16 v[26:29], v[10:13], v[74:77], v[154:157]
	v_mfma_f32_16x16x32_bf16 v[46:49], v[14:17], v[82:85], v[26:29]
	v_mfma_f32_16x16x32_bf16 v[26:29], v[18:21], v[74:77], v[158:161]
	v_mfma_f32_16x16x32_bf16 v[42:45], v[22:25], v[82:85], v[26:29]
	v_mfma_f32_16x16x32_bf16 v[26:29], v[10:13], v[90:93], v[162:165]
	v_mfma_f32_16x16x32_bf16 v[2:5], v[10:13], v[232:235], v[2:5]
	v_mfma_f32_16x16x32_bf16 v[30:33], v[14:17], v[94:97], v[26:29]
	v_mfma_f32_16x16x32_bf16 v[26:29], v[18:21], v[90:93], v[166:169]
	v_mfma_f32_16x16x32_bf16 v[14:17], v[14:17], v[236:239], v[2:5]
	v_mfma_f32_16x16x32_bf16 v[2:5], v[18:21], v[232:235], v[6:9]
	v_mfma_f32_16x16x32_bf16 v[26:29], v[22:25], v[94:97], v[26:29]
	v_mfma_f32_16x16x32_bf16 v[10:13], v[22:25], v[236:239], v[2:5]
	v_mfma_f32_16x16x32_bf16 v[2:5], v[216:219], v[34:37], v[180:183]
	v_mfma_f32_16x16x32_bf16 v[54:57], v[220:223], v[38:41], v[2:5]
	v_mfma_f32_16x16x32_bf16 v[2:5], v[224:227], v[34:37], v[184:187]
	v_mfma_f32_16x16x32_bf16 v[50:53], v[228:231], v[38:41], v[2:5]
	v_mfma_f32_16x16x32_bf16 v[2:5], v[216:219], v[74:77], v[188:191]
	v_mfma_f32_16x16x32_bf16 v[38:41], v[220:223], v[82:85], v[2:5]
	v_mfma_f32_16x16x32_bf16 v[2:5], v[224:227], v[74:77], v[196:199]
	v_mfma_f32_16x16x32_bf16 v[34:37], v[228:231], v[82:85], v[2:5]
	v_mfma_f32_16x16x32_bf16 v[2:5], v[216:219], v[90:93], v[200:203]
	v_mfma_f32_16x16x32_bf16 v[22:25], v[220:223], v[94:97], v[2:5]
	v_mfma_f32_16x16x32_bf16 v[2:5], v[224:227], v[90:93], v[204:207]
	v_mfma_f32_16x16x32_bf16 v[18:21], v[228:231], v[94:97], v[2:5]
	v_mfma_f32_16x16x32_bf16 v[2:5], v[216:219], v[232:235], v[208:211]
	v_mfma_f32_16x16x32_bf16 v[6:9], v[220:223], v[236:239], v[2:5]
	v_mfma_f32_16x16x32_bf16 v[2:5], v[224:227], v[232:235], v[212:215]
	v_mfma_f32_16x16x32_bf16 v[2:5], v[228:231], v[236:239], v[2:5]
	s_setprio 1
	s_barrier
	s_add_u32 s74, s74, 0x80180
	s_addc_u32 s75, s75, 0
	s_add_u32 s57, s76, 0x200
	s_addc_u32 s76, s77, 0
	s_mov_b32 s77, 0
.LBB0_2097:
	ds_read_b128 v[74:77], v1
	ds_read_b128 v[82:85], v1 offset:1024
	ds_read_b128 v[90:93], v1 offset:2048
	ds_read_b128 v[94:97], v1 offset:3072
	ds_read_b128 v[138:141], v192
	ds_read_b128 v[150:153], v192 offset:1024
	ds_read_b128 v[154:157], v192 offset:2048
	ds_read_b128 v[158:161], v192 offset:3072
	s_add_u32 s0, s74, 0xfff80080
	s_addc_u32 s1, s75, -1
	s_cmp_eq_u32 s77, 28
	s_cselect_b32 s1, s67, s1
	s_cselect_b32 s0, s90, s0
	s_cselect_b32 s65, s41, s76
	s_cselect_b32 s64, s91, s57
	s_mov_b32 m0, s85
	v_lshl_add_u64 v[208:209], s[74:75], 0, v[174:175]
	ds_read_b128 v[162:165], v193
	ds_read_b128 v[166:169], v193 offset:1024
	ds_read_b128 v[180:183], v193 offset:2048
	ds_read_b128 v[184:187], v193 offset:3072
	ds_read_b128 v[188:191], v193 offset:4096
	ds_read_b128 v[196:199], v193 offset:5120
	ds_read_b128 v[200:203], v193 offset:6144
	ds_read_b128 v[204:207], v193 offset:7168
	global_load_lds_dwordx4 v[208:209], off
	v_lshl_add_u64 v[208:209], v[208:209], 0, s[28:29]
	s_mov_b32 m0, s87
	s_nop 0
	global_load_lds_dwordx4 v[208:209], off
	s_waitcnt vmcnt(8)
	s_waitcnt lgkmcnt(0)
	s_barrier
	s_waitcnt lgkmcnt(0)
	s_setprio 0
	v_mfma_f32_16x16x32_bf16 v[146:149], v[74:77], v[162:165], v[146:149]
	v_mfma_f32_16x16x32_bf16 v[142:145], v[90:93], v[162:165], v[142:145]
	v_mfma_f32_16x16x32_bf16 v[126:129], v[74:77], v[180:183], v[126:129]
	v_mfma_f32_16x16x32_bf16 v[122:125], v[90:93], v[180:183], v[122:125]
	v_mfma_f32_16x16x32_bf16 v[110:113], v[74:77], v[188:191], v[110:113]
	v_mfma_f32_16x16x32_bf16 v[106:109], v[90:93], v[188:191], v[106:109]
	v_mfma_f32_16x16x32_bf16 v[86:89], v[74:77], v[200:203], v[86:89]
	v_mfma_f32_16x16x32_bf16 v[78:81], v[90:93], v[200:203], v[78:81]
	v_mfma_f32_16x16x32_bf16 v[146:149], v[82:85], v[166:169], v[146:149]
	v_mfma_f32_16x16x32_bf16 v[142:145], v[94:97], v[166:169], v[142:145]
	v_mfma_f32_16x16x32_bf16 v[126:129], v[82:85], v[184:187], v[126:129]
	v_mfma_f32_16x16x32_bf16 v[122:125], v[94:97], v[184:187], v[122:125]
	v_mfma_f32_16x16x32_bf16 v[110:113], v[82:85], v[196:199], v[110:113]
	v_mfma_f32_16x16x32_bf16 v[106:109], v[94:97], v[196:199], v[106:109]
	v_mfma_f32_16x16x32_bf16 v[86:89], v[82:85], v[204:207], v[86:89]
	v_mfma_f32_16x16x32_bf16 v[78:81], v[94:97], v[204:207], v[78:81]
	v_mfma_f32_16x16x32_bf16 v[134:137], v[138:141], v[162:165], v[134:137]
	v_mfma_f32_16x16x32_bf16 v[130:133], v[154:157], v[162:165], v[130:133]
	v_mfma_f32_16x16x32_bf16 v[118:121], v[138:141], v[180:183], v[118:121]
	v_mfma_f32_16x16x32_bf16 v[114:117], v[154:157], v[180:183], v[114:117]
	v_mfma_f32_16x16x32_bf16 v[102:105], v[138:141], v[188:191], v[102:105]
	v_mfma_f32_16x16x32_bf16 v[98:101], v[154:157], v[188:191], v[98:101]
	v_mfma_f32_16x16x32_bf16 v[70:73], v[138:141], v[200:203], v[70:73]
	v_mfma_f32_16x16x32_bf16 v[66:69], v[154:157], v[200:203], v[66:69]
	v_mfma_f32_16x16x32_bf16 v[134:137], v[150:153], v[166:169], v[134:137]
	v_mfma_f32_16x16x32_bf16 v[130:133], v[158:161], v[166:169], v[130:133]
	v_mfma_f32_16x16x32_bf16 v[118:121], v[150:153], v[184:187], v[118:121]
	v_mfma_f32_16x16x32_bf16 v[114:117], v[158:161], v[184:187], v[114:117]
	v_mfma_f32_16x16x32_bf16 v[102:105], v[150:153], v[196:199], v[102:105]
	v_mfma_f32_16x16x32_bf16 v[98:101], v[158:161], v[196:199], v[98:101]
	v_mfma_f32_16x16x32_bf16 v[70:73], v[150:153], v[204:207], v[70:73]
	v_mfma_f32_16x16x32_bf16 v[66:69], v[158:161], v[204:207], v[66:69]
	s_setprio 1
	s_barrier
	s_mov_b32 m0, s92
	v_lshl_add_u64 v[208:209], s[64:65], 0, v[172:173]
	ds_read_b128 v[162:165], v193 offset:16384
	ds_read_b128 v[166:169], v193 offset:17408
	ds_read_b128 v[180:183], v193 offset:18432
	ds_read_b128 v[184:187], v193 offset:19456
	ds_read_b128 v[188:191], v193 offset:20480
	ds_read_b128 v[196:199], v193 offset:21504
	ds_read_b128 v[200:203], v193 offset:22528
	ds_read_b128 v[204:207], v193 offset:23552
	global_load_lds_dwordx4 v[208:209], off
	v_lshl_add_u64 v[210:211], v[208:209], 0, s[28:29]
	s_mov_b32 m0, s93
	s_nop 0
	global_load_lds_dwordx4 v[210:211], off
	v_lshl_add_u64 v[210:211], v[208:209], 0, s[30:31]
	s_mov_b32 m0, s94
	s_nop 0
	global_load_lds_dwordx4 v[210:211], off
	v_lshl_add_u64 v[210:211], v[208:209], 0, s[34:35]
	s_mov_b32 m0, s95
	s_nop 0
	global_load_lds_dwordx4 v[210:211], off
	v_lshl_add_u64 v[210:211], s[0:1], 0, v[170:171]
	s_mov_b32 m0, s47
	v_lshl_add_u64 v[212:213], v[210:211], 0, s[28:29]
	global_load_lds_dwordx4 v[210:211], off
	s_mov_b32 m0, s52
	s_nop 0
	global_load_lds_dwordx4 v[212:213], off
	s_waitcnt vmcnt(8)
	s_waitcnt lgkmcnt(0)
	s_barrier
	s_waitcnt lgkmcnt(0)
	s_setprio 0
	v_mfma_f32_16x16x32_bf16 v[62:65], v[74:77], v[162:165], v[62:65]
	v_mfma_f32_16x16x32_bf16 v[58:61], v[90:93], v[162:165], v[58:61]
	v_mfma_f32_16x16x32_bf16 v[46:49], v[74:77], v[180:183], v[46:49]
	v_mfma_f32_16x16x32_bf16 v[42:45], v[90:93], v[180:183], v[42:45]
	v_mfma_f32_16x16x32_bf16 v[30:33], v[74:77], v[188:191], v[30:33]
	v_mfma_f32_16x16x32_bf16 v[26:29], v[90:93], v[188:191], v[26:29]
	v_mfma_f32_16x16x32_bf16 v[14:17], v[74:77], v[200:203], v[14:17]
	v_mfma_f32_16x16x32_bf16 v[10:13], v[90:93], v[200:203], v[10:13]
	v_mfma_f32_16x16x32_bf16 v[62:65], v[82:85], v[166:169], v[62:65]
	v_mfma_f32_16x16x32_bf16 v[58:61], v[94:97], v[166:169], v[58:61]
	v_mfma_f32_16x16x32_bf16 v[46:49], v[82:85], v[184:187], v[46:49]
	v_mfma_f32_16x16x32_bf16 v[42:45], v[94:97], v[184:187], v[42:45]
	v_mfma_f32_16x16x32_bf16 v[30:33], v[82:85], v[196:199], v[30:33]
	v_mfma_f32_16x16x32_bf16 v[26:29], v[94:97], v[196:199], v[26:29]
	v_mfma_f32_16x16x32_bf16 v[14:17], v[82:85], v[204:207], v[14:17]
	v_mfma_f32_16x16x32_bf16 v[10:13], v[94:97], v[204:207], v[10:13]
	v_mfma_f32_16x16x32_bf16 v[54:57], v[138:141], v[162:165], v[54:57]
	v_mfma_f32_16x16x32_bf16 v[50:53], v[154:157], v[162:165], v[50:53]
	v_mfma_f32_16x16x32_bf16 v[38:41], v[138:141], v[180:183], v[38:41]
	v_mfma_f32_16x16x32_bf16 v[34:37], v[154:157], v[180:183], v[34:37]
	v_mfma_f32_16x16x32_bf16 v[22:25], v[138:141], v[188:191], v[22:25]
	v_mfma_f32_16x16x32_bf16 v[18:21], v[154:157], v[188:191], v[18:21]
	v_mfma_f32_16x16x32_bf16 v[6:9], v[138:141], v[200:203], v[6:9]
	v_mfma_f32_16x16x32_bf16 v[2:5], v[154:157], v[200:203], v[2:5]
	v_mfma_f32_16x16x32_bf16 v[54:57], v[150:153], v[166:169], v[54:57]
	v_mfma_f32_16x16x32_bf16 v[50:53], v[158:161], v[166:169], v[50:53]
	v_mfma_f32_16x16x32_bf16 v[38:41], v[150:153], v[184:187], v[38:41]
	v_mfma_f32_16x16x32_bf16 v[34:37], v[158:161], v[184:187], v[34:37]
	v_mfma_f32_16x16x32_bf16 v[22:25], v[150:153], v[196:199], v[22:25]
	v_mfma_f32_16x16x32_bf16 v[18:21], v[158:161], v[196:199], v[18:21]
	v_mfma_f32_16x16x32_bf16 v[6:9], v[150:153], v[204:207], v[6:9]
	v_mfma_f32_16x16x32_bf16 v[2:5], v[158:161], v[204:207], v[2:5]
	s_setprio 1
	s_barrier
; #define PG8_WAIT_V(n) asm volatile("s_waitcnt vmcnt(" #n ")" ::: "memory")
; template <class Epi, class Sched, bool ALIGN_EPI = true, bool SP2 = true, bool FULLLINE = false, bool NOSTAGE = false, bool FP8 = false>
; __device__ __forceinline__ void gemm_phase(PG8_LAS unsigned char* lds, const Gemm g, const Sched& S, const Epi& E) {
;     ...
;         for (int t = 2; t < nt; t += 2) PG8_ITER(PG8_WAIT_V(8));
	ds_read_b128 v[74:77], v194
	ds_read_b128 v[82:85], v194 offset:1024
	ds_read_b128 v[90:93], v194 offset:2048
	ds_read_b128 v[94:97], v194 offset:3072
	ds_read_b128 v[138:141], v195
	ds_read_b128 v[150:153], v195 offset:1024
	ds_read_b128 v[154:157], v195 offset:2048
	ds_read_b128 v[158:161], v195 offset:3072
	s_mov_b32 m0, s53
	v_lshl_add_u64 v[212:213], v[210:211], 0, s[30:31]
	ds_read_b128 v[162:165], v193 offset:32768
	ds_read_b128 v[166:169], v193 offset:33792
	ds_read_b128 v[180:183], v193 offset:34816
	ds_read_b128 v[184:187], v193 offset:35840
	ds_read_b128 v[188:191], v193 offset:36864
	ds_read_b128 v[196:199], v193 offset:37888
	ds_read_b128 v[200:203], v193 offset:38912
	ds_read_b128 v[204:207], v193 offset:39936
	global_load_lds_dwordx4 v[212:213], off
	v_lshl_add_u64 v[212:213], v[210:211], 0, s[34:35]
	s_mov_b32 m0, s54
	s_nop 0
	global_load_lds_dwordx4 v[212:213], off
	s_waitcnt vmcnt(8)
	s_waitcnt lgkmcnt(0)
	s_barrier
	s_waitcnt lgkmcnt(0)
	s_setprio 0
	v_mfma_f32_16x16x32_bf16 v[146:149], v[74:77], v[162:165], v[146:149]
	v_mfma_f32_16x16x32_bf16 v[142:145], v[90:93], v[162:165], v[142:145]
	v_mfma_f32_16x16x32_bf16 v[126:129], v[74:77], v[180:183], v[126:129]
	v_mfma_f32_16x16x32_bf16 v[122:125], v[90:93], v[180:183], v[122:125]
	v_mfma_f32_16x16x32_bf16 v[110:113], v[74:77], v[188:191], v[110:113]
	v_mfma_f32_16x16x32_bf16 v[106:109], v[90:93], v[188:191], v[106:109]
	v_mfma_f32_16x16x32_bf16 v[86:89], v[74:77], v[200:203], v[86:89]
	v_mfma_f32_16x16x32_bf16 v[78:81], v[90:93], v[200:203], v[78:81]
	v_mfma_f32_16x16x32_bf16 v[146:149], v[82:85], v[166:169], v[146:149]
	v_mfma_f32_16x16x32_bf16 v[142:145], v[94:97], v[166:169], v[142:145]
	v_mfma_f32_16x16x32_bf16 v[126:129], v[82:85], v[184:187], v[126:129]
	v_mfma_f32_16x16x32_bf16 v[122:125], v[94:97], v[184:187], v[122:125]
	v_mfma_f32_16x16x32_bf16 v[110:113], v[82:85], v[196:199], v[110:113]
	v_mfma_f32_16x16x32_bf16 v[106:109], v[94:97], v[196:199], v[106:109]
	v_mfma_f32_16x16x32_bf16 v[86:89], v[82:85], v[204:207], v[86:89]
	v_mfma_f32_16x16x32_bf16 v[78:81], v[94:97], v[204:207], v[78:81]
	v_mfma_f32_16x16x32_bf16 v[134:137], v[138:141], v[162:165], v[134:137]
	v_mfma_f32_16x16x32_bf16 v[130:133], v[154:157], v[162:165], v[130:133]
	v_mfma_f32_16x16x32_bf16 v[118:121], v[138:141], v[180:183], v[118:121]
	v_mfma_f32_16x16x32_bf16 v[114:117], v[154:157], v[180:183], v[114:117]
	v_mfma_f32_16x16x32_bf16 v[102:105], v[138:141], v[188:191], v[102:105]
	v_mfma_f32_16x16x32_bf16 v[98:101], v[154:157], v[188:191], v[98:101]
	v_mfma_f32_16x16x32_bf16 v[70:73], v[138:141], v[200:203], v[70:73]
	v_mfma_f32_16x16x32_bf16 v[66:69], v[154:157], v[200:203], v[66:69]
	v_mfma_f32_16x16x32_bf16 v[134:137], v[150:153], v[166:169], v[134:137]
	v_mfma_f32_16x16x32_bf16 v[130:133], v[158:161], v[166:169], v[130:133]
	v_mfma_f32_16x16x32_bf16 v[118:121], v[150:153], v[184:187], v[118:121]
	v_mfma_f32_16x16x32_bf16 v[114:117], v[158:161], v[184:187], v[114:117]
	v_mfma_f32_16x16x32_bf16 v[102:105], v[150:153], v[196:199], v[102:105]
	v_mfma_f32_16x16x32_bf16 v[98:101], v[158:161], v[196:199], v[98:101]
	v_mfma_f32_16x16x32_bf16 v[70:73], v[150:153], v[204:207], v[70:73]
	v_mfma_f32_16x16x32_bf16 v[66:69], v[158:161], v[204:207], v[66:69]
	s_setprio 1
	s_barrier
	s_mov_b32 m0, s50
	v_lshl_add_u64 v[212:213], v[208:209], 0, s[36:37]
	ds_read_b128 v[162:165], v193 offset:49152
	ds_read_b128 v[166:169], v193 offset:50176
	ds_read_b128 v[180:183], v193 offset:51200
	ds_read_b128 v[184:187], v193 offset:52224
	ds_read_b128 v[188:191], v193 offset:53248
	ds_read_b128 v[196:199], v193 offset:54272
	ds_read_b128 v[200:203], v193 offset:55296
	ds_read_b128 v[204:207], v193 offset:56320
	global_load_lds_dwordx4 v[212:213], off
	v_lshl_add_u64 v[212:213], v[208:209], 0, s[38:39]
	s_mov_b32 m0, s51
	s_nop 0
	global_load_lds_dwordx4 v[212:213], off
	v_lshl_add_u64 v[212:213], v[208:209], 0, s[12:13]
	s_mov_b32 m0, s33
	v_lshl_add_u64 v[208:209], v[208:209], 0, s[14:15]
	global_load_lds_dwordx4 v[212:213], off
	s_mov_b32 m0, s56
	s_nop 0
	global_load_lds_dwordx4 v[208:209], off
	v_lshl_add_u64 v[208:209], v[210:211], 0, s[36:37]
	s_mov_b32 m0, s55
	s_nop 0
	global_load_lds_dwordx4 v[208:209], off
	v_lshl_add_u64 v[208:209], v[210:211], 0, s[38:39]
	s_mov_b32 m0, s62
	s_nop 0
	global_load_lds_dwordx4 v[208:209], off
	s_waitcnt vmcnt(8)
	s_waitcnt lgkmcnt(0)
	s_barrier
	s_waitcnt lgkmcnt(0)
	s_setprio 0
	v_mfma_f32_16x16x32_bf16 v[62:65], v[74:77], v[162:165], v[62:65]
	v_mfma_f32_16x16x32_bf16 v[58:61], v[90:93], v[162:165], v[58:61]
	v_mfma_f32_16x16x32_bf16 v[46:49], v[74:77], v[180:183], v[46:49]
	v_mfma_f32_16x16x32_bf16 v[42:45], v[90:93], v[180:183], v[42:45]
	v_mfma_f32_16x16x32_bf16 v[30:33], v[74:77], v[188:191], v[30:33]
	v_mfma_f32_16x16x32_bf16 v[26:29], v[90:93], v[188:191], v[26:29]
	v_mfma_f32_16x16x32_bf16 v[14:17], v[74:77], v[200:203], v[14:17]
	v_mfma_f32_16x16x32_bf16 v[10:13], v[90:93], v[200:203], v[10:13]
	v_mfma_f32_16x16x32_bf16 v[62:65], v[82:85], v[166:169], v[62:65]
	v_mfma_f32_16x16x32_bf16 v[58:61], v[94:97], v[166:169], v[58:61]
	v_mfma_f32_16x16x32_bf16 v[46:49], v[82:85], v[184:187], v[46:49]
	v_mfma_f32_16x16x32_bf16 v[42:45], v[94:97], v[184:187], v[42:45]
	v_mfma_f32_16x16x32_bf16 v[30:33], v[82:85], v[196:199], v[30:33]
	v_mfma_f32_16x16x32_bf16 v[26:29], v[94:97], v[196:199], v[26:29]
	v_mfma_f32_16x16x32_bf16 v[14:17], v[82:85], v[204:207], v[14:17]
	v_mfma_f32_16x16x32_bf16 v[10:13], v[94:97], v[204:207], v[10:13]
	v_mfma_f32_16x16x32_bf16 v[54:57], v[138:141], v[162:165], v[54:57]
	v_mfma_f32_16x16x32_bf16 v[50:53], v[154:157], v[162:165], v[50:53]
	v_mfma_f32_16x16x32_bf16 v[38:41], v[138:141], v[180:183], v[38:41]
	v_mfma_f32_16x16x32_bf16 v[34:37], v[154:157], v[180:183], v[34:37]
	v_mfma_f32_16x16x32_bf16 v[22:25], v[138:141], v[188:191], v[22:25]
	v_mfma_f32_16x16x32_bf16 v[18:21], v[154:157], v[188:191], v[18:21]
	v_mfma_f32_16x16x32_bf16 v[6:9], v[138:141], v[200:203], v[6:9]
	v_mfma_f32_16x16x32_bf16 v[2:5], v[154:157], v[200:203], v[2:5]
	v_mfma_f32_16x16x32_bf16 v[54:57], v[150:153], v[166:169], v[54:57]
	v_mfma_f32_16x16x32_bf16 v[50:53], v[158:161], v[166:169], v[50:53]
	v_mfma_f32_16x16x32_bf16 v[38:41], v[150:153], v[184:187], v[38:41]
	v_mfma_f32_16x16x32_bf16 v[34:37], v[158:161], v[184:187], v[34:37]
	v_mfma_f32_16x16x32_bf16 v[22:25], v[150:153], v[196:199], v[22:25]
	v_mfma_f32_16x16x32_bf16 v[18:21], v[158:161], v[196:199], v[18:21]
	v_mfma_f32_16x16x32_bf16 v[6:9], v[150:153], v[204:207], v[6:9]
	v_mfma_f32_16x16x32_bf16 v[2:5], v[158:161], v[204:207], v[2:5]
	s_setprio 1
	s_barrier
	s_add_i32 s77, s77, 2
	s_add_u32 s74, s74, 0x100
	s_addc_u32 s75, s75, 0
	s_add_u32 s57, s57, 0x100
	s_addc_u32 s76, s76, 0
	s_cmp_gt_u32 s77, 29
	s_cbranch_scc0 .LBB0_2097
	s_and_b64 vcc, exec, s[10:11]
	s_cbranch_vccz .LBB0_2100
	s_barrier

; template <class Epi, class Sched, bool ALIGN_EPI = true, bool SP2 = true, bool FULLLINE = false, bool NOSTAGE = false, bool FP8 = false>
; __device__ __forceinline__ void gemm_phase(PG8_LAS unsigned char* lds, const Gemm g, const Sched& S, const Epi& E) {
;     ...
;         const bool has_next = S.next(ui + 1, nxt);
;         const char* nA = has_next ? PG8_ABASE(nxt) : cA; const char* nB = has_next ? PG8_BBASE(nxt) : cB;
.LBB0_2286:
	s_ashr_i32 s63, s62, 31
	s_lshl_b64 s[0:1], s[62:63], 20
	s_add_u32 s66, s58, s0
	ds_read_b128 v[2:5], v1
	ds_read_b128 v[6:9], v1 offset:1024
	ds_read_b128 v[10:13], v1 offset:2048
	ds_read_b128 v[14:17], v1 offset:3072
	ds_read_b128 v[18:21], v142
	ds_read_b128 v[22:25], v142 offset:1024
	ds_read_b128 v[26:29], v142 offset:2048
	ds_read_b128 v[30:33], v142 offset:3072
	s_addc_u32 s67, s59, s1
	s_ashr_i32 s41, s40, 31
	s_lshl_b64 s[0:1], s[40:41], 20
	s_add_u32 s68, s3, s0
	s_addc_u32 s69, s42, s1
	s_and_b64 s[0:1], s[8:9], exec
	s_cselect_b32 s41, s67, s75
	s_cselect_b32 s63, s66, s74
	s_cselect_b32 s87, s69, s73
	s_cselect_b32 s88, s68, s72
	v_lshl_add_u64 v[140:141], s[74:75], 0, v[132:133]
	s_mov_b32 m0, s79
	v_lshl_add_u64 v[66:67], v[140:141], 0, s[12:13]
	ds_read_b128 v[34:37], v143
	ds_read_b128 v[38:41], v143 offset:1024
	ds_read_b128 v[42:45], v143 offset:2048
	ds_read_b128 v[46:49], v143 offset:3072
	ds_read_b128 v[50:53], v143 offset:4096
	ds_read_b128 v[54:57], v143 offset:5120
	ds_read_b128 v[58:61], v143 offset:6144
	ds_read_b128 v[62:65], v143 offset:7168
	global_load_lds_dwordx4 v[66:67], off
	v_lshl_add_u64 v[66:67], v[140:141], 0, s[14:15]
	s_mov_b32 m0, s80
	s_nop 0
	global_load_lds_dwordx4 v[66:67], off
	s_waitcnt vmcnt(16)
	s_waitcnt lgkmcnt(0)
	s_barrier
	s_waitcnt lgkmcnt(0)
	s_setprio 0
	v_mfma_f32_16x16x32_bf16 v[86:89], v[10:13], v[50:53], 0
	v_mfma_f32_16x16x32_bf16 v[90:93], v[14:17], v[54:57], v[86:89]
	v_mfma_f32_16x16x32_bf16 v[86:89], v[2:5], v[58:61], 0
	v_mfma_f32_16x16x32_bf16 v[66:69], v[2:5], v[34:37], 0
	v_mfma_f32_16x16x32_bf16 v[70:73], v[10:13], v[34:37], 0
	v_mfma_f32_16x16x32_bf16 v[74:77], v[2:5], v[42:45], 0
	v_mfma_f32_16x16x32_bf16 v[78:81], v[10:13], v[42:45], 0
	v_mfma_f32_16x16x32_bf16 v[82:85], v[2:5], v[50:53], 0
	v_mfma_f32_16x16x32_bf16 v[94:97], v[6:9], v[62:65], v[86:89]
	v_mfma_f32_16x16x32_bf16 v[86:89], v[10:13], v[58:61], 0
	v_mfma_f32_16x16x32_bf16 v[66:69], v[6:9], v[38:41], v[66:69]
	v_mfma_f32_16x16x32_bf16 v[70:73], v[14:17], v[38:41], v[70:73]
	v_mfma_f32_16x16x32_bf16 v[74:77], v[6:9], v[46:49], v[74:77]
	v_mfma_f32_16x16x32_bf16 v[78:81], v[14:17], v[46:49], v[78:81]
	v_mfma_f32_16x16x32_bf16 v[82:85], v[6:9], v[54:57], v[82:85]
	v_mfma_f32_16x16x32_bf16 v[106:109], v[14:17], v[62:65], v[86:89]
	v_mfma_f32_16x16x32_bf16 v[86:89], v[18:21], v[34:37], 0
	v_mfma_f32_16x16x32_bf16 v[34:37], v[26:29], v[34:37], 0
	v_mfma_f32_16x16x32_bf16 v[110:113], v[22:25], v[38:41], v[86:89]
	v_mfma_f32_16x16x32_bf16 v[34:37], v[30:33], v[38:41], v[34:37]
	v_mfma_f32_16x16x32_bf16 v[38:41], v[18:21], v[42:45], 0
	v_mfma_f32_16x16x32_bf16 v[42:45], v[26:29], v[42:45], 0
	v_mfma_f32_16x16x32_bf16 v[38:41], v[22:25], v[46:49], v[38:41]
	v_mfma_f32_16x16x32_bf16 v[42:45], v[30:33], v[46:49], v[42:45]
	v_mfma_f32_16x16x32_bf16 v[46:49], v[18:21], v[50:53], 0
	v_mfma_f32_16x16x32_bf16 v[50:53], v[26:29], v[50:53], 0
	v_mfma_f32_16x16x32_bf16 v[46:49], v[22:25], v[54:57], v[46:49]
	v_mfma_f32_16x16x32_bf16 v[50:53], v[30:33], v[54:57], v[50:53]
	v_mfma_f32_16x16x32_bf16 v[54:57], v[18:21], v[58:61], 0
	v_mfma_f32_16x16x32_bf16 v[58:61], v[26:29], v[58:61], 0
	v_mfma_f32_16x16x32_bf16 v[54:57], v[22:25], v[62:65], v[54:57]
	v_mfma_f32_16x16x32_bf16 v[58:61], v[30:33], v[62:65], v[58:61]
	s_setprio 1
	s_barrier
	v_lshl_add_u64 v[238:239], s[72:73], 0, v[130:131]
	s_mov_b32 m0, s81
	v_lshl_add_u64 v[146:147], v[238:239], 0, s[16:17]
	s_add_i32 s89, s81, 0x2000
	ds_read_b128 v[62:65], v143 offset:16384
	ds_read_b128 v[86:89], v143 offset:17408
	ds_read_b128 v[98:101], v143 offset:18432
	ds_read_b128 v[102:105], v143 offset:19456
	ds_read_b128 v[114:117], v143 offset:20480
	ds_read_b128 v[118:121], v143 offset:21504
	ds_read_b128 v[122:125], v143 offset:22528
	ds_read_b128 v[126:129], v143 offset:23552
	global_load_lds_dwordx4 v[146:147], off
	v_lshl_add_u64 v[146:147], v[238:239], 0, s[18:19]
	s_mov_b32 m0, s89
	s_add_i32 s90, s78, s43
	global_load_lds_dwordx4 v[146:147], off
	v_lshl_add_u64 v[146:147], v[238:239], 0, s[20:21]
	s_mov_b32 m0, s90
	s_add_i32 s91, s90, 0x2000
	global_load_lds_dwordx4 v[146:147], off
	v_lshl_add_u64 v[146:147], v[238:239], 0, s[22:23]
	s_mov_b32 m0, s91
	s_nop 0
	global_load_lds_dwordx4 v[146:147], off
	v_lshl_add_u64 v[146:147], v[140:141], 0, s[16:17]
	s_mov_b32 m0, s45
	s_nop 0
	global_load_lds_dwordx4 v[146:147], off
	v_lshl_add_u64 v[146:147], v[140:141], 0, s[18:19]
	s_mov_b32 m0, s46
	s_nop 0
	global_load_lds_dwordx4 v[146:147], off
	s_waitcnt vmcnt(16)
	s_waitcnt lgkmcnt(0)
	s_barrier
	s_waitcnt lgkmcnt(0)
	s_setprio 0
	v_mfma_f32_16x16x32_bf16 v[146:149], v[2:5], v[62:65], 0
	v_mfma_f32_16x16x32_bf16 v[154:157], v[2:5], v[98:101], 0
	v_mfma_f32_16x16x32_bf16 v[162:165], v[2:5], v[114:117], 0
	v_mfma_f32_16x16x32_bf16 v[2:5], v[2:5], v[122:125], 0
	v_mfma_f32_16x16x32_bf16 v[146:149], v[6:9], v[86:89], v[146:149]
	v_mfma_f32_16x16x32_bf16 v[154:157], v[6:9], v[102:105], v[154:157]
	v_mfma_f32_16x16x32_bf16 v[162:165], v[6:9], v[118:121], v[162:165]
	v_mfma_f32_16x16x32_bf16 v[2:5], v[6:9], v[126:129], v[2:5]
	v_mfma_f32_16x16x32_bf16 v[6:9], v[10:13], v[122:125], 0
	v_mfma_f32_16x16x32_bf16 v[150:153], v[10:13], v[62:65], 0
	v_mfma_f32_16x16x32_bf16 v[158:161], v[10:13], v[98:101], 0
	v_mfma_f32_16x16x32_bf16 v[166:169], v[10:13], v[114:117], 0
	v_mfma_f32_16x16x32_bf16 v[10:13], v[14:17], v[126:129], v[6:9]
	v_mfma_f32_16x16x32_bf16 v[150:153], v[14:17], v[86:89], v[150:153]
	v_mfma_f32_16x16x32_bf16 v[158:161], v[14:17], v[102:105], v[158:161]
	v_mfma_f32_16x16x32_bf16 v[166:169], v[14:17], v[118:121], v[166:169]
	v_mfma_f32_16x16x32_bf16 v[6:9], v[18:21], v[62:65], 0
	v_mfma_f32_16x16x32_bf16 v[14:17], v[22:25], v[86:89], v[6:9]
	v_mfma_f32_16x16x32_bf16 v[6:9], v[26:29], v[62:65], 0
	v_mfma_f32_16x16x32_bf16 v[170:173], v[30:33], v[86:89], v[6:9]
	v_mfma_f32_16x16x32_bf16 v[6:9], v[18:21], v[98:101], 0
	v_mfma_f32_16x16x32_bf16 v[174:177], v[22:25], v[102:105], v[6:9]
	v_mfma_f32_16x16x32_bf16 v[6:9], v[26:29], v[98:101], 0
	v_mfma_f32_16x16x32_bf16 v[178:181], v[30:33], v[102:105], v[6:9]
	v_mfma_f32_16x16x32_bf16 v[6:9], v[18:21], v[114:117], 0
	v_mfma_f32_16x16x32_bf16 v[182:185], v[22:25], v[118:121], v[6:9]
	v_mfma_f32_16x16x32_bf16 v[6:9], v[26:29], v[114:117], 0
	v_mfma_f32_16x16x32_bf16 v[186:189], v[30:33], v[118:121], v[6:9]
	v_mfma_f32_16x16x32_bf16 v[6:9], v[18:21], v[122:125], 0
	v_mfma_f32_16x16x32_bf16 v[190:193], v[22:25], v[126:129], v[6:9]
	v_mfma_f32_16x16x32_bf16 v[6:9], v[26:29], v[122:125], 0
	v_mfma_f32_16x16x32_bf16 v[194:197], v[30:33], v[126:129], v[6:9]
	s_setprio 1
	s_barrier
	s_nop 5
	ds_read_b128 v[6:9], v144
	ds_read_b128 v[26:29], v144 offset:1024
	ds_read_b128 v[30:33], v144 offset:2048
	ds_read_b128 v[62:65], v144 offset:3072
	ds_read_b128 v[198:201], v145
	ds_read_b128 v[202:205], v145 offset:1024
	ds_read_b128 v[206:209], v145 offset:2048
	ds_read_b128 v[210:213], v145 offset:3072
	s_mov_b32 m0, s47
	v_lshl_add_u64 v[86:87], v[140:141], 0, s[20:21]
	ds_read_b128 v[18:21], v143 offset:32768
	ds_read_b128 v[22:25], v143 offset:33792
	ds_read_b128 v[214:217], v143 offset:34816
	ds_read_b128 v[218:221], v143 offset:35840
	ds_read_b128 v[222:225], v143 offset:36864
	ds_read_b128 v[226:229], v143 offset:37888
	ds_read_b128 v[230:233], v143 offset:38912
	ds_read_b128 v[234:237], v143 offset:39936
	global_load_lds_dwordx4 v[86:87], off
	v_lshl_add_u64 v[86:87], v[140:141], 0, s[22:23]
	s_mov_b32 m0, s52
	s_nop 0
	global_load_lds_dwordx4 v[86:87], off
	s_waitcnt vmcnt(8)
	s_waitcnt lgkmcnt(0)
	s_barrier
	s_waitcnt lgkmcnt(0)
	s_setprio 0
	v_mfma_f32_16x16x32_bf16 v[66:69], v[6:9], v[18:21], v[66:69]
	v_mfma_f32_16x16x32_bf16 v[118:121], v[26:29], v[22:25], v[66:69]
	v_mfma_f32_16x16x32_bf16 v[66:69], v[30:33], v[18:21], v[70:73]
	v_mfma_f32_16x16x32_bf16 v[114:117], v[62:65], v[22:25], v[66:69]
	v_mfma_f32_16x16x32_bf16 v[66:69], v[6:9], v[214:217], v[74:77]
	v_mfma_f32_16x16x32_bf16 v[102:105], v[26:29], v[218:221], v[66:69]
	v_mfma_f32_16x16x32_bf16 v[66:69], v[30:33], v[214:217], v[78:81]
	v_mfma_f32_16x16x32_bf16 v[98:101], v[62:65], v[218:221], v[66:69]
	v_mfma_f32_16x16x32_bf16 v[66:69], v[6:9], v[222:225], v[82:85]
	v_mfma_f32_16x16x32_bf16 v[86:89], v[26:29], v[226:229], v[66:69]
	v_mfma_f32_16x16x32_bf16 v[66:69], v[30:33], v[222:225], v[90:93]
	v_mfma_f32_16x16x32_bf16 v[82:85], v[62:65], v[226:229], v[66:69]
	v_mfma_f32_16x16x32_bf16 v[66:69], v[6:9], v[230:233], v[94:97]
	v_mfma_f32_16x16x32_bf16 v[70:73], v[26:29], v[234:237], v[66:69]
	v_mfma_f32_16x16x32_bf16 v[66:69], v[30:33], v[230:233], v[106:109]
	v_mfma_f32_16x16x32_bf16 v[66:69], v[62:65], v[234:237], v[66:69]
	v_mfma_f32_16x16x32_bf16 v[74:77], v[198:201], v[18:21], v[110:113]
	v_mfma_f32_16x16x32_bf16 v[18:21], v[206:209], v[18:21], v[34:37]
	v_mfma_f32_16x16x32_bf16 v[122:125], v[210:213], v[22:25], v[18:21]
	v_mfma_f32_16x16x32_bf16 v[18:21], v[198:201], v[214:217], v[38:41]
	v_mfma_f32_16x16x32_bf16 v[110:113], v[202:205], v[218:221], v[18:21]
	v_mfma_f32_16x16x32_bf16 v[18:21], v[206:209], v[214:217], v[42:45]
	v_mfma_f32_16x16x32_bf16 v[106:109], v[210:213], v[218:221], v[18:21]
	v_mfma_f32_16x16x32_bf16 v[18:21], v[198:201], v[222:225], v[46:49]
	v_mfma_f32_16x16x32_bf16 v[94:97], v[202:205], v[226:229], v[18:21]
	v_mfma_f32_16x16x32_bf16 v[18:21], v[206:209], v[222:225], v[50:53]
	v_mfma_f32_16x16x32_bf16 v[90:93], v[210:213], v[226:229], v[18:21]
	v_mfma_f32_16x16x32_bf16 v[18:21], v[198:201], v[230:233], v[54:57]
	v_mfma_f32_16x16x32_bf16 v[78:81], v[202:205], v[234:237], v[18:21]
	v_mfma_f32_16x16x32_bf16 v[18:21], v[206:209], v[230:233], v[58:61]
	v_mfma_f32_16x16x32_bf16 v[126:129], v[202:205], v[22:25], v[74:77]
	v_mfma_f32_16x16x32_bf16 v[74:77], v[210:213], v[234:237], v[18:21]
	s_setprio 1
	s_barrier
	s_add_i32 s50, s82, s43
	s_nop 3
	v_lshl_add_u64 v[18:19], v[238:239], 0, s[24:25]
	s_mov_b32 m0, s50
	s_add_i32 s51, s50, 0x2000
	ds_read_b128 v[42:45], v143 offset:49152
	ds_read_b128 v[46:49], v143 offset:50176
	ds_read_b128 v[214:217], v143 offset:51200
	ds_read_b128 v[218:221], v143 offset:52224
	ds_read_b128 v[222:225], v143 offset:53248
	ds_read_b128 v[226:229], v143 offset:54272
	ds_read_b128 v[230:233], v143 offset:55296
	ds_read_b128 v[234:237], v143 offset:56320
	global_load_lds_dwordx4 v[18:19], off
	v_lshl_add_u64 v[18:19], v[238:239], 0, s[26:27]
	s_mov_b32 m0, s51
	s_mov_b64 s[0:1], 0x80180
	s_add_i32 s33, s83, s43
	global_load_lds_dwordx4 v[18:19], off
	v_lshl_add_u64 v[18:19], v[238:239], 0, s[0:1]
	s_mov_b32 m0, s33
	s_mov_b64 s[0:1], 0xc0180
	s_add_i32 s56, s33, 0x2000
	global_load_lds_dwordx4 v[18:19], off
	v_lshl_add_u64 v[18:19], v[238:239], 0, s[0:1]
	s_mov_b32 m0, s56
	s_nop 0
	global_load_lds_dwordx4 v[18:19], off
	v_lshl_add_u64 v[18:19], v[140:141], 0, s[24:25]
	s_mov_b32 m0, s53
	s_nop 0
	global_load_lds_dwordx4 v[18:19], off
	v_lshl_add_u64 v[18:19], v[140:141], 0, s[26:27]
	s_mov_b32 m0, s54
	s_nop 0
	global_load_lds_dwordx4 v[18:19], off
	s_waitcnt vmcnt(8)
	s_waitcnt lgkmcnt(0)
	s_barrier
	s_waitcnt lgkmcnt(0)
	s_setprio 0
	v_mfma_f32_16x16x32_bf16 v[18:21], v[6:9], v[42:45], v[146:149]
	v_mfma_f32_16x16x32_bf16 v[54:57], v[26:29], v[46:49], v[18:21]
	v_mfma_f32_16x16x32_bf16 v[18:21], v[30:33], v[42:45], v[150:153]
	v_mfma_f32_16x16x32_bf16 v[50:53], v[62:65], v[46:49], v[18:21]
	v_mfma_f32_16x16x32_bf16 v[18:21], v[6:9], v[214:217], v[154:157]
	v_mfma_f32_16x16x32_bf16 v[38:41], v[26:29], v[218:221], v[18:21]
	v_mfma_f32_16x16x32_bf16 v[18:21], v[30:33], v[214:217], v[158:161]
	v_mfma_f32_16x16x32_bf16 v[34:37], v[62:65], v[218:221], v[18:21]
	v_mfma_f32_16x16x32_bf16 v[18:21], v[6:9], v[222:225], v[162:165]
	v_mfma_f32_16x16x32_bf16 v[2:5], v[6:9], v[230:233], v[2:5]
	v_mfma_f32_16x16x32_bf16 v[22:25], v[26:29], v[226:229], v[18:21]
	v_mfma_f32_16x16x32_bf16 v[18:21], v[30:33], v[222:225], v[166:169]
	v_mfma_f32_16x16x32_bf16 v[6:9], v[26:29], v[234:237], v[2:5]
	v_mfma_f32_16x16x32_bf16 v[2:5], v[30:33], v[230:233], v[10:13]
	v_mfma_f32_16x16x32_bf16 v[18:21], v[62:65], v[226:229], v[18:21]
	v_mfma_f32_16x16x32_bf16 v[2:5], v[62:65], v[234:237], v[2:5]
	v_mfma_f32_16x16x32_bf16 v[10:13], v[198:201], v[42:45], v[14:17]
	v_mfma_f32_16x16x32_bf16 v[62:65], v[202:205], v[46:49], v[10:13]
	v_mfma_f32_16x16x32_bf16 v[10:13], v[206:209], v[42:45], v[170:173]
	v_mfma_f32_16x16x32_bf16 v[58:61], v[210:213], v[46:49], v[10:13]
	v_mfma_f32_16x16x32_bf16 v[10:13], v[198:201], v[214:217], v[174:177]
	v_mfma_f32_16x16x32_bf16 v[46:49], v[202:205], v[218:221], v[10:13]
	v_mfma_f32_16x16x32_bf16 v[10:13], v[206:209], v[214:217], v[178:181]
	v_mfma_f32_16x16x32_bf16 v[42:45], v[210:213], v[218:221], v[10:13]
	v_mfma_f32_16x16x32_bf16 v[10:13], v[198:201], v[222:225], v[182:185]
	v_mfma_f32_16x16x32_bf16 v[30:33], v[202:205], v[226:229], v[10:13]
	v_mfma_f32_16x16x32_bf16 v[10:13], v[206:209], v[222:225], v[186:189]
	v_mfma_f32_16x16x32_bf16 v[26:29], v[210:213], v[226:229], v[10:13]
	v_mfma_f32_16x16x32_bf16 v[10:13], v[198:201], v[230:233], v[190:193]
	v_mfma_f32_16x16x32_bf16 v[14:17], v[202:205], v[234:237], v[10:13]
	v_mfma_f32_16x16x32_bf16 v[10:13], v[206:209], v[230:233], v[194:197]
	v_mfma_f32_16x16x32_bf16 v[10:13], v[210:213], v[234:237], v[10:13]
	s_setprio 1
	s_barrier
	s_add_u32 s74, s74, 0x80180
	s_addc_u32 s75, s75, 0
	s_add_u32 s57, s72, 0x200
	s_addc_u32 s72, s73, 0
	s_mov_b32 s73, 0
.LBB0_2287:
	ds_read_b128 v[146:149], v1
	ds_read_b128 v[150:153], v1 offset:1024
	ds_read_b128 v[154:157], v1 offset:2048
	ds_read_b128 v[158:161], v1 offset:3072
	ds_read_b128 v[162:165], v142
	ds_read_b128 v[166:169], v142 offset:1024
	ds_read_b128 v[170:173], v142 offset:2048
	ds_read_b128 v[174:177], v142 offset:3072
	s_add_u32 s0, s74, 0xfff80080
	s_addc_u32 s1, s75, -1
	s_cmp_eq_u32 s73, 28
	s_cselect_b32 s1, s41, s1
	s_cselect_b32 s0, s63, s0
	s_cselect_b32 s65, s87, s72
	s_cselect_b32 s64, s88, s57
	s_mov_b32 m0, s79
	v_lshl_add_u64 v[140:141], s[74:75], 0, v[134:135]
	ds_read_b128 v[178:181], v143
	ds_read_b128 v[182:185], v143 offset:1024
	ds_read_b128 v[186:189], v143 offset:2048
	ds_read_b128 v[190:193], v143 offset:3072
	ds_read_b128 v[194:197], v143 offset:4096
	ds_read_b128 v[198:201], v143 offset:5120
	ds_read_b128 v[202:205], v143 offset:6144
	ds_read_b128 v[206:209], v143 offset:7168
	global_load_lds_dwordx4 v[140:141], off
	v_lshl_add_u64 v[140:141], v[140:141], 0, s[28:29]
	s_mov_b32 m0, s80
	s_nop 0
	global_load_lds_dwordx4 v[140:141], off
	s_waitcnt vmcnt(8)
	s_waitcnt lgkmcnt(0)
	s_barrier
	s_waitcnt lgkmcnt(0)
	s_setprio 0
	v_mfma_f32_16x16x32_bf16 v[118:121], v[146:149], v[178:181], v[118:121]
	v_mfma_f32_16x16x32_bf16 v[114:117], v[154:157], v[178:181], v[114:117]
	v_mfma_f32_16x16x32_bf16 v[102:105], v[146:149], v[186:189], v[102:105]
	v_mfma_f32_16x16x32_bf16 v[98:101], v[154:157], v[186:189], v[98:101]
	v_mfma_f32_16x16x32_bf16 v[86:89], v[146:149], v[194:197], v[86:89]
	v_mfma_f32_16x16x32_bf16 v[82:85], v[154:157], v[194:197], v[82:85]
	v_mfma_f32_16x16x32_bf16 v[70:73], v[146:149], v[202:205], v[70:73]
	v_mfma_f32_16x16x32_bf16 v[66:69], v[154:157], v[202:205], v[66:69]
	v_mfma_f32_16x16x32_bf16 v[118:121], v[150:153], v[182:185], v[118:121]
	v_mfma_f32_16x16x32_bf16 v[114:117], v[158:161], v[182:185], v[114:117]
	v_mfma_f32_16x16x32_bf16 v[102:105], v[150:153], v[190:193], v[102:105]
	v_mfma_f32_16x16x32_bf16 v[98:101], v[158:161], v[190:193], v[98:101]
	v_mfma_f32_16x16x32_bf16 v[86:89], v[150:153], v[198:201], v[86:89]
	v_mfma_f32_16x16x32_bf16 v[82:85], v[158:161], v[198:201], v[82:85]
	v_mfma_f32_16x16x32_bf16 v[70:73], v[150:153], v[206:209], v[70:73]
	v_mfma_f32_16x16x32_bf16 v[66:69], v[158:161], v[206:209], v[66:69]
	v_mfma_f32_16x16x32_bf16 v[126:129], v[162:165], v[178:181], v[126:129]
	v_mfma_f32_16x16x32_bf16 v[122:125], v[170:173], v[178:181], v[122:125]
	v_mfma_f32_16x16x32_bf16 v[110:113], v[162:165], v[186:189], v[110:113]
	v_mfma_f32_16x16x32_bf16 v[106:109], v[170:173], v[186:189], v[106:109]
	v_mfma_f32_16x16x32_bf16 v[94:97], v[162:165], v[194:197], v[94:97]
	v_mfma_f32_16x16x32_bf16 v[90:93], v[170:173], v[194:197], v[90:93]
	v_mfma_f32_16x16x32_bf16 v[78:81], v[162:165], v[202:205], v[78:81]
	v_mfma_f32_16x16x32_bf16 v[74:77], v[170:173], v[202:205], v[74:77]
	v_mfma_f32_16x16x32_bf16 v[126:129], v[166:169], v[182:185], v[126:129]
	v_mfma_f32_16x16x32_bf16 v[122:125], v[174:177], v[182:185], v[122:125]
	v_mfma_f32_16x16x32_bf16 v[110:113], v[166:169], v[190:193], v[110:113]
	v_mfma_f32_16x16x32_bf16 v[106:109], v[174:177], v[190:193], v[106:109]
	v_mfma_f32_16x16x32_bf16 v[94:97], v[166:169], v[198:201], v[94:97]
	v_mfma_f32_16x16x32_bf16 v[90:93], v[174:177], v[198:201], v[90:93]
	v_mfma_f32_16x16x32_bf16 v[78:81], v[166:169], v[206:209], v[78:81]
	v_mfma_f32_16x16x32_bf16 v[74:77], v[174:177], v[206:209], v[74:77]
	s_setprio 1
	s_barrier
	s_mov_b32 m0, s81
	v_lshl_add_u64 v[140:141], s[64:65], 0, v[130:131]
	ds_read_b128 v[178:181], v143 offset:16384
	ds_read_b128 v[182:185], v143 offset:17408
	ds_read_b128 v[186:189], v143 offset:18432
	ds_read_b128 v[190:193], v143 offset:19456
	ds_read_b128 v[194:197], v143 offset:20480
	ds_read_b128 v[198:201], v143 offset:21504
	ds_read_b128 v[202:205], v143 offset:22528
	ds_read_b128 v[206:209], v143 offset:23552
	global_load_lds_dwordx4 v[140:141], off
	v_lshl_add_u64 v[210:211], v[140:141], 0, s[28:29]
	s_mov_b32 m0, s89
	s_nop 0
	global_load_lds_dwordx4 v[210:211], off
	v_lshl_add_u64 v[210:211], v[140:141], 0, s[30:31]
	s_mov_b32 m0, s90
	s_nop 0
	global_load_lds_dwordx4 v[210:211], off
	v_lshl_add_u64 v[210:211], v[140:141], 0, s[34:35]
	s_mov_b32 m0, s91
	s_nop 0
	global_load_lds_dwordx4 v[210:211], off
	v_lshl_add_u64 v[210:211], s[0:1], 0, v[132:133]
	s_mov_b32 m0, s45
	v_lshl_add_u64 v[212:213], v[210:211], 0, s[28:29]
	global_load_lds_dwordx4 v[210:211], off
	s_mov_b32 m0, s46
	s_nop 0
	global_load_lds_dwordx4 v[212:213], off
	s_waitcnt vmcnt(8)
	s_waitcnt lgkmcnt(0)
	s_barrier
	s_waitcnt lgkmcnt(0)
	s_setprio 0
	v_mfma_f32_16x16x32_bf16 v[54:57], v[146:149], v[178:181], v[54:57]
	v_mfma_f32_16x16x32_bf16 v[50:53], v[154:157], v[178:181], v[50:53]
	v_mfma_f32_16x16x32_bf16 v[38:41], v[146:149], v[186:189], v[38:41]
	v_mfma_f32_16x16x32_bf16 v[34:37], v[154:157], v[186:189], v[34:37]
	v_mfma_f32_16x16x32_bf16 v[22:25], v[146:149], v[194:197], v[22:25]
	v_mfma_f32_16x16x32_bf16 v[18:21], v[154:157], v[194:197], v[18:21]
	v_mfma_f32_16x16x32_bf16 v[6:9], v[146:149], v[202:205], v[6:9]
	v_mfma_f32_16x16x32_bf16 v[2:5], v[154:157], v[202:205], v[2:5]
	v_mfma_f32_16x16x32_bf16 v[54:57], v[150:153], v[182:185], v[54:57]
	v_mfma_f32_16x16x32_bf16 v[50:53], v[158:161], v[182:185], v[50:53]
	v_mfma_f32_16x16x32_bf16 v[38:41], v[150:153], v[190:193], v[38:41]
	v_mfma_f32_16x16x32_bf16 v[34:37], v[158:161], v[190:193], v[34:37]
	v_mfma_f32_16x16x32_bf16 v[22:25], v[150:153], v[198:201], v[22:25]
	v_mfma_f32_16x16x32_bf16 v[18:21], v[158:161], v[198:201], v[18:21]
	v_mfma_f32_16x16x32_bf16 v[6:9], v[150:153], v[206:209], v[6:9]
	v_mfma_f32_16x16x32_bf16 v[2:5], v[158:161], v[206:209], v[2:5]
	v_mfma_f32_16x16x32_bf16 v[62:65], v[162:165], v[178:181], v[62:65]
	v_mfma_f32_16x16x32_bf16 v[58:61], v[170:173], v[178:181], v[58:61]
	v_mfma_f32_16x16x32_bf16 v[46:49], v[162:165], v[186:189], v[46:49]
	v_mfma_f32_16x16x32_bf16 v[42:45], v[170:173], v[186:189], v[42:45]
	v_mfma_f32_16x16x32_bf16 v[30:33], v[162:165], v[194:197], v[30:33]
	v_mfma_f32_16x16x32_bf16 v[26:29], v[170:173], v[194:197], v[26:29]
	v_mfma_f32_16x16x32_bf16 v[14:17], v[162:165], v[202:205], v[14:17]
	v_mfma_f32_16x16x32_bf16 v[10:13], v[170:173], v[202:205], v[10:13]
	v_mfma_f32_16x16x32_bf16 v[62:65], v[166:169], v[182:185], v[62:65]
	v_mfma_f32_16x16x32_bf16 v[58:61], v[174:177], v[182:185], v[58:61]
	v_mfma_f32_16x16x32_bf16 v[46:49], v[166:169], v[190:193], v[46:49]
	v_mfma_f32_16x16x32_bf16 v[42:45], v[174:177], v[190:193], v[42:45]
	v_mfma_f32_16x16x32_bf16 v[30:33], v[166:169], v[198:201], v[30:33]
	v_mfma_f32_16x16x32_bf16 v[26:29], v[174:177], v[198:201], v[26:29]
	v_mfma_f32_16x16x32_bf16 v[14:17], v[166:169], v[206:209], v[14:17]
	v_mfma_f32_16x16x32_bf16 v[10:13], v[174:177], v[206:209], v[10:13]
	s_setprio 1
	s_barrier
	ds_read_b128 v[146:149], v144
	ds_read_b128 v[150:153], v144 offset:1024
	ds_read_b128 v[154:157], v144 offset:2048
	ds_read_b128 v[158:161], v144 offset:3072
	ds_read_b128 v[162:165], v145
	ds_read_b128 v[166:169], v145 offset:1024
	ds_read_b128 v[170:173], v145 offset:2048
	ds_read_b128 v[174:177], v145 offset:3072
	s_mov_b32 m0, s47
	v_lshl_add_u64 v[212:213], v[210:211], 0, s[30:31]
	ds_read_b128 v[178:181], v143 offset:32768
	ds_read_b128 v[182:185], v143 offset:33792
	ds_read_b128 v[186:189], v143 offset:34816
	ds_read_b128 v[190:193], v143 offset:35840
	ds_read_b128 v[194:197], v143 offset:36864
	ds_read_b128 v[198:201], v143 offset:37888
	ds_read_b128 v[202:205], v143 offset:38912
	ds_read_b128 v[206:209], v143 offset:39936
	global_load_lds_dwordx4 v[212:213], off
	v_lshl_add_u64 v[212:213], v[210:211], 0, s[34:35]
	s_mov_b32 m0, s52
	s_nop 0
	global_load_lds_dwordx4 v[212:213], off
	s_waitcnt vmcnt(8)
	s_waitcnt lgkmcnt(0)
	s_barrier
	s_waitcnt lgkmcnt(0)
	s_setprio 0
	v_mfma_f32_16x16x32_bf16 v[118:121], v[146:149], v[178:181], v[118:121]
	v_mfma_f32_16x16x32_bf16 v[114:117], v[154:157], v[178:181], v[114:117]
	v_mfma_f32_16x16x32_bf16 v[102:105], v[146:149], v[186:189], v[102:105]
	v_mfma_f32_16x16x32_bf16 v[98:101], v[154:157], v[186:189], v[98:101]
	v_mfma_f32_16x16x32_bf16 v[86:89], v[146:149], v[194:197], v[86:89]
	v_mfma_f32_16x16x32_bf16 v[82:85], v[154:157], v[194:197], v[82:85]
	v_mfma_f32_16x16x32_bf16 v[70:73], v[146:149], v[202:205], v[70:73]
	v_mfma_f32_16x16x32_bf16 v[66:69], v[154:157], v[202:205], v[66:69]
	v_mfma_f32_16x16x32_bf16 v[118:121], v[150:153], v[182:185], v[118:121]
	v_mfma_f32_16x16x32_bf16 v[114:117], v[158:161], v[182:185], v[114:117]
	v_mfma_f32_16x16x32_bf16 v[102:105], v[150:153], v[190:193], v[102:105]
	v_mfma_f32_16x16x32_bf16 v[98:101], v[158:161], v[190:193], v[98:101]
	v_mfma_f32_16x16x32_bf16 v[86:89], v[150:153], v[198:201], v[86:89]
	v_mfma_f32_16x16x32_bf16 v[82:85], v[158:161], v[198:201], v[82:85]
	v_mfma_f32_16x16x32_bf16 v[70:73], v[150:153], v[206:209], v[70:73]
	v_mfma_f32_16x16x32_bf16 v[66:69], v[158:161], v[206:209], v[66:69]
	v_mfma_f32_16x16x32_bf16 v[126:129], v[162:165], v[178:181], v[126:129]
	v_mfma_f32_16x16x32_bf16 v[122:125], v[170:173], v[178:181], v[122:125]
	v_mfma_f32_16x16x32_bf16 v[110:113], v[162:165], v[186:189], v[110:113]
	v_mfma_f32_16x16x32_bf16 v[106:109], v[170:173], v[186:189], v[106:109]
	v_mfma_f32_16x16x32_bf16 v[94:97], v[162:165], v[194:197], v[94:97]
	v_mfma_f32_16x16x32_bf16 v[90:93], v[170:173], v[194:197], v[90:93]
	v_mfma_f32_16x16x32_bf16 v[78:81], v[162:165], v[202:205], v[78:81]
	v_mfma_f32_16x16x32_bf16 v[74:77], v[170:173], v[202:205], v[74:77]
	v_mfma_f32_16x16x32_bf16 v[126:129], v[166:169], v[182:185], v[126:129]
	v_mfma_f32_16x16x32_bf16 v[122:125], v[174:177], v[182:185], v[122:125]
	v_mfma_f32_16x16x32_bf16 v[110:113], v[166:169], v[190:193], v[110:113]
	v_mfma_f32_16x16x32_bf16 v[106:109], v[174:177], v[190:193], v[106:109]
	v_mfma_f32_16x16x32_bf16 v[94:97], v[166:169], v[198:201], v[94:97]
	v_mfma_f32_16x16x32_bf16 v[90:93], v[174:177], v[198:201], v[90:93]
	v_mfma_f32_16x16x32_bf16 v[78:81], v[166:169], v[206:209], v[78:81]
	v_mfma_f32_16x16x32_bf16 v[74:77], v[174:177], v[206:209], v[74:77]
	s_setprio 1
	s_barrier
; #define PG8_WAIT_V(n) asm volatile("s_waitcnt vmcnt(" #n ")" ::: "memory")
; template <class Epi, class Sched, bool ALIGN_EPI = true, bool SP2 = true, bool FULLLINE = false, bool NOSTAGE = false, bool FP8 = false>
; __device__ __forceinline__ void gemm_phase(PG8_LAS unsigned char* lds, const Gemm g, const Sched& S, const Epi& E) {
;     ...
;         for (int t = 2; t < nt; t += 2) PG8_ITER(PG8_WAIT_V(8));
	s_mov_b32 m0, s50
	v_lshl_add_u64 v[212:213], v[140:141], 0, s[36:37]
	ds_read_b128 v[178:181], v143 offset:49152
	ds_read_b128 v[182:185], v143 offset:50176
	ds_read_b128 v[186:189], v143 offset:51200
	ds_read_b128 v[190:193], v143 offset:52224
	ds_read_b128 v[194:197], v143 offset:53248
	ds_read_b128 v[198:201], v143 offset:54272
	ds_read_b128 v[202:205], v143 offset:55296
	ds_read_b128 v[206:209], v143 offset:56320
	global_load_lds_dwordx4 v[212:213], off
	v_lshl_add_u64 v[212:213], v[140:141], 0, s[38:39]
	s_mov_b32 m0, s51
	s_nop 0
	global_load_lds_dwordx4 v[212:213], off
	v_lshl_add_u64 v[212:213], v[140:141], 0, s[12:13]
	s_mov_b32 m0, s33
	v_lshl_add_u64 v[140:141], v[140:141], 0, s[14:15]
	global_load_lds_dwordx4 v[212:213], off
	s_mov_b32 m0, s56
	s_nop 0
	global_load_lds_dwordx4 v[140:141], off
	v_lshl_add_u64 v[140:141], v[210:211], 0, s[36:37]
	s_mov_b32 m0, s53
	s_nop 0
	global_load_lds_dwordx4 v[140:141], off
	v_lshl_add_u64 v[140:141], v[210:211], 0, s[38:39]
	s_mov_b32 m0, s54
	s_nop 0
	global_load_lds_dwordx4 v[140:141], off
	s_waitcnt vmcnt(8)
	s_waitcnt lgkmcnt(0)
	s_barrier
	s_waitcnt lgkmcnt(0)
	s_setprio 0
	v_mfma_f32_16x16x32_bf16 v[54:57], v[146:149], v[178:181], v[54:57]
	v_mfma_f32_16x16x32_bf16 v[50:53], v[154:157], v[178:181], v[50:53]
	v_mfma_f32_16x16x32_bf16 v[38:41], v[146:149], v[186:189], v[38:41]
	v_mfma_f32_16x16x32_bf16 v[34:37], v[154:157], v[186:189], v[34:37]
	v_mfma_f32_16x16x32_bf16 v[22:25], v[146:149], v[194:197], v[22:25]
	v_mfma_f32_16x16x32_bf16 v[18:21], v[154:157], v[194:197], v[18:21]
	v_mfma_f32_16x16x32_bf16 v[6:9], v[146:149], v[202:205], v[6:9]
	v_mfma_f32_16x16x32_bf16 v[2:5], v[154:157], v[202:205], v[2:5]
	v_mfma_f32_16x16x32_bf16 v[54:57], v[150:153], v[182:185], v[54:57]
	v_mfma_f32_16x16x32_bf16 v[50:53], v[158:161], v[182:185], v[50:53]
	v_mfma_f32_16x16x32_bf16 v[38:41], v[150:153], v[190:193], v[38:41]
	v_mfma_f32_16x16x32_bf16 v[34:37], v[158:161], v[190:193], v[34:37]
	v_mfma_f32_16x16x32_bf16 v[22:25], v[150:153], v[198:201], v[22:25]
	v_mfma_f32_16x16x32_bf16 v[18:21], v[158:161], v[198:201], v[18:21]
	v_mfma_f32_16x16x32_bf16 v[6:9], v[150:153], v[206:209], v[6:9]
	v_mfma_f32_16x16x32_bf16 v[2:5], v[158:161], v[206:209], v[2:5]
	v_mfma_f32_16x16x32_bf16 v[62:65], v[162:165], v[178:181], v[62:65]
	v_mfma_f32_16x16x32_bf16 v[58:61], v[170:173], v[178:181], v[58:61]
	v_mfma_f32_16x16x32_bf16 v[46:49], v[162:165], v[186:189], v[46:49]
	v_mfma_f32_16x16x32_bf16 v[42:45], v[170:173], v[186:189], v[42:45]
	v_mfma_f32_16x16x32_bf16 v[30:33], v[162:165], v[194:197], v[30:33]
	v_mfma_f32_16x16x32_bf16 v[26:29], v[170:173], v[194:197], v[26:29]
	v_mfma_f32_16x16x32_bf16 v[14:17], v[162:165], v[202:205], v[14:17]
	v_mfma_f32_16x16x32_bf16 v[10:13], v[170:173], v[202:205], v[10:13]
	v_mfma_f32_16x16x32_bf16 v[62:65], v[166:169], v[182:185], v[62:65]
	v_mfma_f32_16x16x32_bf16 v[58:61], v[174:177], v[182:185], v[58:61]
	v_mfma_f32_16x16x32_bf16 v[46:49], v[166:169], v[190:193], v[46:49]
	v_mfma_f32_16x16x32_bf16 v[42:45], v[174:177], v[190:193], v[42:45]
	v_mfma_f32_16x16x32_bf16 v[30:33], v[166:169], v[198:201], v[30:33]
	v_mfma_f32_16x16x32_bf16 v[26:29], v[174:177], v[198:201], v[26:29]
	v_mfma_f32_16x16x32_bf16 v[14:17], v[166:169], v[206:209], v[14:17]
	v_mfma_f32_16x16x32_bf16 v[10:13], v[174:177], v[206:209], v[10:13]
	s_setprio 1
	s_barrier
	s_add_i32 s73, s73, 2
	s_add_u32 s74, s74, 0x100
	s_addc_u32 s75, s75, 0
	s_add_u32 s57, s57, 0x100
	s_addc_u32 s72, s72, 0
	s_cmp_gt_u32 s73, 29
	s_cbranch_scc0 .LBB0_2287
	s_and_b64 vcc, exec, s[10:11]
	s_cbranch_vccz .LBB0_2290
	s_barrier

; template <class Epi, class Sched, bool ALIGN_EPI = true, bool SP2 = true, bool FULLLINE = false, bool NOSTAGE = false, bool FP8 = false>
; __device__ __forceinline__ void gemm_phase(PG8_LAS unsigned char* lds, const Gemm g, const Sched& S, const Epi& E) {
;     ...
;         const bool has_next = S.next(ui + 1, nxt);
;         const char* nA = has_next ? PG8_ABASE(nxt) : cA; const char* nB = has_next ? PG8_BBASE(nxt) : cB;
.LBB0_2389:
	ds_read_b128 v[2:5], v1
	ds_read_b128 v[6:9], v1 offset:1024
	ds_read_b128 v[10:13], v1 offset:2048
	ds_read_b128 v[14:17], v1 offset:3072
	ds_read_b128 v[18:21], v192
	ds_read_b128 v[22:25], v192 offset:1024
	ds_read_b128 v[26:29], v192 offset:2048
	ds_read_b128 v[30:33], v192 offset:3072
	v_lshl_add_u64 v[244:245], s[66:67], 0, v[170:171]
	s_add_i32 s83, s45, 0xc000
	v_lshl_add_u64 v[66:67], v[244:245], 0, s[14:15]
	s_mov_b32 m0, s83
	s_add_i32 s84, s45, 0xe000
	ds_read_b128 v[34:37], v193
	ds_read_b128 v[38:41], v193 offset:1024
	ds_read_b128 v[42:45], v193 offset:2048
	ds_read_b128 v[46:49], v193 offset:3072
	ds_read_b128 v[50:53], v193 offset:4096
	ds_read_b128 v[54:57], v193 offset:5120
	ds_read_b128 v[58:61], v193 offset:6144
	ds_read_b128 v[62:65], v193 offset:7168
	global_load_lds_dwordx4 v[66:67], off
	v_lshl_add_u64 v[66:67], v[244:245], 0, s[16:17]
	s_mov_b32 m0, s84
	s_nop 0
	global_load_lds_dwordx4 v[66:67], off
	s_waitcnt vmcnt(24)
	s_waitcnt lgkmcnt(0)
	s_barrier
	s_waitcnt lgkmcnt(0)
	s_setprio 0
	v_mfma_f32_16x16x32_bf16 v[66:69], v[2:5], v[34:37], 0
	v_mfma_f32_16x16x32_bf16 v[70:73], v[10:13], v[34:37], 0
	v_mfma_f32_16x16x32_bf16 v[74:77], v[2:5], v[42:45], 0
	v_mfma_f32_16x16x32_bf16 v[78:81], v[10:13], v[42:45], 0
	v_mfma_f32_16x16x32_bf16 v[90:93], v[2:5], v[58:61], 0
	v_mfma_f32_16x16x32_bf16 v[94:97], v[10:13], v[58:61], 0
	v_mfma_f32_16x16x32_bf16 v[66:69], v[6:9], v[38:41], v[66:69]
	v_mfma_f32_16x16x32_bf16 v[70:73], v[14:17], v[38:41], v[70:73]
	v_mfma_f32_16x16x32_bf16 v[74:77], v[6:9], v[46:49], v[74:77]
	v_mfma_f32_16x16x32_bf16 v[78:81], v[14:17], v[46:49], v[78:81]
	v_mfma_f32_16x16x32_bf16 v[82:85], v[2:5], v[50:53], 0
	v_mfma_f32_16x16x32_bf16 v[86:89], v[10:13], v[50:53], 0
	v_mfma_f32_16x16x32_bf16 v[90:93], v[6:9], v[62:65], v[90:93]
	v_mfma_f32_16x16x32_bf16 v[94:97], v[14:17], v[62:65], v[94:97]
	v_mfma_f32_16x16x32_bf16 v[82:85], v[6:9], v[54:57], v[82:85]
	v_mfma_f32_16x16x32_bf16 v[86:89], v[14:17], v[54:57], v[86:89]
	v_mfma_f32_16x16x32_bf16 v[98:101], v[18:21], v[34:37], 0
	v_mfma_f32_16x16x32_bf16 v[34:37], v[26:29], v[34:37], 0
	v_mfma_f32_16x16x32_bf16 v[98:101], v[22:25], v[38:41], v[98:101]
	v_mfma_f32_16x16x32_bf16 v[34:37], v[30:33], v[38:41], v[34:37]
	v_mfma_f32_16x16x32_bf16 v[38:41], v[18:21], v[42:45], 0
	v_mfma_f32_16x16x32_bf16 v[42:45], v[26:29], v[42:45], 0
	v_mfma_f32_16x16x32_bf16 v[38:41], v[22:25], v[46:49], v[38:41]
	v_mfma_f32_16x16x32_bf16 v[42:45], v[30:33], v[46:49], v[42:45]
	v_mfma_f32_16x16x32_bf16 v[46:49], v[18:21], v[50:53], 0
	v_mfma_f32_16x16x32_bf16 v[50:53], v[26:29], v[50:53], 0
	v_mfma_f32_16x16x32_bf16 v[46:49], v[22:25], v[54:57], v[46:49]
	v_mfma_f32_16x16x32_bf16 v[50:53], v[30:33], v[54:57], v[50:53]
	v_mfma_f32_16x16x32_bf16 v[54:57], v[18:21], v[58:61], 0
	v_mfma_f32_16x16x32_bf16 v[58:61], v[26:29], v[58:61], 0
	v_mfma_f32_16x16x32_bf16 v[54:57], v[22:25], v[62:65], v[54:57]
	v_mfma_f32_16x16x32_bf16 v[58:61], v[30:33], v[62:65], v[58:61]
	s_setprio 1
	s_barrier
	v_lshl_add_u64 v[246:247], s[68:69], 0, v[172:173]
	s_add_i32 s85, s75, s44
	v_lshl_add_u64 v[130:131], v[246:247], 0, s[18:19]
	s_mov_b32 m0, s85
	s_add_i32 s87, s85, 0x2000
	ds_read_b128 v[62:65], v193 offset:16384
	ds_read_b128 v[102:105], v193 offset:17408
	ds_read_b128 v[106:109], v193 offset:18432
	ds_read_b128 v[110:113], v193 offset:19456
	ds_read_b128 v[114:117], v193 offset:20480
	ds_read_b128 v[118:121], v193 offset:21504
	ds_read_b128 v[122:125], v193 offset:22528
	ds_read_b128 v[126:129], v193 offset:23552
	global_load_lds_dwordx4 v[130:131], off
	v_lshl_add_u64 v[130:131], v[246:247], 0, s[20:21]
	s_mov_b32 m0, s87
	s_add_i32 s88, s76, s44
	global_load_lds_dwordx4 v[130:131], off
	v_lshl_add_u64 v[130:131], v[246:247], 0, s[22:23]
	s_mov_b32 m0, s88
	s_add_i32 s89, s88, 0x2000
	global_load_lds_dwordx4 v[130:131], off
	v_lshl_add_u64 v[130:131], v[246:247], 0, s[24:25]
	s_mov_b32 m0, s89
	s_nop 0
	global_load_lds_dwordx4 v[130:131], off
	v_lshl_add_u64 v[130:131], v[244:245], 0, s[18:19]
	s_mov_b32 m0, s45
	s_nop 0
	global_load_lds_dwordx4 v[130:131], off
	v_lshl_add_u64 v[130:131], v[244:245], 0, s[20:21]
	s_mov_b32 m0, s46
	s_nop 0
	global_load_lds_dwordx4 v[130:131], off
	s_waitcnt vmcnt(24)
	s_waitcnt lgkmcnt(0)
	s_barrier
	s_waitcnt lgkmcnt(0)
	s_setprio 0
	v_mfma_f32_16x16x32_bf16 v[130:133], v[2:5], v[62:65], 0
	v_mfma_f32_16x16x32_bf16 v[146:149], v[6:9], v[102:105], v[130:133]
	v_mfma_f32_16x16x32_bf16 v[130:133], v[10:13], v[62:65], 0
	v_mfma_f32_16x16x32_bf16 v[150:153], v[14:17], v[102:105], v[130:133]
	v_mfma_f32_16x16x32_bf16 v[130:133], v[2:5], v[106:109], 0
	v_mfma_f32_16x16x32_bf16 v[154:157], v[6:9], v[110:113], v[130:133]
	v_mfma_f32_16x16x32_bf16 v[130:133], v[10:13], v[106:109], 0
	v_mfma_f32_16x16x32_bf16 v[158:161], v[14:17], v[110:113], v[130:133]
	v_mfma_f32_16x16x32_bf16 v[130:133], v[2:5], v[114:117], 0
	v_mfma_f32_16x16x32_bf16 v[2:5], v[2:5], v[122:125], 0
	v_mfma_f32_16x16x32_bf16 v[162:165], v[6:9], v[118:121], v[130:133]
	v_mfma_f32_16x16x32_bf16 v[2:5], v[6:9], v[126:129], v[2:5]
	v_mfma_f32_16x16x32_bf16 v[6:9], v[10:13], v[122:125], 0
	v_mfma_f32_16x16x32_bf16 v[130:133], v[10:13], v[114:117], 0
	v_mfma_f32_16x16x32_bf16 v[6:9], v[14:17], v[126:129], v[6:9]
	v_mfma_f32_16x16x32_bf16 v[166:169], v[14:17], v[118:121], v[130:133]
	v_mfma_f32_16x16x32_bf16 v[10:13], v[18:21], v[62:65], 0
	v_mfma_f32_16x16x32_bf16 v[180:183], v[22:25], v[102:105], v[10:13]
	v_mfma_f32_16x16x32_bf16 v[10:13], v[26:29], v[62:65], 0
	v_mfma_f32_16x16x32_bf16 v[102:105], v[30:33], v[102:105], v[10:13]
	v_mfma_f32_16x16x32_bf16 v[10:13], v[18:21], v[106:109], 0
	v_mfma_f32_16x16x32_bf16 v[184:187], v[22:25], v[110:113], v[10:13]
	v_mfma_f32_16x16x32_bf16 v[10:13], v[26:29], v[106:109], 0
	v_mfma_f32_16x16x32_bf16 v[188:191], v[30:33], v[110:113], v[10:13]
	v_mfma_f32_16x16x32_bf16 v[10:13], v[18:21], v[114:117], 0
	v_mfma_f32_16x16x32_bf16 v[196:199], v[22:25], v[118:121], v[10:13]
	v_mfma_f32_16x16x32_bf16 v[10:13], v[26:29], v[114:117], 0
	v_mfma_f32_16x16x32_bf16 v[200:203], v[30:33], v[118:121], v[10:13]
	v_mfma_f32_16x16x32_bf16 v[10:13], v[18:21], v[122:125], 0
	v_mfma_f32_16x16x32_bf16 v[204:207], v[22:25], v[126:129], v[10:13]
	v_mfma_f32_16x16x32_bf16 v[10:13], v[26:29], v[122:125], 0
	v_mfma_f32_16x16x32_bf16 v[208:211], v[30:33], v[126:129], v[10:13]
	s_setprio 1
	s_barrier
	s_nop 5
	ds_read_b128 v[10:13], v194
	ds_read_b128 v[14:17], v194 offset:1024
	ds_read_b128 v[18:21], v194 offset:2048
	ds_read_b128 v[22:25], v194 offset:3072
	ds_read_b128 v[212:215], v195
	ds_read_b128 v[216:219], v195 offset:1024
	ds_read_b128 v[220:223], v195 offset:2048
	ds_read_b128 v[224:227], v195 offset:3072
	s_mov_b32 m0, s47
	v_lshl_add_u64 v[106:107], v[244:245], 0, s[22:23]
	ds_read_b128 v[26:29], v193 offset:32768
	ds_read_b128 v[30:33], v193 offset:33792
	ds_read_b128 v[62:65], v193 offset:34816
	ds_read_b128 v[114:117], v193 offset:35840
	ds_read_b128 v[228:231], v193 offset:36864
	ds_read_b128 v[232:235], v193 offset:37888
	ds_read_b128 v[236:239], v193 offset:38912
	ds_read_b128 v[240:243], v193 offset:39936
	global_load_lds_dwordx4 v[106:107], off
	v_lshl_add_u64 v[106:107], v[244:245], 0, s[24:25]
	s_mov_b32 m0, s52
	s_nop 0
	global_load_lds_dwordx4 v[106:107], off
	s_waitcnt vmcnt(8)
	s_waitcnt lgkmcnt(0)
	s_barrier
	s_waitcnt lgkmcnt(0)
	s_setprio 0
	v_mfma_f32_16x16x32_bf16 v[66:69], v[10:13], v[26:29], v[66:69]
	v_mfma_f32_16x16x32_bf16 v[142:145], v[14:17], v[30:33], v[66:69]
	v_mfma_f32_16x16x32_bf16 v[66:69], v[18:21], v[26:29], v[70:73]
	v_mfma_f32_16x16x32_bf16 v[138:141], v[22:25], v[30:33], v[66:69]
	v_mfma_f32_16x16x32_bf16 v[66:69], v[10:13], v[62:65], v[74:77]
	v_mfma_f32_16x16x32_bf16 v[126:129], v[14:17], v[114:117], v[66:69]
	v_mfma_f32_16x16x32_bf16 v[66:69], v[18:21], v[62:65], v[78:81]
	v_mfma_f32_16x16x32_bf16 v[122:125], v[22:25], v[114:117], v[66:69]
	v_mfma_f32_16x16x32_bf16 v[66:69], v[10:13], v[228:231], v[82:85]
	v_mfma_f32_16x16x32_bf16 v[110:113], v[14:17], v[232:235], v[66:69]
	v_mfma_f32_16x16x32_bf16 v[66:69], v[18:21], v[228:231], v[86:89]
	v_mfma_f32_16x16x32_bf16 v[106:109], v[22:25], v[232:235], v[66:69]
	v_mfma_f32_16x16x32_bf16 v[66:69], v[10:13], v[236:239], v[90:93]
	v_mfma_f32_16x16x32_bf16 v[78:81], v[14:17], v[240:243], v[66:69]
	v_mfma_f32_16x16x32_bf16 v[66:69], v[18:21], v[236:239], v[94:97]
	v_mfma_f32_16x16x32_bf16 v[74:77], v[22:25], v[240:243], v[66:69]
	v_mfma_f32_16x16x32_bf16 v[66:69], v[212:215], v[26:29], v[98:101]
	v_mfma_f32_16x16x32_bf16 v[26:29], v[220:223], v[26:29], v[34:37]
	v_mfma_f32_16x16x32_bf16 v[130:133], v[224:227], v[30:33], v[26:29]
	v_mfma_f32_16x16x32_bf16 v[26:29], v[212:215], v[62:65], v[38:41]
	v_mfma_f32_16x16x32_bf16 v[118:121], v[216:219], v[114:117], v[26:29]
	v_mfma_f32_16x16x32_bf16 v[26:29], v[220:223], v[62:65], v[42:45]
	v_mfma_f32_16x16x32_bf16 v[114:117], v[224:227], v[114:117], v[26:29]
	v_mfma_f32_16x16x32_bf16 v[26:29], v[212:215], v[228:231], v[46:49]
	v_mfma_f32_16x16x32_bf16 v[94:97], v[216:219], v[232:235], v[26:29]
	v_mfma_f32_16x16x32_bf16 v[26:29], v[220:223], v[228:231], v[50:53]
	v_mfma_f32_16x16x32_bf16 v[90:93], v[224:227], v[232:235], v[26:29]
	v_mfma_f32_16x16x32_bf16 v[26:29], v[212:215], v[236:239], v[54:57]
	v_mfma_f32_16x16x32_bf16 v[70:73], v[216:219], v[240:243], v[26:29]
	v_mfma_f32_16x16x32_bf16 v[26:29], v[220:223], v[236:239], v[58:61]
	v_mfma_f32_16x16x32_bf16 v[134:137], v[216:219], v[30:33], v[66:69]
	v_mfma_f32_16x16x32_bf16 v[66:69], v[224:227], v[240:243], v[26:29]
	s_setprio 1
	s_barrier
	s_add_i32 s50, s77, s44
	s_nop 3
	v_lshl_add_u64 v[26:27], v[246:247], 0, s[26:27]
	s_mov_b32 m0, s50
	s_add_i32 s51, s50, 0x2000
	ds_read_b128 v[34:37], v193 offset:49152
	ds_read_b128 v[38:41], v193 offset:50176
	ds_read_b128 v[82:85], v193 offset:51200
	ds_read_b128 v[86:89], v193 offset:52224
	ds_read_b128 v[98:101], v193 offset:53248
	ds_read_b128 v[228:231], v193 offset:54272
	ds_read_b128 v[232:235], v193 offset:55296
	ds_read_b128 v[236:239], v193 offset:56320
	global_load_lds_dwordx4 v[26:27], off
	v_lshl_add_u64 v[26:27], v[246:247], 0, s[28:29]
	s_mov_b32 m0, s51
	s_mov_b64 s[0:1], 0x160180
	s_add_i32 s33, s78, s44
	global_load_lds_dwordx4 v[26:27], off
	v_lshl_add_u64 v[26:27], v[246:247], 0, s[0:1]
	s_mov_b32 m0, s33
	s_mov_b64 s[0:1], 0x210180
	s_add_i32 s56, s33, 0x2000
	global_load_lds_dwordx4 v[26:27], off
	v_lshl_add_u64 v[26:27], v[246:247], 0, s[0:1]
	s_mov_b32 m0, s56
	s_nop 0
	global_load_lds_dwordx4 v[26:27], off
	v_lshl_add_u64 v[26:27], v[244:245], 0, s[26:27]
	s_mov_b32 m0, s53
	s_nop 0
	global_load_lds_dwordx4 v[26:27], off
	v_lshl_add_u64 v[26:27], v[244:245], 0, s[28:29]
	s_mov_b32 m0, s54
	s_nop 0
	global_load_lds_dwordx4 v[26:27], off
	s_waitcnt vmcnt(8)
	s_waitcnt lgkmcnt(0)
	s_barrier
	s_waitcnt lgkmcnt(0)
	s_setprio 0
	v_mfma_f32_16x16x32_bf16 v[26:29], v[10:13], v[34:37], v[146:149]
	v_mfma_f32_16x16x32_bf16 v[62:65], v[14:17], v[38:41], v[26:29]
	v_mfma_f32_16x16x32_bf16 v[26:29], v[18:21], v[34:37], v[150:153]
	v_mfma_f32_16x16x32_bf16 v[58:61], v[22:25], v[38:41], v[26:29]
	v_mfma_f32_16x16x32_bf16 v[26:29], v[10:13], v[82:85], v[154:157]
	v_mfma_f32_16x16x32_bf16 v[46:49], v[14:17], v[86:89], v[26:29]
	v_mfma_f32_16x16x32_bf16 v[26:29], v[18:21], v[82:85], v[158:161]
	v_mfma_f32_16x16x32_bf16 v[42:45], v[22:25], v[86:89], v[26:29]
	v_mfma_f32_16x16x32_bf16 v[26:29], v[10:13], v[98:101], v[162:165]
	v_mfma_f32_16x16x32_bf16 v[2:5], v[10:13], v[232:235], v[2:5]
	v_mfma_f32_16x16x32_bf16 v[30:33], v[14:17], v[228:231], v[26:29]
	v_mfma_f32_16x16x32_bf16 v[26:29], v[18:21], v[98:101], v[166:169]
	v_mfma_f32_16x16x32_bf16 v[14:17], v[14:17], v[236:239], v[2:5]
	v_mfma_f32_16x16x32_bf16 v[2:5], v[18:21], v[232:235], v[6:9]
	v_mfma_f32_16x16x32_bf16 v[26:29], v[22:25], v[228:231], v[26:29]
	v_mfma_f32_16x16x32_bf16 v[10:13], v[22:25], v[236:239], v[2:5]
	v_mfma_f32_16x16x32_bf16 v[2:5], v[212:215], v[34:37], v[180:183]
	v_mfma_f32_16x16x32_bf16 v[54:57], v[216:219], v[38:41], v[2:5]
	v_mfma_f32_16x16x32_bf16 v[2:5], v[220:223], v[34:37], v[102:105]
	v_mfma_f32_16x16x32_bf16 v[50:53], v[224:227], v[38:41], v[2:5]
	v_mfma_f32_16x16x32_bf16 v[2:5], v[212:215], v[82:85], v[184:187]
	v_mfma_f32_16x16x32_bf16 v[38:41], v[216:219], v[86:89], v[2:5]
	v_mfma_f32_16x16x32_bf16 v[2:5], v[220:223], v[82:85], v[188:191]
	v_mfma_f32_16x16x32_bf16 v[34:37], v[224:227], v[86:89], v[2:5]
	v_mfma_f32_16x16x32_bf16 v[2:5], v[212:215], v[98:101], v[196:199]
	v_mfma_f32_16x16x32_bf16 v[22:25], v[216:219], v[228:231], v[2:5]
	v_mfma_f32_16x16x32_bf16 v[2:5], v[220:223], v[98:101], v[200:203]
	v_mfma_f32_16x16x32_bf16 v[18:21], v[224:227], v[228:231], v[2:5]
	v_mfma_f32_16x16x32_bf16 v[2:5], v[212:215], v[232:235], v[204:207]
	v_mfma_f32_16x16x32_bf16 v[6:9], v[216:219], v[236:239], v[2:5]
	v_mfma_f32_16x16x32_bf16 v[2:5], v[220:223], v[232:235], v[208:211]
	v_mfma_f32_16x16x32_bf16 v[2:5], v[224:227], v[236:239], v[2:5]
	s_setprio 1
	s_barrier
	s_add_u32 s66, s66, 0x160180
	s_addc_u32 s67, s67, 0
	s_add_u32 s57, s68, 0x200
	s_addc_u32 s68, s69, 0
	s_mov_b32 s69, 0
.LBB0_2390:
	ds_read_b128 v[82:85], v1
	ds_read_b128 v[86:89], v1 offset:1024
	ds_read_b128 v[98:101], v1 offset:2048
	ds_read_b128 v[102:105], v1 offset:3072
	ds_read_b128 v[146:149], v192
	ds_read_b128 v[150:153], v192 offset:1024
	ds_read_b128 v[154:157], v192 offset:2048
	ds_read_b128 v[158:161], v192 offset:3072
	s_add_u32 s0, s66, 0xffea0080
	s_addc_u32 s1, s67, -1
	s_cmpk_eq_i32 s69, 0x54
	s_cselect_b32 s1, s11, s1
	s_cselect_b32 s0, s10, s0
	s_cselect_b32 s65, s63, s68
	s_cselect_b32 s64, s62, s57
	s_mov_b32 m0, s83
	v_lshl_add_u64 v[208:209], s[66:67], 0, v[174:175]
	ds_read_b128 v[162:165], v193
	ds_read_b128 v[166:169], v193 offset:1024
	ds_read_b128 v[180:183], v193 offset:2048
	ds_read_b128 v[184:187], v193 offset:3072
	ds_read_b128 v[188:191], v193 offset:4096
	ds_read_b128 v[196:199], v193 offset:5120
	ds_read_b128 v[200:203], v193 offset:6144
	ds_read_b128 v[204:207], v193 offset:7168
	global_load_lds_dwordx4 v[208:209], off
	v_lshl_add_u64 v[208:209], v[208:209], 0, s[30:31]
	s_mov_b32 m0, s84
	s_nop 0
	global_load_lds_dwordx4 v[208:209], off
	s_waitcnt vmcnt(8)
	s_waitcnt lgkmcnt(0)
	s_barrier
	s_waitcnt lgkmcnt(0)
	s_setprio 0
	v_mfma_f32_16x16x32_bf16 v[142:145], v[82:85], v[162:165], v[142:145]
	v_mfma_f32_16x16x32_bf16 v[138:141], v[98:101], v[162:165], v[138:141]
	v_mfma_f32_16x16x32_bf16 v[126:129], v[82:85], v[180:183], v[126:129]
	v_mfma_f32_16x16x32_bf16 v[122:125], v[98:101], v[180:183], v[122:125]
	v_mfma_f32_16x16x32_bf16 v[110:113], v[82:85], v[188:191], v[110:113]
	v_mfma_f32_16x16x32_bf16 v[106:109], v[98:101], v[188:191], v[106:109]
	v_mfma_f32_16x16x32_bf16 v[78:81], v[82:85], v[200:203], v[78:81]
	v_mfma_f32_16x16x32_bf16 v[74:77], v[98:101], v[200:203], v[74:77]
	v_mfma_f32_16x16x32_bf16 v[142:145], v[86:89], v[166:169], v[142:145]
	v_mfma_f32_16x16x32_bf16 v[138:141], v[102:105], v[166:169], v[138:141]
	v_mfma_f32_16x16x32_bf16 v[126:129], v[86:89], v[184:187], v[126:129]
	v_mfma_f32_16x16x32_bf16 v[122:125], v[102:105], v[184:187], v[122:125]
	v_mfma_f32_16x16x32_bf16 v[110:113], v[86:89], v[196:199], v[110:113]
	v_mfma_f32_16x16x32_bf16 v[106:109], v[102:105], v[196:199], v[106:109]
	v_mfma_f32_16x16x32_bf16 v[78:81], v[86:89], v[204:207], v[78:81]
	v_mfma_f32_16x16x32_bf16 v[74:77], v[102:105], v[204:207], v[74:77]
	v_mfma_f32_16x16x32_bf16 v[134:137], v[146:149], v[162:165], v[134:137]
	v_mfma_f32_16x16x32_bf16 v[130:133], v[154:157], v[162:165], v[130:133]
	v_mfma_f32_16x16x32_bf16 v[118:121], v[146:149], v[180:183], v[118:121]
	v_mfma_f32_16x16x32_bf16 v[114:117], v[154:157], v[180:183], v[114:117]
	v_mfma_f32_16x16x32_bf16 v[94:97], v[146:149], v[188:191], v[94:97]
	v_mfma_f32_16x16x32_bf16 v[90:93], v[154:157], v[188:191], v[90:93]
	v_mfma_f32_16x16x32_bf16 v[70:73], v[146:149], v[200:203], v[70:73]
	v_mfma_f32_16x16x32_bf16 v[66:69], v[154:157], v[200:203], v[66:69]
	v_mfma_f32_16x16x32_bf16 v[134:137], v[150:153], v[166:169], v[134:137]
	v_mfma_f32_16x16x32_bf16 v[130:133], v[158:161], v[166:169], v[130:133]
	v_mfma_f32_16x16x32_bf16 v[118:121], v[150:153], v[184:187], v[118:121]
	v_mfma_f32_16x16x32_bf16 v[114:117], v[158:161], v[184:187], v[114:117]
	v_mfma_f32_16x16x32_bf16 v[94:97], v[150:153], v[196:199], v[94:97]
	v_mfma_f32_16x16x32_bf16 v[90:93], v[158:161], v[196:199], v[90:93]
	v_mfma_f32_16x16x32_bf16 v[70:73], v[150:153], v[204:207], v[70:73]
	v_mfma_f32_16x16x32_bf16 v[66:69], v[158:161], v[204:207], v[66:69]
	s_setprio 1
	s_barrier
	s_mov_b32 m0, s85
	v_lshl_add_u64 v[208:209], s[64:65], 0, v[172:173]
	ds_read_b128 v[162:165], v193 offset:16384
	ds_read_b128 v[166:169], v193 offset:17408
	ds_read_b128 v[180:183], v193 offset:18432
	ds_read_b128 v[184:187], v193 offset:19456
	ds_read_b128 v[188:191], v193 offset:20480
	ds_read_b128 v[196:199], v193 offset:21504
	ds_read_b128 v[200:203], v193 offset:22528
	ds_read_b128 v[204:207], v193 offset:23552
	global_load_lds_dwordx4 v[208:209], off
	v_lshl_add_u64 v[210:211], v[208:209], 0, s[30:31]
	s_mov_b32 m0, s87
	s_nop 0
	global_load_lds_dwordx4 v[210:211], off
	v_lshl_add_u64 v[210:211], v[208:209], 0, s[34:35]
	s_mov_b32 m0, s88
	s_nop 0
	global_load_lds_dwordx4 v[210:211], off
	v_lshl_add_u64 v[210:211], v[208:209], 0, s[36:37]
	s_mov_b32 m0, s89
	s_nop 0
	global_load_lds_dwordx4 v[210:211], off
	v_lshl_add_u64 v[210:211], s[0:1], 0, v[170:171]
	s_mov_b32 m0, s45
	v_lshl_add_u64 v[212:213], v[210:211], 0, s[30:31]
	global_load_lds_dwordx4 v[210:211], off
	s_mov_b32 m0, s46
	s_nop 0
	global_load_lds_dwordx4 v[212:213], off
	s_waitcnt vmcnt(8)
	s_waitcnt lgkmcnt(0)
	s_barrier
	s_waitcnt lgkmcnt(0)
	s_setprio 0
	v_mfma_f32_16x16x32_bf16 v[62:65], v[82:85], v[162:165], v[62:65]
	v_mfma_f32_16x16x32_bf16 v[58:61], v[98:101], v[162:165], v[58:61]
	v_mfma_f32_16x16x32_bf16 v[46:49], v[82:85], v[180:183], v[46:49]
	v_mfma_f32_16x16x32_bf16 v[42:45], v[98:101], v[180:183], v[42:45]
	v_mfma_f32_16x16x32_bf16 v[30:33], v[82:85], v[188:191], v[30:33]
	v_mfma_f32_16x16x32_bf16 v[26:29], v[98:101], v[188:191], v[26:29]
	v_mfma_f32_16x16x32_bf16 v[14:17], v[82:85], v[200:203], v[14:17]
	v_mfma_f32_16x16x32_bf16 v[10:13], v[98:101], v[200:203], v[10:13]
	v_mfma_f32_16x16x32_bf16 v[62:65], v[86:89], v[166:169], v[62:65]
	v_mfma_f32_16x16x32_bf16 v[58:61], v[102:105], v[166:169], v[58:61]
	v_mfma_f32_16x16x32_bf16 v[46:49], v[86:89], v[184:187], v[46:49]
	v_mfma_f32_16x16x32_bf16 v[42:45], v[102:105], v[184:187], v[42:45]
	v_mfma_f32_16x16x32_bf16 v[30:33], v[86:89], v[196:199], v[30:33]
	v_mfma_f32_16x16x32_bf16 v[26:29], v[102:105], v[196:199], v[26:29]
	v_mfma_f32_16x16x32_bf16 v[14:17], v[86:89], v[204:207], v[14:17]
	v_mfma_f32_16x16x32_bf16 v[10:13], v[102:105], v[204:207], v[10:13]
	v_mfma_f32_16x16x32_bf16 v[54:57], v[146:149], v[162:165], v[54:57]
	v_mfma_f32_16x16x32_bf16 v[50:53], v[154:157], v[162:165], v[50:53]
	v_mfma_f32_16x16x32_bf16 v[38:41], v[146:149], v[180:183], v[38:41]
	v_mfma_f32_16x16x32_bf16 v[34:37], v[154:157], v[180:183], v[34:37]
	v_mfma_f32_16x16x32_bf16 v[22:25], v[146:149], v[188:191], v[22:25]
	v_mfma_f32_16x16x32_bf16 v[18:21], v[154:157], v[188:191], v[18:21]
	v_mfma_f32_16x16x32_bf16 v[6:9], v[146:149], v[200:203], v[6:9]
	v_mfma_f32_16x16x32_bf16 v[2:5], v[154:157], v[200:203], v[2:5]
	v_mfma_f32_16x16x32_bf16 v[54:57], v[150:153], v[166:169], v[54:57]
	v_mfma_f32_16x16x32_bf16 v[50:53], v[158:161], v[166:169], v[50:53]
	v_mfma_f32_16x16x32_bf16 v[38:41], v[150:153], v[184:187], v[38:41]
	v_mfma_f32_16x16x32_bf16 v[34:37], v[158:161], v[184:187], v[34:37]
	v_mfma_f32_16x16x32_bf16 v[22:25], v[150:153], v[196:199], v[22:25]
	v_mfma_f32_16x16x32_bf16 v[18:21], v[158:161], v[196:199], v[18:21]
	v_mfma_f32_16x16x32_bf16 v[6:9], v[150:153], v[204:207], v[6:9]
	v_mfma_f32_16x16x32_bf16 v[2:5], v[158:161], v[204:207], v[2:5]
	s_setprio 1
	s_barrier
	ds_read_b128 v[82:85], v194
	ds_read_b128 v[86:89], v194 offset:1024
	ds_read_b128 v[98:101], v194 offset:2048
	ds_read_b128 v[102:105], v194 offset:3072
	ds_read_b128 v[146:149], v195
	ds_read_b128 v[150:153], v195 offset:1024
	ds_read_b128 v[154:157], v195 offset:2048
	ds_read_b128 v[158:161], v195 offset:3072
	s_mov_b32 m0, s47
	v_lshl_add_u64 v[212:213], v[210:211], 0, s[34:35]
	ds_read_b128 v[162:165], v193 offset:32768
	ds_read_b128 v[166:169], v193 offset:33792
	ds_read_b128 v[180:183], v193 offset:34816
	ds_read_b128 v[184:187], v193 offset:35840
	ds_read_b128 v[188:191], v193 offset:36864
	ds_read_b128 v[196:199], v193 offset:37888
	ds_read_b128 v[200:203], v193 offset:38912
	ds_read_b128 v[204:207], v193 offset:39936
	global_load_lds_dwordx4 v[212:213], off
	v_lshl_add_u64 v[212:213], v[210:211], 0, s[36:37]
	s_mov_b32 m0, s52
	s_nop 0
	global_load_lds_dwordx4 v[212:213], off
	s_waitcnt vmcnt(8)
	s_waitcnt lgkmcnt(0)
	s_barrier
	s_waitcnt lgkmcnt(0)
	s_setprio 0
	v_mfma_f32_16x16x32_bf16 v[142:145], v[82:85], v[162:165], v[142:145]
	v_mfma_f32_16x16x32_bf16 v[138:141], v[98:101], v[162:165], v[138:141]
	v_mfma_f32_16x16x32_bf16 v[126:129], v[82:85], v[180:183], v[126:129]
	v_mfma_f32_16x16x32_bf16 v[122:125], v[98:101], v[180:183], v[122:125]
	v_mfma_f32_16x16x32_bf16 v[110:113], v[82:85], v[188:191], v[110:113]
	v_mfma_f32_16x16x32_bf16 v[106:109], v[98:101], v[188:191], v[106:109]
	v_mfma_f32_16x16x32_bf16 v[78:81], v[82:85], v[200:203], v[78:81]
	v_mfma_f32_16x16x32_bf16 v[74:77], v[98:101], v[200:203], v[74:77]
	v_mfma_f32_16x16x32_bf16 v[142:145], v[86:89], v[166:169], v[142:145]
	v_mfma_f32_16x16x32_bf16 v[138:141], v[102:105], v[166:169], v[138:141]
	v_mfma_f32_16x16x32_bf16 v[126:129], v[86:89], v[184:187], v[126:129]
	v_mfma_f32_16x16x32_bf16 v[122:125], v[102:105], v[184:187], v[122:125]
	v_mfma_f32_16x16x32_bf16 v[110:113], v[86:89], v[196:199], v[110:113]
	v_mfma_f32_16x16x32_bf16 v[106:109], v[102:105], v[196:199], v[106:109]
	v_mfma_f32_16x16x32_bf16 v[78:81], v[86:89], v[204:207], v[78:81]
	v_mfma_f32_16x16x32_bf16 v[74:77], v[102:105], v[204:207], v[74:77]
	v_mfma_f32_16x16x32_bf16 v[134:137], v[146:149], v[162:165], v[134:137]
	v_mfma_f32_16x16x32_bf16 v[130:133], v[154:157], v[162:165], v[130:133]
	v_mfma_f32_16x16x32_bf16 v[118:121], v[146:149], v[180:183], v[118:121]
	v_mfma_f32_16x16x32_bf16 v[114:117], v[154:157], v[180:183], v[114:117]
	v_mfma_f32_16x16x32_bf16 v[94:97], v[146:149], v[188:191], v[94:97]
	v_mfma_f32_16x16x32_bf16 v[90:93], v[154:157], v[188:191], v[90:93]
	v_mfma_f32_16x16x32_bf16 v[70:73], v[146:149], v[200:203], v[70:73]
	v_mfma_f32_16x16x32_bf16 v[66:69], v[154:157], v[200:203], v[66:69]
	v_mfma_f32_16x16x32_bf16 v[134:137], v[150:153], v[166:169], v[134:137]
	v_mfma_f32_16x16x32_bf16 v[130:133], v[158:161], v[166:169], v[130:133]
	v_mfma_f32_16x16x32_bf16 v[118:121], v[150:153], v[184:187], v[118:121]
	v_mfma_f32_16x16x32_bf16 v[114:117], v[158:161], v[184:187], v[114:117]
	v_mfma_f32_16x16x32_bf16 v[94:97], v[150:153], v[196:199], v[94:97]
	v_mfma_f32_16x16x32_bf16 v[90:93], v[158:161], v[196:199], v[90:93]
	v_mfma_f32_16x16x32_bf16 v[70:73], v[150:153], v[204:207], v[70:73]
	v_mfma_f32_16x16x32_bf16 v[66:69], v[158:161], v[204:207], v[66:69]
	s_setprio 1
	s_barrier
; #define PG8_WAIT_V(n) asm volatile("s_waitcnt vmcnt(" #n ")" ::: "memory")
; template <class Epi, class Sched, bool ALIGN_EPI = true, bool SP2 = true, bool FULLLINE = false, bool NOSTAGE = false, bool FP8 = false>
; __device__ __forceinline__ void gemm_phase(PG8_LAS unsigned char* lds, const Gemm g, const Sched& S, const Epi& E) {
;     ...
;         for (int t = 2; t < nt; t += 2) PG8_ITER(PG8_WAIT_V(8));
	s_mov_b32 m0, s50
	v_lshl_add_u64 v[212:213], v[208:209], 0, s[38:39]
	ds_read_b128 v[162:165], v193 offset:49152
	ds_read_b128 v[166:169], v193 offset:50176
	ds_read_b128 v[180:183], v193 offset:51200
	ds_read_b128 v[184:187], v193 offset:52224
	ds_read_b128 v[188:191], v193 offset:53248
	ds_read_b128 v[196:199], v193 offset:54272
	ds_read_b128 v[200:203], v193 offset:55296
	ds_read_b128 v[204:207], v193 offset:56320
	global_load_lds_dwordx4 v[212:213], off
	v_lshl_add_u64 v[212:213], v[208:209], 0, s[40:41]
	s_mov_b32 m0, s51
	s_nop 0
	global_load_lds_dwordx4 v[212:213], off
	v_lshl_add_u64 v[212:213], v[208:209], 0, s[14:15]
	s_mov_b32 m0, s33
	v_lshl_add_u64 v[208:209], v[208:209], 0, s[16:17]
	global_load_lds_dwordx4 v[212:213], off
	s_mov_b32 m0, s56
	s_nop 0
	global_load_lds_dwordx4 v[208:209], off
	v_lshl_add_u64 v[208:209], v[210:211], 0, s[38:39]
	s_mov_b32 m0, s53
	s_nop 0
	global_load_lds_dwordx4 v[208:209], off
	v_lshl_add_u64 v[208:209], v[210:211], 0, s[40:41]
	s_mov_b32 m0, s54
	s_nop 0
	global_load_lds_dwordx4 v[208:209], off
	s_waitcnt vmcnt(8)
	s_waitcnt lgkmcnt(0)
	s_barrier
	s_waitcnt lgkmcnt(0)
	s_setprio 0
	v_mfma_f32_16x16x32_bf16 v[62:65], v[82:85], v[162:165], v[62:65]
	v_mfma_f32_16x16x32_bf16 v[58:61], v[98:101], v[162:165], v[58:61]
	v_mfma_f32_16x16x32_bf16 v[46:49], v[82:85], v[180:183], v[46:49]
	v_mfma_f32_16x16x32_bf16 v[42:45], v[98:101], v[180:183], v[42:45]
	v_mfma_f32_16x16x32_bf16 v[30:33], v[82:85], v[188:191], v[30:33]
	v_mfma_f32_16x16x32_bf16 v[26:29], v[98:101], v[188:191], v[26:29]
	v_mfma_f32_16x16x32_bf16 v[14:17], v[82:85], v[200:203], v[14:17]
	v_mfma_f32_16x16x32_bf16 v[10:13], v[98:101], v[200:203], v[10:13]
	v_mfma_f32_16x16x32_bf16 v[62:65], v[86:89], v[166:169], v[62:65]
	v_mfma_f32_16x16x32_bf16 v[58:61], v[102:105], v[166:169], v[58:61]
	v_mfma_f32_16x16x32_bf16 v[46:49], v[86:89], v[184:187], v[46:49]
	v_mfma_f32_16x16x32_bf16 v[42:45], v[102:105], v[184:187], v[42:45]
	v_mfma_f32_16x16x32_bf16 v[30:33], v[86:89], v[196:199], v[30:33]
	v_mfma_f32_16x16x32_bf16 v[26:29], v[102:105], v[196:199], v[26:29]
	v_mfma_f32_16x16x32_bf16 v[14:17], v[86:89], v[204:207], v[14:17]
	v_mfma_f32_16x16x32_bf16 v[10:13], v[102:105], v[204:207], v[10:13]
	v_mfma_f32_16x16x32_bf16 v[54:57], v[146:149], v[162:165], v[54:57]
	v_mfma_f32_16x16x32_bf16 v[50:53], v[154:157], v[162:165], v[50:53]
	v_mfma_f32_16x16x32_bf16 v[38:41], v[146:149], v[180:183], v[38:41]
	v_mfma_f32_16x16x32_bf16 v[34:37], v[154:157], v[180:183], v[34:37]
	v_mfma_f32_16x16x32_bf16 v[22:25], v[146:149], v[188:191], v[22:25]
	v_mfma_f32_16x16x32_bf16 v[18:21], v[154:157], v[188:191], v[18:21]
	v_mfma_f32_16x16x32_bf16 v[6:9], v[146:149], v[200:203], v[6:9]
	v_mfma_f32_16x16x32_bf16 v[2:5], v[154:157], v[200:203], v[2:5]
	v_mfma_f32_16x16x32_bf16 v[54:57], v[150:153], v[166:169], v[54:57]
	v_mfma_f32_16x16x32_bf16 v[50:53], v[158:161], v[166:169], v[50:53]
	v_mfma_f32_16x16x32_bf16 v[38:41], v[150:153], v[184:187], v[38:41]
	v_mfma_f32_16x16x32_bf16 v[34:37], v[158:161], v[184:187], v[34:37]
	v_mfma_f32_16x16x32_bf16 v[22:25], v[150:153], v[196:199], v[22:25]
	v_mfma_f32_16x16x32_bf16 v[18:21], v[158:161], v[196:199], v[18:21]
	v_mfma_f32_16x16x32_bf16 v[6:9], v[150:153], v[204:207], v[6:9]
	v_mfma_f32_16x16x32_bf16 v[2:5], v[158:161], v[204:207], v[2:5]
	s_setprio 1
	s_barrier
	s_add_i32 s69, s69, 2
	s_add_u32 s66, s66, 0x100
	s_addc_u32 s67, s67, 0
	s_add_u32 s57, s57, 0x100
	s_addc_u32 s68, s68, 0
	s_cmpk_gt_u32 s69, 0x55
	s_cbranch_scc0 .LBB0_2390
	s_and_b64 vcc, exec, s[12:13]
	s_cbranch_vccz .LBB0_2393
	s_barrier

; template <class Epi, class Sched, bool ALIGN_EPI = true, bool SP2 = true, bool FULLLINE = false, bool NOSTAGE = false, bool FP8 = false>
; __device__ __forceinline__ void gemm_phase(PG8_LAS unsigned char* lds, const Gemm g, const Sched& S, const Epi& E) {
;     ...
;         const bool has_next = S.next(ui + 1, nxt);
;         const char* nA = has_next ? PG8_ABASE(nxt) : cA; const char* nB = has_next ? PG8_BBASE(nxt) : cB;
.LBB0_2681:
	ds_read_b128 v[2:5], v1
	ds_read_b128 v[6:9], v1 offset:1024
	ds_read_b128 v[10:13], v1 offset:2048
	ds_read_b128 v[14:17], v1 offset:3072
	ds_read_b128 v[18:21], v200
	ds_read_b128 v[22:25], v200 offset:1024
	ds_read_b128 v[26:29], v200 offset:2048
	ds_read_b128 v[30:33], v200 offset:3072
	s_ashr_i32 s31, s30, 31
	s_lshl_b64 s[0:1], s[30:31], 18
	s_add_u32 s38, s43, s0
	s_addc_u32 s39, s46, s1
	s_and_b64 s[0:1], s[10:11], exec
	s_cselect_b32 s31, s39, s63
	s_cselect_b32 s35, s38, s62
	v_lshl_add_u64 v[244:245], s[66:67], 0, v[178:179]
	s_mov_b64 s[0:1], 0x80080
	s_add_i32 s79, s41, 0xc000
	v_lshl_add_u64 v[66:67], v[244:245], 0, s[0:1]
	s_mov_b32 m0, s79
	s_mov_b64 s[0:1], 0xc0080
	s_add_i32 s80, s41, 0xe000
	ds_read_b128 v[34:37], v201
	ds_read_b128 v[38:41], v201 offset:1024
	ds_read_b128 v[42:45], v201 offset:2048
	ds_read_b128 v[46:49], v201 offset:3072
	ds_read_b128 v[50:53], v201 offset:4096
	ds_read_b128 v[54:57], v201 offset:5120
	ds_read_b128 v[58:61], v201 offset:6144
	ds_read_b128 v[62:65], v201 offset:7168
	global_load_lds_dwordx4 v[66:67], off
	v_lshl_add_u64 v[66:67], v[244:245], 0, s[0:1]
	s_mov_b32 m0, s80
	s_nop 0
	global_load_lds_dwordx4 v[66:67], off
	s_waitcnt vmcnt(24)
	s_waitcnt lgkmcnt(0)
	s_barrier
	s_waitcnt lgkmcnt(0)
	s_setprio 0
	v_mfma_f32_16x16x32_bf16 v[66:69], v[2:5], v[34:37], 0
	v_mfma_f32_16x16x32_bf16 v[70:73], v[10:13], v[34:37], 0
	v_mfma_f32_16x16x32_bf16 v[74:77], v[2:5], v[42:45], 0
	v_mfma_f32_16x16x32_bf16 v[78:81], v[10:13], v[42:45], 0
	v_mfma_f32_16x16x32_bf16 v[82:85], v[2:5], v[50:53], 0
	v_mfma_f32_16x16x32_bf16 v[90:93], v[2:5], v[58:61], 0
	v_mfma_f32_16x16x32_bf16 v[66:69], v[6:9], v[38:41], v[66:69]
	v_mfma_f32_16x16x32_bf16 v[70:73], v[14:17], v[38:41], v[70:73]
	v_mfma_f32_16x16x32_bf16 v[74:77], v[6:9], v[46:49], v[74:77]
	v_mfma_f32_16x16x32_bf16 v[78:81], v[14:17], v[46:49], v[78:81]
	v_mfma_f32_16x16x32_bf16 v[82:85], v[6:9], v[54:57], v[82:85]
	v_mfma_f32_16x16x32_bf16 v[86:89], v[10:13], v[50:53], 0
	v_mfma_f32_16x16x32_bf16 v[90:93], v[6:9], v[62:65], v[90:93]
	v_mfma_f32_16x16x32_bf16 v[94:97], v[10:13], v[58:61], 0
	v_mfma_f32_16x16x32_bf16 v[86:89], v[14:17], v[54:57], v[86:89]
	v_mfma_f32_16x16x32_bf16 v[94:97], v[14:17], v[62:65], v[94:97]
	v_mfma_f32_16x16x32_bf16 v[98:101], v[18:21], v[34:37], 0
	v_mfma_f32_16x16x32_bf16 v[34:37], v[26:29], v[34:37], 0
	v_mfma_f32_16x16x32_bf16 v[102:105], v[22:25], v[38:41], v[98:101]
	v_mfma_f32_16x16x32_bf16 v[34:37], v[30:33], v[38:41], v[34:37]
	v_mfma_f32_16x16x32_bf16 v[38:41], v[18:21], v[42:45], 0
	v_mfma_f32_16x16x32_bf16 v[42:45], v[26:29], v[42:45], 0
	v_mfma_f32_16x16x32_bf16 v[38:41], v[22:25], v[46:49], v[38:41]
	v_mfma_f32_16x16x32_bf16 v[42:45], v[30:33], v[46:49], v[42:45]
	v_mfma_f32_16x16x32_bf16 v[46:49], v[18:21], v[50:53], 0
	v_mfma_f32_16x16x32_bf16 v[50:53], v[26:29], v[50:53], 0
	v_mfma_f32_16x16x32_bf16 v[46:49], v[22:25], v[54:57], v[46:49]
	v_mfma_f32_16x16x32_bf16 v[50:53], v[30:33], v[54:57], v[50:53]
	v_mfma_f32_16x16x32_bf16 v[54:57], v[18:21], v[58:61], 0
	v_mfma_f32_16x16x32_bf16 v[58:61], v[26:29], v[58:61], 0
	v_mfma_f32_16x16x32_bf16 v[54:57], v[22:25], v[62:65], v[54:57]
	v_mfma_f32_16x16x32_bf16 v[58:61], v[30:33], v[62:65], v[58:61]
	s_setprio 1
	s_barrier
	v_lshl_add_u64 v[246:247], s[62:63], 0, v[180:181]
	s_add_i32 s81, s75, s47
	v_lshl_add_u64 v[130:131], v[246:247], 0, s[18:19]
	s_mov_b32 m0, s81
	s_mov_b64 s[0:1], 0x10100
	s_add_i32 s82, s81, 0x2000
	ds_read_b128 v[62:65], v201 offset:16384
	ds_read_b128 v[98:101], v201 offset:17408
	ds_read_b128 v[106:109], v201 offset:18432
	ds_read_b128 v[110:113], v201 offset:19456
	ds_read_b128 v[114:117], v201 offset:20480
	ds_read_b128 v[118:121], v201 offset:21504
	ds_read_b128 v[122:125], v201 offset:22528
	ds_read_b128 v[126:129], v201 offset:23552
	global_load_lds_dwordx4 v[130:131], off
	v_lshl_add_u64 v[130:131], v[246:247], 0, s[0:1]
	s_mov_b32 m0, s82
	s_mov_b64 s[0:1], 0x20100
	s_add_i32 s83, s76, s47
	global_load_lds_dwordx4 v[130:131], off
	v_lshl_add_u64 v[130:131], v[246:247], 0, s[0:1]
	s_mov_b32 m0, s83
	s_mov_b64 s[0:1], 0x30100
	s_add_i32 s84, s83, 0x2000
	global_load_lds_dwordx4 v[130:131], off
	v_lshl_add_u64 v[130:131], v[246:247], 0, s[0:1]
	s_mov_b32 m0, s84
	s_mov_b64 s[0:1], 0x40100
	global_load_lds_dwordx4 v[130:131], off
	v_lshl_add_u64 v[130:131], v[244:245], 0, s[18:19]
	s_mov_b32 m0, s41
	s_nop 0
	global_load_lds_dwordx4 v[130:131], off
	v_lshl_add_u64 v[130:131], v[244:245], 0, s[0:1]
	s_mov_b32 m0, s45
	s_nop 0
	global_load_lds_dwordx4 v[130:131], off
	s_waitcnt vmcnt(24)
	s_waitcnt lgkmcnt(0)
	s_barrier
	s_waitcnt lgkmcnt(0)
	s_setprio 0
	v_mfma_f32_16x16x32_bf16 v[130:133], v[2:5], v[62:65], 0
	v_mfma_f32_16x16x32_bf16 v[146:149], v[6:9], v[98:101], v[130:133]
	v_mfma_f32_16x16x32_bf16 v[130:133], v[10:13], v[62:65], 0
	v_mfma_f32_16x16x32_bf16 v[150:153], v[14:17], v[98:101], v[130:133]
	v_mfma_f32_16x16x32_bf16 v[130:133], v[2:5], v[106:109], 0
	v_mfma_f32_16x16x32_bf16 v[154:157], v[6:9], v[110:113], v[130:133]
	v_mfma_f32_16x16x32_bf16 v[130:133], v[10:13], v[106:109], 0
	v_mfma_f32_16x16x32_bf16 v[158:161], v[14:17], v[110:113], v[130:133]
	v_mfma_f32_16x16x32_bf16 v[130:133], v[2:5], v[114:117], 0
	v_mfma_f32_16x16x32_bf16 v[2:5], v[2:5], v[122:125], 0
	v_mfma_f32_16x16x32_bf16 v[162:165], v[6:9], v[118:121], v[130:133]
	v_mfma_f32_16x16x32_bf16 v[2:5], v[6:9], v[126:129], v[2:5]
	v_mfma_f32_16x16x32_bf16 v[6:9], v[10:13], v[122:125], 0
	v_mfma_f32_16x16x32_bf16 v[130:133], v[10:13], v[114:117], 0
	v_mfma_f32_16x16x32_bf16 v[6:9], v[14:17], v[126:129], v[6:9]
	v_mfma_f32_16x16x32_bf16 v[166:169], v[14:17], v[118:121], v[130:133]
	v_mfma_f32_16x16x32_bf16 v[10:13], v[18:21], v[62:65], 0
	v_mfma_f32_16x16x32_bf16 v[170:173], v[22:25], v[98:101], v[10:13]
	v_mfma_f32_16x16x32_bf16 v[10:13], v[26:29], v[62:65], 0
	v_mfma_f32_16x16x32_bf16 v[174:177], v[30:33], v[98:101], v[10:13]
	v_mfma_f32_16x16x32_bf16 v[10:13], v[18:21], v[106:109], 0
	v_mfma_f32_16x16x32_bf16 v[188:191], v[22:25], v[110:113], v[10:13]
	v_mfma_f32_16x16x32_bf16 v[10:13], v[26:29], v[106:109], 0
	v_mfma_f32_16x16x32_bf16 v[106:109], v[30:33], v[110:113], v[10:13]
	v_mfma_f32_16x16x32_bf16 v[10:13], v[18:21], v[114:117], 0
	v_mfma_f32_16x16x32_bf16 v[192:195], v[22:25], v[118:121], v[10:13]
	v_mfma_f32_16x16x32_bf16 v[10:13], v[26:29], v[114:117], 0
	v_mfma_f32_16x16x32_bf16 v[196:199], v[30:33], v[118:121], v[10:13]
	v_mfma_f32_16x16x32_bf16 v[10:13], v[18:21], v[122:125], 0
	v_mfma_f32_16x16x32_bf16 v[204:207], v[22:25], v[126:129], v[10:13]
	v_mfma_f32_16x16x32_bf16 v[10:13], v[26:29], v[122:125], 0
	v_mfma_f32_16x16x32_bf16 v[208:211], v[30:33], v[126:129], v[10:13]
	s_setprio 1
	s_barrier
	s_nop 5
	ds_read_b128 v[10:13], v202
	ds_read_b128 v[14:17], v202 offset:1024
	ds_read_b128 v[18:21], v202 offset:2048
	ds_read_b128 v[22:25], v202 offset:3072
	ds_read_b128 v[212:215], v203
	ds_read_b128 v[216:219], v203 offset:1024
	ds_read_b128 v[220:223], v203 offset:2048
	ds_read_b128 v[224:227], v203 offset:3072
	s_mov_b64 s[0:1], 0x80100
	s_mov_b32 m0, s52
	v_lshl_add_u64 v[98:99], v[244:245], 0, s[0:1]
	s_mov_b64 s[0:1], 0xc0100
	ds_read_b128 v[26:29], v201 offset:32768
	ds_read_b128 v[30:33], v201 offset:33792
	ds_read_b128 v[62:65], v201 offset:34816
	ds_read_b128 v[114:117], v201 offset:35840
	ds_read_b128 v[228:231], v201 offset:36864
	ds_read_b128 v[232:235], v201 offset:37888
	ds_read_b128 v[236:239], v201 offset:38912
	ds_read_b128 v[240:243], v201 offset:39936
	global_load_lds_dwordx4 v[98:99], off
	v_lshl_add_u64 v[98:99], v[244:245], 0, s[0:1]
	s_mov_b32 m0, s53
	s_nop 0
	global_load_lds_dwordx4 v[98:99], off
	s_waitcnt vmcnt(8)
	s_waitcnt lgkmcnt(0)
	s_barrier
	s_waitcnt lgkmcnt(0)
	s_setprio 0
	v_mfma_f32_16x16x32_bf16 v[66:69], v[10:13], v[26:29], v[66:69]
	v_mfma_f32_16x16x32_bf16 v[134:137], v[14:17], v[30:33], v[66:69]
	v_mfma_f32_16x16x32_bf16 v[66:69], v[18:21], v[26:29], v[70:73]
	v_mfma_f32_16x16x32_bf16 v[130:133], v[22:25], v[30:33], v[66:69]
	v_mfma_f32_16x16x32_bf16 v[66:69], v[10:13], v[62:65], v[74:77]
	v_mfma_f32_16x16x32_bf16 v[126:129], v[14:17], v[114:117], v[66:69]
	v_mfma_f32_16x16x32_bf16 v[66:69], v[18:21], v[62:65], v[78:81]
	v_mfma_f32_16x16x32_bf16 v[122:125], v[22:25], v[114:117], v[66:69]
	v_mfma_f32_16x16x32_bf16 v[66:69], v[10:13], v[228:231], v[82:85]
	v_mfma_f32_16x16x32_bf16 v[110:113], v[14:17], v[232:235], v[66:69]
	v_mfma_f32_16x16x32_bf16 v[66:69], v[18:21], v[228:231], v[86:89]
	v_mfma_f32_16x16x32_bf16 v[98:101], v[22:25], v[232:235], v[66:69]
	v_mfma_f32_16x16x32_bf16 v[66:69], v[10:13], v[236:239], v[90:93]
	v_mfma_f32_16x16x32_bf16 v[78:81], v[14:17], v[240:243], v[66:69]
	v_mfma_f32_16x16x32_bf16 v[66:69], v[18:21], v[236:239], v[94:97]
	v_mfma_f32_16x16x32_bf16 v[74:77], v[22:25], v[240:243], v[66:69]
	v_mfma_f32_16x16x32_bf16 v[66:69], v[212:215], v[26:29], v[102:105]
	v_mfma_f32_16x16x32_bf16 v[26:29], v[220:223], v[26:29], v[34:37]
	v_mfma_f32_16x16x32_bf16 v[138:141], v[224:227], v[30:33], v[26:29]
	v_mfma_f32_16x16x32_bf16 v[26:29], v[212:215], v[62:65], v[38:41]
	v_mfma_f32_16x16x32_bf16 v[118:121], v[216:219], v[114:117], v[26:29]
	v_mfma_f32_16x16x32_bf16 v[26:29], v[220:223], v[62:65], v[42:45]
	v_mfma_f32_16x16x32_bf16 v[114:117], v[224:227], v[114:117], v[26:29]
	v_mfma_f32_16x16x32_bf16 v[26:29], v[212:215], v[228:231], v[46:49]
	v_mfma_f32_16x16x32_bf16 v[90:93], v[216:219], v[232:235], v[26:29]
	v_mfma_f32_16x16x32_bf16 v[26:29], v[220:223], v[228:231], v[50:53]
	v_mfma_f32_16x16x32_bf16 v[82:85], v[224:227], v[232:235], v[26:29]
	v_mfma_f32_16x16x32_bf16 v[26:29], v[212:215], v[236:239], v[54:57]
	v_mfma_f32_16x16x32_bf16 v[70:73], v[216:219], v[240:243], v[26:29]
	v_mfma_f32_16x16x32_bf16 v[26:29], v[220:223], v[236:239], v[58:61]
	v_mfma_f32_16x16x32_bf16 v[142:145], v[216:219], v[30:33], v[66:69]
	v_mfma_f32_16x16x32_bf16 v[66:69], v[224:227], v[240:243], v[26:29]
	s_setprio 1
	s_barrier
; #define PG8_WAIT_V(n) asm volatile("s_waitcnt vmcnt(" #n ")" ::: "memory")
; template <class Epi, class Sched, bool ALIGN_EPI = true, bool SP2 = true, bool FULLLINE = false, bool NOSTAGE = false, bool FP8 = false>
; __device__ __forceinline__ void gemm_phase(PG8_LAS unsigned char* lds, const Gemm g, const Sched& S, const Epi& E) {
;     ...
;         for (int t = 2; t < nt; t += 2) PG8_ITER(PG8_WAIT_V(8));
	s_add_i32 s85, s77, s47
	s_nop 3
	v_lshl_add_u64 v[26:27], v[246:247], 0, s[20:21]
	s_mov_b32 m0, s85
	s_mov_b64 s[0:1], 0x10180
	s_add_i32 s87, s85, 0x2000
	ds_read_b128 v[34:37], v201 offset:49152
	ds_read_b128 v[38:41], v201 offset:50176
	ds_read_b128 v[86:89], v201 offset:51200
	ds_read_b128 v[94:97], v201 offset:52224
	ds_read_b128 v[102:105], v201 offset:53248
	ds_read_b128 v[228:231], v201 offset:54272
	ds_read_b128 v[232:235], v201 offset:55296
	ds_read_b128 v[236:239], v201 offset:56320
	global_load_lds_dwordx4 v[26:27], off
	v_lshl_add_u64 v[26:27], v[246:247], 0, s[0:1]
	s_mov_b32 m0, s87
	s_mov_b64 s[0:1], 0x20180
	s_add_i32 s50, s78, s47
	global_load_lds_dwordx4 v[26:27], off
	v_lshl_add_u64 v[26:27], v[246:247], 0, s[0:1]
	s_mov_b32 m0, s50
	s_mov_b64 s[0:1], 0x30180
	s_add_i32 s51, s50, 0x2000
	global_load_lds_dwordx4 v[26:27], off
	v_lshl_add_u64 v[26:27], v[246:247], 0, s[0:1]
	s_mov_b32 m0, s51
	s_mov_b64 s[0:1], 0x40180
	global_load_lds_dwordx4 v[26:27], off
	v_lshl_add_u64 v[26:27], v[244:245], 0, s[20:21]
	s_mov_b32 m0, s54
	s_nop 0
	global_load_lds_dwordx4 v[26:27], off
	v_lshl_add_u64 v[26:27], v[244:245], 0, s[0:1]
	s_mov_b32 m0, s55
	s_nop 0
	global_load_lds_dwordx4 v[26:27], off
	s_waitcnt vmcnt(8)
	s_waitcnt lgkmcnt(0)
	s_barrier
	s_waitcnt lgkmcnt(0)
	s_setprio 0
	v_mfma_f32_16x16x32_bf16 v[26:29], v[10:13], v[34:37], v[146:149]
	v_mfma_f32_16x16x32_bf16 v[62:65], v[14:17], v[38:41], v[26:29]
	v_mfma_f32_16x16x32_bf16 v[26:29], v[18:21], v[34:37], v[150:153]
	v_mfma_f32_16x16x32_bf16 v[58:61], v[22:25], v[38:41], v[26:29]
	v_mfma_f32_16x16x32_bf16 v[26:29], v[10:13], v[86:89], v[154:157]
	v_mfma_f32_16x16x32_bf16 v[46:49], v[14:17], v[94:97], v[26:29]
	v_mfma_f32_16x16x32_bf16 v[26:29], v[18:21], v[86:89], v[158:161]
	v_mfma_f32_16x16x32_bf16 v[42:45], v[22:25], v[94:97], v[26:29]
	v_mfma_f32_16x16x32_bf16 v[26:29], v[10:13], v[102:105], v[162:165]
	v_mfma_f32_16x16x32_bf16 v[2:5], v[10:13], v[232:235], v[2:5]
	v_mfma_f32_16x16x32_bf16 v[30:33], v[14:17], v[228:231], v[26:29]
	v_mfma_f32_16x16x32_bf16 v[26:29], v[18:21], v[102:105], v[166:169]
	v_mfma_f32_16x16x32_bf16 v[14:17], v[14:17], v[236:239], v[2:5]
	v_mfma_f32_16x16x32_bf16 v[2:5], v[18:21], v[232:235], v[6:9]
	v_mfma_f32_16x16x32_bf16 v[26:29], v[22:25], v[228:231], v[26:29]
	v_mfma_f32_16x16x32_bf16 v[10:13], v[22:25], v[236:239], v[2:5]
	v_mfma_f32_16x16x32_bf16 v[2:5], v[212:215], v[34:37], v[170:173]
	v_mfma_f32_16x16x32_bf16 v[54:57], v[216:219], v[38:41], v[2:5]
	v_mfma_f32_16x16x32_bf16 v[2:5], v[220:223], v[34:37], v[174:177]
	v_mfma_f32_16x16x32_bf16 v[50:53], v[224:227], v[38:41], v[2:5]
	v_mfma_f32_16x16x32_bf16 v[2:5], v[212:215], v[86:89], v[188:191]
	v_mfma_f32_16x16x32_bf16 v[38:41], v[216:219], v[94:97], v[2:5]
	v_mfma_f32_16x16x32_bf16 v[2:5], v[220:223], v[86:89], v[106:109]
	v_mfma_f32_16x16x32_bf16 v[34:37], v[224:227], v[94:97], v[2:5]
	v_mfma_f32_16x16x32_bf16 v[2:5], v[212:215], v[102:105], v[192:195]
	v_mfma_f32_16x16x32_bf16 v[22:25], v[216:219], v[228:231], v[2:5]
	v_mfma_f32_16x16x32_bf16 v[2:5], v[220:223], v[102:105], v[196:199]
	v_mfma_f32_16x16x32_bf16 v[18:21], v[224:227], v[228:231], v[2:5]
	v_mfma_f32_16x16x32_bf16 v[2:5], v[212:215], v[232:235], v[204:207]
	v_mfma_f32_16x16x32_bf16 v[6:9], v[216:219], v[236:239], v[2:5]
	v_mfma_f32_16x16x32_bf16 v[2:5], v[220:223], v[232:235], v[208:211]
	v_mfma_f32_16x16x32_bf16 v[2:5], v[224:227], v[236:239], v[2:5]
	s_setprio 1
	s_barrier
	s_add_u32 s10, s66, 0x80180
	s_addc_u32 s11, s67, 0
	s_add_u32 s33, s62, 0x200
	s_addc_u32 s56, s63, 0
	s_mov_b32 s57, 0
.LBB0_2682:
	ds_read_b128 v[86:89], v1
	ds_read_b128 v[94:97], v1 offset:1024
	ds_read_b128 v[102:105], v1 offset:2048
	ds_read_b128 v[106:109], v1 offset:3072
	ds_read_b128 v[146:149], v200
	ds_read_b128 v[150:153], v200 offset:1024
	ds_read_b128 v[154:157], v200 offset:2048
	ds_read_b128 v[158:161], v200 offset:3072
	s_add_u32 s0, s10, 0xfff80080
	s_addc_u32 s1, s11, -1
	s_cmp_eq_u32 s57, 4
	s_cselect_b32 s1, s37, s1
	s_cselect_b32 s0, s36, s0
	s_cselect_b32 s63, s31, s56
	s_cselect_b32 s62, s35, s33
	s_mov_b32 m0, s79
	v_lshl_add_u64 v[208:209], s[10:11], 0, v[182:183]
	ds_read_b128 v[162:165], v201
	ds_read_b128 v[166:169], v201 offset:1024
	ds_read_b128 v[170:173], v201 offset:2048
	ds_read_b128 v[174:177], v201 offset:3072
	ds_read_b128 v[188:191], v201 offset:4096
	ds_read_b128 v[192:195], v201 offset:5120
	ds_read_b128 v[196:199], v201 offset:6144
	ds_read_b128 v[204:207], v201 offset:7168
	global_load_lds_dwordx4 v[208:209], off
	v_lshl_add_u64 v[208:209], v[208:209], 0, s[22:23]
	s_mov_b32 m0, s80
	s_nop 0
	global_load_lds_dwordx4 v[208:209], off
	s_waitcnt vmcnt(8)
	s_waitcnt lgkmcnt(0)
	s_barrier
	s_waitcnt lgkmcnt(0)
	s_setprio 0
	v_mfma_f32_16x16x32_bf16 v[134:137], v[86:89], v[162:165], v[134:137]
	v_mfma_f32_16x16x32_bf16 v[130:133], v[102:105], v[162:165], v[130:133]
	v_mfma_f32_16x16x32_bf16 v[126:129], v[86:89], v[170:173], v[126:129]
	v_mfma_f32_16x16x32_bf16 v[122:125], v[102:105], v[170:173], v[122:125]
	v_mfma_f32_16x16x32_bf16 v[110:113], v[86:89], v[188:191], v[110:113]
	v_mfma_f32_16x16x32_bf16 v[98:101], v[102:105], v[188:191], v[98:101]
	v_mfma_f32_16x16x32_bf16 v[78:81], v[86:89], v[196:199], v[78:81]
	v_mfma_f32_16x16x32_bf16 v[74:77], v[102:105], v[196:199], v[74:77]
	v_mfma_f32_16x16x32_bf16 v[134:137], v[94:97], v[166:169], v[134:137]
	v_mfma_f32_16x16x32_bf16 v[130:133], v[106:109], v[166:169], v[130:133]
	v_mfma_f32_16x16x32_bf16 v[126:129], v[94:97], v[174:177], v[126:129]
	v_mfma_f32_16x16x32_bf16 v[122:125], v[106:109], v[174:177], v[122:125]
	v_mfma_f32_16x16x32_bf16 v[110:113], v[94:97], v[192:195], v[110:113]
	v_mfma_f32_16x16x32_bf16 v[98:101], v[106:109], v[192:195], v[98:101]
	v_mfma_f32_16x16x32_bf16 v[78:81], v[94:97], v[204:207], v[78:81]
	v_mfma_f32_16x16x32_bf16 v[74:77], v[106:109], v[204:207], v[74:77]
	v_mfma_f32_16x16x32_bf16 v[142:145], v[146:149], v[162:165], v[142:145]
	v_mfma_f32_16x16x32_bf16 v[138:141], v[154:157], v[162:165], v[138:141]
	v_mfma_f32_16x16x32_bf16 v[118:121], v[146:149], v[170:173], v[118:121]
	v_mfma_f32_16x16x32_bf16 v[114:117], v[154:157], v[170:173], v[114:117]
	v_mfma_f32_16x16x32_bf16 v[90:93], v[146:149], v[188:191], v[90:93]
	v_mfma_f32_16x16x32_bf16 v[82:85], v[154:157], v[188:191], v[82:85]
	v_mfma_f32_16x16x32_bf16 v[70:73], v[146:149], v[196:199], v[70:73]
	v_mfma_f32_16x16x32_bf16 v[66:69], v[154:157], v[196:199], v[66:69]
	v_mfma_f32_16x16x32_bf16 v[142:145], v[150:153], v[166:169], v[142:145]
	v_mfma_f32_16x16x32_bf16 v[138:141], v[158:161], v[166:169], v[138:141]
	v_mfma_f32_16x16x32_bf16 v[118:121], v[150:153], v[174:177], v[118:121]
	v_mfma_f32_16x16x32_bf16 v[114:117], v[158:161], v[174:177], v[114:117]
	v_mfma_f32_16x16x32_bf16 v[90:93], v[150:153], v[192:195], v[90:93]
	v_mfma_f32_16x16x32_bf16 v[82:85], v[158:161], v[192:195], v[82:85]
	v_mfma_f32_16x16x32_bf16 v[70:73], v[150:153], v[204:207], v[70:73]
	v_mfma_f32_16x16x32_bf16 v[66:69], v[158:161], v[204:207], v[66:69]
	s_setprio 1
	s_barrier
	s_mov_b32 m0, s81
	v_lshl_add_u64 v[208:209], s[62:63], 0, v[180:181]
	s_mov_b64 s[62:63], 0x10000
	ds_read_b128 v[162:165], v201 offset:16384
	ds_read_b128 v[166:169], v201 offset:17408
	ds_read_b128 v[170:173], v201 offset:18432
	ds_read_b128 v[174:177], v201 offset:19456
	ds_read_b128 v[188:191], v201 offset:20480
	ds_read_b128 v[192:195], v201 offset:21504
	ds_read_b128 v[196:199], v201 offset:22528
	ds_read_b128 v[204:207], v201 offset:23552
	global_load_lds_dwordx4 v[208:209], off
	v_lshl_add_u64 v[210:211], v[208:209], 0, s[62:63]
	s_mov_b32 m0, s82
	s_mov_b64 s[62:63], 0x20000
	global_load_lds_dwordx4 v[210:211], off
	v_lshl_add_u64 v[210:211], v[208:209], 0, s[62:63]
	s_mov_b32 m0, s83
	s_mov_b64 s[62:63], 0x30000
	global_load_lds_dwordx4 v[210:211], off
	v_lshl_add_u64 v[210:211], v[208:209], 0, s[62:63]
	s_mov_b32 m0, s84
	s_nop 0
	global_load_lds_dwordx4 v[210:211], off
	v_lshl_add_u64 v[210:211], s[0:1], 0, v[178:179]
	s_mov_b32 m0, s41
	v_lshl_add_u64 v[212:213], v[210:211], 0, s[22:23]
	global_load_lds_dwordx4 v[210:211], off
	s_mov_b32 m0, s45
	s_nop 0
	global_load_lds_dwordx4 v[212:213], off
	s_waitcnt vmcnt(8)
	s_waitcnt lgkmcnt(0)
	s_barrier
	s_waitcnt lgkmcnt(0)
	s_setprio 0
	v_mfma_f32_16x16x32_bf16 v[62:65], v[86:89], v[162:165], v[62:65]
	v_mfma_f32_16x16x32_bf16 v[58:61], v[102:105], v[162:165], v[58:61]
	v_mfma_f32_16x16x32_bf16 v[46:49], v[86:89], v[170:173], v[46:49]
	v_mfma_f32_16x16x32_bf16 v[42:45], v[102:105], v[170:173], v[42:45]
	v_mfma_f32_16x16x32_bf16 v[30:33], v[86:89], v[188:191], v[30:33]
	v_mfma_f32_16x16x32_bf16 v[26:29], v[102:105], v[188:191], v[26:29]
	v_mfma_f32_16x16x32_bf16 v[14:17], v[86:89], v[196:199], v[14:17]
	v_mfma_f32_16x16x32_bf16 v[10:13], v[102:105], v[196:199], v[10:13]
	v_mfma_f32_16x16x32_bf16 v[62:65], v[94:97], v[166:169], v[62:65]
	v_mfma_f32_16x16x32_bf16 v[58:61], v[106:109], v[166:169], v[58:61]
	v_mfma_f32_16x16x32_bf16 v[46:49], v[94:97], v[174:177], v[46:49]
	v_mfma_f32_16x16x32_bf16 v[42:45], v[106:109], v[174:177], v[42:45]
	v_mfma_f32_16x16x32_bf16 v[30:33], v[94:97], v[192:195], v[30:33]
	v_mfma_f32_16x16x32_bf16 v[26:29], v[106:109], v[192:195], v[26:29]
	v_mfma_f32_16x16x32_bf16 v[14:17], v[94:97], v[204:207], v[14:17]
	v_mfma_f32_16x16x32_bf16 v[10:13], v[106:109], v[204:207], v[10:13]
	v_mfma_f32_16x16x32_bf16 v[54:57], v[146:149], v[162:165], v[54:57]
	v_mfma_f32_16x16x32_bf16 v[50:53], v[154:157], v[162:165], v[50:53]
	v_mfma_f32_16x16x32_bf16 v[38:41], v[146:149], v[170:173], v[38:41]
	v_mfma_f32_16x16x32_bf16 v[34:37], v[154:157], v[170:173], v[34:37]
	v_mfma_f32_16x16x32_bf16 v[22:25], v[146:149], v[188:191], v[22:25]
	v_mfma_f32_16x16x32_bf16 v[18:21], v[154:157], v[188:191], v[18:21]
	v_mfma_f32_16x16x32_bf16 v[6:9], v[146:149], v[196:199], v[6:9]
	v_mfma_f32_16x16x32_bf16 v[2:5], v[154:157], v[196:199], v[2:5]
	v_mfma_f32_16x16x32_bf16 v[54:57], v[150:153], v[166:169], v[54:57]
	v_mfma_f32_16x16x32_bf16 v[50:53], v[158:161], v[166:169], v[50:53]
	v_mfma_f32_16x16x32_bf16 v[38:41], v[150:153], v[174:177], v[38:41]
	v_mfma_f32_16x16x32_bf16 v[34:37], v[158:161], v[174:177], v[34:37]
	v_mfma_f32_16x16x32_bf16 v[22:25], v[150:153], v[192:195], v[22:25]
	v_mfma_f32_16x16x32_bf16 v[18:21], v[158:161], v[192:195], v[18:21]
	v_mfma_f32_16x16x32_bf16 v[6:9], v[150:153], v[204:207], v[6:9]
	v_mfma_f32_16x16x32_bf16 v[2:5], v[158:161], v[204:207], v[2:5]
	s_setprio 1
	s_barrier
; #define PG8_WAIT_V(n) asm volatile("s_waitcnt vmcnt(" #n ")" ::: "memory")
; template <class Epi, class Sched, bool ALIGN_EPI = true, bool SP2 = true, bool FULLLINE = false, bool NOSTAGE = false, bool FP8 = false>
; __device__ __forceinline__ void gemm_phase(PG8_LAS unsigned char* lds, const Gemm g, const Sched& S, const Epi& E) {
;     ...
;         for (int t = 2; t < nt; t += 2) PG8_ITER(PG8_WAIT_V(8));
	ds_read_b128 v[86:89], v202
	ds_read_b128 v[94:97], v202 offset:1024
	ds_read_b128 v[102:105], v202 offset:2048
	ds_read_b128 v[106:109], v202 offset:3072
	ds_read_b128 v[146:149], v203
	ds_read_b128 v[150:153], v203 offset:1024
	ds_read_b128 v[154:157], v203 offset:2048
	ds_read_b128 v[158:161], v203 offset:3072
	s_mov_b32 m0, s52
	v_lshl_add_u64 v[212:213], v[210:211], 0, s[24:25]
	s_mov_b64 s[0:1], 0xc0000
	ds_read_b128 v[162:165], v201 offset:32768
	ds_read_b128 v[166:169], v201 offset:33792
	ds_read_b128 v[170:173], v201 offset:34816
	ds_read_b128 v[174:177], v201 offset:35840
	ds_read_b128 v[188:191], v201 offset:36864
	ds_read_b128 v[192:195], v201 offset:37888
	ds_read_b128 v[196:199], v201 offset:38912
	ds_read_b128 v[204:207], v201 offset:39936
	global_load_lds_dwordx4 v[212:213], off
	v_lshl_add_u64 v[212:213], v[210:211], 0, s[0:1]
	s_mov_b32 m0, s53
	s_nop 0
	global_load_lds_dwordx4 v[212:213], off
	s_waitcnt vmcnt(8)
	s_waitcnt lgkmcnt(0)
	s_barrier
	s_waitcnt lgkmcnt(0)
	s_setprio 0
	v_mfma_f32_16x16x32_bf16 v[134:137], v[86:89], v[162:165], v[134:137]
	v_mfma_f32_16x16x32_bf16 v[130:133], v[102:105], v[162:165], v[130:133]
	v_mfma_f32_16x16x32_bf16 v[126:129], v[86:89], v[170:173], v[126:129]
	v_mfma_f32_16x16x32_bf16 v[122:125], v[102:105], v[170:173], v[122:125]
	v_mfma_f32_16x16x32_bf16 v[110:113], v[86:89], v[188:191], v[110:113]
	v_mfma_f32_16x16x32_bf16 v[98:101], v[102:105], v[188:191], v[98:101]
	v_mfma_f32_16x16x32_bf16 v[78:81], v[86:89], v[196:199], v[78:81]
	v_mfma_f32_16x16x32_bf16 v[74:77], v[102:105], v[196:199], v[74:77]
	v_mfma_f32_16x16x32_bf16 v[134:137], v[94:97], v[166:169], v[134:137]
	v_mfma_f32_16x16x32_bf16 v[130:133], v[106:109], v[166:169], v[130:133]
	v_mfma_f32_16x16x32_bf16 v[126:129], v[94:97], v[174:177], v[126:129]
	v_mfma_f32_16x16x32_bf16 v[122:125], v[106:109], v[174:177], v[122:125]
	v_mfma_f32_16x16x32_bf16 v[110:113], v[94:97], v[192:195], v[110:113]
	v_mfma_f32_16x16x32_bf16 v[98:101], v[106:109], v[192:195], v[98:101]
	v_mfma_f32_16x16x32_bf16 v[78:81], v[94:97], v[204:207], v[78:81]
	v_mfma_f32_16x16x32_bf16 v[74:77], v[106:109], v[204:207], v[74:77]
	v_mfma_f32_16x16x32_bf16 v[142:145], v[146:149], v[162:165], v[142:145]
	v_mfma_f32_16x16x32_bf16 v[138:141], v[154:157], v[162:165], v[138:141]
	v_mfma_f32_16x16x32_bf16 v[118:121], v[146:149], v[170:173], v[118:121]
	v_mfma_f32_16x16x32_bf16 v[114:117], v[154:157], v[170:173], v[114:117]
	v_mfma_f32_16x16x32_bf16 v[90:93], v[146:149], v[188:191], v[90:93]
	v_mfma_f32_16x16x32_bf16 v[82:85], v[154:157], v[188:191], v[82:85]
	v_mfma_f32_16x16x32_bf16 v[70:73], v[146:149], v[196:199], v[70:73]
	v_mfma_f32_16x16x32_bf16 v[66:69], v[154:157], v[196:199], v[66:69]
	v_mfma_f32_16x16x32_bf16 v[142:145], v[150:153], v[166:169], v[142:145]
	v_mfma_f32_16x16x32_bf16 v[138:141], v[158:161], v[166:169], v[138:141]
	v_mfma_f32_16x16x32_bf16 v[118:121], v[150:153], v[174:177], v[118:121]
	v_mfma_f32_16x16x32_bf16 v[114:117], v[158:161], v[174:177], v[114:117]
	v_mfma_f32_16x16x32_bf16 v[90:93], v[150:153], v[192:195], v[90:93]
	v_mfma_f32_16x16x32_bf16 v[82:85], v[158:161], v[192:195], v[82:85]
	v_mfma_f32_16x16x32_bf16 v[70:73], v[150:153], v[204:207], v[70:73]
	v_mfma_f32_16x16x32_bf16 v[66:69], v[158:161], v[204:207], v[66:69]
	s_setprio 1
	s_barrier
	s_mov_b32 m0, s85
	v_lshl_add_u64 v[212:213], v[208:209], 0, s[26:27]
	s_mov_b64 s[0:1], 0x10080
	ds_read_b128 v[162:165], v201 offset:49152
	ds_read_b128 v[166:169], v201 offset:50176
	ds_read_b128 v[170:173], v201 offset:51200
	ds_read_b128 v[174:177], v201 offset:52224
	ds_read_b128 v[188:191], v201 offset:53248
	ds_read_b128 v[192:195], v201 offset:54272
	ds_read_b128 v[196:199], v201 offset:55296
	ds_read_b128 v[204:207], v201 offset:56320
	global_load_lds_dwordx4 v[212:213], off
	v_lshl_add_u64 v[212:213], v[208:209], 0, s[0:1]
	s_mov_b32 m0, s87
	s_mov_b64 s[0:1], 0x20080
	global_load_lds_dwordx4 v[212:213], off
	v_lshl_add_u64 v[212:213], v[208:209], 0, s[0:1]
	s_mov_b32 m0, s50
	s_mov_b64 s[0:1], 0x30080
	global_load_lds_dwordx4 v[212:213], off
	v_lshl_add_u64 v[208:209], v[208:209], 0, s[0:1]
	s_mov_b32 m0, s51
	s_mov_b64 s[0:1], 0x40080
	global_load_lds_dwordx4 v[208:209], off
	v_lshl_add_u64 v[208:209], v[210:211], 0, s[26:27]
	s_mov_b32 m0, s54
	s_nop 0
	global_load_lds_dwordx4 v[208:209], off
	v_lshl_add_u64 v[208:209], v[210:211], 0, s[0:1]
	s_mov_b32 m0, s55
	s_nop 0
	global_load_lds_dwordx4 v[208:209], off
	s_waitcnt vmcnt(8)
	s_waitcnt lgkmcnt(0)
	s_barrier
	s_waitcnt lgkmcnt(0)
	s_setprio 0
	v_mfma_f32_16x16x32_bf16 v[62:65], v[86:89], v[162:165], v[62:65]
	v_mfma_f32_16x16x32_bf16 v[58:61], v[102:105], v[162:165], v[58:61]
	v_mfma_f32_16x16x32_bf16 v[46:49], v[86:89], v[170:173], v[46:49]
	v_mfma_f32_16x16x32_bf16 v[42:45], v[102:105], v[170:173], v[42:45]
	v_mfma_f32_16x16x32_bf16 v[30:33], v[86:89], v[188:191], v[30:33]
	v_mfma_f32_16x16x32_bf16 v[26:29], v[102:105], v[188:191], v[26:29]
	v_mfma_f32_16x16x32_bf16 v[14:17], v[86:89], v[196:199], v[14:17]
	v_mfma_f32_16x16x32_bf16 v[10:13], v[102:105], v[196:199], v[10:13]
	v_mfma_f32_16x16x32_bf16 v[62:65], v[94:97], v[166:169], v[62:65]
	v_mfma_f32_16x16x32_bf16 v[58:61], v[106:109], v[166:169], v[58:61]
	v_mfma_f32_16x16x32_bf16 v[46:49], v[94:97], v[174:177], v[46:49]
	v_mfma_f32_16x16x32_bf16 v[42:45], v[106:109], v[174:177], v[42:45]
	v_mfma_f32_16x16x32_bf16 v[30:33], v[94:97], v[192:195], v[30:33]
	v_mfma_f32_16x16x32_bf16 v[26:29], v[106:109], v[192:195], v[26:29]
	v_mfma_f32_16x16x32_bf16 v[14:17], v[94:97], v[204:207], v[14:17]
	v_mfma_f32_16x16x32_bf16 v[10:13], v[106:109], v[204:207], v[10:13]
	v_mfma_f32_16x16x32_bf16 v[54:57], v[146:149], v[162:165], v[54:57]
	v_mfma_f32_16x16x32_bf16 v[50:53], v[154:157], v[162:165], v[50:53]
	v_mfma_f32_16x16x32_bf16 v[38:41], v[146:149], v[170:173], v[38:41]
	v_mfma_f32_16x16x32_bf16 v[34:37], v[154:157], v[170:173], v[34:37]
	v_mfma_f32_16x16x32_bf16 v[22:25], v[146:149], v[188:191], v[22:25]
	v_mfma_f32_16x16x32_bf16 v[18:21], v[154:157], v[188:191], v[18:21]
	v_mfma_f32_16x16x32_bf16 v[6:9], v[146:149], v[196:199], v[6:9]
	v_mfma_f32_16x16x32_bf16 v[2:5], v[154:157], v[196:199], v[2:5]
	v_mfma_f32_16x16x32_bf16 v[54:57], v[150:153], v[166:169], v[54:57]
	v_mfma_f32_16x16x32_bf16 v[50:53], v[158:161], v[166:169], v[50:53]
	v_mfma_f32_16x16x32_bf16 v[38:41], v[150:153], v[174:177], v[38:41]
	v_mfma_f32_16x16x32_bf16 v[34:37], v[158:161], v[174:177], v[34:37]
	v_mfma_f32_16x16x32_bf16 v[22:25], v[150:153], v[192:195], v[22:25]
	v_mfma_f32_16x16x32_bf16 v[18:21], v[158:161], v[192:195], v[18:21]
	v_mfma_f32_16x16x32_bf16 v[6:9], v[150:153], v[204:207], v[6:9]
	v_mfma_f32_16x16x32_bf16 v[2:5], v[158:161], v[204:207], v[2:5]
	s_setprio 1
	s_barrier
	s_add_i32 s57, s57, 2
	s_add_u32 s10, s10, 0x100
	s_addc_u32 s11, s11, 0
	s_add_u32 s33, s33, 0x100
	s_addc_u32 s56, s56, 0
	s_cmp_gt_u32 s57, 5
	s_cbranch_scc0 .LBB0_2682
	s_and_b64 vcc, exec, s[14:15]
	s_cbranch_vccz .LBB0_2685
	s_barrier

; template <class Epi, class Sched, bool ALIGN_EPI = true, bool SP2 = true, bool FULLLINE = false, bool NOSTAGE = false, bool FP8 = false>
; __device__ __forceinline__ void gemm_phase(PG8_LAS unsigned char* lds, const Gemm g, const Sched& S, const Epi& E) {
;     ...
;         const bool has_next = S.next(ui + 1, nxt);
;         const char* nA = has_next ? PG8_ABASE(nxt) : cA; const char* nB = has_next ? PG8_BBASE(nxt) : cB;
.LBB0_2861:
	s_ashr_i32 s45, s44, 31
	s_lshl_b64 s[0:1], s[44:45], 20
	s_add_u32 s46, s58, s0
	ds_read_b128 v[2:5], v1
	ds_read_b128 v[6:9], v1 offset:1024
	ds_read_b128 v[10:13], v1 offset:2048
	ds_read_b128 v[14:17], v1 offset:3072
	ds_read_b128 v[18:21], v142
	ds_read_b128 v[22:25], v142 offset:1024
	ds_read_b128 v[26:29], v142 offset:2048
	ds_read_b128 v[30:33], v142 offset:3072
	s_addc_u32 s47, s59, s1
	s_ashr_i32 s41, s40, 31
	s_lshl_b64 s[0:1], s[40:41], 20
	s_add_u32 s62, s3, s0
	s_addc_u32 s63, s42, s1
	s_and_b64 s[0:1], s[8:9], exec
	s_cselect_b32 s41, s47, s71
	s_cselect_b32 s45, s46, s70
	s_cselect_b32 s87, s63, s69
	s_cselect_b32 s88, s62, s68
	v_lshl_add_u64 v[140:141], s[70:71], 0, v[132:133]
	s_mov_b32 m0, s79
	v_lshl_add_u64 v[66:67], v[140:141], 0, s[12:13]
	ds_read_b128 v[34:37], v143
	ds_read_b128 v[38:41], v143 offset:1024
	ds_read_b128 v[42:45], v143 offset:2048
	ds_read_b128 v[46:49], v143 offset:3072
	ds_read_b128 v[50:53], v143 offset:4096
	ds_read_b128 v[54:57], v143 offset:5120
	ds_read_b128 v[58:61], v143 offset:6144
	ds_read_b128 v[62:65], v143 offset:7168
	global_load_lds_dwordx4 v[66:67], off
	v_lshl_add_u64 v[66:67], v[140:141], 0, s[14:15]
	s_mov_b32 m0, s80
	s_nop 0
	global_load_lds_dwordx4 v[66:67], off
	s_waitcnt vmcnt(16)
	s_waitcnt lgkmcnt(0)
	s_barrier
	s_waitcnt lgkmcnt(0)
	s_setprio 0
	v_mfma_f32_16x16x32_bf16 v[86:89], v[10:13], v[50:53], 0
	v_mfma_f32_16x16x32_bf16 v[90:93], v[14:17], v[54:57], v[86:89]
	v_mfma_f32_16x16x32_bf16 v[86:89], v[2:5], v[58:61], 0
	v_mfma_f32_16x16x32_bf16 v[66:69], v[2:5], v[34:37], 0
	v_mfma_f32_16x16x32_bf16 v[70:73], v[10:13], v[34:37], 0
	v_mfma_f32_16x16x32_bf16 v[74:77], v[2:5], v[42:45], 0
	v_mfma_f32_16x16x32_bf16 v[78:81], v[10:13], v[42:45], 0
	v_mfma_f32_16x16x32_bf16 v[82:85], v[2:5], v[50:53], 0
	v_mfma_f32_16x16x32_bf16 v[94:97], v[6:9], v[62:65], v[86:89]
	v_mfma_f32_16x16x32_bf16 v[86:89], v[10:13], v[58:61], 0
	v_mfma_f32_16x16x32_bf16 v[66:69], v[6:9], v[38:41], v[66:69]
	v_mfma_f32_16x16x32_bf16 v[70:73], v[14:17], v[38:41], v[70:73]
	v_mfma_f32_16x16x32_bf16 v[74:77], v[6:9], v[46:49], v[74:77]
	v_mfma_f32_16x16x32_bf16 v[78:81], v[14:17], v[46:49], v[78:81]
	v_mfma_f32_16x16x32_bf16 v[82:85], v[6:9], v[54:57], v[82:85]
	v_mfma_f32_16x16x32_bf16 v[106:109], v[14:17], v[62:65], v[86:89]
	v_mfma_f32_16x16x32_bf16 v[86:89], v[18:21], v[34:37], 0
	v_mfma_f32_16x16x32_bf16 v[34:37], v[26:29], v[34:37], 0
	v_mfma_f32_16x16x32_bf16 v[110:113], v[22:25], v[38:41], v[86:89]
	v_mfma_f32_16x16x32_bf16 v[34:37], v[30:33], v[38:41], v[34:37]
	v_mfma_f32_16x16x32_bf16 v[38:41], v[18:21], v[42:45], 0
	v_mfma_f32_16x16x32_bf16 v[42:45], v[26:29], v[42:45], 0
	v_mfma_f32_16x16x32_bf16 v[38:41], v[22:25], v[46:49], v[38:41]
	v_mfma_f32_16x16x32_bf16 v[42:45], v[30:33], v[46:49], v[42:45]
	v_mfma_f32_16x16x32_bf16 v[46:49], v[18:21], v[50:53], 0
	v_mfma_f32_16x16x32_bf16 v[50:53], v[26:29], v[50:53], 0
	v_mfma_f32_16x16x32_bf16 v[46:49], v[22:25], v[54:57], v[46:49]
	v_mfma_f32_16x16x32_bf16 v[50:53], v[30:33], v[54:57], v[50:53]
	v_mfma_f32_16x16x32_bf16 v[54:57], v[18:21], v[58:61], 0
	v_mfma_f32_16x16x32_bf16 v[58:61], v[26:29], v[58:61], 0
	v_mfma_f32_16x16x32_bf16 v[54:57], v[22:25], v[62:65], v[54:57]
	v_mfma_f32_16x16x32_bf16 v[58:61], v[30:33], v[62:65], v[58:61]
	s_setprio 1
	s_barrier
	v_lshl_add_u64 v[238:239], s[68:69], 0, v[130:131]
	s_mov_b32 m0, s81
	v_lshl_add_u64 v[146:147], v[238:239], 0, s[16:17]
	s_add_i32 s89, s81, 0x2000
	ds_read_b128 v[62:65], v143 offset:16384
	ds_read_b128 v[86:89], v143 offset:17408
	ds_read_b128 v[98:101], v143 offset:18432
	ds_read_b128 v[102:105], v143 offset:19456
	ds_read_b128 v[114:117], v143 offset:20480
	ds_read_b128 v[118:121], v143 offset:21504
	ds_read_b128 v[122:125], v143 offset:22528
	ds_read_b128 v[126:129], v143 offset:23552
	global_load_lds_dwordx4 v[146:147], off
	v_lshl_add_u64 v[146:147], v[238:239], 0, s[18:19]
	s_mov_b32 m0, s89
	s_add_i32 s90, s78, s43
	global_load_lds_dwordx4 v[146:147], off
	v_lshl_add_u64 v[146:147], v[238:239], 0, s[20:21]
	s_mov_b32 m0, s90
	s_add_i32 s91, s90, 0x2000
	global_load_lds_dwordx4 v[146:147], off
	v_lshl_add_u64 v[146:147], v[238:239], 0, s[22:23]
	s_mov_b32 m0, s91
	s_nop 0
	global_load_lds_dwordx4 v[146:147], off
	v_lshl_add_u64 v[146:147], v[140:141], 0, s[16:17]
	s_mov_b32 m0, s53
	s_nop 0
	global_load_lds_dwordx4 v[146:147], off
	v_lshl_add_u64 v[146:147], v[140:141], 0, s[18:19]
	s_mov_b32 m0, s54
	s_nop 0
	global_load_lds_dwordx4 v[146:147], off
	s_waitcnt vmcnt(16)
	s_waitcnt lgkmcnt(0)
	s_barrier
	s_waitcnt lgkmcnt(0)
	s_setprio 0
	v_mfma_f32_16x16x32_bf16 v[146:149], v[2:5], v[62:65], 0
	v_mfma_f32_16x16x32_bf16 v[154:157], v[2:5], v[98:101], 0
	v_mfma_f32_16x16x32_bf16 v[162:165], v[2:5], v[114:117], 0
	v_mfma_f32_16x16x32_bf16 v[2:5], v[2:5], v[122:125], 0
	v_mfma_f32_16x16x32_bf16 v[146:149], v[6:9], v[86:89], v[146:149]
	v_mfma_f32_16x16x32_bf16 v[154:157], v[6:9], v[102:105], v[154:157]
	v_mfma_f32_16x16x32_bf16 v[162:165], v[6:9], v[118:121], v[162:165]
	v_mfma_f32_16x16x32_bf16 v[2:5], v[6:9], v[126:129], v[2:5]
	v_mfma_f32_16x16x32_bf16 v[6:9], v[10:13], v[122:125], 0
	v_mfma_f32_16x16x32_bf16 v[150:153], v[10:13], v[62:65], 0
	v_mfma_f32_16x16x32_bf16 v[158:161], v[10:13], v[98:101], 0
	v_mfma_f32_16x16x32_bf16 v[166:169], v[10:13], v[114:117], 0
	v_mfma_f32_16x16x32_bf16 v[10:13], v[14:17], v[126:129], v[6:9]
	v_mfma_f32_16x16x32_bf16 v[150:153], v[14:17], v[86:89], v[150:153]
	v_mfma_f32_16x16x32_bf16 v[158:161], v[14:17], v[102:105], v[158:161]
	v_mfma_f32_16x16x32_bf16 v[166:169], v[14:17], v[118:121], v[166:169]
	v_mfma_f32_16x16x32_bf16 v[6:9], v[18:21], v[62:65], 0
	v_mfma_f32_16x16x32_bf16 v[14:17], v[22:25], v[86:89], v[6:9]
	v_mfma_f32_16x16x32_bf16 v[6:9], v[26:29], v[62:65], 0
	v_mfma_f32_16x16x32_bf16 v[170:173], v[30:33], v[86:89], v[6:9]
	v_mfma_f32_16x16x32_bf16 v[6:9], v[18:21], v[98:101], 0
	v_mfma_f32_16x16x32_bf16 v[174:177], v[22:25], v[102:105], v[6:9]
	v_mfma_f32_16x16x32_bf16 v[6:9], v[26:29], v[98:101], 0
	v_mfma_f32_16x16x32_bf16 v[178:181], v[30:33], v[102:105], v[6:9]
	v_mfma_f32_16x16x32_bf16 v[6:9], v[18:21], v[114:117], 0
	v_mfma_f32_16x16x32_bf16 v[182:185], v[22:25], v[118:121], v[6:9]
	v_mfma_f32_16x16x32_bf16 v[6:9], v[26:29], v[114:117], 0
	v_mfma_f32_16x16x32_bf16 v[186:189], v[30:33], v[118:121], v[6:9]
	v_mfma_f32_16x16x32_bf16 v[6:9], v[18:21], v[122:125], 0
	v_mfma_f32_16x16x32_bf16 v[190:193], v[22:25], v[126:129], v[6:9]
	v_mfma_f32_16x16x32_bf16 v[6:9], v[26:29], v[122:125], 0
	v_mfma_f32_16x16x32_bf16 v[194:197], v[30:33], v[126:129], v[6:9]
	s_setprio 1
	s_barrier
	s_nop 5
	ds_read_b128 v[6:9], v144
	ds_read_b128 v[26:29], v144 offset:1024
	ds_read_b128 v[30:33], v144 offset:2048
	ds_read_b128 v[62:65], v144 offset:3072
	ds_read_b128 v[198:201], v145
	ds_read_b128 v[202:205], v145 offset:1024
	ds_read_b128 v[206:209], v145 offset:2048
	ds_read_b128 v[210:213], v145 offset:3072
	s_mov_b32 m0, s55
	v_lshl_add_u64 v[86:87], v[140:141], 0, s[20:21]
	ds_read_b128 v[18:21], v143 offset:32768
	ds_read_b128 v[22:25], v143 offset:33792
	ds_read_b128 v[214:217], v143 offset:34816
	ds_read_b128 v[218:221], v143 offset:35840
	ds_read_b128 v[222:225], v143 offset:36864
	ds_read_b128 v[226:229], v143 offset:37888
	ds_read_b128 v[230:233], v143 offset:38912
	ds_read_b128 v[234:237], v143 offset:39936
	global_load_lds_dwordx4 v[86:87], off
	v_lshl_add_u64 v[86:87], v[140:141], 0, s[22:23]
	s_mov_b32 m0, s67
	s_nop 0
	global_load_lds_dwordx4 v[86:87], off
	s_waitcnt vmcnt(8)
	s_waitcnt lgkmcnt(0)
	s_barrier
	s_waitcnt lgkmcnt(0)
	s_setprio 0
	v_mfma_f32_16x16x32_bf16 v[66:69], v[6:9], v[18:21], v[66:69]
	v_mfma_f32_16x16x32_bf16 v[118:121], v[26:29], v[22:25], v[66:69]
	v_mfma_f32_16x16x32_bf16 v[66:69], v[30:33], v[18:21], v[70:73]
	v_mfma_f32_16x16x32_bf16 v[114:117], v[62:65], v[22:25], v[66:69]
	v_mfma_f32_16x16x32_bf16 v[66:69], v[6:9], v[214:217], v[74:77]
	v_mfma_f32_16x16x32_bf16 v[102:105], v[26:29], v[218:221], v[66:69]
	v_mfma_f32_16x16x32_bf16 v[66:69], v[30:33], v[214:217], v[78:81]
	v_mfma_f32_16x16x32_bf16 v[98:101], v[62:65], v[218:221], v[66:69]
	v_mfma_f32_16x16x32_bf16 v[66:69], v[6:9], v[222:225], v[82:85]
	v_mfma_f32_16x16x32_bf16 v[86:89], v[26:29], v[226:229], v[66:69]
	v_mfma_f32_16x16x32_bf16 v[66:69], v[30:33], v[222:225], v[90:93]
	v_mfma_f32_16x16x32_bf16 v[82:85], v[62:65], v[226:229], v[66:69]
	v_mfma_f32_16x16x32_bf16 v[66:69], v[6:9], v[230:233], v[94:97]
	v_mfma_f32_16x16x32_bf16 v[70:73], v[26:29], v[234:237], v[66:69]
	v_mfma_f32_16x16x32_bf16 v[66:69], v[30:33], v[230:233], v[106:109]
	v_mfma_f32_16x16x32_bf16 v[66:69], v[62:65], v[234:237], v[66:69]
	v_mfma_f32_16x16x32_bf16 v[74:77], v[198:201], v[18:21], v[110:113]
	v_mfma_f32_16x16x32_bf16 v[18:21], v[206:209], v[18:21], v[34:37]
	v_mfma_f32_16x16x32_bf16 v[122:125], v[210:213], v[22:25], v[18:21]
	v_mfma_f32_16x16x32_bf16 v[18:21], v[198:201], v[214:217], v[38:41]
	v_mfma_f32_16x16x32_bf16 v[110:113], v[202:205], v[218:221], v[18:21]
	v_mfma_f32_16x16x32_bf16 v[18:21], v[206:209], v[214:217], v[42:45]
	v_mfma_f32_16x16x32_bf16 v[106:109], v[210:213], v[218:221], v[18:21]
	v_mfma_f32_16x16x32_bf16 v[18:21], v[198:201], v[222:225], v[46:49]
	v_mfma_f32_16x16x32_bf16 v[94:97], v[202:205], v[226:229], v[18:21]
	v_mfma_f32_16x16x32_bf16 v[18:21], v[206:209], v[222:225], v[50:53]
	v_mfma_f32_16x16x32_bf16 v[90:93], v[210:213], v[226:229], v[18:21]
	v_mfma_f32_16x16x32_bf16 v[18:21], v[198:201], v[230:233], v[54:57]
	v_mfma_f32_16x16x32_bf16 v[78:81], v[202:205], v[234:237], v[18:21]
	v_mfma_f32_16x16x32_bf16 v[18:21], v[206:209], v[230:233], v[58:61]
	v_mfma_f32_16x16x32_bf16 v[126:129], v[202:205], v[22:25], v[74:77]
	v_mfma_f32_16x16x32_bf16 v[74:77], v[210:213], v[234:237], v[18:21]
	s_setprio 1
	s_barrier
	s_add_i32 s50, s82, s43
	s_nop 3
	v_lshl_add_u64 v[18:19], v[238:239], 0, s[24:25]
	s_mov_b32 m0, s50
	s_add_i32 s51, s50, 0x2000
	ds_read_b128 v[42:45], v143 offset:49152
	ds_read_b128 v[46:49], v143 offset:50176
	ds_read_b128 v[214:217], v143 offset:51200
	ds_read_b128 v[218:221], v143 offset:52224
	ds_read_b128 v[222:225], v143 offset:53248
	ds_read_b128 v[226:229], v143 offset:54272
	ds_read_b128 v[230:233], v143 offset:55296
	ds_read_b128 v[234:237], v143 offset:56320
	global_load_lds_dwordx4 v[18:19], off
	v_lshl_add_u64 v[18:19], v[238:239], 0, s[26:27]
	s_mov_b32 m0, s51
	s_mov_b64 s[0:1], 0x80180
	s_add_i32 s33, s83, s43
	global_load_lds_dwordx4 v[18:19], off
	v_lshl_add_u64 v[18:19], v[238:239], 0, s[0:1]
	s_mov_b32 m0, s33
	s_mov_b64 s[0:1], 0xc0180
	s_add_i32 s56, s33, 0x2000
	global_load_lds_dwordx4 v[18:19], off
	v_lshl_add_u64 v[18:19], v[238:239], 0, s[0:1]
	s_mov_b32 m0, s56
	s_nop 0
	global_load_lds_dwordx4 v[18:19], off
	v_lshl_add_u64 v[18:19], v[140:141], 0, s[24:25]
	s_mov_b32 m0, s72
	s_nop 0
	global_load_lds_dwordx4 v[18:19], off
	v_lshl_add_u64 v[18:19], v[140:141], 0, s[26:27]
	s_mov_b32 m0, s73
	s_nop 0
	global_load_lds_dwordx4 v[18:19], off
	s_waitcnt vmcnt(8)
	s_waitcnt lgkmcnt(0)
	s_barrier
	s_waitcnt lgkmcnt(0)
	s_setprio 0
	v_mfma_f32_16x16x32_bf16 v[18:21], v[6:9], v[42:45], v[146:149]
	v_mfma_f32_16x16x32_bf16 v[54:57], v[26:29], v[46:49], v[18:21]
	v_mfma_f32_16x16x32_bf16 v[18:21], v[30:33], v[42:45], v[150:153]
	v_mfma_f32_16x16x32_bf16 v[50:53], v[62:65], v[46:49], v[18:21]
	v_mfma_f32_16x16x32_bf16 v[18:21], v[6:9], v[214:217], v[154:157]
	v_mfma_f32_16x16x32_bf16 v[38:41], v[26:29], v[218:221], v[18:21]
	v_mfma_f32_16x16x32_bf16 v[18:21], v[30:33], v[214:217], v[158:161]
	v_mfma_f32_16x16x32_bf16 v[34:37], v[62:65], v[218:221], v[18:21]
	v_mfma_f32_16x16x32_bf16 v[18:21], v[6:9], v[222:225], v[162:165]
	v_mfma_f32_16x16x32_bf16 v[2:5], v[6:9], v[230:233], v[2:5]
	v_mfma_f32_16x16x32_bf16 v[22:25], v[26:29], v[226:229], v[18:21]
	v_mfma_f32_16x16x32_bf16 v[18:21], v[30:33], v[222:225], v[166:169]
	v_mfma_f32_16x16x32_bf16 v[6:9], v[26:29], v[234:237], v[2:5]
	v_mfma_f32_16x16x32_bf16 v[2:5], v[30:33], v[230:233], v[10:13]
	v_mfma_f32_16x16x32_bf16 v[18:21], v[62:65], v[226:229], v[18:21]
	v_mfma_f32_16x16x32_bf16 v[2:5], v[62:65], v[234:237], v[2:5]
	v_mfma_f32_16x16x32_bf16 v[10:13], v[198:201], v[42:45], v[14:17]
	v_mfma_f32_16x16x32_bf16 v[62:65], v[202:205], v[46:49], v[10:13]
	v_mfma_f32_16x16x32_bf16 v[10:13], v[206:209], v[42:45], v[170:173]
	v_mfma_f32_16x16x32_bf16 v[58:61], v[210:213], v[46:49], v[10:13]
	v_mfma_f32_16x16x32_bf16 v[10:13], v[198:201], v[214:217], v[174:177]
	v_mfma_f32_16x16x32_bf16 v[46:49], v[202:205], v[218:221], v[10:13]
	v_mfma_f32_16x16x32_bf16 v[10:13], v[206:209], v[214:217], v[178:181]
	v_mfma_f32_16x16x32_bf16 v[42:45], v[210:213], v[218:221], v[10:13]
	v_mfma_f32_16x16x32_bf16 v[10:13], v[198:201], v[222:225], v[182:185]
	v_mfma_f32_16x16x32_bf16 v[30:33], v[202:205], v[226:229], v[10:13]
	v_mfma_f32_16x16x32_bf16 v[10:13], v[206:209], v[222:225], v[186:189]
	v_mfma_f32_16x16x32_bf16 v[26:29], v[210:213], v[226:229], v[10:13]
	v_mfma_f32_16x16x32_bf16 v[10:13], v[198:201], v[230:233], v[190:193]
	v_mfma_f32_16x16x32_bf16 v[14:17], v[202:205], v[234:237], v[10:13]
	v_mfma_f32_16x16x32_bf16 v[10:13], v[206:209], v[230:233], v[194:197]
	v_mfma_f32_16x16x32_bf16 v[10:13], v[210:213], v[234:237], v[10:13]
	s_setprio 1
	s_barrier
	s_add_u32 s70, s70, 0x80180
	s_addc_u32 s71, s71, 0
	s_add_u32 s57, s68, 0x200
	s_addc_u32 s68, s69, 0
	s_mov_b32 s69, 0
.LBB0_2862:
	ds_read_b128 v[146:149], v1
	ds_read_b128 v[150:153], v1 offset:1024
	ds_read_b128 v[154:157], v1 offset:2048
	ds_read_b128 v[158:161], v1 offset:3072
	ds_read_b128 v[162:165], v142
	ds_read_b128 v[166:169], v142 offset:1024
	ds_read_b128 v[170:173], v142 offset:2048
	ds_read_b128 v[174:177], v142 offset:3072
	s_add_u32 s0, s70, 0xfff80080
	s_addc_u32 s1, s71, -1
	s_cmp_eq_u32 s69, 28
	s_cselect_b32 s1, s41, s1
	s_cselect_b32 s0, s45, s0
	s_cselect_b32 s65, s87, s68
	s_cselect_b32 s64, s88, s57
	s_mov_b32 m0, s79
	v_lshl_add_u64 v[140:141], s[70:71], 0, v[134:135]
	ds_read_b128 v[178:181], v143
	ds_read_b128 v[182:185], v143 offset:1024
	ds_read_b128 v[186:189], v143 offset:2048
	ds_read_b128 v[190:193], v143 offset:3072
	ds_read_b128 v[194:197], v143 offset:4096
	ds_read_b128 v[198:201], v143 offset:5120
	ds_read_b128 v[202:205], v143 offset:6144
	ds_read_b128 v[206:209], v143 offset:7168
	global_load_lds_dwordx4 v[140:141], off
	v_lshl_add_u64 v[140:141], v[140:141], 0, s[28:29]
	s_mov_b32 m0, s80
	s_nop 0
	global_load_lds_dwordx4 v[140:141], off
	s_waitcnt vmcnt(8)
	s_waitcnt lgkmcnt(0)
	s_barrier
	s_waitcnt lgkmcnt(0)
	s_setprio 0
	v_mfma_f32_16x16x32_bf16 v[118:121], v[146:149], v[178:181], v[118:121]
	v_mfma_f32_16x16x32_bf16 v[114:117], v[154:157], v[178:181], v[114:117]
	v_mfma_f32_16x16x32_bf16 v[102:105], v[146:149], v[186:189], v[102:105]
	v_mfma_f32_16x16x32_bf16 v[98:101], v[154:157], v[186:189], v[98:101]
	v_mfma_f32_16x16x32_bf16 v[86:89], v[146:149], v[194:197], v[86:89]
	v_mfma_f32_16x16x32_bf16 v[82:85], v[154:157], v[194:197], v[82:85]
	v_mfma_f32_16x16x32_bf16 v[70:73], v[146:149], v[202:205], v[70:73]
	v_mfma_f32_16x16x32_bf16 v[66:69], v[154:157], v[202:205], v[66:69]
	v_mfma_f32_16x16x32_bf16 v[118:121], v[150:153], v[182:185], v[118:121]
	v_mfma_f32_16x16x32_bf16 v[114:117], v[158:161], v[182:185], v[114:117]
	v_mfma_f32_16x16x32_bf16 v[102:105], v[150:153], v[190:193], v[102:105]
	v_mfma_f32_16x16x32_bf16 v[98:101], v[158:161], v[190:193], v[98:101]
	v_mfma_f32_16x16x32_bf16 v[86:89], v[150:153], v[198:201], v[86:89]
	v_mfma_f32_16x16x32_bf16 v[82:85], v[158:161], v[198:201], v[82:85]
	v_mfma_f32_16x16x32_bf16 v[70:73], v[150:153], v[206:209], v[70:73]
	v_mfma_f32_16x16x32_bf16 v[66:69], v[158:161], v[206:209], v[66:69]
	v_mfma_f32_16x16x32_bf16 v[126:129], v[162:165], v[178:181], v[126:129]
	v_mfma_f32_16x16x32_bf16 v[122:125], v[170:173], v[178:181], v[122:125]
	v_mfma_f32_16x16x32_bf16 v[110:113], v[162:165], v[186:189], v[110:113]
	v_mfma_f32_16x16x32_bf16 v[106:109], v[170:173], v[186:189], v[106:109]
	v_mfma_f32_16x16x32_bf16 v[94:97], v[162:165], v[194:197], v[94:97]
	v_mfma_f32_16x16x32_bf16 v[90:93], v[170:173], v[194:197], v[90:93]
	v_mfma_f32_16x16x32_bf16 v[78:81], v[162:165], v[202:205], v[78:81]
	v_mfma_f32_16x16x32_bf16 v[74:77], v[170:173], v[202:205], v[74:77]
	v_mfma_f32_16x16x32_bf16 v[126:129], v[166:169], v[182:185], v[126:129]
	v_mfma_f32_16x16x32_bf16 v[122:125], v[174:177], v[182:185], v[122:125]
	v_mfma_f32_16x16x32_bf16 v[110:113], v[166:169], v[190:193], v[110:113]
	v_mfma_f32_16x16x32_bf16 v[106:109], v[174:177], v[190:193], v[106:109]
	v_mfma_f32_16x16x32_bf16 v[94:97], v[166:169], v[198:201], v[94:97]
	v_mfma_f32_16x16x32_bf16 v[90:93], v[174:177], v[198:201], v[90:93]
	v_mfma_f32_16x16x32_bf16 v[78:81], v[166:169], v[206:209], v[78:81]
	v_mfma_f32_16x16x32_bf16 v[74:77], v[174:177], v[206:209], v[74:77]
	s_setprio 1
	s_barrier
	s_mov_b32 m0, s81
	v_lshl_add_u64 v[140:141], s[64:65], 0, v[130:131]
	ds_read_b128 v[178:181], v143 offset:16384
	ds_read_b128 v[182:185], v143 offset:17408
	ds_read_b128 v[186:189], v143 offset:18432
	ds_read_b128 v[190:193], v143 offset:19456
	ds_read_b128 v[194:197], v143 offset:20480
	ds_read_b128 v[198:201], v143 offset:21504
	ds_read_b128 v[202:205], v143 offset:22528
	ds_read_b128 v[206:209], v143 offset:23552
	global_load_lds_dwordx4 v[140:141], off
	v_lshl_add_u64 v[210:211], v[140:141], 0, s[28:29]
	s_mov_b32 m0, s89
	s_nop 0
	global_load_lds_dwordx4 v[210:211], off
	v_lshl_add_u64 v[210:211], v[140:141], 0, s[30:31]
	s_mov_b32 m0, s90
	s_nop 0
	global_load_lds_dwordx4 v[210:211], off
	v_lshl_add_u64 v[210:211], v[140:141], 0, s[34:35]
	s_mov_b32 m0, s91
	s_nop 0
	global_load_lds_dwordx4 v[210:211], off
	v_lshl_add_u64 v[210:211], s[0:1], 0, v[132:133]
	s_mov_b32 m0, s53
	v_lshl_add_u64 v[212:213], v[210:211], 0, s[28:29]
	global_load_lds_dwordx4 v[210:211], off
	s_mov_b32 m0, s54
	s_nop 0
	global_load_lds_dwordx4 v[212:213], off
	s_waitcnt vmcnt(8)
	s_waitcnt lgkmcnt(0)
	s_barrier
	s_waitcnt lgkmcnt(0)
	s_setprio 0
	v_mfma_f32_16x16x32_bf16 v[54:57], v[146:149], v[178:181], v[54:57]
	v_mfma_f32_16x16x32_bf16 v[50:53], v[154:157], v[178:181], v[50:53]
	v_mfma_f32_16x16x32_bf16 v[38:41], v[146:149], v[186:189], v[38:41]
	v_mfma_f32_16x16x32_bf16 v[34:37], v[154:157], v[186:189], v[34:37]
	v_mfma_f32_16x16x32_bf16 v[22:25], v[146:149], v[194:197], v[22:25]
	v_mfma_f32_16x16x32_bf16 v[18:21], v[154:157], v[194:197], v[18:21]
	v_mfma_f32_16x16x32_bf16 v[6:9], v[146:149], v[202:205], v[6:9]
	v_mfma_f32_16x16x32_bf16 v[2:5], v[154:157], v[202:205], v[2:5]
	v_mfma_f32_16x16x32_bf16 v[54:57], v[150:153], v[182:185], v[54:57]
	v_mfma_f32_16x16x32_bf16 v[50:53], v[158:161], v[182:185], v[50:53]
	v_mfma_f32_16x16x32_bf16 v[38:41], v[150:153], v[190:193], v[38:41]
	v_mfma_f32_16x16x32_bf16 v[34:37], v[158:161], v[190:193], v[34:37]
	v_mfma_f32_16x16x32_bf16 v[22:25], v[150:153], v[198:201], v[22:25]
	v_mfma_f32_16x16x32_bf16 v[18:21], v[158:161], v[198:201], v[18:21]
	v_mfma_f32_16x16x32_bf16 v[6:9], v[150:153], v[206:209], v[6:9]
	v_mfma_f32_16x16x32_bf16 v[2:5], v[158:161], v[206:209], v[2:5]
	v_mfma_f32_16x16x32_bf16 v[62:65], v[162:165], v[178:181], v[62:65]
	v_mfma_f32_16x16x32_bf16 v[58:61], v[170:173], v[178:181], v[58:61]
	v_mfma_f32_16x16x32_bf16 v[46:49], v[162:165], v[186:189], v[46:49]
	v_mfma_f32_16x16x32_bf16 v[42:45], v[170:173], v[186:189], v[42:45]
	v_mfma_f32_16x16x32_bf16 v[30:33], v[162:165], v[194:197], v[30:33]
	v_mfma_f32_16x16x32_bf16 v[26:29], v[170:173], v[194:197], v[26:29]
	v_mfma_f32_16x16x32_bf16 v[14:17], v[162:165], v[202:205], v[14:17]
	v_mfma_f32_16x16x32_bf16 v[10:13], v[170:173], v[202:205], v[10:13]
	v_mfma_f32_16x16x32_bf16 v[62:65], v[166:169], v[182:185], v[62:65]
	v_mfma_f32_16x16x32_bf16 v[58:61], v[174:177], v[182:185], v[58:61]
	v_mfma_f32_16x16x32_bf16 v[46:49], v[166:169], v[190:193], v[46:49]
	v_mfma_f32_16x16x32_bf16 v[42:45], v[174:177], v[190:193], v[42:45]
	v_mfma_f32_16x16x32_bf16 v[30:33], v[166:169], v[198:201], v[30:33]
	v_mfma_f32_16x16x32_bf16 v[26:29], v[174:177], v[198:201], v[26:29]
	v_mfma_f32_16x16x32_bf16 v[14:17], v[166:169], v[206:209], v[14:17]
	v_mfma_f32_16x16x32_bf16 v[10:13], v[174:177], v[206:209], v[10:13]
	s_setprio 1
	s_barrier
	ds_read_b128 v[146:149], v144
	ds_read_b128 v[150:153], v144 offset:1024
	ds_read_b128 v[154:157], v144 offset:2048
	ds_read_b128 v[158:161], v144 offset:3072
	ds_read_b128 v[162:165], v145
	ds_read_b128 v[166:169], v145 offset:1024
	ds_read_b128 v[170:173], v145 offset:2048
	ds_read_b128 v[174:177], v145 offset:3072
	s_mov_b32 m0, s55
	v_lshl_add_u64 v[212:213], v[210:211], 0, s[30:31]
	ds_read_b128 v[178:181], v143 offset:32768
	ds_read_b128 v[182:185], v143 offset:33792
	ds_read_b128 v[186:189], v143 offset:34816
	ds_read_b128 v[190:193], v143 offset:35840
	ds_read_b128 v[194:197], v143 offset:36864
	ds_read_b128 v[198:201], v143 offset:37888
	ds_read_b128 v[202:205], v143 offset:38912
	ds_read_b128 v[206:209], v143 offset:39936
	global_load_lds_dwordx4 v[212:213], off
	v_lshl_add_u64 v[212:213], v[210:211], 0, s[34:35]
	s_mov_b32 m0, s67
	s_nop 0
	global_load_lds_dwordx4 v[212:213], off
	s_waitcnt vmcnt(8)
	s_waitcnt lgkmcnt(0)
	s_barrier
	s_waitcnt lgkmcnt(0)
	s_setprio 0
	v_mfma_f32_16x16x32_bf16 v[118:121], v[146:149], v[178:181], v[118:121]
	v_mfma_f32_16x16x32_bf16 v[114:117], v[154:157], v[178:181], v[114:117]
	v_mfma_f32_16x16x32_bf16 v[102:105], v[146:149], v[186:189], v[102:105]
	v_mfma_f32_16x16x32_bf16 v[98:101], v[154:157], v[186:189], v[98:101]
	v_mfma_f32_16x16x32_bf16 v[86:89], v[146:149], v[194:197], v[86:89]
	v_mfma_f32_16x16x32_bf16 v[82:85], v[154:157], v[194:197], v[82:85]
	v_mfma_f32_16x16x32_bf16 v[70:73], v[146:149], v[202:205], v[70:73]
	v_mfma_f32_16x16x32_bf16 v[66:69], v[154:157], v[202:205], v[66:69]
	v_mfma_f32_16x16x32_bf16 v[118:121], v[150:153], v[182:185], v[118:121]
	v_mfma_f32_16x16x32_bf16 v[114:117], v[158:161], v[182:185], v[114:117]
	v_mfma_f32_16x16x32_bf16 v[102:105], v[150:153], v[190:193], v[102:105]
	v_mfma_f32_16x16x32_bf16 v[98:101], v[158:161], v[190:193], v[98:101]
	v_mfma_f32_16x16x32_bf16 v[86:89], v[150:153], v[198:201], v[86:89]
	v_mfma_f32_16x16x32_bf16 v[82:85], v[158:161], v[198:201], v[82:85]
	v_mfma_f32_16x16x32_bf16 v[70:73], v[150:153], v[206:209], v[70:73]
	v_mfma_f32_16x16x32_bf16 v[66:69], v[158:161], v[206:209], v[66:69]
	v_mfma_f32_16x16x32_bf16 v[126:129], v[162:165], v[178:181], v[126:129]
	v_mfma_f32_16x16x32_bf16 v[122:125], v[170:173], v[178:181], v[122:125]
	v_mfma_f32_16x16x32_bf16 v[110:113], v[162:165], v[186:189], v[110:113]
	v_mfma_f32_16x16x32_bf16 v[106:109], v[170:173], v[186:189], v[106:109]
	v_mfma_f32_16x16x32_bf16 v[94:97], v[162:165], v[194:197], v[94:97]
	v_mfma_f32_16x16x32_bf16 v[90:93], v[170:173], v[194:197], v[90:93]
	v_mfma_f32_16x16x32_bf16 v[78:81], v[162:165], v[202:205], v[78:81]
	v_mfma_f32_16x16x32_bf16 v[74:77], v[170:173], v[202:205], v[74:77]
	v_mfma_f32_16x16x32_bf16 v[126:129], v[166:169], v[182:185], v[126:129]
	v_mfma_f32_16x16x32_bf16 v[122:125], v[174:177], v[182:185], v[122:125]
	v_mfma_f32_16x16x32_bf16 v[110:113], v[166:169], v[190:193], v[110:113]
	v_mfma_f32_16x16x32_bf16 v[106:109], v[174:177], v[190:193], v[106:109]
	v_mfma_f32_16x16x32_bf16 v[94:97], v[166:169], v[198:201], v[94:97]
	v_mfma_f32_16x16x32_bf16 v[90:93], v[174:177], v[198:201], v[90:93]
	v_mfma_f32_16x16x32_bf16 v[78:81], v[166:169], v[206:209], v[78:81]
	v_mfma_f32_16x16x32_bf16 v[74:77], v[174:177], v[206:209], v[74:77]
	s_setprio 1
	s_barrier
; #define PG8_WAIT_V(n) asm volatile("s_waitcnt vmcnt(" #n ")" ::: "memory")
; template <class Epi, class Sched, bool ALIGN_EPI = true, bool SP2 = true, bool FULLLINE = false, bool NOSTAGE = false, bool FP8 = false>
; __device__ __forceinline__ void gemm_phase(PG8_LAS unsigned char* lds, const Gemm g, const Sched& S, const Epi& E) {
;     ...
;         for (int t = 2; t < nt; t += 2) PG8_ITER(PG8_WAIT_V(8));
	s_mov_b32 m0, s50
	v_lshl_add_u64 v[212:213], v[140:141], 0, s[36:37]
	ds_read_b128 v[178:181], v143 offset:49152
	ds_read_b128 v[182:185], v143 offset:50176
	ds_read_b128 v[186:189], v143 offset:51200
	ds_read_b128 v[190:193], v143 offset:52224
	ds_read_b128 v[194:197], v143 offset:53248
	ds_read_b128 v[198:201], v143 offset:54272
	ds_read_b128 v[202:205], v143 offset:55296
	ds_read_b128 v[206:209], v143 offset:56320
	global_load_lds_dwordx4 v[212:213], off
	v_lshl_add_u64 v[212:213], v[140:141], 0, s[38:39]
	s_mov_b32 m0, s51
	s_nop 0
	global_load_lds_dwordx4 v[212:213], off
	v_lshl_add_u64 v[212:213], v[140:141], 0, s[12:13]
	s_mov_b32 m0, s33
	v_lshl_add_u64 v[140:141], v[140:141], 0, s[14:15]
	global_load_lds_dwordx4 v[212:213], off
	s_mov_b32 m0, s56
	s_nop 0
	global_load_lds_dwordx4 v[140:141], off
	v_lshl_add_u64 v[140:141], v[210:211], 0, s[36:37]
	s_mov_b32 m0, s72
	s_nop 0
	global_load_lds_dwordx4 v[140:141], off
	v_lshl_add_u64 v[140:141], v[210:211], 0, s[38:39]
	s_mov_b32 m0, s73
	s_nop 0
	global_load_lds_dwordx4 v[140:141], off
	s_waitcnt vmcnt(8)
	s_waitcnt lgkmcnt(0)
	s_barrier
	s_waitcnt lgkmcnt(0)
	s_setprio 0
	v_mfma_f32_16x16x32_bf16 v[54:57], v[146:149], v[178:181], v[54:57]
	v_mfma_f32_16x16x32_bf16 v[50:53], v[154:157], v[178:181], v[50:53]
	v_mfma_f32_16x16x32_bf16 v[38:41], v[146:149], v[186:189], v[38:41]
	v_mfma_f32_16x16x32_bf16 v[34:37], v[154:157], v[186:189], v[34:37]
	v_mfma_f32_16x16x32_bf16 v[22:25], v[146:149], v[194:197], v[22:25]
	v_mfma_f32_16x16x32_bf16 v[18:21], v[154:157], v[194:197], v[18:21]
	v_mfma_f32_16x16x32_bf16 v[6:9], v[146:149], v[202:205], v[6:9]
	v_mfma_f32_16x16x32_bf16 v[2:5], v[154:157], v[202:205], v[2:5]
	v_mfma_f32_16x16x32_bf16 v[54:57], v[150:153], v[182:185], v[54:57]
	v_mfma_f32_16x16x32_bf16 v[50:53], v[158:161], v[182:185], v[50:53]
	v_mfma_f32_16x16x32_bf16 v[38:41], v[150:153], v[190:193], v[38:41]
	v_mfma_f32_16x16x32_bf16 v[34:37], v[158:161], v[190:193], v[34:37]
	v_mfma_f32_16x16x32_bf16 v[22:25], v[150:153], v[198:201], v[22:25]
	v_mfma_f32_16x16x32_bf16 v[18:21], v[158:161], v[198:201], v[18:21]
	v_mfma_f32_16x16x32_bf16 v[6:9], v[150:153], v[206:209], v[6:9]
	v_mfma_f32_16x16x32_bf16 v[2:5], v[158:161], v[206:209], v[2:5]
	v_mfma_f32_16x16x32_bf16 v[62:65], v[162:165], v[178:181], v[62:65]
	v_mfma_f32_16x16x32_bf16 v[58:61], v[170:173], v[178:181], v[58:61]
	v_mfma_f32_16x16x32_bf16 v[46:49], v[162:165], v[186:189], v[46:49]
	v_mfma_f32_16x16x32_bf16 v[42:45], v[170:173], v[186:189], v[42:45]
	v_mfma_f32_16x16x32_bf16 v[30:33], v[162:165], v[194:197], v[30:33]
	v_mfma_f32_16x16x32_bf16 v[26:29], v[170:173], v[194:197], v[26:29]
	v_mfma_f32_16x16x32_bf16 v[14:17], v[162:165], v[202:205], v[14:17]
	v_mfma_f32_16x16x32_bf16 v[10:13], v[170:173], v[202:205], v[10:13]
	v_mfma_f32_16x16x32_bf16 v[62:65], v[166:169], v[182:185], v[62:65]
	v_mfma_f32_16x16x32_bf16 v[58:61], v[174:177], v[182:185], v[58:61]
	v_mfma_f32_16x16x32_bf16 v[46:49], v[166:169], v[190:193], v[46:49]
	v_mfma_f32_16x16x32_bf16 v[42:45], v[174:177], v[190:193], v[42:45]
	v_mfma_f32_16x16x32_bf16 v[30:33], v[166:169], v[198:201], v[30:33]
	v_mfma_f32_16x16x32_bf16 v[26:29], v[174:177], v[198:201], v[26:29]
	v_mfma_f32_16x16x32_bf16 v[14:17], v[166:169], v[206:209], v[14:17]
	v_mfma_f32_16x16x32_bf16 v[10:13], v[174:177], v[206:209], v[10:13]
	s_setprio 1
	s_barrier
	s_add_i32 s69, s69, 2
	s_add_u32 s70, s70, 0x100
	s_addc_u32 s71, s71, 0
	s_add_u32 s57, s57, 0x100
	s_addc_u32 s68, s68, 0
	s_cmp_gt_u32 s69, 29
	s_cbranch_scc0 .LBB0_2862
	s_and_b64 vcc, exec, s[10:11]
	s_cbranch_vccz .LBB0_2865
	s_barrier

.LBB0_2964:
	ds_read_b128 v[2:5], v1
	ds_read_b128 v[6:9], v1 offset:1024
	ds_read_b128 v[10:13], v1 offset:2048
	ds_read_b128 v[14:17], v1 offset:3072
	ds_read_b128 v[18:21], v168
	ds_read_b128 v[22:25], v168 offset:1024
	ds_read_b128 v[26:29], v168 offset:2048
	ds_read_b128 v[30:33], v168 offset:3072
	v_lshl_add_u64 v[244:245], s[46:47], 0, v[150:151]
	s_add_i32 s81, s53, 0xc000
	v_lshl_add_u64 v[66:67], v[244:245], 0, s[14:15]
	s_mov_b32 m0, s81
	s_add_i32 s82, s53, 0xe000
	ds_read_b128 v[34:37], v169
	ds_read_b128 v[38:41], v169 offset:1024
	ds_read_b128 v[42:45], v169 offset:2048
	ds_read_b128 v[46:49], v169 offset:3072
	ds_read_b128 v[50:53], v169 offset:4096
	ds_read_b128 v[54:57], v169 offset:5120
	ds_read_b128 v[58:61], v169 offset:6144
	ds_read_b128 v[62:65], v169 offset:7168
	global_load_lds_dwordx4 v[66:67], off
	v_lshl_add_u64 v[66:67], v[244:245], 0, s[16:17]
	s_mov_b32 m0, s82
	s_nop 0
	global_load_lds_dwordx4 v[66:67], off
	s_waitcnt vmcnt(24)
	s_waitcnt lgkmcnt(0)
	s_barrier
	s_waitcnt lgkmcnt(0)
	s_setprio 0
	v_mfma_f32_16x16x32_bf16 v[66:69], v[2:5], v[34:37], 0
	v_mfma_f32_16x16x32_bf16 v[70:73], v[10:13], v[34:37], 0
	v_mfma_f32_16x16x32_bf16 v[74:77], v[2:5], v[42:45], 0
	v_mfma_f32_16x16x32_bf16 v[78:81], v[10:13], v[42:45], 0
	v_mfma_f32_16x16x32_bf16 v[90:93], v[2:5], v[58:61], 0
	v_mfma_f32_16x16x32_bf16 v[66:69], v[6:9], v[38:41], v[66:69]
	v_mfma_f32_16x16x32_bf16 v[70:73], v[14:17], v[38:41], v[70:73]
	v_mfma_f32_16x16x32_bf16 v[74:77], v[6:9], v[46:49], v[74:77]
	v_mfma_f32_16x16x32_bf16 v[78:81], v[14:17], v[46:49], v[78:81]
	v_mfma_f32_16x16x32_bf16 v[82:85], v[2:5], v[50:53], 0
	v_mfma_f32_16x16x32_bf16 v[86:89], v[10:13], v[50:53], 0
	v_mfma_f32_16x16x32_bf16 v[90:93], v[6:9], v[62:65], v[90:93]
	v_mfma_f32_16x16x32_bf16 v[94:97], v[10:13], v[58:61], 0
	v_mfma_f32_16x16x32_bf16 v[82:85], v[6:9], v[54:57], v[82:85]
	v_mfma_f32_16x16x32_bf16 v[86:89], v[14:17], v[54:57], v[86:89]
	v_mfma_f32_16x16x32_bf16 v[94:97], v[14:17], v[62:65], v[94:97]
	v_mfma_f32_16x16x32_bf16 v[98:101], v[18:21], v[34:37], 0
	v_mfma_f32_16x16x32_bf16 v[34:37], v[26:29], v[34:37], 0
	v_mfma_f32_16x16x32_bf16 v[98:101], v[22:25], v[38:41], v[98:101]
	v_mfma_f32_16x16x32_bf16 v[34:37], v[30:33], v[38:41], v[34:37]
	v_mfma_f32_16x16x32_bf16 v[38:41], v[18:21], v[42:45], 0
	v_mfma_f32_16x16x32_bf16 v[42:45], v[26:29], v[42:45], 0
	v_mfma_f32_16x16x32_bf16 v[38:41], v[22:25], v[46:49], v[38:41]
	v_mfma_f32_16x16x32_bf16 v[42:45], v[30:33], v[46:49], v[42:45]
	v_mfma_f32_16x16x32_bf16 v[46:49], v[18:21], v[50:53], 0
	v_mfma_f32_16x16x32_bf16 v[50:53], v[26:29], v[50:53], 0
	v_mfma_f32_16x16x32_bf16 v[46:49], v[22:25], v[54:57], v[46:49]
	v_mfma_f32_16x16x32_bf16 v[50:53], v[30:33], v[54:57], v[50:53]
	v_mfma_f32_16x16x32_bf16 v[54:57], v[18:21], v[58:61], 0
	v_mfma_f32_16x16x32_bf16 v[58:61], v[26:29], v[58:61], 0
	v_mfma_f32_16x16x32_bf16 v[54:57], v[22:25], v[62:65], v[54:57]
	v_mfma_f32_16x16x32_bf16 v[58:61], v[30:33], v[62:65], v[58:61]
	s_setprio 1
	s_barrier
	v_lshl_add_u64 v[246:247], s[58:59], 0, v[152:153]
	s_add_i32 s83, s73, s52
	v_lshl_add_u64 v[130:131], v[246:247], 0, s[18:19]
	s_mov_b32 m0, s83
	s_add_i32 s84, s83, 0x2000
	ds_read_b128 v[62:65], v169 offset:16384
	ds_read_b128 v[102:105], v169 offset:17408
	ds_read_b128 v[106:109], v169 offset:18432
	ds_read_b128 v[110:113], v169 offset:19456
	ds_read_b128 v[114:117], v169 offset:20480
	ds_read_b128 v[118:121], v169 offset:21504
	ds_read_b128 v[122:125], v169 offset:22528
	ds_read_b128 v[126:129], v169 offset:23552
	global_load_lds_dwordx4 v[130:131], off
	v_lshl_add_u64 v[130:131], v[246:247], 0, s[20:21]
	s_mov_b32 m0, s84
	s_add_i32 s85, s74, s52
	global_load_lds_dwordx4 v[130:131], off
	v_lshl_add_u64 v[130:131], v[246:247], 0, s[22:23]
	s_mov_b32 m0, s85
	s_add_i32 s87, s85, 0x2000
	global_load_lds_dwordx4 v[130:131], off
	v_lshl_add_u64 v[130:131], v[246:247], 0, s[24:25]
	s_mov_b32 m0, s87
	s_nop 0
	global_load_lds_dwordx4 v[130:131], off
	v_lshl_add_u64 v[130:131], v[244:245], 0, s[18:19]
	s_mov_b32 m0, s53
	s_nop 0
	global_load_lds_dwordx4 v[130:131], off
	v_lshl_add_u64 v[130:131], v[244:245], 0, s[20:21]
	s_mov_b32 m0, s54
	s_nop 0
	global_load_lds_dwordx4 v[130:131], off
	s_waitcnt vmcnt(24)
	s_waitcnt lgkmcnt(0)
	s_barrier
	s_waitcnt lgkmcnt(0)
	s_setprio 0
	v_mfma_f32_16x16x32_bf16 v[130:133], v[2:5], v[62:65], 0
	v_mfma_f32_16x16x32_bf16 v[146:149], v[6:9], v[102:105], v[130:133]
	v_mfma_f32_16x16x32_bf16 v[130:133], v[10:13], v[62:65], 0
	v_mfma_f32_16x16x32_bf16 v[160:163], v[14:17], v[102:105], v[130:133]
	v_mfma_f32_16x16x32_bf16 v[130:133], v[2:5], v[106:109], 0
	v_mfma_f32_16x16x32_bf16 v[164:167], v[6:9], v[110:113], v[130:133]
	v_mfma_f32_16x16x32_bf16 v[130:133], v[10:13], v[106:109], 0
	v_mfma_f32_16x16x32_bf16 v[172:175], v[14:17], v[110:113], v[130:133]
	v_mfma_f32_16x16x32_bf16 v[130:133], v[2:5], v[114:117], 0
	v_mfma_f32_16x16x32_bf16 v[2:5], v[2:5], v[122:125], 0
	v_mfma_f32_16x16x32_bf16 v[176:179], v[6:9], v[118:121], v[130:133]
	v_mfma_f32_16x16x32_bf16 v[2:5], v[6:9], v[126:129], v[2:5]
	v_mfma_f32_16x16x32_bf16 v[6:9], v[10:13], v[122:125], 0
	v_mfma_f32_16x16x32_bf16 v[130:133], v[10:13], v[114:117], 0
	v_mfma_f32_16x16x32_bf16 v[6:9], v[14:17], v[126:129], v[6:9]
	v_mfma_f32_16x16x32_bf16 v[180:183], v[14:17], v[118:121], v[130:133]
	v_mfma_f32_16x16x32_bf16 v[10:13], v[18:21], v[62:65], 0
	v_mfma_f32_16x16x32_bf16 v[184:187], v[22:25], v[102:105], v[10:13]
	v_mfma_f32_16x16x32_bf16 v[10:13], v[26:29], v[62:65], 0
	v_mfma_f32_16x16x32_bf16 v[102:105], v[30:33], v[102:105], v[10:13]
	v_mfma_f32_16x16x32_bf16 v[10:13], v[18:21], v[106:109], 0
	v_mfma_f32_16x16x32_bf16 v[188:191], v[22:25], v[110:113], v[10:13]
	v_mfma_f32_16x16x32_bf16 v[10:13], v[26:29], v[106:109], 0
	v_mfma_f32_16x16x32_bf16 v[192:195], v[30:33], v[110:113], v[10:13]
	v_mfma_f32_16x16x32_bf16 v[10:13], v[18:21], v[114:117], 0
	v_mfma_f32_16x16x32_bf16 v[196:199], v[22:25], v[118:121], v[10:13]
	v_mfma_f32_16x16x32_bf16 v[10:13], v[26:29], v[114:117], 0
	v_mfma_f32_16x16x32_bf16 v[200:203], v[30:33], v[118:121], v[10:13]
	v_mfma_f32_16x16x32_bf16 v[10:13], v[18:21], v[122:125], 0
	v_mfma_f32_16x16x32_bf16 v[204:207], v[22:25], v[126:129], v[10:13]
	v_mfma_f32_16x16x32_bf16 v[10:13], v[26:29], v[122:125], 0
	v_mfma_f32_16x16x32_bf16 v[208:211], v[30:33], v[126:129], v[10:13]
	s_setprio 1
	s_barrier
	s_nop 5
	ds_read_b128 v[10:13], v170
	ds_read_b128 v[14:17], v170 offset:1024
	ds_read_b128 v[18:21], v170 offset:2048
	ds_read_b128 v[22:25], v170 offset:3072
	ds_read_b128 v[212:215], v171
	ds_read_b128 v[216:219], v171 offset:1024
	ds_read_b128 v[220:223], v171 offset:2048
	ds_read_b128 v[224:227], v171 offset:3072
	s_mov_b32 m0, s55
	v_lshl_add_u64 v[106:107], v[244:245], 0, s[22:23]
	ds_read_b128 v[26:29], v169 offset:32768
	ds_read_b128 v[30:33], v169 offset:33792
	ds_read_b128 v[62:65], v169 offset:34816
	ds_read_b128 v[114:117], v169 offset:35840
	ds_read_b128 v[228:231], v169 offset:36864
	ds_read_b128 v[232:235], v169 offset:37888
	ds_read_b128 v[236:239], v169 offset:38912
	ds_read_b128 v[240:243], v169 offset:39936
	global_load_lds_dwordx4 v[106:107], off
	v_lshl_add_u64 v[106:107], v[244:245], 0, s[24:25]
	s_mov_b32 m0, s62
	s_nop 0
	global_load_lds_dwordx4 v[106:107], off
	s_waitcnt vmcnt(8)
	s_waitcnt lgkmcnt(0)
	s_barrier
	s_waitcnt lgkmcnt(0)
	s_setprio 0
	v_mfma_f32_16x16x32_bf16 v[66:69], v[10:13], v[26:29], v[66:69]
	v_mfma_f32_16x16x32_bf16 v[138:141], v[14:17], v[30:33], v[66:69]
	v_mfma_f32_16x16x32_bf16 v[66:69], v[18:21], v[26:29], v[70:73]
	v_mfma_f32_16x16x32_bf16 v[134:137], v[22:25], v[30:33], v[66:69]
	v_mfma_f32_16x16x32_bf16 v[66:69], v[10:13], v[62:65], v[74:77]
	v_mfma_f32_16x16x32_bf16 v[126:129], v[14:17], v[114:117], v[66:69]
	v_mfma_f32_16x16x32_bf16 v[66:69], v[18:21], v[62:65], v[78:81]
	v_mfma_f32_16x16x32_bf16 v[122:125], v[22:25], v[114:117], v[66:69]
	v_mfma_f32_16x16x32_bf16 v[66:69], v[10:13], v[228:231], v[82:85]
	v_mfma_f32_16x16x32_bf16 v[110:113], v[14:17], v[232:235], v[66:69]
	v_mfma_f32_16x16x32_bf16 v[66:69], v[18:21], v[228:231], v[86:89]
	v_mfma_f32_16x16x32_bf16 v[106:109], v[22:25], v[232:235], v[66:69]
	v_mfma_f32_16x16x32_bf16 v[66:69], v[10:13], v[236:239], v[90:93]
	v_mfma_f32_16x16x32_bf16 v[78:81], v[14:17], v[240:243], v[66:69]
	v_mfma_f32_16x16x32_bf16 v[66:69], v[18:21], v[236:239], v[94:97]
	v_mfma_f32_16x16x32_bf16 v[74:77], v[22:25], v[240:243], v[66:69]
	v_mfma_f32_16x16x32_bf16 v[66:69], v[212:215], v[26:29], v[98:101]
	v_mfma_f32_16x16x32_bf16 v[26:29], v[220:223], v[26:29], v[34:37]
	v_mfma_f32_16x16x32_bf16 v[130:133], v[224:227], v[30:33], v[26:29]
	v_mfma_f32_16x16x32_bf16 v[26:29], v[212:215], v[62:65], v[38:41]
	v_mfma_f32_16x16x32_bf16 v[118:121], v[216:219], v[114:117], v[26:29]
	v_mfma_f32_16x16x32_bf16 v[26:29], v[220:223], v[62:65], v[42:45]
	v_mfma_f32_16x16x32_bf16 v[114:117], v[224:227], v[114:117], v[26:29]
	v_mfma_f32_16x16x32_bf16 v[26:29], v[212:215], v[228:231], v[46:49]
	v_mfma_f32_16x16x32_bf16 v[98:101], v[216:219], v[232:235], v[26:29]
	v_mfma_f32_16x16x32_bf16 v[26:29], v[220:223], v[228:231], v[50:53]
	v_mfma_f32_16x16x32_bf16 v[90:93], v[224:227], v[232:235], v[26:29]
	v_mfma_f32_16x16x32_bf16 v[26:29], v[212:215], v[236:239], v[54:57]
	v_mfma_f32_16x16x32_bf16 v[70:73], v[216:219], v[240:243], v[26:29]
	v_mfma_f32_16x16x32_bf16 v[26:29], v[220:223], v[236:239], v[58:61]
	v_mfma_f32_16x16x32_bf16 v[142:145], v[216:219], v[30:33], v[66:69]
	v_mfma_f32_16x16x32_bf16 v[66:69], v[224:227], v[240:243], v[26:29]
	s_setprio 1
	s_barrier
	s_add_i32 s50, s75, s52
	s_nop 3
	v_lshl_add_u64 v[26:27], v[246:247], 0, s[26:27]
	s_mov_b32 m0, s50
	s_add_i32 s51, s50, 0x2000
	ds_read_b128 v[34:37], v169 offset:49152
	ds_read_b128 v[38:41], v169 offset:50176
	ds_read_b128 v[82:85], v169 offset:51200
	ds_read_b128 v[86:89], v169 offset:52224
	ds_read_b128 v[94:97], v169 offset:53248
	ds_read_b128 v[228:231], v169 offset:54272
	ds_read_b128 v[232:235], v169 offset:55296
	ds_read_b128 v[236:239], v169 offset:56320
	global_load_lds_dwordx4 v[26:27], off
	v_lshl_add_u64 v[26:27], v[246:247], 0, s[28:29]
	s_mov_b32 m0, s51
	s_mov_b64 s[0:1], 0x160180
	s_add_i32 s33, s76, s52
	global_load_lds_dwordx4 v[26:27], off
	v_lshl_add_u64 v[26:27], v[246:247], 0, s[0:1]
	s_mov_b32 m0, s33
	s_mov_b64 s[0:1], 0x210180
	s_add_i32 s56, s33, 0x2000
	global_load_lds_dwordx4 v[26:27], off
	v_lshl_add_u64 v[26:27], v[246:247], 0, s[0:1]
	s_mov_b32 m0, s56
	s_nop 0
	global_load_lds_dwordx4 v[26:27], off
	v_lshl_add_u64 v[26:27], v[244:245], 0, s[26:27]
	s_mov_b32 m0, s63
	s_nop 0
	global_load_lds_dwordx4 v[26:27], off
	v_lshl_add_u64 v[26:27], v[244:245], 0, s[28:29]
	s_mov_b32 m0, s66
	s_nop 0
	global_load_lds_dwordx4 v[26:27], off
	s_waitcnt vmcnt(8)
	s_waitcnt lgkmcnt(0)
	s_barrier
	s_waitcnt lgkmcnt(0)
	s_setprio 0
	v_mfma_f32_16x16x32_bf16 v[26:29], v[10:13], v[34:37], v[146:149]
	v_mfma_f32_16x16x32_bf16 v[62:65], v[14:17], v[38:41], v[26:29]
	v_mfma_f32_16x16x32_bf16 v[26:29], v[18:21], v[34:37], v[160:163]
	v_mfma_f32_16x16x32_bf16 v[58:61], v[22:25], v[38:41], v[26:29]
	v_mfma_f32_16x16x32_bf16 v[26:29], v[10:13], v[82:85], v[164:167]
	v_mfma_f32_16x16x32_bf16 v[46:49], v[14:17], v[86:89], v[26:29]
	v_mfma_f32_16x16x32_bf16 v[26:29], v[18:21], v[82:85], v[172:175]
	v_mfma_f32_16x16x32_bf16 v[42:45], v[22:25], v[86:89], v[26:29]
	v_mfma_f32_16x16x32_bf16 v[26:29], v[10:13], v[94:97], v[176:179]
	v_mfma_f32_16x16x32_bf16 v[2:5], v[10:13], v[232:235], v[2:5]
	v_mfma_f32_16x16x32_bf16 v[30:33], v[14:17], v[228:231], v[26:29]
	v_mfma_f32_16x16x32_bf16 v[26:29], v[18:21], v[94:97], v[180:183]
	v_mfma_f32_16x16x32_bf16 v[14:17], v[14:17], v[236:239], v[2:5]
	v_mfma_f32_16x16x32_bf16 v[2:5], v[18:21], v[232:235], v[6:9]
	v_mfma_f32_16x16x32_bf16 v[26:29], v[22:25], v[228:231], v[26:29]
	v_mfma_f32_16x16x32_bf16 v[10:13], v[22:25], v[236:239], v[2:5]
	v_mfma_f32_16x16x32_bf16 v[2:5], v[212:215], v[34:37], v[184:187]
	v_mfma_f32_16x16x32_bf16 v[54:57], v[216:219], v[38:41], v[2:5]
	v_mfma_f32_16x16x32_bf16 v[2:5], v[220:223], v[34:37], v[102:105]
	v_mfma_f32_16x16x32_bf16 v[50:53], v[224:227], v[38:41], v[2:5]
	v_mfma_f32_16x16x32_bf16 v[2:5], v[212:215], v[82:85], v[188:191]
	v_mfma_f32_16x16x32_bf16 v[38:41], v[216:219], v[86:89], v[2:5]
	v_mfma_f32_16x16x32_bf16 v[2:5], v[220:223], v[82:85], v[192:195]
	v_mfma_f32_16x16x32_bf16 v[34:37], v[224:227], v[86:89], v[2:5]
	v_mfma_f32_16x16x32_bf16 v[2:5], v[212:215], v[94:97], v[196:199]
	v_mfma_f32_16x16x32_bf16 v[22:25], v[216:219], v[228:231], v[2:5]
	v_mfma_f32_16x16x32_bf16 v[2:5], v[220:223], v[94:97], v[200:203]
	v_mfma_f32_16x16x32_bf16 v[18:21], v[224:227], v[228:231], v[2:5]
	v_mfma_f32_16x16x32_bf16 v[2:5], v[212:215], v[232:235], v[204:207]
	v_mfma_f32_16x16x32_bf16 v[6:9], v[216:219], v[236:239], v[2:5]
	v_mfma_f32_16x16x32_bf16 v[2:5], v[220:223], v[232:235], v[208:211]
	v_mfma_f32_16x16x32_bf16 v[2:5], v[224:227], v[236:239], v[2:5]
	s_setprio 1
	s_barrier
	s_add_u32 s46, s46, 0x160180
	s_addc_u32 s47, s47, 0
	s_add_u32 s57, s58, 0x200
	s_addc_u32 s58, s59, 0
	s_mov_b32 s59, 0
; template <class Epi, class Sched, bool ALIGN_EPI = true, bool SP2 = true, bool FULLLINE = false, bool NOSTAGE = false, bool FP8 = false>
; __device__ __forceinline__ void gemm_phase(PG8_LAS unsigned char* lds, const Gemm g, const Sched& S, const Epi& E) {
;     ...
;         const bool has_next = S.next(ui + 1, nxt);
;         const char* nA = has_next ? PG8_ABASE(nxt) : cA; const char* nB = has_next ? PG8_BBASE(nxt) : cB;
.LBB0_2965:
	ds_read_b128 v[82:85], v1
	ds_read_b128 v[86:89], v1 offset:1024
	ds_read_b128 v[94:97], v1 offset:2048
	ds_read_b128 v[102:105], v1 offset:3072
	ds_read_b128 v[146:149], v168
	ds_read_b128 v[160:163], v168 offset:1024
	ds_read_b128 v[164:167], v168 offset:2048
	ds_read_b128 v[172:175], v168 offset:3072
	s_add_u32 s0, s46, 0xffea0080
	s_addc_u32 s1, s47, -1
	s_cmpk_eq_i32 s59, 0x54
	s_cselect_b32 s1, s11, s1
	s_cselect_b32 s0, s10, s0
	s_cselect_b32 s65, s45, s58
	s_cselect_b32 s64, s44, s57
	s_mov_b32 m0, s81
	v_lshl_add_u64 v[208:209], s[46:47], 0, v[154:155]
	ds_read_b128 v[176:179], v169
	ds_read_b128 v[180:183], v169 offset:1024
	ds_read_b128 v[184:187], v169 offset:2048
	ds_read_b128 v[188:191], v169 offset:3072
	ds_read_b128 v[192:195], v169 offset:4096
	ds_read_b128 v[196:199], v169 offset:5120
	ds_read_b128 v[200:203], v169 offset:6144
	ds_read_b128 v[204:207], v169 offset:7168
	global_load_lds_dwordx4 v[208:209], off
	v_lshl_add_u64 v[208:209], v[208:209], 0, s[30:31]
	s_mov_b32 m0, s82
	s_nop 0
	global_load_lds_dwordx4 v[208:209], off
	s_waitcnt vmcnt(8)
	s_waitcnt lgkmcnt(0)
	s_barrier
	s_waitcnt lgkmcnt(0)
	s_setprio 0
	v_mfma_f32_16x16x32_bf16 v[138:141], v[82:85], v[176:179], v[138:141]
	v_mfma_f32_16x16x32_bf16 v[134:137], v[94:97], v[176:179], v[134:137]
	v_mfma_f32_16x16x32_bf16 v[126:129], v[82:85], v[184:187], v[126:129]
	v_mfma_f32_16x16x32_bf16 v[122:125], v[94:97], v[184:187], v[122:125]
	v_mfma_f32_16x16x32_bf16 v[110:113], v[82:85], v[192:195], v[110:113]
	v_mfma_f32_16x16x32_bf16 v[106:109], v[94:97], v[192:195], v[106:109]
	v_mfma_f32_16x16x32_bf16 v[78:81], v[82:85], v[200:203], v[78:81]
	v_mfma_f32_16x16x32_bf16 v[74:77], v[94:97], v[200:203], v[74:77]
	v_mfma_f32_16x16x32_bf16 v[138:141], v[86:89], v[180:183], v[138:141]
	v_mfma_f32_16x16x32_bf16 v[134:137], v[102:105], v[180:183], v[134:137]
	v_mfma_f32_16x16x32_bf16 v[126:129], v[86:89], v[188:191], v[126:129]
	v_mfma_f32_16x16x32_bf16 v[122:125], v[102:105], v[188:191], v[122:125]
	v_mfma_f32_16x16x32_bf16 v[110:113], v[86:89], v[196:199], v[110:113]
	v_mfma_f32_16x16x32_bf16 v[106:109], v[102:105], v[196:199], v[106:109]
	v_mfma_f32_16x16x32_bf16 v[78:81], v[86:89], v[204:207], v[78:81]
	v_mfma_f32_16x16x32_bf16 v[74:77], v[102:105], v[204:207], v[74:77]
	v_mfma_f32_16x16x32_bf16 v[142:145], v[146:149], v[176:179], v[142:145]
	v_mfma_f32_16x16x32_bf16 v[130:133], v[164:167], v[176:179], v[130:133]
	v_mfma_f32_16x16x32_bf16 v[118:121], v[146:149], v[184:187], v[118:121]
	v_mfma_f32_16x16x32_bf16 v[114:117], v[164:167], v[184:187], v[114:117]
	v_mfma_f32_16x16x32_bf16 v[98:101], v[146:149], v[192:195], v[98:101]
	v_mfma_f32_16x16x32_bf16 v[90:93], v[164:167], v[192:195], v[90:93]
	v_mfma_f32_16x16x32_bf16 v[70:73], v[146:149], v[200:203], v[70:73]
	v_mfma_f32_16x16x32_bf16 v[66:69], v[164:167], v[200:203], v[66:69]
	v_mfma_f32_16x16x32_bf16 v[142:145], v[160:163], v[180:183], v[142:145]
	v_mfma_f32_16x16x32_bf16 v[130:133], v[172:175], v[180:183], v[130:133]
	v_mfma_f32_16x16x32_bf16 v[118:121], v[160:163], v[188:191], v[118:121]
	v_mfma_f32_16x16x32_bf16 v[114:117], v[172:175], v[188:191], v[114:117]
	v_mfma_f32_16x16x32_bf16 v[98:101], v[160:163], v[196:199], v[98:101]
	v_mfma_f32_16x16x32_bf16 v[90:93], v[172:175], v[196:199], v[90:93]
	v_mfma_f32_16x16x32_bf16 v[70:73], v[160:163], v[204:207], v[70:73]
	v_mfma_f32_16x16x32_bf16 v[66:69], v[172:175], v[204:207], v[66:69]
	s_setprio 1
	s_barrier
	s_mov_b32 m0, s83
	v_lshl_add_u64 v[208:209], s[64:65], 0, v[152:153]
	ds_read_b128 v[176:179], v169 offset:16384
	ds_read_b128 v[180:183], v169 offset:17408
	ds_read_b128 v[184:187], v169 offset:18432
	ds_read_b128 v[188:191], v169 offset:19456
	ds_read_b128 v[192:195], v169 offset:20480
	ds_read_b128 v[196:199], v169 offset:21504
	ds_read_b128 v[200:203], v169 offset:22528
	ds_read_b128 v[204:207], v169 offset:23552
	global_load_lds_dwordx4 v[208:209], off
	v_lshl_add_u64 v[210:211], v[208:209], 0, s[30:31]
	s_mov_b32 m0, s84
	s_nop 0
	global_load_lds_dwordx4 v[210:211], off
	v_lshl_add_u64 v[210:211], v[208:209], 0, s[34:35]
	s_mov_b32 m0, s85
	s_nop 0
	global_load_lds_dwordx4 v[210:211], off
	v_lshl_add_u64 v[210:211], v[208:209], 0, s[36:37]
	s_mov_b32 m0, s87
	s_nop 0
	global_load_lds_dwordx4 v[210:211], off
	v_lshl_add_u64 v[210:211], s[0:1], 0, v[150:151]
	s_mov_b32 m0, s53
	v_lshl_add_u64 v[212:213], v[210:211], 0, s[30:31]
	global_load_lds_dwordx4 v[210:211], off
	s_mov_b32 m0, s54
	s_nop 0
	global_load_lds_dwordx4 v[212:213], off
	s_waitcnt vmcnt(8)
	s_waitcnt lgkmcnt(0)
	s_barrier
	s_waitcnt lgkmcnt(0)
	s_setprio 0
	v_mfma_f32_16x16x32_bf16 v[62:65], v[82:85], v[176:179], v[62:65]
	v_mfma_f32_16x16x32_bf16 v[58:61], v[94:97], v[176:179], v[58:61]
	v_mfma_f32_16x16x32_bf16 v[46:49], v[82:85], v[184:187], v[46:49]
	v_mfma_f32_16x16x32_bf16 v[42:45], v[94:97], v[184:187], v[42:45]
	v_mfma_f32_16x16x32_bf16 v[30:33], v[82:85], v[192:195], v[30:33]
	v_mfma_f32_16x16x32_bf16 v[26:29], v[94:97], v[192:195], v[26:29]
	v_mfma_f32_16x16x32_bf16 v[14:17], v[82:85], v[200:203], v[14:17]
	v_mfma_f32_16x16x32_bf16 v[10:13], v[94:97], v[200:203], v[10:13]
	v_mfma_f32_16x16x32_bf16 v[62:65], v[86:89], v[180:183], v[62:65]
	v_mfma_f32_16x16x32_bf16 v[58:61], v[102:105], v[180:183], v[58:61]
	v_mfma_f32_16x16x32_bf16 v[46:49], v[86:89], v[188:191], v[46:49]
	v_mfma_f32_16x16x32_bf16 v[42:45], v[102:105], v[188:191], v[42:45]
	v_mfma_f32_16x16x32_bf16 v[30:33], v[86:89], v[196:199], v[30:33]
	v_mfma_f32_16x16x32_bf16 v[26:29], v[102:105], v[196:199], v[26:29]
	v_mfma_f32_16x16x32_bf16 v[14:17], v[86:89], v[204:207], v[14:17]
	v_mfma_f32_16x16x32_bf16 v[10:13], v[102:105], v[204:207], v[10:13]
	v_mfma_f32_16x16x32_bf16 v[54:57], v[146:149], v[176:179], v[54:57]
	v_mfma_f32_16x16x32_bf16 v[50:53], v[164:167], v[176:179], v[50:53]
	v_mfma_f32_16x16x32_bf16 v[38:41], v[146:149], v[184:187], v[38:41]
	v_mfma_f32_16x16x32_bf16 v[34:37], v[164:167], v[184:187], v[34:37]
	v_mfma_f32_16x16x32_bf16 v[22:25], v[146:149], v[192:195], v[22:25]
	v_mfma_f32_16x16x32_bf16 v[18:21], v[164:167], v[192:195], v[18:21]
	v_mfma_f32_16x16x32_bf16 v[6:9], v[146:149], v[200:203], v[6:9]
	v_mfma_f32_16x16x32_bf16 v[2:5], v[164:167], v[200:203], v[2:5]
	v_mfma_f32_16x16x32_bf16 v[54:57], v[160:163], v[180:183], v[54:57]
	v_mfma_f32_16x16x32_bf16 v[50:53], v[172:175], v[180:183], v[50:53]
	v_mfma_f32_16x16x32_bf16 v[38:41], v[160:163], v[188:191], v[38:41]
	v_mfma_f32_16x16x32_bf16 v[34:37], v[172:175], v[188:191], v[34:37]
	v_mfma_f32_16x16x32_bf16 v[22:25], v[160:163], v[196:199], v[22:25]
	v_mfma_f32_16x16x32_bf16 v[18:21], v[172:175], v[196:199], v[18:21]
	v_mfma_f32_16x16x32_bf16 v[6:9], v[160:163], v[204:207], v[6:9]
	v_mfma_f32_16x16x32_bf16 v[2:5], v[172:175], v[204:207], v[2:5]
	s_setprio 1
	s_barrier
	ds_read_b128 v[82:85], v170
	ds_read_b128 v[86:89], v170 offset:1024
	ds_read_b128 v[94:97], v170 offset:2048
	ds_read_b128 v[102:105], v170 offset:3072
	ds_read_b128 v[146:149], v171
	ds_read_b128 v[160:163], v171 offset:1024
	ds_read_b128 v[164:167], v171 offset:2048
	ds_read_b128 v[172:175], v171 offset:3072
	s_mov_b32 m0, s55
	v_lshl_add_u64 v[212:213], v[210:211], 0, s[34:35]
	ds_read_b128 v[176:179], v169 offset:32768
	ds_read_b128 v[180:183], v169 offset:33792
	ds_read_b128 v[184:187], v169 offset:34816
	ds_read_b128 v[188:191], v169 offset:35840
	ds_read_b128 v[192:195], v169 offset:36864
	ds_read_b128 v[196:199], v169 offset:37888
	ds_read_b128 v[200:203], v169 offset:38912
	ds_read_b128 v[204:207], v169 offset:39936
	global_load_lds_dwordx4 v[212:213], off
	v_lshl_add_u64 v[212:213], v[210:211], 0, s[36:37]
	s_mov_b32 m0, s62
	s_nop 0
	global_load_lds_dwordx4 v[212:213], off
	s_waitcnt vmcnt(8)
	s_waitcnt lgkmcnt(0)
	s_barrier
	s_waitcnt lgkmcnt(0)
	s_setprio 0
	v_mfma_f32_16x16x32_bf16 v[138:141], v[82:85], v[176:179], v[138:141]
	v_mfma_f32_16x16x32_bf16 v[134:137], v[94:97], v[176:179], v[134:137]
	v_mfma_f32_16x16x32_bf16 v[126:129], v[82:85], v[184:187], v[126:129]
	v_mfma_f32_16x16x32_bf16 v[122:125], v[94:97], v[184:187], v[122:125]
	v_mfma_f32_16x16x32_bf16 v[110:113], v[82:85], v[192:195], v[110:113]
	v_mfma_f32_16x16x32_bf16 v[106:109], v[94:97], v[192:195], v[106:109]
	v_mfma_f32_16x16x32_bf16 v[78:81], v[82:85], v[200:203], v[78:81]
	v_mfma_f32_16x16x32_bf16 v[74:77], v[94:97], v[200:203], v[74:77]
	v_mfma_f32_16x16x32_bf16 v[138:141], v[86:89], v[180:183], v[138:141]
	v_mfma_f32_16x16x32_bf16 v[134:137], v[102:105], v[180:183], v[134:137]
	v_mfma_f32_16x16x32_bf16 v[126:129], v[86:89], v[188:191], v[126:129]
	v_mfma_f32_16x16x32_bf16 v[122:125], v[102:105], v[188:191], v[122:125]
	v_mfma_f32_16x16x32_bf16 v[110:113], v[86:89], v[196:199], v[110:113]
	v_mfma_f32_16x16x32_bf16 v[106:109], v[102:105], v[196:199], v[106:109]
	v_mfma_f32_16x16x32_bf16 v[78:81], v[86:89], v[204:207], v[78:81]
	v_mfma_f32_16x16x32_bf16 v[74:77], v[102:105], v[204:207], v[74:77]
	v_mfma_f32_16x16x32_bf16 v[142:145], v[146:149], v[176:179], v[142:145]
	v_mfma_f32_16x16x32_bf16 v[130:133], v[164:167], v[176:179], v[130:133]
	v_mfma_f32_16x16x32_bf16 v[118:121], v[146:149], v[184:187], v[118:121]
	v_mfma_f32_16x16x32_bf16 v[114:117], v[164:167], v[184:187], v[114:117]
	v_mfma_f32_16x16x32_bf16 v[98:101], v[146:149], v[192:195], v[98:101]
	v_mfma_f32_16x16x32_bf16 v[90:93], v[164:167], v[192:195], v[90:93]
	v_mfma_f32_16x16x32_bf16 v[70:73], v[146:149], v[200:203], v[70:73]
	v_mfma_f32_16x16x32_bf16 v[66:69], v[164:167], v[200:203], v[66:69]
	v_mfma_f32_16x16x32_bf16 v[142:145], v[160:163], v[180:183], v[142:145]
	v_mfma_f32_16x16x32_bf16 v[130:133], v[172:175], v[180:183], v[130:133]
	v_mfma_f32_16x16x32_bf16 v[118:121], v[160:163], v[188:191], v[118:121]
	v_mfma_f32_16x16x32_bf16 v[114:117], v[172:175], v[188:191], v[114:117]
	v_mfma_f32_16x16x32_bf16 v[98:101], v[160:163], v[196:199], v[98:101]
	v_mfma_f32_16x16x32_bf16 v[90:93], v[172:175], v[196:199], v[90:93]
	v_mfma_f32_16x16x32_bf16 v[70:73], v[160:163], v[204:207], v[70:73]
	v_mfma_f32_16x16x32_bf16 v[66:69], v[172:175], v[204:207], v[66:69]
	s_setprio 1
	s_barrier
; #define PG8_WAIT_V(n) asm volatile("s_waitcnt vmcnt(" #n ")" ::: "memory")
; template <class Epi, class Sched, bool ALIGN_EPI = true, bool SP2 = true, bool FULLLINE = false, bool NOSTAGE = false, bool FP8 = false>
; __device__ __forceinline__ void gemm_phase(PG8_LAS unsigned char* lds, const Gemm g, const Sched& S, const Epi& E) {
;     ...
;         static_assert(SP2, "only the SP2 loop is kept");
;         { const int t = 0; if constexpr (Epi::NST == 16) PG8_ITER(PG8_WAIT_V(24)); else if constexpr (Epi::NST == 8) PG8_ITER(PG8_WAIT_V(16)); else PG8_ITER(PG8_WAIT_V(8)); }
;         for (int t = 2; t < nt; t += 2) PG8_ITER(PG8_WAIT_V(8));
	s_mov_b32 m0, s50
	v_lshl_add_u64 v[212:213], v[208:209], 0, s[38:39]
	ds_read_b128 v[176:179], v169 offset:49152
	ds_read_b128 v[180:183], v169 offset:50176
	ds_read_b128 v[184:187], v169 offset:51200
	ds_read_b128 v[188:191], v169 offset:52224
	ds_read_b128 v[192:195], v169 offset:53248
	ds_read_b128 v[196:199], v169 offset:54272
	ds_read_b128 v[200:203], v169 offset:55296
	ds_read_b128 v[204:207], v169 offset:56320
	global_load_lds_dwordx4 v[212:213], off
	v_lshl_add_u64 v[212:213], v[208:209], 0, s[40:41]
	s_mov_b32 m0, s51
	s_nop 0
	global_load_lds_dwordx4 v[212:213], off
	v_lshl_add_u64 v[212:213], v[208:209], 0, s[14:15]
	s_mov_b32 m0, s33
	v_lshl_add_u64 v[208:209], v[208:209], 0, s[16:17]
	global_load_lds_dwordx4 v[212:213], off
	s_mov_b32 m0, s56
	s_nop 0
	global_load_lds_dwordx4 v[208:209], off
	v_lshl_add_u64 v[208:209], v[210:211], 0, s[38:39]
	s_mov_b32 m0, s63
	s_nop 0
	global_load_lds_dwordx4 v[208:209], off
	v_lshl_add_u64 v[208:209], v[210:211], 0, s[40:41]
	s_mov_b32 m0, s66
	s_nop 0
	global_load_lds_dwordx4 v[208:209], off
	s_waitcnt vmcnt(8)
	s_waitcnt lgkmcnt(0)
	s_barrier
	s_waitcnt lgkmcnt(0)
	s_setprio 0
	v_mfma_f32_16x16x32_bf16 v[62:65], v[82:85], v[176:179], v[62:65]
	v_mfma_f32_16x16x32_bf16 v[58:61], v[94:97], v[176:179], v[58:61]
	v_mfma_f32_16x16x32_bf16 v[46:49], v[82:85], v[184:187], v[46:49]
	v_mfma_f32_16x16x32_bf16 v[42:45], v[94:97], v[184:187], v[42:45]
	v_mfma_f32_16x16x32_bf16 v[30:33], v[82:85], v[192:195], v[30:33]
	v_mfma_f32_16x16x32_bf16 v[26:29], v[94:97], v[192:195], v[26:29]
	v_mfma_f32_16x16x32_bf16 v[14:17], v[82:85], v[200:203], v[14:17]
	v_mfma_f32_16x16x32_bf16 v[10:13], v[94:97], v[200:203], v[10:13]
	v_mfma_f32_16x16x32_bf16 v[62:65], v[86:89], v[180:183], v[62:65]
	v_mfma_f32_16x16x32_bf16 v[58:61], v[102:105], v[180:183], v[58:61]
	v_mfma_f32_16x16x32_bf16 v[46:49], v[86:89], v[188:191], v[46:49]
	v_mfma_f32_16x16x32_bf16 v[42:45], v[102:105], v[188:191], v[42:45]
	v_mfma_f32_16x16x32_bf16 v[30:33], v[86:89], v[196:199], v[30:33]
	v_mfma_f32_16x16x32_bf16 v[26:29], v[102:105], v[196:199], v[26:29]
	v_mfma_f32_16x16x32_bf16 v[14:17], v[86:89], v[204:207], v[14:17]
	v_mfma_f32_16x16x32_bf16 v[10:13], v[102:105], v[204:207], v[10:13]
	v_mfma_f32_16x16x32_bf16 v[54:57], v[146:149], v[176:179], v[54:57]
	v_mfma_f32_16x16x32_bf16 v[50:53], v[164:167], v[176:179], v[50:53]
	v_mfma_f32_16x16x32_bf16 v[38:41], v[146:149], v[184:187], v[38:41]
	v_mfma_f32_16x16x32_bf16 v[34:37], v[164:167], v[184:187], v[34:37]
	v_mfma_f32_16x16x32_bf16 v[22:25], v[146:149], v[192:195], v[22:25]
	v_mfma_f32_16x16x32_bf16 v[18:21], v[164:167], v[192:195], v[18:21]
	v_mfma_f32_16x16x32_bf16 v[6:9], v[146:149], v[200:203], v[6:9]
	v_mfma_f32_16x16x32_bf16 v[2:5], v[164:167], v[200:203], v[2:5]
	v_mfma_f32_16x16x32_bf16 v[54:57], v[160:163], v[180:183], v[54:57]
	v_mfma_f32_16x16x32_bf16 v[50:53], v[172:175], v[180:183], v[50:53]
	v_mfma_f32_16x16x32_bf16 v[38:41], v[160:163], v[188:191], v[38:41]
	v_mfma_f32_16x16x32_bf16 v[34:37], v[172:175], v[188:191], v[34:37]
	v_mfma_f32_16x16x32_bf16 v[22:25], v[160:163], v[196:199], v[22:25]
	v_mfma_f32_16x16x32_bf16 v[18:21], v[172:175], v[196:199], v[18:21]
	v_mfma_f32_16x16x32_bf16 v[6:9], v[160:163], v[204:207], v[6:9]
	v_mfma_f32_16x16x32_bf16 v[2:5], v[172:175], v[204:207], v[2:5]
	s_setprio 1
	s_barrier
	s_add_i32 s59, s59, 2
	s_add_u32 s46, s46, 0x100
	s_addc_u32 s47, s47, 0
	s_add_u32 s57, s57, 0x100
	s_addc_u32 s58, s58, 0
	s_cmpk_gt_u32 s59, 0x55
	s_cbranch_scc0 .LBB0_2965
	s_and_b64 vcc, exec, s[12:13]
	s_cbranch_vccz .LBB0_2968
	s_barrier
